# GEMM K-loops: priority inverted (raised during the LDS/DMA load segments, lowered during MFMA clusters)
# baseline (speedup 1.0000x reference)
.LBB0_155:
	ds_read_b128 v[154:157], v150
	ds_read_b128 v[158:161], v150 offset:1024
	ds_read_b128 v[162:165], v150 offset:2048
	ds_read_b128 v[166:169], v150 offset:3072
	s_add_u32 s26, s20, 0xfffc0080
	s_addc_u32 s27, s21, -1
	s_cmp_eq_u32 s86, 12
	s_cselect_b32 s29, s15, s27
	s_cselect_b32 s28, s82, s26
	s_cselect_b32 s27, s13, s85
	s_cselect_b32 s26, s83, s84
	v_lshl_add_u64 v[202:203], s[20:21], 0, v[138:139]
	s_add_i32 m0, s11, 0xc000
	ds_read_b128 v[170:173], v151
	ds_read_b128 v[174:177], v151 offset:1024
	ds_read_b128 v[178:181], v151 offset:2048
	ds_read_b128 v[182:185], v151 offset:3072
	ds_read_b128 v[186:189], v151 offset:4096
	ds_read_b128 v[190:193], v151 offset:5120
	ds_read_b128 v[194:197], v151 offset:6144
	ds_read_b128 v[198:201], v151 offset:7168
	global_load_lds_dwordx4 v[202:203], off
	v_lshl_add_u64 v[202:203], s[20:21], 0, v[140:141]
	s_add_i32 m0, s11, 0xe000
	s_nop 0
	global_load_lds_dwordx4 v[202:203], off
	s_waitcnt lgkmcnt(8)
	s_barrier
	s_waitcnt lgkmcnt(0)
	s_setprio 0
	s_waitcnt lgkmcnt(0)
	v_mfma_f32_16x16x32_bf16 v[124:127], v[154:157], v[170:173], v[124:127]
	v_mfma_f32_16x16x32_bf16 v[120:123], v[162:165], v[170:173], v[120:123]
	v_mfma_f32_16x16x32_bf16 v[116:119], v[154:157], v[178:181], v[116:119]
	v_mfma_f32_16x16x32_bf16 v[112:115], v[162:165], v[178:181], v[112:115]
	v_mfma_f32_16x16x32_bf16 v[100:103], v[154:157], v[186:189], v[100:103]
	v_mfma_f32_16x16x32_bf16 v[96:99], v[162:165], v[186:189], v[96:99]
	v_mfma_f32_16x16x32_bf16 v[84:87], v[154:157], v[194:197], v[84:87]
	v_mfma_f32_16x16x32_bf16 v[80:83], v[162:165], v[194:197], v[80:83]
	v_mfma_f32_16x16x32_bf16 v[124:127], v[158:161], v[174:177], v[124:127]
	v_mfma_f32_16x16x32_bf16 v[120:123], v[166:169], v[174:177], v[120:123]
	v_mfma_f32_16x16x32_bf16 v[116:119], v[158:161], v[182:185], v[116:119]
	v_mfma_f32_16x16x32_bf16 v[112:115], v[166:169], v[182:185], v[112:115]
	v_mfma_f32_16x16x32_bf16 v[100:103], v[158:161], v[190:193], v[100:103]
	v_mfma_f32_16x16x32_bf16 v[96:99], v[166:169], v[190:193], v[96:99]
	v_mfma_f32_16x16x32_bf16 v[84:87], v[158:161], v[198:201], v[84:87]
	v_mfma_f32_16x16x32_bf16 v[80:83], v[166:169], v[198:201], v[80:83]
	s_setprio 1
	s_barrier
	s_add_i32 s87, s72, s34
	v_lshl_add_u64 v[218:219], s[26:27], 0, v[134:135]
	s_mov_b32 m0, s87
	ds_read_b128 v[202:205], v152
	ds_read_b128 v[206:209], v152 offset:1024
	ds_read_b128 v[210:213], v152 offset:2048
	ds_read_b128 v[214:217], v152 offset:3072
	global_load_lds_dwordx4 v[218:219], off
	v_lshl_add_u64 v[220:221], s[26:27], 0, v[130:131]
	s_add_i32 m0, s87, 0x2000
	s_nop 0
	global_load_lds_dwordx4 v[220:221], off
	s_barrier
	s_waitcnt lgkmcnt(0)
	s_setprio 0
	s_waitcnt lgkmcnt(0)
	v_mfma_f32_16x16x32_bf16 v[108:111], v[202:205], v[170:173], v[108:111]
	v_mfma_f32_16x16x32_bf16 v[104:107], v[210:213], v[170:173], v[104:107]
	v_mfma_f32_16x16x32_bf16 v[92:95], v[202:205], v[178:181], v[92:95]
	v_mfma_f32_16x16x32_bf16 v[88:91], v[210:213], v[178:181], v[88:91]
	v_mfma_f32_16x16x32_bf16 v[76:79], v[202:205], v[186:189], v[76:79]
	v_mfma_f32_16x16x32_bf16 v[72:75], v[210:213], v[186:189], v[72:75]
	v_mfma_f32_16x16x32_bf16 v[68:71], v[202:205], v[194:197], v[68:71]
	v_mfma_f32_16x16x32_bf16 v[64:67], v[210:213], v[194:197], v[64:67]
	v_mfma_f32_16x16x32_bf16 v[108:111], v[206:209], v[174:177], v[108:111]
	v_mfma_f32_16x16x32_bf16 v[104:107], v[214:217], v[174:177], v[104:107]
	v_mfma_f32_16x16x32_bf16 v[92:95], v[206:209], v[182:185], v[92:95]
	v_mfma_f32_16x16x32_bf16 v[88:91], v[214:217], v[182:185], v[88:91]
	v_mfma_f32_16x16x32_bf16 v[76:79], v[206:209], v[190:193], v[76:79]
	v_mfma_f32_16x16x32_bf16 v[72:75], v[214:217], v[190:193], v[72:75]
	v_mfma_f32_16x16x32_bf16 v[68:71], v[206:209], v[198:201], v[68:71]
	v_mfma_f32_16x16x32_bf16 v[64:67], v[214:217], v[198:201], v[64:67]
	s_setprio 1
	s_mov_b32 m0, s11
	v_lshl_add_u64 v[222:223], s[28:29], 0, v[136:137]
	s_barrier
	ds_read_b128 v[170:173], v151 offset:16384
	ds_read_b128 v[174:177], v151 offset:17408
	ds_read_b128 v[178:181], v151 offset:18432
	ds_read_b128 v[182:185], v151 offset:19456
	ds_read_b128 v[186:189], v151 offset:20480
	ds_read_b128 v[190:193], v151 offset:21504
	ds_read_b128 v[194:197], v151 offset:22528
	ds_read_b128 v[198:201], v151 offset:23552
	global_load_lds_dwordx4 v[222:223], off
	v_lshl_add_u64 v[224:225], s[28:29], 0, v[132:133]
	s_mov_b32 m0, s35
	s_nop 0
	global_load_lds_dwordx4 v[224:225], off
	s_barrier
	s_waitcnt lgkmcnt(0)
	s_setprio 0
	s_waitcnt lgkmcnt(0)
	v_mfma_f32_16x16x32_bf16 v[60:63], v[154:157], v[170:173], v[60:63]
	v_mfma_f32_16x16x32_bf16 v[56:59], v[162:165], v[170:173], v[56:59]
	v_mfma_f32_16x16x32_bf16 v[52:55], v[154:157], v[178:181], v[52:55]
	v_mfma_f32_16x16x32_bf16 v[48:51], v[162:165], v[178:181], v[48:51]
	v_mfma_f32_16x16x32_bf16 v[36:39], v[154:157], v[186:189], v[36:39]
	v_mfma_f32_16x16x32_bf16 v[32:35], v[162:165], v[186:189], v[32:35]
	v_mfma_f32_16x16x32_bf16 v[20:23], v[154:157], v[194:197], v[20:23]
	v_mfma_f32_16x16x32_bf16 v[16:19], v[162:165], v[194:197], v[16:19]
	v_mfma_f32_16x16x32_bf16 v[60:63], v[158:161], v[174:177], v[60:63]
	v_mfma_f32_16x16x32_bf16 v[56:59], v[166:169], v[174:177], v[56:59]
	v_mfma_f32_16x16x32_bf16 v[52:55], v[158:161], v[182:185], v[52:55]
	v_mfma_f32_16x16x32_bf16 v[48:51], v[166:169], v[182:185], v[48:51]
	v_mfma_f32_16x16x32_bf16 v[36:39], v[158:161], v[190:193], v[36:39]
	v_mfma_f32_16x16x32_bf16 v[32:35], v[166:169], v[190:193], v[32:35]
	v_mfma_f32_16x16x32_bf16 v[20:23], v[158:161], v[198:201], v[20:23]
	v_mfma_f32_16x16x32_bf16 v[16:19], v[166:169], v[198:201], v[16:19]
	s_setprio 1
	s_barrier
	s_add_u32 s88, s26, 0x40000
	s_addc_u32 s89, s27, 0
	s_add_i32 s87, s73, s34
	v_lshl_add_u64 v[154:155], s[88:89], 0, v[134:135]
	s_mov_b32 m0, s87
	s_nop 0
	global_load_lds_dwordx4 v[154:155], off
	v_lshl_add_u64 v[154:155], s[88:89], 0, v[130:131]
	s_add_i32 m0, s87, 0x2000
	s_nop 0
	global_load_lds_dwordx4 v[154:155], off
	s_waitcnt vmcnt(6)
	s_barrier
	s_setprio 0
	v_mfma_f32_16x16x32_bf16 v[44:47], v[202:205], v[170:173], v[44:47]
	v_mfma_f32_16x16x32_bf16 v[40:43], v[210:213], v[170:173], v[40:43]
	v_mfma_f32_16x16x32_bf16 v[28:31], v[202:205], v[178:181], v[28:31]
	v_mfma_f32_16x16x32_bf16 v[24:27], v[210:213], v[178:181], v[24:27]
	v_mfma_f32_16x16x32_bf16 v[12:15], v[202:205], v[186:189], v[12:15]
	v_mfma_f32_16x16x32_bf16 v[8:11], v[210:213], v[186:189], v[8:11]
	v_mfma_f32_16x16x32_bf16 v[4:7], v[202:205], v[194:197], v[4:7]
	v_mfma_f32_16x16x32_bf16 v[0:3], v[210:213], v[194:197], v[0:3]
	v_mfma_f32_16x16x32_bf16 v[44:47], v[206:209], v[174:177], v[44:47]
	v_mfma_f32_16x16x32_bf16 v[40:43], v[214:217], v[174:177], v[40:43]
	v_mfma_f32_16x16x32_bf16 v[28:31], v[206:209], v[182:185], v[28:31]
	v_mfma_f32_16x16x32_bf16 v[24:27], v[214:217], v[182:185], v[24:27]
	v_mfma_f32_16x16x32_bf16 v[12:15], v[206:209], v[190:193], v[12:15]
	v_mfma_f32_16x16x32_bf16 v[8:11], v[214:217], v[190:193], v[8:11]
	v_mfma_f32_16x16x32_bf16 v[4:7], v[206:209], v[198:201], v[4:7]
	v_mfma_f32_16x16x32_bf16 v[0:3], v[214:217], v[198:201], v[0:3]
	s_setprio 1
	s_add_i32 s87, 0, 0x18000
	v_add_u32_e32 v153, s87, v148
	s_barrier
	ds_read_b128 v[154:157], v153
	ds_read_b128 v[158:161], v153 offset:1024
	ds_read_b128 v[162:165], v153 offset:2048
	ds_read_b128 v[166:169], v153 offset:3072
	s_add_u32 s28, s28, 0x40000
	s_addc_u32 s29, s29, 0
	s_mov_b32 m0, s54
	v_lshl_add_u64 v[202:203], s[28:29], 0, v[136:137]
	ds_read_b128 v[170:173], v151 offset:32768
	ds_read_b128 v[174:177], v151 offset:33792
	ds_read_b128 v[178:181], v151 offset:34816
	ds_read_b128 v[182:185], v151 offset:35840
	ds_read_b128 v[186:189], v151 offset:36864
	ds_read_b128 v[190:193], v151 offset:37888
	ds_read_b128 v[194:197], v151 offset:38912
	ds_read_b128 v[198:201], v151 offset:39936
	global_load_lds_dwordx4 v[202:203], off
	v_lshl_add_u64 v[202:203], s[28:29], 0, v[132:133]
	s_mov_b32 m0, s55
	s_nop 0
	global_load_lds_dwordx4 v[202:203], off
	s_waitcnt lgkmcnt(8)
	s_barrier
	s_waitcnt lgkmcnt(0)
	s_setprio 0
	s_waitcnt lgkmcnt(0)
	v_mfma_f32_16x16x32_bf16 v[124:127], v[154:157], v[170:173], v[124:127]
	v_mfma_f32_16x16x32_bf16 v[120:123], v[162:165], v[170:173], v[120:123]
	v_mfma_f32_16x16x32_bf16 v[116:119], v[154:157], v[178:181], v[116:119]
	v_mfma_f32_16x16x32_bf16 v[112:115], v[162:165], v[178:181], v[112:115]
	v_mfma_f32_16x16x32_bf16 v[100:103], v[154:157], v[186:189], v[100:103]
	v_mfma_f32_16x16x32_bf16 v[96:99], v[162:165], v[186:189], v[96:99]
	v_mfma_f32_16x16x32_bf16 v[84:87], v[154:157], v[194:197], v[84:87]
	v_mfma_f32_16x16x32_bf16 v[80:83], v[162:165], v[194:197], v[80:83]
	v_mfma_f32_16x16x32_bf16 v[124:127], v[158:161], v[174:177], v[124:127]
	v_mfma_f32_16x16x32_bf16 v[120:123], v[166:169], v[174:177], v[120:123]
	v_mfma_f32_16x16x32_bf16 v[116:119], v[158:161], v[182:185], v[116:119]
	v_mfma_f32_16x16x32_bf16 v[112:115], v[166:169], v[182:185], v[112:115]
	v_mfma_f32_16x16x32_bf16 v[100:103], v[158:161], v[190:193], v[100:103]
	v_mfma_f32_16x16x32_bf16 v[96:99], v[166:169], v[190:193], v[96:99]
	v_mfma_f32_16x16x32_bf16 v[84:87], v[158:161], v[198:201], v[84:87]
	v_mfma_f32_16x16x32_bf16 v[80:83], v[166:169], v[198:201], v[80:83]
	s_setprio 1
	s_barrier
	s_add_i32 s28, 0, 0x1c000
	s_add_i32 s29, s87, s34
	v_add_u32_e32 v153, s28, v148
	v_lshl_add_u64 v[218:219], v[218:219], 0, s[8:9]
	s_mov_b32 m0, s29
	ds_read_b128 v[202:205], v153
	ds_read_b128 v[206:209], v153 offset:1024
	ds_read_b128 v[210:213], v153 offset:2048
	ds_read_b128 v[214:217], v153 offset:3072
	global_load_lds_dwordx4 v[218:219], off
	v_lshl_add_u64 v[218:219], v[220:221], 0, s[8:9]
	s_add_i32 m0, s29, 0x2000
	s_nop 0
	global_load_lds_dwordx4 v[218:219], off
	s_barrier
	s_waitcnt lgkmcnt(0)
	s_setprio 0
	s_waitcnt lgkmcnt(0)
	v_mfma_f32_16x16x32_bf16 v[108:111], v[202:205], v[170:173], v[108:111]
	v_mfma_f32_16x16x32_bf16 v[104:107], v[210:213], v[170:173], v[104:107]
	v_mfma_f32_16x16x32_bf16 v[92:95], v[202:205], v[178:181], v[92:95]
	v_mfma_f32_16x16x32_bf16 v[88:91], v[210:213], v[178:181], v[88:91]
	v_mfma_f32_16x16x32_bf16 v[76:79], v[202:205], v[186:189], v[76:79]
	v_mfma_f32_16x16x32_bf16 v[72:75], v[210:213], v[186:189], v[72:75]
	v_mfma_f32_16x16x32_bf16 v[68:71], v[202:205], v[194:197], v[68:71]
	v_mfma_f32_16x16x32_bf16 v[64:67], v[210:213], v[194:197], v[64:67]
	v_mfma_f32_16x16x32_bf16 v[108:111], v[206:209], v[174:177], v[108:111]
	v_mfma_f32_16x16x32_bf16 v[104:107], v[214:217], v[174:177], v[104:107]
	v_mfma_f32_16x16x32_bf16 v[92:95], v[206:209], v[182:185], v[92:95]
	v_mfma_f32_16x16x32_bf16 v[88:91], v[214:217], v[182:185], v[88:91]
	v_mfma_f32_16x16x32_bf16 v[76:79], v[206:209], v[190:193], v[76:79]
	v_mfma_f32_16x16x32_bf16 v[72:75], v[214:217], v[190:193], v[72:75]
	v_mfma_f32_16x16x32_bf16 v[68:71], v[206:209], v[198:201], v[68:71]
	v_mfma_f32_16x16x32_bf16 v[64:67], v[214:217], v[198:201], v[64:67]
	s_setprio 1
	s_mov_b32 m0, s57
	v_lshl_add_u64 v[218:219], v[222:223], 0, s[8:9]
	s_barrier
	ds_read_b128 v[170:173], v151 offset:49152
	ds_read_b128 v[174:177], v151 offset:50176
	ds_read_b128 v[178:181], v151 offset:51200
	ds_read_b128 v[182:185], v151 offset:52224
	ds_read_b128 v[186:189], v151 offset:53248
	ds_read_b128 v[190:193], v151 offset:54272
	ds_read_b128 v[194:197], v151 offset:55296
	ds_read_b128 v[198:201], v151 offset:56320
	global_load_lds_dwordx4 v[218:219], off
	v_lshl_add_u64 v[218:219], v[224:225], 0, s[8:9]
	s_mov_b32 m0, s70
	s_nop 0
	global_load_lds_dwordx4 v[218:219], off
	s_barrier
	s_waitcnt lgkmcnt(0)
	s_setprio 0
	s_waitcnt lgkmcnt(0)
	v_mfma_f32_16x16x32_bf16 v[60:63], v[154:157], v[170:173], v[60:63]
	v_mfma_f32_16x16x32_bf16 v[56:59], v[162:165], v[170:173], v[56:59]
	v_mfma_f32_16x16x32_bf16 v[52:55], v[154:157], v[178:181], v[52:55]
	v_mfma_f32_16x16x32_bf16 v[48:51], v[162:165], v[178:181], v[48:51]
	v_mfma_f32_16x16x32_bf16 v[36:39], v[154:157], v[186:189], v[36:39]
	v_mfma_f32_16x16x32_bf16 v[32:35], v[162:165], v[186:189], v[32:35]
	v_mfma_f32_16x16x32_bf16 v[20:23], v[154:157], v[194:197], v[20:23]
	v_mfma_f32_16x16x32_bf16 v[16:19], v[162:165], v[194:197], v[16:19]
	v_mfma_f32_16x16x32_bf16 v[60:63], v[158:161], v[174:177], v[60:63]
	v_mfma_f32_16x16x32_bf16 v[56:59], v[166:169], v[174:177], v[56:59]
	v_mfma_f32_16x16x32_bf16 v[52:55], v[158:161], v[182:185], v[52:55]
	v_mfma_f32_16x16x32_bf16 v[48:51], v[166:169], v[182:185], v[48:51]
	v_mfma_f32_16x16x32_bf16 v[36:39], v[158:161], v[190:193], v[36:39]
	v_mfma_f32_16x16x32_bf16 v[32:35], v[166:169], v[190:193], v[32:35]
	v_mfma_f32_16x16x32_bf16 v[20:23], v[158:161], v[198:201], v[20:23]
	v_mfma_f32_16x16x32_bf16 v[16:19], v[166:169], v[198:201], v[16:19]
	s_setprio 1
	s_barrier
	s_add_u32 s26, s26, 0x40080
	s_addc_u32 s27, s27, 0
	s_add_i32 s28, s28, s34
	v_lshl_add_u64 v[154:155], s[26:27], 0, v[134:135]
	s_mov_b32 m0, s28
	s_nop 0
	global_load_lds_dwordx4 v[154:155], off
	v_lshl_add_u64 v[154:155], s[26:27], 0, v[130:131]
	s_add_i32 m0, s28, 0x2000
	s_nop 0
	global_load_lds_dwordx4 v[154:155], off
	s_waitcnt vmcnt(6)
	s_barrier
	s_setprio 0
	v_mfma_f32_16x16x32_bf16 v[44:47], v[202:205], v[170:173], v[44:47]
	v_mfma_f32_16x16x32_bf16 v[40:43], v[210:213], v[170:173], v[40:43]
	v_mfma_f32_16x16x32_bf16 v[28:31], v[202:205], v[178:181], v[28:31]
	v_mfma_f32_16x16x32_bf16 v[24:27], v[210:213], v[178:181], v[24:27]
	v_mfma_f32_16x16x32_bf16 v[12:15], v[202:205], v[186:189], v[12:15]
	v_mfma_f32_16x16x32_bf16 v[8:11], v[210:213], v[186:189], v[8:11]
	v_mfma_f32_16x16x32_bf16 v[4:7], v[202:205], v[194:197], v[4:7]
	v_mfma_f32_16x16x32_bf16 v[0:3], v[210:213], v[194:197], v[0:3]
	v_mfma_f32_16x16x32_bf16 v[44:47], v[206:209], v[174:177], v[44:47]
	v_mfma_f32_16x16x32_bf16 v[40:43], v[214:217], v[174:177], v[40:43]
	v_mfma_f32_16x16x32_bf16 v[28:31], v[206:209], v[182:185], v[28:31]
	v_mfma_f32_16x16x32_bf16 v[24:27], v[214:217], v[182:185], v[24:27]
	v_mfma_f32_16x16x32_bf16 v[12:15], v[206:209], v[190:193], v[12:15]
	v_mfma_f32_16x16x32_bf16 v[8:11], v[214:217], v[190:193], v[8:11]
	v_mfma_f32_16x16x32_bf16 v[4:7], v[206:209], v[198:201], v[4:7]
	v_mfma_f32_16x16x32_bf16 v[0:3], v[214:217], v[198:201], v[0:3]
	s_setprio 1
	s_add_i32 s86, s86, 2
	s_add_u32 s20, s20, 0x100
	s_addc_u32 s21, s21, 0
	s_add_u32 s84, s84, 0x100
	s_addc_u32 s85, s85, 0
	s_cmp_gt_u32 s86, 13
	s_barrier
	s_cbranch_scc0 .LBB0_155
	v_lshl_add_u32 v153, s10, 8, v147
	v_lshl_or_b32 v154, s75, 8, v149
	v_mov_b64_e32 v[156:157], s[46:47]
	v_ashrrev_i32_e32 v155, 31, v154
	v_cvt_pk_bf16_f32 v68, v68, v69
	v_cvt_pk_bf16_f32 v69, v70, v71
	v_cvt_pk_bf16_f32 v70, v64, v65
	v_add_u32_e32 v64, 0x80, v153
	v_mad_i64_i32 v[158:159], s[20:21], v153, s74, v[156:157]
	v_cvt_pk_bf16_f32 v124, v124, v125
	v_cvt_pk_bf16_f32 v125, v126, v127
	v_cvt_pk_bf16_f32 v126, v120, v121
	v_lshlrev_b64 v[120:121], 1, v[154:155]
	v_mad_i64_i32 v[64:65], s[20:21], v64, s74, v[156:157]
	v_cvt_pk_bf16_f32 v127, v122, v123
	v_lshl_add_u64 v[122:123], v[158:159], 0, v[120:121]
	v_cvt_pk_bf16_f32 v108, v108, v109
	v_cvt_pk_bf16_f32 v109, v110, v111
	v_cvt_pk_bf16_f32 v110, v104, v105
	v_cvt_pk_bf16_f32 v111, v106, v107
	v_or_b32_e32 v104, 16, v153
	v_cvt_pk_bf16_f32 v60, v60, v61
	v_cvt_pk_bf16_f32 v61, v62, v63
	v_cvt_pk_bf16_f32 v62, v56, v57
	v_lshl_add_u64 v[56:57], v[64:65], 0, v[120:121]
	v_cvt_pk_bf16_f32 v44, v44, v45
	v_cvt_pk_bf16_f32 v45, v46, v47
	v_cvt_pk_bf16_f32 v46, v40, v41
	v_cvt_pk_bf16_f32 v47, v42, v43
	v_add_u32_e32 v40, 0x90, v153
	global_store_dwordx4 v[122:123], v[108:111], off offset:256
	global_store_dwordx4 v[56:57], v[44:47], off offset:256
	v_cvt_pk_bf16_f32 v92, v92, v93
	v_mad_i64_i32 v[108:109], s[20:21], v104, s74, v[156:157]
	v_mad_i64_i32 v[44:45], s[20:21], v40, s74, v[156:157]
	v_lshl_add_u64 v[108:109], v[108:109], 0, v[120:121]
	v_cvt_pk_bf16_f32 v93, v94, v95
	v_cvt_pk_bf16_f32 v94, v88, v89
	v_cvt_pk_bf16_f32 v95, v90, v91
	v_or_b32_e32 v88, 32, v153
	v_lshl_add_u64 v[44:45], v[44:45], 0, v[120:121]
	v_cvt_pk_bf16_f32 v28, v28, v29
	v_cvt_pk_bf16_f32 v29, v30, v31
	v_cvt_pk_bf16_f32 v30, v24, v25
	v_cvt_pk_bf16_f32 v31, v26, v27
	v_add_u32_e32 v24, 0xa0, v153
	global_store_dwordx4 v[108:109], v[92:95], off offset:256
	global_store_dwordx4 v[44:45], v[28:31], off offset:256
	v_cvt_pk_bf16_f32 v76, v76, v77
	v_mad_i64_i32 v[92:93], s[20:21], v88, s74, v[156:157]
	v_mad_i64_i32 v[28:29], s[20:21], v24, s74, v[156:157]
	v_lshl_add_u64 v[92:93], v[92:93], 0, v[120:121]
	v_cvt_pk_bf16_f32 v77, v78, v79
	v_cvt_pk_bf16_f32 v78, v72, v73
	v_cvt_pk_bf16_f32 v79, v74, v75
	v_or_b32_e32 v72, 48, v153
	v_lshl_add_u64 v[28:29], v[28:29], 0, v[120:121]
	v_cvt_pk_bf16_f32 v12, v12, v13
	v_cvt_pk_bf16_f32 v13, v14, v15
	v_cvt_pk_bf16_f32 v14, v8, v9
	v_cvt_pk_bf16_f32 v15, v10, v11
	v_add_u32_e32 v8, 0xb0, v153
	global_store_dwordx4 v[92:93], v[76:79], off offset:256
	global_store_dwordx4 v[28:29], v[12:15], off offset:256
	v_cvt_pk_bf16_f32 v104, v116, v117
	v_mad_i64_i32 v[76:77], s[20:21], v72, s74, v[156:157]
	v_mad_i64_i32 v[12:13], s[20:21], v8, s74, v[156:157]
	v_cvt_pk_bf16_f32 v105, v118, v119
	v_cvt_pk_bf16_f32 v106, v112, v113
	v_cvt_pk_bf16_f32 v107, v114, v115
	v_cvt_pk_bf16_f32 v88, v100, v101
	v_cvt_pk_bf16_f32 v89, v102, v103
	v_cvt_pk_bf16_f32 v90, v96, v97
	v_cvt_pk_bf16_f32 v91, v98, v99
	v_cvt_pk_bf16_f32 v72, v84, v85
	v_cvt_pk_bf16_f32 v73, v86, v87
	v_cvt_pk_bf16_f32 v74, v80, v81
	v_cvt_pk_bf16_f32 v75, v82, v83
	v_lshl_add_u64 v[76:77], v[76:77], 0, v[120:121]
	v_cvt_pk_bf16_f32 v71, v66, v67
	v_cvt_pk_bf16_f32 v63, v58, v59
	v_cvt_pk_bf16_f32 v40, v52, v53
	v_cvt_pk_bf16_f32 v41, v54, v55
	v_cvt_pk_bf16_f32 v42, v48, v49
	v_cvt_pk_bf16_f32 v43, v50, v51
	v_cvt_pk_bf16_f32 v24, v36, v37
	v_cvt_pk_bf16_f32 v25, v38, v39
	v_cvt_pk_bf16_f32 v26, v32, v33
	v_cvt_pk_bf16_f32 v27, v34, v35
	v_cvt_pk_bf16_f32 v8, v20, v21
	v_cvt_pk_bf16_f32 v9, v22, v23
	v_cvt_pk_bf16_f32 v10, v16, v17
	v_cvt_pk_bf16_f32 v11, v18, v19
	v_lshl_add_u64 v[12:13], v[12:13], 0, v[120:121]
	v_cvt_pk_bf16_f32 v4, v4, v5
	v_cvt_pk_bf16_f32 v5, v6, v7
	v_cvt_pk_bf16_f32 v6, v0, v1
	v_cvt_pk_bf16_f32 v7, v2, v3
	s_and_b64 vcc, exec, s[4:5]
	s_mov_b32 s75, s12
	s_mov_b32 s10, s14
	s_mov_b64 s[26:27], s[18:19]
	s_mov_b64 s[20:21], s[16:17]
	global_store_dwordx4 v[122:123], v[124:127], off
	global_store_dwordx4 v[108:109], v[104:107], off
	global_store_dwordx4 v[92:93], v[88:91], off
	global_store_dwordx4 v[76:77], v[72:75], off
	global_store_dwordx4 v[76:77], v[68:71], off offset:256
	global_store_dwordx4 v[56:57], v[60:63], off
	global_store_dwordx4 v[44:45], v[40:43], off
	global_store_dwordx4 v[28:29], v[24:27], off
	global_store_dwordx4 v[12:13], v[8:11], off
	global_store_dwordx4 v[12:13], v[4:7], off offset:256
	s_cbranch_vccz .LBB0_152
	s_waitcnt vmcnt(0)
	s_cmpk_gt_u32 s30, 0xff
	s_cbranch_scc1 .LBB0_159
	s_barrier

.LBB0_486:
	ds_read_b128 v[154:157], v151
	ds_read_b128 v[158:161], v151 offset:1024
	ds_read_b128 v[162:165], v151 offset:2048
	ds_read_b128 v[166:169], v151 offset:3072
	s_add_u32 s30, s28, 0xfffc0080
	s_addc_u32 s31, s29, -1
	s_cmp_eq_u32 s84, 12
	s_cselect_b32 s35, s19, s31
	s_cselect_b32 s34, s80, s30
	s_cselect_b32 s31, s17, s83
	s_cselect_b32 s30, s81, s82
	v_lshl_add_u64 v[202:203], s[28:29], 0, v[138:139]
	s_add_i32 m0, s15, 0xc000
	ds_read_b128 v[170:173], v152
	ds_read_b128 v[174:177], v152 offset:1024
	ds_read_b128 v[178:181], v152 offset:2048
	ds_read_b128 v[182:185], v152 offset:3072
	ds_read_b128 v[186:189], v152 offset:4096
	ds_read_b128 v[190:193], v152 offset:5120
	ds_read_b128 v[194:197], v152 offset:6144
	ds_read_b128 v[198:201], v152 offset:7168
	global_load_lds_dwordx4 v[202:203], off
	v_lshl_add_u64 v[202:203], s[28:29], 0, v[140:141]
	s_add_i32 m0, s15, 0xe000
	s_nop 0
	global_load_lds_dwordx4 v[202:203], off
	s_waitcnt lgkmcnt(8)
	s_barrier
	s_waitcnt lgkmcnt(0)
	s_setprio 0
	s_waitcnt lgkmcnt(0)
	v_mfma_f32_16x16x32_bf16 v[124:127], v[154:157], v[170:173], v[124:127]
	v_mfma_f32_16x16x32_bf16 v[120:123], v[162:165], v[170:173], v[120:123]
	v_mfma_f32_16x16x32_bf16 v[116:119], v[154:157], v[178:181], v[116:119]
	v_mfma_f32_16x16x32_bf16 v[112:115], v[162:165], v[178:181], v[112:115]
	v_mfma_f32_16x16x32_bf16 v[100:103], v[154:157], v[186:189], v[100:103]
	v_mfma_f32_16x16x32_bf16 v[96:99], v[162:165], v[186:189], v[96:99]
	v_mfma_f32_16x16x32_bf16 v[84:87], v[154:157], v[194:197], v[84:87]
	v_mfma_f32_16x16x32_bf16 v[80:83], v[162:165], v[194:197], v[80:83]
	v_mfma_f32_16x16x32_bf16 v[124:127], v[158:161], v[174:177], v[124:127]
	v_mfma_f32_16x16x32_bf16 v[120:123], v[166:169], v[174:177], v[120:123]
	v_mfma_f32_16x16x32_bf16 v[116:119], v[158:161], v[182:185], v[116:119]
	v_mfma_f32_16x16x32_bf16 v[112:115], v[166:169], v[182:185], v[112:115]
	v_mfma_f32_16x16x32_bf16 v[100:103], v[158:161], v[190:193], v[100:103]
	v_mfma_f32_16x16x32_bf16 v[96:99], v[166:169], v[190:193], v[96:99]
	v_mfma_f32_16x16x32_bf16 v[84:87], v[158:161], v[198:201], v[84:87]
	v_mfma_f32_16x16x32_bf16 v[80:83], v[166:169], v[198:201], v[80:83]
	s_setprio 1
	s_barrier
	s_add_i32 s85, s74, s55
	v_lshl_add_u64 v[218:219], s[30:31], 0, v[134:135]
	s_mov_b32 m0, s85
	ds_read_b128 v[202:205], v153
	ds_read_b128 v[206:209], v153 offset:1024
	ds_read_b128 v[210:213], v153 offset:2048
	ds_read_b128 v[214:217], v153 offset:3072
	global_load_lds_dwordx4 v[218:219], off
	v_lshl_add_u64 v[220:221], s[30:31], 0, v[130:131]
	s_add_i32 m0, s85, 0x2000
	s_nop 0
	global_load_lds_dwordx4 v[220:221], off
	s_barrier
	s_waitcnt lgkmcnt(0)
	s_setprio 0
	s_waitcnt lgkmcnt(0)
	v_mfma_f32_16x16x32_bf16 v[108:111], v[202:205], v[170:173], v[108:111]
	v_mfma_f32_16x16x32_bf16 v[104:107], v[210:213], v[170:173], v[104:107]
	v_mfma_f32_16x16x32_bf16 v[92:95], v[202:205], v[178:181], v[92:95]
	v_mfma_f32_16x16x32_bf16 v[88:91], v[210:213], v[178:181], v[88:91]
	v_mfma_f32_16x16x32_bf16 v[76:79], v[202:205], v[186:189], v[76:79]
	v_mfma_f32_16x16x32_bf16 v[72:75], v[210:213], v[186:189], v[72:75]
	v_mfma_f32_16x16x32_bf16 v[68:71], v[202:205], v[194:197], v[68:71]
	v_mfma_f32_16x16x32_bf16 v[64:67], v[210:213], v[194:197], v[64:67]
	v_mfma_f32_16x16x32_bf16 v[108:111], v[206:209], v[174:177], v[108:111]
	v_mfma_f32_16x16x32_bf16 v[104:107], v[214:217], v[174:177], v[104:107]
	v_mfma_f32_16x16x32_bf16 v[92:95], v[206:209], v[182:185], v[92:95]
	v_mfma_f32_16x16x32_bf16 v[88:91], v[214:217], v[182:185], v[88:91]
	v_mfma_f32_16x16x32_bf16 v[76:79], v[206:209], v[190:193], v[76:79]
	v_mfma_f32_16x16x32_bf16 v[72:75], v[214:217], v[190:193], v[72:75]
	v_mfma_f32_16x16x32_bf16 v[68:71], v[206:209], v[198:201], v[68:71]
	v_mfma_f32_16x16x32_bf16 v[64:67], v[214:217], v[198:201], v[64:67]
	s_setprio 1
	s_mov_b32 m0, s15
	v_lshl_add_u64 v[222:223], s[34:35], 0, v[136:137]
	s_barrier
	ds_read_b128 v[170:173], v152 offset:16384
	ds_read_b128 v[174:177], v152 offset:17408
	ds_read_b128 v[178:181], v152 offset:18432
	ds_read_b128 v[182:185], v152 offset:19456
	ds_read_b128 v[186:189], v152 offset:20480
	ds_read_b128 v[190:193], v152 offset:21504
	ds_read_b128 v[194:197], v152 offset:22528
	ds_read_b128 v[198:201], v152 offset:23552
	global_load_lds_dwordx4 v[222:223], off
	v_lshl_add_u64 v[224:225], s[34:35], 0, v[132:133]
	s_mov_b32 m0, s57
	s_nop 0
	global_load_lds_dwordx4 v[224:225], off
	s_barrier
	s_waitcnt lgkmcnt(0)
	s_setprio 0
	s_waitcnt lgkmcnt(0)
	v_mfma_f32_16x16x32_bf16 v[60:63], v[154:157], v[170:173], v[60:63]
	v_mfma_f32_16x16x32_bf16 v[56:59], v[162:165], v[170:173], v[56:59]
	v_mfma_f32_16x16x32_bf16 v[52:55], v[154:157], v[178:181], v[52:55]
	v_mfma_f32_16x16x32_bf16 v[48:51], v[162:165], v[178:181], v[48:51]
	v_mfma_f32_16x16x32_bf16 v[36:39], v[154:157], v[186:189], v[36:39]
	v_mfma_f32_16x16x32_bf16 v[32:35], v[162:165], v[186:189], v[32:35]
	v_mfma_f32_16x16x32_bf16 v[20:23], v[154:157], v[194:197], v[20:23]
	v_mfma_f32_16x16x32_bf16 v[16:19], v[162:165], v[194:197], v[16:19]
	v_mfma_f32_16x16x32_bf16 v[60:63], v[158:161], v[174:177], v[60:63]
	v_mfma_f32_16x16x32_bf16 v[56:59], v[166:169], v[174:177], v[56:59]
	v_mfma_f32_16x16x32_bf16 v[52:55], v[158:161], v[182:185], v[52:55]
	v_mfma_f32_16x16x32_bf16 v[48:51], v[166:169], v[182:185], v[48:51]
	v_mfma_f32_16x16x32_bf16 v[36:39], v[158:161], v[190:193], v[36:39]
	v_mfma_f32_16x16x32_bf16 v[32:35], v[166:169], v[190:193], v[32:35]
	v_mfma_f32_16x16x32_bf16 v[20:23], v[158:161], v[198:201], v[20:23]
	v_mfma_f32_16x16x32_bf16 v[16:19], v[166:169], v[198:201], v[16:19]
	s_setprio 1
	s_barrier
	s_add_u32 s86, s30, 0x40000
	s_addc_u32 s87, s31, 0
	s_add_i32 s85, s75, s55
	v_lshl_add_u64 v[154:155], s[86:87], 0, v[134:135]
	s_mov_b32 m0, s85
	s_nop 0
	global_load_lds_dwordx4 v[154:155], off
	v_lshl_add_u64 v[154:155], s[86:87], 0, v[130:131]
	s_add_i32 m0, s85, 0x2000
	s_nop 0
	global_load_lds_dwordx4 v[154:155], off
	s_waitcnt vmcnt(6)
	s_barrier
	s_setprio 0
	v_mfma_f32_16x16x32_bf16 v[44:47], v[202:205], v[170:173], v[44:47]
	v_mfma_f32_16x16x32_bf16 v[40:43], v[210:213], v[170:173], v[40:43]
	v_mfma_f32_16x16x32_bf16 v[28:31], v[202:205], v[178:181], v[28:31]
	v_mfma_f32_16x16x32_bf16 v[24:27], v[210:213], v[178:181], v[24:27]
	v_mfma_f32_16x16x32_bf16 v[12:15], v[202:205], v[186:189], v[12:15]
	v_mfma_f32_16x16x32_bf16 v[8:11], v[210:213], v[186:189], v[8:11]
	v_mfma_f32_16x16x32_bf16 v[4:7], v[202:205], v[194:197], v[4:7]
	v_mfma_f32_16x16x32_bf16 v[0:3], v[210:213], v[194:197], v[0:3]
	v_mfma_f32_16x16x32_bf16 v[44:47], v[206:209], v[174:177], v[44:47]
	v_mfma_f32_16x16x32_bf16 v[40:43], v[214:217], v[174:177], v[40:43]
	v_mfma_f32_16x16x32_bf16 v[28:31], v[206:209], v[182:185], v[28:31]
	v_mfma_f32_16x16x32_bf16 v[24:27], v[214:217], v[182:185], v[24:27]
	v_mfma_f32_16x16x32_bf16 v[12:15], v[206:209], v[190:193], v[12:15]
	v_mfma_f32_16x16x32_bf16 v[8:11], v[214:217], v[190:193], v[8:11]
	v_mfma_f32_16x16x32_bf16 v[4:7], v[206:209], v[198:201], v[4:7]
	v_mfma_f32_16x16x32_bf16 v[0:3], v[214:217], v[198:201], v[0:3]
	s_setprio 1
	s_add_i32 s85, 0, 0x18000
	v_add_u32_e32 v166, s85, v149
	s_barrier
	ds_read_b128 v[154:157], v166
	ds_read_b128 v[158:161], v166 offset:1024
	ds_read_b128 v[162:165], v166 offset:2048
	ds_read_b128 v[166:169], v166 offset:3072
	s_add_u32 s34, s34, 0x40000
	s_addc_u32 s35, s35, 0
	s_mov_b32 m0, s60
	v_lshl_add_u64 v[202:203], s[34:35], 0, v[136:137]
	ds_read_b128 v[170:173], v152 offset:32768
	ds_read_b128 v[174:177], v152 offset:33792
	ds_read_b128 v[178:181], v152 offset:34816
	ds_read_b128 v[182:185], v152 offset:35840
	ds_read_b128 v[186:189], v152 offset:36864
	ds_read_b128 v[190:193], v152 offset:37888
	ds_read_b128 v[194:197], v152 offset:38912
	ds_read_b128 v[198:201], v152 offset:39936
	global_load_lds_dwordx4 v[202:203], off
	v_lshl_add_u64 v[202:203], s[34:35], 0, v[132:133]
	s_mov_b32 m0, s61
	s_nop 0
	global_load_lds_dwordx4 v[202:203], off
	s_waitcnt lgkmcnt(8)
	s_barrier
	s_waitcnt lgkmcnt(0)
	s_setprio 0
	s_waitcnt lgkmcnt(0)
	v_mfma_f32_16x16x32_bf16 v[124:127], v[154:157], v[170:173], v[124:127]
	v_mfma_f32_16x16x32_bf16 v[120:123], v[162:165], v[170:173], v[120:123]
	v_mfma_f32_16x16x32_bf16 v[116:119], v[154:157], v[178:181], v[116:119]
	v_mfma_f32_16x16x32_bf16 v[112:115], v[162:165], v[178:181], v[112:115]
	v_mfma_f32_16x16x32_bf16 v[100:103], v[154:157], v[186:189], v[100:103]
	v_mfma_f32_16x16x32_bf16 v[96:99], v[162:165], v[186:189], v[96:99]
	v_mfma_f32_16x16x32_bf16 v[84:87], v[154:157], v[194:197], v[84:87]
	v_mfma_f32_16x16x32_bf16 v[80:83], v[162:165], v[194:197], v[80:83]
	v_mfma_f32_16x16x32_bf16 v[124:127], v[158:161], v[174:177], v[124:127]
	v_mfma_f32_16x16x32_bf16 v[120:123], v[166:169], v[174:177], v[120:123]
	v_mfma_f32_16x16x32_bf16 v[116:119], v[158:161], v[182:185], v[116:119]
	v_mfma_f32_16x16x32_bf16 v[112:115], v[166:169], v[182:185], v[112:115]
	v_mfma_f32_16x16x32_bf16 v[100:103], v[158:161], v[190:193], v[100:103]
	v_mfma_f32_16x16x32_bf16 v[96:99], v[166:169], v[190:193], v[96:99]
	v_mfma_f32_16x16x32_bf16 v[84:87], v[158:161], v[198:201], v[84:87]
	v_mfma_f32_16x16x32_bf16 v[80:83], v[166:169], v[198:201], v[80:83]
	s_setprio 1
	s_barrier
	s_add_i32 s34, 0, 0x1c000
	s_add_i32 s35, s85, s55
	v_add_u32_e32 v214, s34, v149
	v_lshl_add_u64 v[218:219], v[218:219], 0, s[8:9]
	s_mov_b32 m0, s35
	ds_read_b128 v[202:205], v214
	ds_read_b128 v[206:209], v214 offset:1024
	ds_read_b128 v[210:213], v214 offset:2048
	ds_read_b128 v[214:217], v214 offset:3072
	global_load_lds_dwordx4 v[218:219], off
	v_lshl_add_u64 v[218:219], v[220:221], 0, s[8:9]
	s_add_i32 m0, s35, 0x2000
	s_nop 0
	global_load_lds_dwordx4 v[218:219], off
	s_barrier
	s_waitcnt lgkmcnt(0)
	s_setprio 0
	s_waitcnt lgkmcnt(0)
	v_mfma_f32_16x16x32_bf16 v[108:111], v[202:205], v[170:173], v[108:111]
	v_mfma_f32_16x16x32_bf16 v[104:107], v[210:213], v[170:173], v[104:107]
	v_mfma_f32_16x16x32_bf16 v[92:95], v[202:205], v[178:181], v[92:95]
	v_mfma_f32_16x16x32_bf16 v[88:91], v[210:213], v[178:181], v[88:91]
	v_mfma_f32_16x16x32_bf16 v[76:79], v[202:205], v[186:189], v[76:79]
	v_mfma_f32_16x16x32_bf16 v[72:75], v[210:213], v[186:189], v[72:75]
	v_mfma_f32_16x16x32_bf16 v[68:71], v[202:205], v[194:197], v[68:71]
	v_mfma_f32_16x16x32_bf16 v[64:67], v[210:213], v[194:197], v[64:67]
	v_mfma_f32_16x16x32_bf16 v[108:111], v[206:209], v[174:177], v[108:111]
	v_mfma_f32_16x16x32_bf16 v[104:107], v[214:217], v[174:177], v[104:107]
	v_mfma_f32_16x16x32_bf16 v[92:95], v[206:209], v[182:185], v[92:95]
	v_mfma_f32_16x16x32_bf16 v[88:91], v[214:217], v[182:185], v[88:91]
	v_mfma_f32_16x16x32_bf16 v[76:79], v[206:209], v[190:193], v[76:79]
	v_mfma_f32_16x16x32_bf16 v[72:75], v[214:217], v[190:193], v[72:75]
	v_mfma_f32_16x16x32_bf16 v[68:71], v[206:209], v[198:201], v[68:71]
	v_mfma_f32_16x16x32_bf16 v[64:67], v[214:217], v[198:201], v[64:67]
	s_setprio 1
	s_mov_b32 m0, s71
	v_lshl_add_u64 v[218:219], v[222:223], 0, s[8:9]
	s_barrier
	ds_read_b128 v[170:173], v152 offset:49152
	ds_read_b128 v[174:177], v152 offset:50176
	ds_read_b128 v[178:181], v152 offset:51200
	ds_read_b128 v[182:185], v152 offset:52224
	ds_read_b128 v[186:189], v152 offset:53248
	ds_read_b128 v[190:193], v152 offset:54272
	ds_read_b128 v[194:197], v152 offset:55296
	ds_read_b128 v[198:201], v152 offset:56320
	global_load_lds_dwordx4 v[218:219], off
	v_lshl_add_u64 v[218:219], v[224:225], 0, s[8:9]
	s_mov_b32 m0, s72
	s_nop 0
	global_load_lds_dwordx4 v[218:219], off
	s_barrier
	s_waitcnt lgkmcnt(0)
	s_setprio 0
	s_waitcnt lgkmcnt(0)
	v_mfma_f32_16x16x32_bf16 v[60:63], v[154:157], v[170:173], v[60:63]
	v_mfma_f32_16x16x32_bf16 v[56:59], v[162:165], v[170:173], v[56:59]
	v_mfma_f32_16x16x32_bf16 v[52:55], v[154:157], v[178:181], v[52:55]
	v_mfma_f32_16x16x32_bf16 v[48:51], v[162:165], v[178:181], v[48:51]
	v_mfma_f32_16x16x32_bf16 v[36:39], v[154:157], v[186:189], v[36:39]
	v_mfma_f32_16x16x32_bf16 v[32:35], v[162:165], v[186:189], v[32:35]
	v_mfma_f32_16x16x32_bf16 v[20:23], v[154:157], v[194:197], v[20:23]
	v_mfma_f32_16x16x32_bf16 v[16:19], v[162:165], v[194:197], v[16:19]
	v_mfma_f32_16x16x32_bf16 v[60:63], v[158:161], v[174:177], v[60:63]
	v_mfma_f32_16x16x32_bf16 v[56:59], v[166:169], v[174:177], v[56:59]
	v_mfma_f32_16x16x32_bf16 v[52:55], v[158:161], v[182:185], v[52:55]
	v_mfma_f32_16x16x32_bf16 v[48:51], v[166:169], v[182:185], v[48:51]
	v_mfma_f32_16x16x32_bf16 v[36:39], v[158:161], v[190:193], v[36:39]
	v_mfma_f32_16x16x32_bf16 v[32:35], v[166:169], v[190:193], v[32:35]
	v_mfma_f32_16x16x32_bf16 v[20:23], v[158:161], v[198:201], v[20:23]
	v_mfma_f32_16x16x32_bf16 v[16:19], v[166:169], v[198:201], v[16:19]
	s_setprio 1
	s_barrier
	s_add_u32 s30, s30, 0x40080
	s_addc_u32 s31, s31, 0
	s_add_i32 s34, s34, s55
	v_lshl_add_u64 v[154:155], s[30:31], 0, v[134:135]
	s_mov_b32 m0, s34
	s_nop 0
	global_load_lds_dwordx4 v[154:155], off
	v_lshl_add_u64 v[154:155], s[30:31], 0, v[130:131]
	s_add_i32 m0, s34, 0x2000
	s_nop 0
	global_load_lds_dwordx4 v[154:155], off
	s_waitcnt vmcnt(6)
	s_barrier
	s_setprio 0
	v_mfma_f32_16x16x32_bf16 v[44:47], v[202:205], v[170:173], v[44:47]
	v_mfma_f32_16x16x32_bf16 v[40:43], v[210:213], v[170:173], v[40:43]
	v_mfma_f32_16x16x32_bf16 v[28:31], v[202:205], v[178:181], v[28:31]
	v_mfma_f32_16x16x32_bf16 v[24:27], v[210:213], v[178:181], v[24:27]
	v_mfma_f32_16x16x32_bf16 v[12:15], v[202:205], v[186:189], v[12:15]
	v_mfma_f32_16x16x32_bf16 v[8:11], v[210:213], v[186:189], v[8:11]
	v_mfma_f32_16x16x32_bf16 v[4:7], v[202:205], v[194:197], v[4:7]
	v_mfma_f32_16x16x32_bf16 v[0:3], v[210:213], v[194:197], v[0:3]
	v_mfma_f32_16x16x32_bf16 v[44:47], v[206:209], v[174:177], v[44:47]
	v_mfma_f32_16x16x32_bf16 v[40:43], v[214:217], v[174:177], v[40:43]
	v_mfma_f32_16x16x32_bf16 v[28:31], v[206:209], v[182:185], v[28:31]
	v_mfma_f32_16x16x32_bf16 v[24:27], v[214:217], v[182:185], v[24:27]
	v_mfma_f32_16x16x32_bf16 v[12:15], v[206:209], v[190:193], v[12:15]
	v_mfma_f32_16x16x32_bf16 v[8:11], v[214:217], v[190:193], v[8:11]
	v_mfma_f32_16x16x32_bf16 v[4:7], v[206:209], v[198:201], v[4:7]
	v_mfma_f32_16x16x32_bf16 v[0:3], v[214:217], v[198:201], v[0:3]
	s_setprio 1
	s_add_i32 s84, s84, 2
	s_add_u32 s28, s28, 0x100
	s_addc_u32 s29, s29, 0
	s_add_u32 s82, s82, 0x100
	s_addc_u32 s83, s83, 0
	s_cmp_gt_u32 s84, 13
	s_barrier
	s_cbranch_scc0 .LBB0_486
	v_lshl_add_u32 v154, s14, 8, v148
	v_lshl_or_b32 v156, s79, 8, v150
	v_ashrrev_i32_e32 v155, 31, v154
	v_lshlrev_b64 v[158:159], 11, v[154:155]
	v_ashrrev_i32_e32 v157, 31, v156
	v_lshl_add_u64 v[158:159], s[46:47], 0, v[158:159]
	v_cvt_pk_bf16_f32 v124, v124, v125
	v_cvt_pk_bf16_f32 v125, v126, v127
	v_cvt_pk_bf16_f32 v126, v120, v121
	v_lshlrev_b64 v[120:121], 1, v[156:157]
	v_cvt_pk_bf16_f32 v127, v122, v123
	v_lshl_add_u64 v[122:123], v[158:159], 0, v[120:121]
	s_mov_b32 s14, 0x40000
	v_cvt_pk_bf16_f32 v108, v108, v109
	v_cvt_pk_bf16_f32 v109, v110, v111
	v_cvt_pk_bf16_f32 v110, v104, v105
	v_or_b32_e32 v104, 16, v154
	v_cvt_pk_bf16_f32 v60, v60, v61
	v_cvt_pk_bf16_f32 v61, v62, v63
	v_cvt_pk_bf16_f32 v63, v58, v59
	s_mov_b64 s[28:29], 0x40000
	v_add_co_u32_e32 v58, vcc, s14, v122
	v_ashrrev_i32_e32 v105, 31, v104
	v_cvt_pk_bf16_f32 v62, v56, v57
	v_lshl_add_u64 v[56:57], v[122:123], 0, s[28:29]
	v_addc_co_u32_e32 v59, vcc, 0, v123, vcc
	v_cvt_pk_bf16_f32 v44, v44, v45
	v_cvt_pk_bf16_f32 v45, v46, v47
	v_cvt_pk_bf16_f32 v46, v40, v41
	v_cvt_pk_bf16_f32 v47, v42, v43
	v_cvt_pk_bf16_f32 v111, v106, v107
	v_lshlrev_b64 v[104:105], 11, v[104:105]
	v_cvt_pk_bf16_f32 v92, v92, v93
	v_cvt_pk_bf16_f32 v93, v94, v95
	v_cvt_pk_bf16_f32 v94, v88, v89
	v_or_b32_e32 v88, 32, v154
	global_store_dwordx4 v[56:57], v[44:47], off offset:256
	s_mov_b64 s[28:29], 0x48000
	global_store_dwordx4 v[122:123], v[108:111], off offset:256
	v_add_co_u32_e32 v46, vcc, s76, v122
	s_nop 0
	v_lshl_add_u64 v[108:109], s[46:47], 0, v[104:105]
	v_ashrrev_i32_e32 v89, 31, v88
	v_lshl_add_u64 v[44:45], v[122:123], 0, s[28:29]
	v_addc_co_u32_e32 v47, vcc, 0, v123, vcc
	v_cvt_pk_bf16_f32 v28, v28, v29
	v_cvt_pk_bf16_f32 v29, v30, v31
	v_cvt_pk_bf16_f32 v30, v24, v25
	v_cvt_pk_bf16_f32 v31, v26, v27
	v_lshl_add_u64 v[108:109], v[108:109], 0, v[120:121]
	v_cvt_pk_bf16_f32 v95, v90, v91
	v_lshlrev_b64 v[88:89], 11, v[88:89]
	v_cvt_pk_bf16_f32 v76, v76, v77
	v_cvt_pk_bf16_f32 v77, v78, v79
	v_cvt_pk_bf16_f32 v78, v72, v73
	v_or_b32_e32 v72, 48, v154
	global_store_dwordx4 v[44:45], v[28:31], off offset:256
	global_store_dwordx4 v[108:109], v[92:95], off offset:256
	v_ashrrev_i32_e32 v73, 31, v72
	v_add_co_u32_e32 v30, vcc, s77, v122
	v_lshl_add_u64 v[92:93], s[46:47], 0, v[88:89]
	v_lshl_add_u64 v[28:29], v[122:123], 0, s[10:11]
	v_addc_co_u32_e32 v31, vcc, 0, v123, vcc
	v_cvt_pk_bf16_f32 v12, v12, v13
	v_cvt_pk_bf16_f32 v13, v14, v15
	v_cvt_pk_bf16_f32 v14, v8, v9
	v_cvt_pk_bf16_f32 v15, v10, v11
	v_lshl_add_u64 v[92:93], v[92:93], 0, v[120:121]
	v_cvt_pk_bf16_f32 v79, v74, v75
	v_lshlrev_b64 v[72:73], 11, v[72:73]
	global_store_dwordx4 v[28:29], v[12:15], off offset:256
	global_store_dwordx4 v[92:93], v[76:79], off offset:256
	v_cvt_pk_bf16_f32 v104, v116, v117
	v_add_co_u32_e32 v14, vcc, s78, v122
	v_lshl_add_u64 v[76:77], s[46:47], 0, v[72:73]
	s_nop 0
	v_addc_co_u32_e32 v15, vcc, 0, v123, vcc
	v_cvt_pk_bf16_f32 v105, v118, v119
	v_cvt_pk_bf16_f32 v106, v112, v113
	v_cvt_pk_bf16_f32 v107, v114, v115
	v_cvt_pk_bf16_f32 v88, v100, v101
	v_cvt_pk_bf16_f32 v89, v102, v103
	v_cvt_pk_bf16_f32 v90, v96, v97
	v_cvt_pk_bf16_f32 v91, v98, v99
	v_cvt_pk_bf16_f32 v72, v84, v85
	v_cvt_pk_bf16_f32 v73, v86, v87
	v_cvt_pk_bf16_f32 v74, v80, v81
	v_cvt_pk_bf16_f32 v75, v82, v83
	v_lshl_add_u64 v[76:77], v[76:77], 0, v[120:121]
	v_cvt_pk_bf16_f32 v68, v68, v69
	v_cvt_pk_bf16_f32 v69, v70, v71
	v_cvt_pk_bf16_f32 v70, v64, v65
	v_cvt_pk_bf16_f32 v71, v66, v67
	v_cvt_pk_bf16_f32 v40, v52, v53
	v_cvt_pk_bf16_f32 v41, v54, v55
	v_cvt_pk_bf16_f32 v42, v48, v49
	v_cvt_pk_bf16_f32 v43, v50, v51
	v_cvt_pk_bf16_f32 v24, v36, v37
	v_cvt_pk_bf16_f32 v25, v38, v39
	v_cvt_pk_bf16_f32 v26, v32, v33
	v_cvt_pk_bf16_f32 v27, v34, v35
	v_cvt_pk_bf16_f32 v8, v20, v21
	v_cvt_pk_bf16_f32 v9, v22, v23
	v_cvt_pk_bf16_f32 v10, v16, v17
	v_cvt_pk_bf16_f32 v11, v18, v19
	v_lshl_add_u64 v[12:13], v[122:123], 0, s[12:13]
	v_cvt_pk_bf16_f32 v4, v4, v5
	v_cvt_pk_bf16_f32 v5, v6, v7
	v_cvt_pk_bf16_f32 v6, v0, v1
	v_cvt_pk_bf16_f32 v7, v2, v3
	s_and_b64 vcc, exec, s[4:5]
	s_mov_b32 s79, s16
	s_mov_b32 s14, s18
	s_mov_b64 s[30:31], s[26:27]
	s_mov_b64 s[28:29], s[20:21]
	global_store_dwordx4 v[122:123], v[124:127], off
	global_store_dwordx4 v[108:109], v[104:107], off
	global_store_dwordx4 v[92:93], v[88:91], off
	global_store_dwordx4 v[76:77], v[72:75], off
	global_store_dwordx4 v[76:77], v[68:71], off offset:256
	global_store_dwordx4 v[58:59], v[60:63], off
	global_store_dwordx4 v[46:47], v[40:43], off
	global_store_dwordx4 v[30:31], v[24:27], off
	global_store_dwordx4 v[14:15], v[8:11], off
	global_store_dwordx4 v[12:13], v[4:7], off offset:256
	s_cbranch_vccz .LBB0_483
	s_waitcnt vmcnt(0)
	s_cmpk_gt_u32 s54, 0xff
	s_cbranch_scc1 .LBB0_490
	s_barrier

.LBB0_683:
	ds_read_b128 v[154:157], v151
	ds_read_b128 v[158:161], v151 offset:1024
	ds_read_b128 v[162:165], v151 offset:2048
	ds_read_b128 v[166:169], v151 offset:3072
	s_add_u32 s34, s30, 0xfffc0080
	s_addc_u32 s35, s31, -1
	s_cmp_eq_u32 s85, 12
	s_cselect_b32 s55, s19, s35
	s_cselect_b32 s54, s81, s34
	s_cselect_b32 s35, s17, s84
	s_cselect_b32 s34, s82, s83
	v_lshl_add_u64 v[202:203], s[30:31], 0, v[138:139]
	s_add_i32 m0, s29, 0xc000
	ds_read_b128 v[170:173], v152
	ds_read_b128 v[174:177], v152 offset:1024
	ds_read_b128 v[178:181], v152 offset:2048
	ds_read_b128 v[182:185], v152 offset:3072
	ds_read_b128 v[186:189], v152 offset:4096
	ds_read_b128 v[190:193], v152 offset:5120
	ds_read_b128 v[194:197], v152 offset:6144
	ds_read_b128 v[198:201], v152 offset:7168
	global_load_lds_dwordx4 v[202:203], off
	v_lshl_add_u64 v[202:203], s[30:31], 0, v[140:141]
	s_add_i32 m0, s29, 0xe000
	s_nop 0
	global_load_lds_dwordx4 v[202:203], off
	s_waitcnt lgkmcnt(8)
	s_barrier
	s_waitcnt lgkmcnt(0)
	s_setprio 0
	s_waitcnt lgkmcnt(0)
	v_mfma_f32_16x16x32_bf16 v[124:127], v[154:157], v[170:173], v[124:127]
	v_mfma_f32_16x16x32_bf16 v[120:123], v[162:165], v[170:173], v[120:123]
	v_mfma_f32_16x16x32_bf16 v[108:111], v[154:157], v[178:181], v[108:111]
	v_mfma_f32_16x16x32_bf16 v[104:107], v[162:165], v[178:181], v[104:107]
	v_mfma_f32_16x16x32_bf16 v[92:95], v[154:157], v[186:189], v[92:95]
	v_mfma_f32_16x16x32_bf16 v[88:91], v[162:165], v[186:189], v[88:91]
	v_mfma_f32_16x16x32_bf16 v[76:79], v[154:157], v[194:197], v[76:79]
	v_mfma_f32_16x16x32_bf16 v[72:75], v[162:165], v[194:197], v[72:75]
	v_mfma_f32_16x16x32_bf16 v[124:127], v[158:161], v[174:177], v[124:127]
	v_mfma_f32_16x16x32_bf16 v[120:123], v[166:169], v[174:177], v[120:123]
	v_mfma_f32_16x16x32_bf16 v[108:111], v[158:161], v[182:185], v[108:111]
	v_mfma_f32_16x16x32_bf16 v[104:107], v[166:169], v[182:185], v[104:107]
	v_mfma_f32_16x16x32_bf16 v[92:95], v[158:161], v[190:193], v[92:95]
	v_mfma_f32_16x16x32_bf16 v[88:91], v[166:169], v[190:193], v[88:91]
	v_mfma_f32_16x16x32_bf16 v[76:79], v[158:161], v[198:201], v[76:79]
	v_mfma_f32_16x16x32_bf16 v[72:75], v[166:169], v[198:201], v[72:75]
	s_setprio 1
	s_barrier
	s_add_i32 s86, s74, s60
	v_lshl_add_u64 v[218:219], s[34:35], 0, v[132:133]
	s_mov_b32 m0, s86
	ds_read_b128 v[202:205], v153
	ds_read_b128 v[206:209], v153 offset:1024
	ds_read_b128 v[210:213], v153 offset:2048
	ds_read_b128 v[214:217], v153 offset:3072
	global_load_lds_dwordx4 v[218:219], off
	v_lshl_add_u64 v[220:221], s[34:35], 0, v[136:137]
	s_add_i32 m0, s86, 0x2000
	s_nop 0
	global_load_lds_dwordx4 v[220:221], off
	s_barrier
	s_waitcnt lgkmcnt(0)
	s_setprio 0
	s_waitcnt lgkmcnt(0)
	v_mfma_f32_16x16x32_bf16 v[116:119], v[202:205], v[170:173], v[116:119]
	v_mfma_f32_16x16x32_bf16 v[112:115], v[210:213], v[170:173], v[112:115]
	v_mfma_f32_16x16x32_bf16 v[100:103], v[202:205], v[178:181], v[100:103]
	v_mfma_f32_16x16x32_bf16 v[96:99], v[210:213], v[178:181], v[96:99]
	v_mfma_f32_16x16x32_bf16 v[84:87], v[202:205], v[186:189], v[84:87]
	v_mfma_f32_16x16x32_bf16 v[80:83], v[210:213], v[186:189], v[80:83]
	v_mfma_f32_16x16x32_bf16 v[68:71], v[202:205], v[194:197], v[68:71]
	v_mfma_f32_16x16x32_bf16 v[64:67], v[210:213], v[194:197], v[64:67]
	v_mfma_f32_16x16x32_bf16 v[116:119], v[206:209], v[174:177], v[116:119]
	v_mfma_f32_16x16x32_bf16 v[112:115], v[214:217], v[174:177], v[112:115]
	v_mfma_f32_16x16x32_bf16 v[100:103], v[206:209], v[182:185], v[100:103]
	v_mfma_f32_16x16x32_bf16 v[96:99], v[214:217], v[182:185], v[96:99]
	v_mfma_f32_16x16x32_bf16 v[84:87], v[206:209], v[190:193], v[84:87]
	v_mfma_f32_16x16x32_bf16 v[80:83], v[214:217], v[190:193], v[80:83]
	v_mfma_f32_16x16x32_bf16 v[68:71], v[206:209], v[198:201], v[68:71]
	v_mfma_f32_16x16x32_bf16 v[64:67], v[214:217], v[198:201], v[64:67]
	s_setprio 1
	s_mov_b32 m0, s29
	v_lshl_add_u64 v[222:223], s[54:55], 0, v[130:131]
	s_barrier
	ds_read_b128 v[170:173], v152 offset:16384
	ds_read_b128 v[174:177], v152 offset:17408
	ds_read_b128 v[178:181], v152 offset:18432
	ds_read_b128 v[182:185], v152 offset:19456
	ds_read_b128 v[186:189], v152 offset:20480
	ds_read_b128 v[190:193], v152 offset:21504
	ds_read_b128 v[194:197], v152 offset:22528
	ds_read_b128 v[198:201], v152 offset:23552
	global_load_lds_dwordx4 v[222:223], off
	v_lshl_add_u64 v[224:225], s[54:55], 0, v[134:135]
	s_mov_b32 m0, s61
	s_nop 0
	global_load_lds_dwordx4 v[224:225], off
	s_barrier
	s_waitcnt lgkmcnt(0)
	s_setprio 0
	s_waitcnt lgkmcnt(0)
	v_mfma_f32_16x16x32_bf16 v[60:63], v[154:157], v[170:173], v[60:63]
	v_mfma_f32_16x16x32_bf16 v[56:59], v[162:165], v[170:173], v[56:59]
	v_mfma_f32_16x16x32_bf16 v[44:47], v[154:157], v[178:181], v[44:47]
	v_mfma_f32_16x16x32_bf16 v[40:43], v[162:165], v[178:181], v[40:43]
	v_mfma_f32_16x16x32_bf16 v[28:31], v[154:157], v[186:189], v[28:31]
	v_mfma_f32_16x16x32_bf16 v[24:27], v[162:165], v[186:189], v[24:27]
	v_mfma_f32_16x16x32_bf16 v[12:15], v[154:157], v[194:197], v[12:15]
	v_mfma_f32_16x16x32_bf16 v[8:11], v[162:165], v[194:197], v[8:11]
	v_mfma_f32_16x16x32_bf16 v[60:63], v[158:161], v[174:177], v[60:63]
	v_mfma_f32_16x16x32_bf16 v[56:59], v[166:169], v[174:177], v[56:59]
	v_mfma_f32_16x16x32_bf16 v[44:47], v[158:161], v[182:185], v[44:47]
	v_mfma_f32_16x16x32_bf16 v[40:43], v[166:169], v[182:185], v[40:43]
	v_mfma_f32_16x16x32_bf16 v[28:31], v[158:161], v[190:193], v[28:31]
	v_mfma_f32_16x16x32_bf16 v[24:27], v[166:169], v[190:193], v[24:27]
	v_mfma_f32_16x16x32_bf16 v[12:15], v[158:161], v[198:201], v[12:15]
	v_mfma_f32_16x16x32_bf16 v[8:11], v[166:169], v[198:201], v[8:11]
	s_setprio 1
	s_barrier
	s_add_u32 s86, s34, 0x40000
	s_addc_u32 s87, s35, 0
	s_add_i32 s88, s75, s60
	v_lshl_add_u64 v[154:155], s[86:87], 0, v[132:133]
	s_mov_b32 m0, s88
	s_nop 0
	global_load_lds_dwordx4 v[154:155], off
	v_lshl_add_u64 v[154:155], s[86:87], 0, v[136:137]
	s_add_i32 m0, s88, 0x2000
	s_nop 0
	global_load_lds_dwordx4 v[154:155], off
	s_waitcnt vmcnt(6)
	s_barrier
	s_setprio 0
	v_mfma_f32_16x16x32_bf16 v[52:55], v[202:205], v[170:173], v[52:55]
	v_mfma_f32_16x16x32_bf16 v[48:51], v[210:213], v[170:173], v[48:51]
	v_mfma_f32_16x16x32_bf16 v[36:39], v[202:205], v[178:181], v[36:39]
	v_mfma_f32_16x16x32_bf16 v[32:35], v[210:213], v[178:181], v[32:35]
	v_mfma_f32_16x16x32_bf16 v[20:23], v[202:205], v[186:189], v[20:23]
	v_mfma_f32_16x16x32_bf16 v[16:19], v[210:213], v[186:189], v[16:19]
	v_mfma_f32_16x16x32_bf16 v[4:7], v[202:205], v[194:197], v[4:7]
	v_mfma_f32_16x16x32_bf16 v[0:3], v[210:213], v[194:197], v[0:3]
	v_mfma_f32_16x16x32_bf16 v[52:55], v[206:209], v[174:177], v[52:55]
	v_mfma_f32_16x16x32_bf16 v[48:51], v[214:217], v[174:177], v[48:51]
	v_mfma_f32_16x16x32_bf16 v[36:39], v[206:209], v[182:185], v[36:39]
	v_mfma_f32_16x16x32_bf16 v[32:35], v[214:217], v[182:185], v[32:35]
	v_mfma_f32_16x16x32_bf16 v[20:23], v[206:209], v[190:193], v[20:23]
	v_mfma_f32_16x16x32_bf16 v[16:19], v[214:217], v[190:193], v[16:19]
	v_mfma_f32_16x16x32_bf16 v[4:7], v[206:209], v[198:201], v[4:7]
	v_mfma_f32_16x16x32_bf16 v[0:3], v[214:217], v[198:201], v[0:3]
	s_setprio 1
	s_add_i32 s86, 0, 0x18000
	v_add_u32_e32 v166, s86, v149
	s_barrier
	ds_read_b128 v[154:157], v166
	ds_read_b128 v[158:161], v166 offset:1024
	ds_read_b128 v[162:165], v166 offset:2048
	ds_read_b128 v[166:169], v166 offset:3072
	s_add_u32 s54, s54, 0x40000
	s_addc_u32 s55, s55, 0
	s_mov_b32 m0, s62
	v_lshl_add_u64 v[202:203], s[54:55], 0, v[130:131]
	ds_read_b128 v[170:173], v152 offset:32768
	ds_read_b128 v[174:177], v152 offset:33792
	ds_read_b128 v[178:181], v152 offset:34816
	ds_read_b128 v[182:185], v152 offset:35840
	ds_read_b128 v[186:189], v152 offset:36864
	ds_read_b128 v[190:193], v152 offset:37888
	ds_read_b128 v[194:197], v152 offset:38912
	ds_read_b128 v[198:201], v152 offset:39936
	global_load_lds_dwordx4 v[202:203], off
	v_lshl_add_u64 v[202:203], s[54:55], 0, v[134:135]
	s_mov_b32 m0, s63
	s_nop 0
	global_load_lds_dwordx4 v[202:203], off
	s_waitcnt lgkmcnt(8)
	s_barrier
	s_waitcnt lgkmcnt(0)
	s_setprio 0
	s_waitcnt lgkmcnt(0)
	v_mfma_f32_16x16x32_bf16 v[124:127], v[154:157], v[170:173], v[124:127]
	v_mfma_f32_16x16x32_bf16 v[120:123], v[162:165], v[170:173], v[120:123]
	v_mfma_f32_16x16x32_bf16 v[108:111], v[154:157], v[178:181], v[108:111]
	v_mfma_f32_16x16x32_bf16 v[104:107], v[162:165], v[178:181], v[104:107]
	v_mfma_f32_16x16x32_bf16 v[92:95], v[154:157], v[186:189], v[92:95]
	v_mfma_f32_16x16x32_bf16 v[88:91], v[162:165], v[186:189], v[88:91]
	v_mfma_f32_16x16x32_bf16 v[76:79], v[154:157], v[194:197], v[76:79]
	v_mfma_f32_16x16x32_bf16 v[72:75], v[162:165], v[194:197], v[72:75]
	v_mfma_f32_16x16x32_bf16 v[124:127], v[158:161], v[174:177], v[124:127]
	v_mfma_f32_16x16x32_bf16 v[120:123], v[166:169], v[174:177], v[120:123]
	v_mfma_f32_16x16x32_bf16 v[108:111], v[158:161], v[182:185], v[108:111]
	v_mfma_f32_16x16x32_bf16 v[104:107], v[166:169], v[182:185], v[104:107]
	v_mfma_f32_16x16x32_bf16 v[92:95], v[158:161], v[190:193], v[92:95]
	v_mfma_f32_16x16x32_bf16 v[88:91], v[166:169], v[190:193], v[88:91]
	v_mfma_f32_16x16x32_bf16 v[76:79], v[158:161], v[198:201], v[76:79]
	v_mfma_f32_16x16x32_bf16 v[72:75], v[166:169], v[198:201], v[72:75]
	s_setprio 1
	s_barrier
	s_add_i32 s54, 0, 0x1c000
	s_add_i32 s55, s86, s60
	v_add_u32_e32 v214, s54, v149
	v_lshl_add_u64 v[218:219], v[218:219], 0, s[8:9]
	s_mov_b32 m0, s55
	ds_read_b128 v[202:205], v214
	ds_read_b128 v[206:209], v214 offset:1024
	ds_read_b128 v[210:213], v214 offset:2048
	ds_read_b128 v[214:217], v214 offset:3072
	global_load_lds_dwordx4 v[218:219], off
	v_lshl_add_u64 v[218:219], v[220:221], 0, s[8:9]
	s_add_i32 m0, s55, 0x2000
	s_nop 0
	global_load_lds_dwordx4 v[218:219], off
	s_barrier
	s_waitcnt lgkmcnt(0)
	s_setprio 0
	s_waitcnt lgkmcnt(0)
	v_mfma_f32_16x16x32_bf16 v[116:119], v[202:205], v[170:173], v[116:119]
	v_mfma_f32_16x16x32_bf16 v[112:115], v[210:213], v[170:173], v[112:115]
	v_mfma_f32_16x16x32_bf16 v[100:103], v[202:205], v[178:181], v[100:103]
	v_mfma_f32_16x16x32_bf16 v[96:99], v[210:213], v[178:181], v[96:99]
	v_mfma_f32_16x16x32_bf16 v[84:87], v[202:205], v[186:189], v[84:87]
	v_mfma_f32_16x16x32_bf16 v[80:83], v[210:213], v[186:189], v[80:83]
	v_mfma_f32_16x16x32_bf16 v[68:71], v[202:205], v[194:197], v[68:71]
	v_mfma_f32_16x16x32_bf16 v[64:67], v[210:213], v[194:197], v[64:67]
	v_mfma_f32_16x16x32_bf16 v[116:119], v[206:209], v[174:177], v[116:119]
	v_mfma_f32_16x16x32_bf16 v[112:115], v[214:217], v[174:177], v[112:115]
	v_mfma_f32_16x16x32_bf16 v[100:103], v[206:209], v[182:185], v[100:103]
	v_mfma_f32_16x16x32_bf16 v[96:99], v[214:217], v[182:185], v[96:99]
	v_mfma_f32_16x16x32_bf16 v[84:87], v[206:209], v[190:193], v[84:87]
	v_mfma_f32_16x16x32_bf16 v[80:83], v[214:217], v[190:193], v[80:83]
	v_mfma_f32_16x16x32_bf16 v[68:71], v[206:209], v[198:201], v[68:71]
	v_mfma_f32_16x16x32_bf16 v[64:67], v[214:217], v[198:201], v[64:67]
	s_setprio 1
	s_mov_b32 m0, s71
	v_lshl_add_u64 v[218:219], v[222:223], 0, s[8:9]
	s_barrier
	ds_read_b128 v[170:173], v152 offset:49152
	ds_read_b128 v[174:177], v152 offset:50176
	ds_read_b128 v[178:181], v152 offset:51200
	ds_read_b128 v[182:185], v152 offset:52224
	ds_read_b128 v[186:189], v152 offset:53248
	ds_read_b128 v[190:193], v152 offset:54272
	ds_read_b128 v[194:197], v152 offset:55296
	ds_read_b128 v[198:201], v152 offset:56320
	global_load_lds_dwordx4 v[218:219], off
	v_lshl_add_u64 v[218:219], v[224:225], 0, s[8:9]
	s_mov_b32 m0, s72
	s_nop 0
	global_load_lds_dwordx4 v[218:219], off
	s_barrier
	s_waitcnt lgkmcnt(0)
	s_setprio 0
	s_waitcnt lgkmcnt(0)
	v_mfma_f32_16x16x32_bf16 v[60:63], v[154:157], v[170:173], v[60:63]
	v_mfma_f32_16x16x32_bf16 v[56:59], v[162:165], v[170:173], v[56:59]
	v_mfma_f32_16x16x32_bf16 v[44:47], v[154:157], v[178:181], v[44:47]
	v_mfma_f32_16x16x32_bf16 v[40:43], v[162:165], v[178:181], v[40:43]
	v_mfma_f32_16x16x32_bf16 v[28:31], v[154:157], v[186:189], v[28:31]
	v_mfma_f32_16x16x32_bf16 v[24:27], v[162:165], v[186:189], v[24:27]
	v_mfma_f32_16x16x32_bf16 v[12:15], v[154:157], v[194:197], v[12:15]
	v_mfma_f32_16x16x32_bf16 v[8:11], v[162:165], v[194:197], v[8:11]
	v_mfma_f32_16x16x32_bf16 v[60:63], v[158:161], v[174:177], v[60:63]
	v_mfma_f32_16x16x32_bf16 v[56:59], v[166:169], v[174:177], v[56:59]
	v_mfma_f32_16x16x32_bf16 v[44:47], v[158:161], v[182:185], v[44:47]
	v_mfma_f32_16x16x32_bf16 v[40:43], v[166:169], v[182:185], v[40:43]
	v_mfma_f32_16x16x32_bf16 v[28:31], v[158:161], v[190:193], v[28:31]
	v_mfma_f32_16x16x32_bf16 v[24:27], v[166:169], v[190:193], v[24:27]
	v_mfma_f32_16x16x32_bf16 v[12:15], v[158:161], v[198:201], v[12:15]
	v_mfma_f32_16x16x32_bf16 v[8:11], v[166:169], v[198:201], v[8:11]
	s_setprio 1
	s_barrier
	s_add_u32 s34, s34, 0x40080
	s_addc_u32 s35, s35, 0
	s_add_i32 s54, s54, s60
	v_lshl_add_u64 v[154:155], s[34:35], 0, v[132:133]
	s_mov_b32 m0, s54
	s_nop 0
	global_load_lds_dwordx4 v[154:155], off
	v_lshl_add_u64 v[154:155], s[34:35], 0, v[136:137]
	s_add_i32 m0, s54, 0x2000
	s_nop 0
	global_load_lds_dwordx4 v[154:155], off
	s_waitcnt vmcnt(6)
	s_barrier
	s_setprio 0
	v_mfma_f32_16x16x32_bf16 v[52:55], v[202:205], v[170:173], v[52:55]
	v_mfma_f32_16x16x32_bf16 v[48:51], v[210:213], v[170:173], v[48:51]
	v_mfma_f32_16x16x32_bf16 v[36:39], v[202:205], v[178:181], v[36:39]
	v_mfma_f32_16x16x32_bf16 v[32:35], v[210:213], v[178:181], v[32:35]
	v_mfma_f32_16x16x32_bf16 v[20:23], v[202:205], v[186:189], v[20:23]
	v_mfma_f32_16x16x32_bf16 v[16:19], v[210:213], v[186:189], v[16:19]
	v_mfma_f32_16x16x32_bf16 v[4:7], v[202:205], v[194:197], v[4:7]
	v_mfma_f32_16x16x32_bf16 v[0:3], v[210:213], v[194:197], v[0:3]
	v_mfma_f32_16x16x32_bf16 v[52:55], v[206:209], v[174:177], v[52:55]
	v_mfma_f32_16x16x32_bf16 v[48:51], v[214:217], v[174:177], v[48:51]
	v_mfma_f32_16x16x32_bf16 v[36:39], v[206:209], v[182:185], v[36:39]
	v_mfma_f32_16x16x32_bf16 v[32:35], v[214:217], v[182:185], v[32:35]
	v_mfma_f32_16x16x32_bf16 v[20:23], v[206:209], v[190:193], v[20:23]
	v_mfma_f32_16x16x32_bf16 v[16:19], v[214:217], v[190:193], v[16:19]
	v_mfma_f32_16x16x32_bf16 v[4:7], v[206:209], v[198:201], v[4:7]
	v_mfma_f32_16x16x32_bf16 v[0:3], v[214:217], v[198:201], v[0:3]
	s_setprio 1
	s_add_i32 s85, s85, 2
	s_add_u32 s30, s30, 0x100
	s_addc_u32 s31, s31, 0
	s_add_u32 s83, s83, 0x100
	s_addc_u32 s84, s84, 0
	s_cmp_gt_u32 s85, 13
	s_barrier
	s_cbranch_scc0 .LBB0_683
	v_lshl_add_u32 v154, s28, 8, v148
	v_max_f32_e32 v126, v126, v126
	v_max_f32_e32 v127, v127, v127
	v_lshl_or_b32 v156, s80, 8, v150
	v_ashrrev_i32_e32 v155, 31, v154
	v_max_f32_e32 v124, v124, v124
	v_max_f32_e32 v120, v120, v120
	v_max_f32_e32 v125, v125, v125
	v_max_f32_e32 v121, v121, v121
	v_max_f32_e32 v126, 0, v126
	v_max_f32_e32 v122, v122, v122
	v_max_f32_e32 v127, 0, v127
	v_max_f32_e32 v123, v123, v123
	v_lshlrev_b64 v[158:159], 13, v[154:155]
	v_max_f32_e32 v124, 0, v124
	v_max_f32_e32 v120, 0, v120
	v_max_f32_e32 v125, 0, v125
	v_max_f32_e32 v121, 0, v121
	v_max_f32_e32 v122, 0, v122
	v_max_f32_e32 v123, 0, v123
	v_pk_mul_f32 v[126:127], v[126:127], v[126:127]
	v_ashrrev_i32_e32 v157, 31, v156
	v_lshl_add_u64 v[158:159], s[46:47], 0, v[158:159]
	v_pk_mul_f32 v[124:125], v[124:125], v[124:125]
	v_pk_mul_f32 v[120:121], v[120:121], v[120:121]
	v_pk_mul_f32 v[160:161], v[122:123], v[122:123]
	v_cvt_pk_bf16_f32 v123, v126, v127
	v_lshlrev_b64 v[126:127], 1, v[156:157]
	v_max_f32_e32 v112, v112, v112
	v_max_f32_e32 v113, v113, v113
	v_cvt_pk_bf16_f32 v122, v124, v125
	v_cvt_pk_bf16_f32 v124, v120, v121
	v_cvt_pk_bf16_f32 v125, v160, v161
	v_lshl_add_u64 v[120:121], v[158:159], 0, v[126:127]
	v_max_f32_e32 v112, 0, v112
	v_max_f32_e32 v113, 0, v113
	global_store_dwordx4 v[120:121], v[122:125], off
	v_max_f32_e32 v116, v116, v116
	v_max_f32_e32 v117, v117, v117
	v_pk_mul_f32 v[122:123], v[112:113], v[112:113]
	v_max_f32_e32 v113, v114, v114
	v_max_f32_e32 v112, v118, v118
	v_max_f32_e32 v114, 0, v113
	v_max_f32_e32 v113, v119, v119
	v_max_f32_e32 v115, v115, v115
	v_max_f32_e32 v116, 0, v116
	v_max_f32_e32 v117, 0, v117
	v_max_f32_e32 v112, 0, v112
	v_max_f32_e32 v113, 0, v113
	v_max_f32_e32 v115, 0, v115
	v_pk_mul_f32 v[116:117], v[116:117], v[116:117]
	v_pk_mul_f32 v[118:119], v[112:113], v[112:113]
	v_pk_mul_f32 v[124:125], v[114:115], v[114:115]
	v_max_f32_e32 v104, v104, v104
	v_max_f32_e32 v105, v105, v105
	v_cvt_pk_bf16_f32 v112, v116, v117
	v_cvt_pk_bf16_f32 v113, v118, v119
	v_cvt_pk_bf16_f32 v114, v122, v123
	v_cvt_pk_bf16_f32 v115, v124, v125
	v_max_f32_e32 v104, 0, v104
	v_max_f32_e32 v105, 0, v105
	global_store_dwordx4 v[120:121], v[112:115], off offset:256
	v_max_f32_e32 v108, v108, v108
	v_max_f32_e32 v109, v109, v109
	v_or_b32_e32 v112, 16, v154
	v_pk_mul_f32 v[114:115], v[104:105], v[104:105]
	v_max_f32_e32 v105, v106, v106
	v_ashrrev_i32_e32 v113, 31, v112
	v_max_f32_e32 v104, v110, v110
	v_max_f32_e32 v106, 0, v105
	v_max_f32_e32 v105, v111, v111
	v_max_f32_e32 v107, v107, v107
	v_lshlrev_b64 v[112:113], 13, v[112:113]
	v_max_f32_e32 v108, 0, v108
	v_max_f32_e32 v109, 0, v109
	v_max_f32_e32 v104, 0, v104
	v_max_f32_e32 v105, 0, v105
	v_max_f32_e32 v107, 0, v107
	v_lshl_add_u64 v[112:113], s[46:47], 0, v[112:113]
	v_pk_mul_f32 v[108:109], v[108:109], v[108:109]
	v_pk_mul_f32 v[110:111], v[104:105], v[104:105]
	v_pk_mul_f32 v[116:117], v[106:107], v[106:107]
	v_max_f32_e32 v96, v96, v96
	v_max_f32_e32 v97, v97, v97
	v_cvt_pk_bf16_f32 v104, v108, v109
	v_cvt_pk_bf16_f32 v105, v110, v111
	v_cvt_pk_bf16_f32 v106, v114, v115
	v_cvt_pk_bf16_f32 v107, v116, v117
	v_lshl_add_u64 v[108:109], v[112:113], 0, v[126:127]
	v_max_f32_e32 v96, 0, v96
	v_max_f32_e32 v97, 0, v97
	global_store_dwordx4 v[108:109], v[104:107], off
	v_max_f32_e32 v100, v100, v100
	v_max_f32_e32 v101, v101, v101
	v_pk_mul_f32 v[104:105], v[96:97], v[96:97]
	v_max_f32_e32 v97, v98, v98
	v_max_f32_e32 v96, v102, v102
	v_max_f32_e32 v98, 0, v97
	v_max_f32_e32 v97, v103, v103
	v_max_f32_e32 v99, v99, v99
	v_max_f32_e32 v100, 0, v100
	v_max_f32_e32 v101, 0, v101
	v_max_f32_e32 v96, 0, v96
	v_max_f32_e32 v97, 0, v97
	v_max_f32_e32 v99, 0, v99
	v_pk_mul_f32 v[100:101], v[100:101], v[100:101]
	v_pk_mul_f32 v[102:103], v[96:97], v[96:97]
	v_pk_mul_f32 v[106:107], v[98:99], v[98:99]
	v_max_f32_e32 v88, v88, v88
	v_max_f32_e32 v89, v89, v89
	v_cvt_pk_bf16_f32 v96, v100, v101
	v_cvt_pk_bf16_f32 v97, v102, v103
	v_cvt_pk_bf16_f32 v98, v104, v105
	v_cvt_pk_bf16_f32 v99, v106, v107
	v_max_f32_e32 v88, 0, v88
	v_max_f32_e32 v89, 0, v89
	global_store_dwordx4 v[108:109], v[96:99], off offset:256
	v_max_f32_e32 v92, v92, v92
	v_max_f32_e32 v93, v93, v93
	v_or_b32_e32 v96, 32, v154
	v_pk_mul_f32 v[98:99], v[88:89], v[88:89]
	v_max_f32_e32 v89, v90, v90
	v_ashrrev_i32_e32 v97, 31, v96
	v_max_f32_e32 v88, v94, v94
	v_max_f32_e32 v90, 0, v89
	v_max_f32_e32 v89, v95, v95
	v_max_f32_e32 v91, v91, v91
	v_lshlrev_b64 v[96:97], 13, v[96:97]
	v_max_f32_e32 v92, 0, v92
	v_max_f32_e32 v93, 0, v93
	v_max_f32_e32 v88, 0, v88
	v_max_f32_e32 v89, 0, v89
	v_max_f32_e32 v91, 0, v91
	v_lshl_add_u64 v[96:97], s[46:47], 0, v[96:97]
	v_pk_mul_f32 v[92:93], v[92:93], v[92:93]
	v_pk_mul_f32 v[94:95], v[88:89], v[88:89]
	v_pk_mul_f32 v[100:101], v[90:91], v[90:91]
	v_max_f32_e32 v80, v80, v80
	v_max_f32_e32 v81, v81, v81
	v_cvt_pk_bf16_f32 v88, v92, v93
	v_cvt_pk_bf16_f32 v89, v94, v95
	v_cvt_pk_bf16_f32 v90, v98, v99
	v_cvt_pk_bf16_f32 v91, v100, v101
	v_lshl_add_u64 v[92:93], v[96:97], 0, v[126:127]
	v_max_f32_e32 v80, 0, v80
	v_max_f32_e32 v81, 0, v81
	global_store_dwordx4 v[92:93], v[88:91], off
	v_max_f32_e32 v84, v84, v84
	v_max_f32_e32 v85, v85, v85
	v_pk_mul_f32 v[88:89], v[80:81], v[80:81]
	v_max_f32_e32 v81, v82, v82
	v_max_f32_e32 v80, v86, v86
	v_max_f32_e32 v82, 0, v81
	v_max_f32_e32 v81, v87, v87
	v_max_f32_e32 v83, v83, v83
	v_max_f32_e32 v84, 0, v84
	v_max_f32_e32 v85, 0, v85
	v_max_f32_e32 v80, 0, v80
	v_max_f32_e32 v81, 0, v81
	v_max_f32_e32 v83, 0, v83
	v_pk_mul_f32 v[84:85], v[84:85], v[84:85]
	v_pk_mul_f32 v[86:87], v[80:81], v[80:81]
	v_pk_mul_f32 v[90:91], v[82:83], v[82:83]
	v_max_f32_e32 v72, v72, v72
	v_max_f32_e32 v73, v73, v73
	v_cvt_pk_bf16_f32 v80, v84, v85
	v_cvt_pk_bf16_f32 v81, v86, v87
	v_cvt_pk_bf16_f32 v82, v88, v89
	v_cvt_pk_bf16_f32 v83, v90, v91
	v_max_f32_e32 v72, 0, v72
	v_max_f32_e32 v73, 0, v73
	global_store_dwordx4 v[92:93], v[80:83], off offset:256
	v_max_f32_e32 v76, v76, v76
	v_max_f32_e32 v77, v77, v77
	v_or_b32_e32 v80, 48, v154
	v_pk_mul_f32 v[82:83], v[72:73], v[72:73]
	v_max_f32_e32 v73, v74, v74
	v_ashrrev_i32_e32 v81, 31, v80
	v_max_f32_e32 v72, v78, v78
	v_max_f32_e32 v74, 0, v73
	v_max_f32_e32 v73, v79, v79
	v_max_f32_e32 v75, v75, v75
	v_lshlrev_b64 v[80:81], 13, v[80:81]
	v_max_f32_e32 v76, 0, v76
	v_max_f32_e32 v77, 0, v77
	v_max_f32_e32 v72, 0, v72
	v_max_f32_e32 v73, 0, v73
	v_max_f32_e32 v75, 0, v75
	v_lshl_add_u64 v[80:81], s[46:47], 0, v[80:81]
	v_pk_mul_f32 v[76:77], v[76:77], v[76:77]
	v_pk_mul_f32 v[78:79], v[72:73], v[72:73]
	v_pk_mul_f32 v[84:85], v[74:75], v[74:75]
	v_max_f32_e32 v64, v64, v64
	v_max_f32_e32 v65, v65, v65
	v_cvt_pk_bf16_f32 v72, v76, v77
	v_cvt_pk_bf16_f32 v73, v78, v79
	v_cvt_pk_bf16_f32 v74, v82, v83
	v_cvt_pk_bf16_f32 v75, v84, v85
	v_lshl_add_u64 v[76:77], v[80:81], 0, v[126:127]
	v_max_f32_e32 v64, 0, v64
	v_max_f32_e32 v65, 0, v65
	global_store_dwordx4 v[76:77], v[72:75], off
	v_max_f32_e32 v68, v68, v68
	v_max_f32_e32 v69, v69, v69
	v_pk_mul_f32 v[72:73], v[64:65], v[64:65]
	v_max_f32_e32 v65, v66, v66
	v_max_f32_e32 v64, v70, v70
	v_max_f32_e32 v66, 0, v65
	v_max_f32_e32 v65, v71, v71
	v_max_f32_e32 v67, v67, v67
	v_max_f32_e32 v68, 0, v68
	v_max_f32_e32 v69, 0, v69
	v_max_f32_e32 v64, 0, v64
	v_max_f32_e32 v65, 0, v65
	v_max_f32_e32 v67, 0, v67
	v_pk_mul_f32 v[68:69], v[68:69], v[68:69]
	v_pk_mul_f32 v[70:71], v[64:65], v[64:65]
	v_pk_mul_f32 v[74:75], v[66:67], v[66:67]
	v_max_f32_e32 v56, v56, v56
	v_max_f32_e32 v57, v57, v57
	v_cvt_pk_bf16_f32 v64, v68, v69
	v_cvt_pk_bf16_f32 v65, v70, v71
	v_cvt_pk_bf16_f32 v66, v72, v73
	v_cvt_pk_bf16_f32 v67, v74, v75
	v_max_f32_e32 v56, 0, v56
	v_max_f32_e32 v57, 0, v57
	global_store_dwordx4 v[76:77], v[64:67], off offset:256
	v_max_f32_e32 v60, v60, v60
	v_max_f32_e32 v61, v61, v61
	v_pk_mul_f32 v[64:65], v[56:57], v[56:57]
	v_max_f32_e32 v57, v58, v58
	v_max_f32_e32 v56, v62, v62
	v_max_f32_e32 v58, 0, v57
	v_max_f32_e32 v57, v63, v63
	v_max_f32_e32 v56, 0, v56
	v_max_f32_e32 v57, 0, v57
	v_max_f32_e32 v59, v59, v59
	v_max_f32_e32 v60, 0, v60
	v_max_f32_e32 v61, 0, v61
	v_max_f32_e32 v59, 0, v59
	v_pk_mul_f32 v[62:63], v[56:57], v[56:57]
	v_pk_mul_f32 v[60:61], v[60:61], v[60:61]
	v_pk_mul_f32 v[66:67], v[58:59], v[58:59]
	v_cvt_pk_bf16_f32 v57, v62, v63
	v_add_co_u32_e32 v62, vcc, s76, v120
	v_max_f32_e32 v48, v48, v48
	v_max_f32_e32 v49, v49, v49
	v_cvt_pk_bf16_f32 v56, v60, v61
	v_cvt_pk_bf16_f32 v58, v64, v65
	v_cvt_pk_bf16_f32 v59, v66, v67
	v_addc_co_u32_e32 v63, vcc, 0, v121, vcc
	v_max_f32_e32 v48, 0, v48
	v_max_f32_e32 v49, 0, v49
	global_store_dwordx4 v[62:63], v[56:59], off
	v_max_f32_e32 v52, v52, v52
	v_max_f32_e32 v53, v53, v53
	v_pk_mul_f32 v[56:57], v[48:49], v[48:49]
	v_max_f32_e32 v49, v50, v50
	v_max_f32_e32 v48, v54, v54
	v_max_f32_e32 v50, 0, v49
	v_max_f32_e32 v49, v55, v55
	v_max_f32_e32 v51, v51, v51
	v_max_f32_e32 v52, 0, v52
	v_max_f32_e32 v53, 0, v53
	v_max_f32_e32 v48, 0, v48
	v_max_f32_e32 v49, 0, v49
	v_max_f32_e32 v51, 0, v51
	s_mov_b64 s[30:31], 0x100000
	v_pk_mul_f32 v[52:53], v[52:53], v[52:53]
	v_pk_mul_f32 v[54:55], v[48:49], v[48:49]
	v_pk_mul_f32 v[58:59], v[50:51], v[50:51]
	v_max_f32_e32 v40, v40, v40
	v_max_f32_e32 v41, v41, v41
	v_lshl_add_u64 v[60:61], v[120:121], 0, s[30:31]
	v_cvt_pk_bf16_f32 v48, v52, v53
	v_cvt_pk_bf16_f32 v49, v54, v55
	v_cvt_pk_bf16_f32 v50, v56, v57
	v_cvt_pk_bf16_f32 v51, v58, v59
	v_max_f32_e32 v40, 0, v40
	v_max_f32_e32 v41, 0, v41
	global_store_dwordx4 v[60:61], v[48:51], off offset:256
	v_max_f32_e32 v44, v44, v44
	v_max_f32_e32 v45, v45, v45
	v_pk_mul_f32 v[48:49], v[40:41], v[40:41]
	v_max_f32_e32 v41, v42, v42
	v_max_f32_e32 v40, v46, v46
	v_max_f32_e32 v42, 0, v41
	v_max_f32_e32 v41, v47, v47
	v_max_f32_e32 v40, 0, v40
	v_max_f32_e32 v41, 0, v41
	v_max_f32_e32 v43, v43, v43
	v_max_f32_e32 v44, 0, v44
	v_max_f32_e32 v45, 0, v45
	v_max_f32_e32 v43, 0, v43
	v_pk_mul_f32 v[46:47], v[40:41], v[40:41]
	v_pk_mul_f32 v[44:45], v[44:45], v[44:45]
	v_pk_mul_f32 v[50:51], v[42:43], v[42:43]
	v_cvt_pk_bf16_f32 v41, v46, v47
	v_add_co_u32_e32 v46, vcc, s77, v120
	v_max_f32_e32 v32, v32, v32
	v_max_f32_e32 v33, v33, v33
	v_cvt_pk_bf16_f32 v40, v44, v45
	v_cvt_pk_bf16_f32 v42, v48, v49
	v_cvt_pk_bf16_f32 v43, v50, v51
	v_addc_co_u32_e32 v47, vcc, 0, v121, vcc
	v_max_f32_e32 v32, 0, v32
	v_max_f32_e32 v33, 0, v33
	global_store_dwordx4 v[46:47], v[40:43], off
	v_max_f32_e32 v36, v36, v36
	v_max_f32_e32 v37, v37, v37
	v_pk_mul_f32 v[40:41], v[32:33], v[32:33]
	v_max_f32_e32 v33, v34, v34
	v_max_f32_e32 v32, v38, v38
	v_max_f32_e32 v34, 0, v33
	v_max_f32_e32 v33, v39, v39
	v_max_f32_e32 v35, v35, v35
	v_max_f32_e32 v36, 0, v36
	v_max_f32_e32 v37, 0, v37
	v_max_f32_e32 v32, 0, v32
	v_max_f32_e32 v33, 0, v33
	v_max_f32_e32 v35, 0, v35
	v_pk_mul_f32 v[36:37], v[36:37], v[36:37]
	v_pk_mul_f32 v[38:39], v[32:33], v[32:33]
	v_pk_mul_f32 v[42:43], v[34:35], v[34:35]
	v_max_f32_e32 v24, v24, v24
	v_max_f32_e32 v25, v25, v25
	v_lshl_add_u64 v[44:45], v[120:121], 0, s[10:11]
	v_cvt_pk_bf16_f32 v32, v36, v37
	v_cvt_pk_bf16_f32 v33, v38, v39
	v_cvt_pk_bf16_f32 v34, v40, v41
	v_cvt_pk_bf16_f32 v35, v42, v43
	v_max_f32_e32 v24, 0, v24
	v_max_f32_e32 v25, 0, v25
	global_store_dwordx4 v[44:45], v[32:35], off offset:256
	v_max_f32_e32 v28, v28, v28
	v_max_f32_e32 v29, v29, v29
	v_pk_mul_f32 v[32:33], v[24:25], v[24:25]
	v_max_f32_e32 v25, v26, v26
	v_max_f32_e32 v24, v30, v30
	v_max_f32_e32 v26, 0, v25
	v_max_f32_e32 v25, v31, v31
	v_max_f32_e32 v24, 0, v24
	v_max_f32_e32 v25, 0, v25
	v_max_f32_e32 v27, v27, v27
	v_max_f32_e32 v28, 0, v28
	v_max_f32_e32 v29, 0, v29
	v_max_f32_e32 v27, 0, v27
	v_pk_mul_f32 v[30:31], v[24:25], v[24:25]
	v_pk_mul_f32 v[28:29], v[28:29], v[28:29]
	v_pk_mul_f32 v[34:35], v[26:27], v[26:27]
	v_cvt_pk_bf16_f32 v25, v30, v31
	v_add_co_u32_e32 v30, vcc, s78, v120
	v_max_f32_e32 v16, v16, v16
	v_max_f32_e32 v17, v17, v17
	v_cvt_pk_bf16_f32 v24, v28, v29
	v_cvt_pk_bf16_f32 v26, v32, v33
	v_cvt_pk_bf16_f32 v27, v34, v35
	v_addc_co_u32_e32 v31, vcc, 0, v121, vcc
	v_max_f32_e32 v16, 0, v16
	v_max_f32_e32 v17, 0, v17
	global_store_dwordx4 v[30:31], v[24:27], off
	v_max_f32_e32 v20, v20, v20
	v_max_f32_e32 v21, v21, v21
	v_pk_mul_f32 v[24:25], v[16:17], v[16:17]
	v_max_f32_e32 v17, v18, v18
	v_max_f32_e32 v16, v22, v22
	v_max_f32_e32 v18, 0, v17
	v_max_f32_e32 v17, v23, v23
	v_max_f32_e32 v19, v19, v19
	v_max_f32_e32 v20, 0, v20
	v_max_f32_e32 v21, 0, v21
	v_max_f32_e32 v16, 0, v16
	v_max_f32_e32 v17, 0, v17
	v_max_f32_e32 v19, 0, v19
	v_pk_mul_f32 v[20:21], v[20:21], v[20:21]
	v_pk_mul_f32 v[22:23], v[16:17], v[16:17]
	v_pk_mul_f32 v[26:27], v[18:19], v[18:19]
	v_max_f32_e32 v8, v8, v8
	v_max_f32_e32 v9, v9, v9
	v_lshl_add_u64 v[28:29], v[120:121], 0, s[12:13]
	v_cvt_pk_bf16_f32 v16, v20, v21
	v_cvt_pk_bf16_f32 v17, v22, v23
	v_cvt_pk_bf16_f32 v18, v24, v25
	v_cvt_pk_bf16_f32 v19, v26, v27
	v_max_f32_e32 v8, 0, v8
	v_max_f32_e32 v9, 0, v9
	global_store_dwordx4 v[28:29], v[16:19], off offset:256
	v_max_f32_e32 v12, v12, v12
	v_max_f32_e32 v13, v13, v13
	v_pk_mul_f32 v[16:17], v[8:9], v[8:9]
	v_max_f32_e32 v9, v10, v10
	v_max_f32_e32 v8, v14, v14
	v_max_f32_e32 v10, 0, v9
	v_max_f32_e32 v9, v15, v15
	v_max_f32_e32 v8, 0, v8
	v_max_f32_e32 v9, 0, v9
	v_max_f32_e32 v11, v11, v11
	v_max_f32_e32 v12, 0, v12
	v_max_f32_e32 v13, 0, v13
	v_max_f32_e32 v11, 0, v11
	v_pk_mul_f32 v[14:15], v[8:9], v[8:9]
	v_pk_mul_f32 v[12:13], v[12:13], v[12:13]
	v_pk_mul_f32 v[18:19], v[10:11], v[10:11]
	v_cvt_pk_bf16_f32 v9, v14, v15
	v_add_co_u32_e32 v14, vcc, s79, v120
	v_max_f32_e32 v0, v0, v0
	v_max_f32_e32 v1, v1, v1
	v_cvt_pk_bf16_f32 v8, v12, v13
	v_cvt_pk_bf16_f32 v10, v16, v17
	v_cvt_pk_bf16_f32 v11, v18, v19
	v_addc_co_u32_e32 v15, vcc, 0, v121, vcc
	v_max_f32_e32 v0, 0, v0
	v_max_f32_e32 v1, 0, v1
	global_store_dwordx4 v[14:15], v[8:11], off
	v_max_f32_e32 v4, v4, v4
	v_max_f32_e32 v5, v5, v5
	v_pk_mul_f32 v[8:9], v[0:1], v[0:1]
	v_max_f32_e32 v1, v2, v2
	v_max_f32_e32 v0, v6, v6
	v_max_f32_e32 v2, 0, v1
	v_max_f32_e32 v1, v7, v7
	v_max_f32_e32 v3, v3, v3
	v_max_f32_e32 v4, 0, v4
	v_max_f32_e32 v5, 0, v5
	v_max_f32_e32 v0, 0, v0
	v_max_f32_e32 v1, 0, v1
	v_max_f32_e32 v3, 0, v3
	v_pk_mul_f32 v[4:5], v[4:5], v[4:5]
	v_pk_mul_f32 v[6:7], v[0:1], v[0:1]
	v_pk_mul_f32 v[10:11], v[2:3], v[2:3]
	v_lshl_add_u64 v[12:13], v[120:121], 0, s[14:15]
	v_cvt_pk_bf16_f32 v0, v4, v5
	v_cvt_pk_bf16_f32 v1, v6, v7
	v_cvt_pk_bf16_f32 v2, v8, v9
	v_cvt_pk_bf16_f32 v3, v10, v11
	s_and_b64 vcc, exec, s[4:5]
	s_mov_b32 s80, s16
	s_mov_b32 s28, s18
	s_mov_b64 s[34:35], s[26:27]
	s_mov_b64 s[30:31], s[20:21]
	global_store_dwordx4 v[12:13], v[0:3], off offset:256
	s_cbranch_vccz .LBB0_676
	s_waitcnt vmcnt(0)
	s_cmpk_gt_u32 s56, 0xff
	s_cbranch_scc1 .LBB0_687
	s_barrier

.LBB0_776:
	ds_read_b128 v[156:159], v152
	ds_read_b128 v[160:163], v152 offset:1024
	ds_read_b128 v[164:167], v152 offset:2048
	ds_read_b128 v[168:171], v152 offset:3072
	s_add_u32 s34, s30, 0xfff00080
	s_addc_u32 s35, s31, -1
	s_cmp_eq_u32 s85, 60
	s_cselect_b32 s55, s21, s35
	s_cselect_b32 s54, s81, s34
	s_cselect_b32 s35, s19, s84
	s_cselect_b32 s34, s82, s83
	v_lshl_add_u64 v[204:205], s[30:31], 0, v[138:139]
	s_add_i32 m0, s17, 0xc000
	ds_read_b128 v[172:175], v153
	ds_read_b128 v[176:179], v153 offset:1024
	ds_read_b128 v[180:183], v153 offset:2048
	ds_read_b128 v[184:187], v153 offset:3072
	ds_read_b128 v[188:191], v153 offset:4096
	ds_read_b128 v[192:195], v153 offset:5120
	ds_read_b128 v[196:199], v153 offset:6144
	ds_read_b128 v[200:203], v153 offset:7168
	global_load_lds_dwordx4 v[204:205], off
	v_lshl_add_u64 v[204:205], s[30:31], 0, v[140:141]
	s_add_i32 m0, s17, 0xe000
	s_nop 0
	global_load_lds_dwordx4 v[204:205], off
	s_waitcnt lgkmcnt(8)
	s_barrier
	s_waitcnt lgkmcnt(0)
	s_setprio 0
	s_waitcnt lgkmcnt(0)
	v_mfma_f32_16x16x32_bf16 v[124:127], v[156:159], v[172:175], v[124:127]
	v_mfma_f32_16x16x32_bf16 v[120:123], v[164:167], v[172:175], v[120:123]
	v_mfma_f32_16x16x32_bf16 v[116:119], v[156:159], v[180:183], v[116:119]
	v_mfma_f32_16x16x32_bf16 v[112:115], v[164:167], v[180:183], v[112:115]
	v_mfma_f32_16x16x32_bf16 v[100:103], v[156:159], v[188:191], v[100:103]
	v_mfma_f32_16x16x32_bf16 v[96:99], v[164:167], v[188:191], v[96:99]
	v_mfma_f32_16x16x32_bf16 v[84:87], v[156:159], v[196:199], v[84:87]
	v_mfma_f32_16x16x32_bf16 v[80:83], v[164:167], v[196:199], v[80:83]
	v_mfma_f32_16x16x32_bf16 v[124:127], v[160:163], v[176:179], v[124:127]
	v_mfma_f32_16x16x32_bf16 v[120:123], v[168:171], v[176:179], v[120:123]
	v_mfma_f32_16x16x32_bf16 v[116:119], v[160:163], v[184:187], v[116:119]
	v_mfma_f32_16x16x32_bf16 v[112:115], v[168:171], v[184:187], v[112:115]
	v_mfma_f32_16x16x32_bf16 v[100:103], v[160:163], v[192:195], v[100:103]
	v_mfma_f32_16x16x32_bf16 v[96:99], v[168:171], v[192:195], v[96:99]
	v_mfma_f32_16x16x32_bf16 v[84:87], v[160:163], v[200:203], v[84:87]
	v_mfma_f32_16x16x32_bf16 v[80:83], v[168:171], v[200:203], v[80:83]
	s_setprio 1
	s_barrier
	s_add_i32 s86, s74, s57
	v_lshl_add_u64 v[220:221], s[34:35], 0, v[134:135]
	s_mov_b32 m0, s86
	ds_read_b128 v[204:207], v154
	ds_read_b128 v[208:211], v154 offset:1024
	ds_read_b128 v[212:215], v154 offset:2048
	ds_read_b128 v[216:219], v154 offset:3072
	global_load_lds_dwordx4 v[220:221], off
	v_lshl_add_u64 v[222:223], s[34:35], 0, v[130:131]
	s_add_i32 m0, s86, 0x2000
	s_nop 0
	global_load_lds_dwordx4 v[222:223], off
	s_barrier
	s_waitcnt lgkmcnt(0)
	s_setprio 0
	s_waitcnt lgkmcnt(0)
	v_mfma_f32_16x16x32_bf16 v[108:111], v[204:207], v[172:175], v[108:111]
	v_mfma_f32_16x16x32_bf16 v[104:107], v[212:215], v[172:175], v[104:107]
	v_mfma_f32_16x16x32_bf16 v[92:95], v[204:207], v[180:183], v[92:95]
	v_mfma_f32_16x16x32_bf16 v[88:91], v[212:215], v[180:183], v[88:91]
	v_mfma_f32_16x16x32_bf16 v[76:79], v[204:207], v[188:191], v[76:79]
	v_mfma_f32_16x16x32_bf16 v[72:75], v[212:215], v[188:191], v[72:75]
	v_mfma_f32_16x16x32_bf16 v[68:71], v[204:207], v[196:199], v[68:71]
	v_mfma_f32_16x16x32_bf16 v[64:67], v[212:215], v[196:199], v[64:67]
	v_mfma_f32_16x16x32_bf16 v[108:111], v[208:211], v[176:179], v[108:111]
	v_mfma_f32_16x16x32_bf16 v[104:107], v[216:219], v[176:179], v[104:107]
	v_mfma_f32_16x16x32_bf16 v[92:95], v[208:211], v[184:187], v[92:95]
	v_mfma_f32_16x16x32_bf16 v[88:91], v[216:219], v[184:187], v[88:91]
	v_mfma_f32_16x16x32_bf16 v[76:79], v[208:211], v[192:195], v[76:79]
	v_mfma_f32_16x16x32_bf16 v[72:75], v[216:219], v[192:195], v[72:75]
	v_mfma_f32_16x16x32_bf16 v[68:71], v[208:211], v[200:203], v[68:71]
	v_mfma_f32_16x16x32_bf16 v[64:67], v[216:219], v[200:203], v[64:67]
	s_setprio 1
	s_mov_b32 m0, s17
	v_lshl_add_u64 v[224:225], s[54:55], 0, v[136:137]
	s_barrier
	ds_read_b128 v[172:175], v153 offset:16384
	ds_read_b128 v[176:179], v153 offset:17408
	ds_read_b128 v[180:183], v153 offset:18432
	ds_read_b128 v[184:187], v153 offset:19456
	ds_read_b128 v[188:191], v153 offset:20480
	ds_read_b128 v[192:195], v153 offset:21504
	ds_read_b128 v[196:199], v153 offset:22528
	ds_read_b128 v[200:203], v153 offset:23552
	global_load_lds_dwordx4 v[224:225], off
	v_lshl_add_u64 v[226:227], s[54:55], 0, v[132:133]
	s_mov_b32 m0, s61
	s_nop 0
	global_load_lds_dwordx4 v[226:227], off
	s_barrier
	s_waitcnt lgkmcnt(0)
	s_setprio 0
	s_waitcnt lgkmcnt(0)
	v_mfma_f32_16x16x32_bf16 v[60:63], v[156:159], v[172:175], v[60:63]
	v_mfma_f32_16x16x32_bf16 v[56:59], v[164:167], v[172:175], v[56:59]
	v_mfma_f32_16x16x32_bf16 v[52:55], v[156:159], v[180:183], v[52:55]
	v_mfma_f32_16x16x32_bf16 v[48:51], v[164:167], v[180:183], v[48:51]
	v_mfma_f32_16x16x32_bf16 v[36:39], v[156:159], v[188:191], v[36:39]
	v_mfma_f32_16x16x32_bf16 v[32:35], v[164:167], v[188:191], v[32:35]
	v_mfma_f32_16x16x32_bf16 v[20:23], v[156:159], v[196:199], v[20:23]
	v_mfma_f32_16x16x32_bf16 v[16:19], v[164:167], v[196:199], v[16:19]
	v_mfma_f32_16x16x32_bf16 v[60:63], v[160:163], v[176:179], v[60:63]
	v_mfma_f32_16x16x32_bf16 v[56:59], v[168:171], v[176:179], v[56:59]
	v_mfma_f32_16x16x32_bf16 v[52:55], v[160:163], v[184:187], v[52:55]
	v_mfma_f32_16x16x32_bf16 v[48:51], v[168:171], v[184:187], v[48:51]
	v_mfma_f32_16x16x32_bf16 v[36:39], v[160:163], v[192:195], v[36:39]
	v_mfma_f32_16x16x32_bf16 v[32:35], v[168:171], v[192:195], v[32:35]
	v_mfma_f32_16x16x32_bf16 v[20:23], v[160:163], v[200:203], v[20:23]
	v_mfma_f32_16x16x32_bf16 v[16:19], v[168:171], v[200:203], v[16:19]
	s_setprio 1
	s_barrier
	s_add_u32 s86, s34, 0x100000
	s_addc_u32 s87, s35, 0
	s_add_i32 s88, s75, s57
	v_lshl_add_u64 v[156:157], s[86:87], 0, v[134:135]
	s_mov_b32 m0, s88
	s_nop 0
	global_load_lds_dwordx4 v[156:157], off
	v_lshl_add_u64 v[156:157], s[86:87], 0, v[130:131]
	s_add_i32 m0, s88, 0x2000
	s_nop 0
	global_load_lds_dwordx4 v[156:157], off
	s_waitcnt vmcnt(6)
	s_barrier
	s_setprio 0
	v_mfma_f32_16x16x32_bf16 v[44:47], v[204:207], v[172:175], v[44:47]
	v_mfma_f32_16x16x32_bf16 v[40:43], v[212:215], v[172:175], v[40:43]
	v_mfma_f32_16x16x32_bf16 v[28:31], v[204:207], v[180:183], v[28:31]
	v_mfma_f32_16x16x32_bf16 v[24:27], v[212:215], v[180:183], v[24:27]
	v_mfma_f32_16x16x32_bf16 v[12:15], v[204:207], v[188:191], v[12:15]
	v_mfma_f32_16x16x32_bf16 v[8:11], v[212:215], v[188:191], v[8:11]
	v_mfma_f32_16x16x32_bf16 v[4:7], v[204:207], v[196:199], v[4:7]
	v_mfma_f32_16x16x32_bf16 v[0:3], v[212:215], v[196:199], v[0:3]
	v_mfma_f32_16x16x32_bf16 v[44:47], v[208:211], v[176:179], v[44:47]
	v_mfma_f32_16x16x32_bf16 v[40:43], v[216:219], v[176:179], v[40:43]
	v_mfma_f32_16x16x32_bf16 v[28:31], v[208:211], v[184:187], v[28:31]
	v_mfma_f32_16x16x32_bf16 v[24:27], v[216:219], v[184:187], v[24:27]
	v_mfma_f32_16x16x32_bf16 v[12:15], v[208:211], v[192:195], v[12:15]
	v_mfma_f32_16x16x32_bf16 v[8:11], v[216:219], v[192:195], v[8:11]
	v_mfma_f32_16x16x32_bf16 v[4:7], v[208:211], v[200:203], v[4:7]
	v_mfma_f32_16x16x32_bf16 v[0:3], v[216:219], v[200:203], v[0:3]
	s_setprio 1
	s_add_i32 s86, 0, 0x18000
	v_add_u32_e32 v155, s86, v150
	s_barrier
	ds_read_b128 v[156:159], v155
	ds_read_b128 v[160:163], v155 offset:1024
	ds_read_b128 v[164:167], v155 offset:2048
	ds_read_b128 v[168:171], v155 offset:3072
	s_add_u32 s54, s54, 0x100000
	s_addc_u32 s55, s55, 0
	s_mov_b32 m0, s62
	v_lshl_add_u64 v[204:205], s[54:55], 0, v[136:137]
	ds_read_b128 v[172:175], v153 offset:32768
	ds_read_b128 v[176:179], v153 offset:33792
	ds_read_b128 v[180:183], v153 offset:34816
	ds_read_b128 v[184:187], v153 offset:35840
	ds_read_b128 v[188:191], v153 offset:36864
	ds_read_b128 v[192:195], v153 offset:37888
	ds_read_b128 v[196:199], v153 offset:38912
	ds_read_b128 v[200:203], v153 offset:39936
	global_load_lds_dwordx4 v[204:205], off
	v_lshl_add_u64 v[204:205], s[54:55], 0, v[132:133]
	s_mov_b32 m0, s63
	s_nop 0
	global_load_lds_dwordx4 v[204:205], off
	s_waitcnt lgkmcnt(8)
	s_barrier
	s_waitcnt lgkmcnt(0)
	s_setprio 0
	s_waitcnt lgkmcnt(0)
	v_mfma_f32_16x16x32_bf16 v[124:127], v[156:159], v[172:175], v[124:127]
	v_mfma_f32_16x16x32_bf16 v[120:123], v[164:167], v[172:175], v[120:123]
	v_mfma_f32_16x16x32_bf16 v[116:119], v[156:159], v[180:183], v[116:119]
	v_mfma_f32_16x16x32_bf16 v[112:115], v[164:167], v[180:183], v[112:115]
	v_mfma_f32_16x16x32_bf16 v[100:103], v[156:159], v[188:191], v[100:103]
	v_mfma_f32_16x16x32_bf16 v[96:99], v[164:167], v[188:191], v[96:99]
	v_mfma_f32_16x16x32_bf16 v[84:87], v[156:159], v[196:199], v[84:87]
	v_mfma_f32_16x16x32_bf16 v[80:83], v[164:167], v[196:199], v[80:83]
	v_mfma_f32_16x16x32_bf16 v[124:127], v[160:163], v[176:179], v[124:127]
	v_mfma_f32_16x16x32_bf16 v[120:123], v[168:171], v[176:179], v[120:123]
	v_mfma_f32_16x16x32_bf16 v[116:119], v[160:163], v[184:187], v[116:119]
	v_mfma_f32_16x16x32_bf16 v[112:115], v[168:171], v[184:187], v[112:115]
	v_mfma_f32_16x16x32_bf16 v[100:103], v[160:163], v[192:195], v[100:103]
	v_mfma_f32_16x16x32_bf16 v[96:99], v[168:171], v[192:195], v[96:99]
	v_mfma_f32_16x16x32_bf16 v[84:87], v[160:163], v[200:203], v[84:87]
	v_mfma_f32_16x16x32_bf16 v[80:83], v[168:171], v[200:203], v[80:83]
	s_setprio 1
	s_barrier
	s_add_i32 s54, 0, 0x1c000
	s_add_i32 s55, s86, s57
	v_add_u32_e32 v155, s54, v150
	v_lshl_add_u64 v[220:221], v[220:221], 0, s[8:9]
	s_mov_b32 m0, s55
	ds_read_b128 v[204:207], v155
	ds_read_b128 v[208:211], v155 offset:1024
	ds_read_b128 v[212:215], v155 offset:2048
	ds_read_b128 v[216:219], v155 offset:3072
	global_load_lds_dwordx4 v[220:221], off
	v_lshl_add_u64 v[220:221], v[222:223], 0, s[8:9]
	s_add_i32 m0, s55, 0x2000
	s_nop 0
	global_load_lds_dwordx4 v[220:221], off
	s_barrier
	s_waitcnt lgkmcnt(0)
	s_setprio 0
	s_waitcnt lgkmcnt(0)
	v_mfma_f32_16x16x32_bf16 v[108:111], v[204:207], v[172:175], v[108:111]
	v_mfma_f32_16x16x32_bf16 v[104:107], v[212:215], v[172:175], v[104:107]
	v_mfma_f32_16x16x32_bf16 v[92:95], v[204:207], v[180:183], v[92:95]
	v_mfma_f32_16x16x32_bf16 v[88:91], v[212:215], v[180:183], v[88:91]
	v_mfma_f32_16x16x32_bf16 v[76:79], v[204:207], v[188:191], v[76:79]
	v_mfma_f32_16x16x32_bf16 v[72:75], v[212:215], v[188:191], v[72:75]
	v_mfma_f32_16x16x32_bf16 v[68:71], v[204:207], v[196:199], v[68:71]
	v_mfma_f32_16x16x32_bf16 v[64:67], v[212:215], v[196:199], v[64:67]
	v_mfma_f32_16x16x32_bf16 v[108:111], v[208:211], v[176:179], v[108:111]
	v_mfma_f32_16x16x32_bf16 v[104:107], v[216:219], v[176:179], v[104:107]
	v_mfma_f32_16x16x32_bf16 v[92:95], v[208:211], v[184:187], v[92:95]
	v_mfma_f32_16x16x32_bf16 v[88:91], v[216:219], v[184:187], v[88:91]
	v_mfma_f32_16x16x32_bf16 v[76:79], v[208:211], v[192:195], v[76:79]
	v_mfma_f32_16x16x32_bf16 v[72:75], v[216:219], v[192:195], v[72:75]
	v_mfma_f32_16x16x32_bf16 v[68:71], v[208:211], v[200:203], v[68:71]
	v_mfma_f32_16x16x32_bf16 v[64:67], v[216:219], v[200:203], v[64:67]
	s_setprio 1
	s_mov_b32 m0, s71
	v_lshl_add_u64 v[220:221], v[224:225], 0, s[8:9]
	s_barrier
	ds_read_b128 v[172:175], v153 offset:49152
	ds_read_b128 v[176:179], v153 offset:50176
	ds_read_b128 v[180:183], v153 offset:51200
	ds_read_b128 v[184:187], v153 offset:52224
	ds_read_b128 v[188:191], v153 offset:53248
	ds_read_b128 v[192:195], v153 offset:54272
	ds_read_b128 v[196:199], v153 offset:55296
	ds_read_b128 v[200:203], v153 offset:56320
	global_load_lds_dwordx4 v[220:221], off
	v_lshl_add_u64 v[220:221], v[226:227], 0, s[8:9]
	s_mov_b32 m0, s72
	s_nop 0
	global_load_lds_dwordx4 v[220:221], off
	s_barrier
	s_waitcnt lgkmcnt(0)
	s_setprio 0
	s_waitcnt lgkmcnt(0)
	v_mfma_f32_16x16x32_bf16 v[60:63], v[156:159], v[172:175], v[60:63]
	v_mfma_f32_16x16x32_bf16 v[56:59], v[164:167], v[172:175], v[56:59]
	v_mfma_f32_16x16x32_bf16 v[52:55], v[156:159], v[180:183], v[52:55]
	v_mfma_f32_16x16x32_bf16 v[48:51], v[164:167], v[180:183], v[48:51]
	v_mfma_f32_16x16x32_bf16 v[36:39], v[156:159], v[188:191], v[36:39]
	v_mfma_f32_16x16x32_bf16 v[32:35], v[164:167], v[188:191], v[32:35]
	v_mfma_f32_16x16x32_bf16 v[20:23], v[156:159], v[196:199], v[20:23]
	v_mfma_f32_16x16x32_bf16 v[16:19], v[164:167], v[196:199], v[16:19]
	v_mfma_f32_16x16x32_bf16 v[60:63], v[160:163], v[176:179], v[60:63]
	v_mfma_f32_16x16x32_bf16 v[56:59], v[168:171], v[176:179], v[56:59]
	v_mfma_f32_16x16x32_bf16 v[52:55], v[160:163], v[184:187], v[52:55]
	v_mfma_f32_16x16x32_bf16 v[48:51], v[168:171], v[184:187], v[48:51]
	v_mfma_f32_16x16x32_bf16 v[36:39], v[160:163], v[192:195], v[36:39]
	v_mfma_f32_16x16x32_bf16 v[32:35], v[168:171], v[192:195], v[32:35]
	v_mfma_f32_16x16x32_bf16 v[20:23], v[160:163], v[200:203], v[20:23]
	v_mfma_f32_16x16x32_bf16 v[16:19], v[168:171], v[200:203], v[16:19]
	s_setprio 1
	s_barrier
	s_add_u32 s34, s34, 0x100080
	s_addc_u32 s35, s35, 0
	s_add_i32 s54, s54, s57
	v_lshl_add_u64 v[156:157], s[34:35], 0, v[134:135]
	s_mov_b32 m0, s54
	s_nop 0
	global_load_lds_dwordx4 v[156:157], off
	v_lshl_add_u64 v[156:157], s[34:35], 0, v[130:131]
	s_add_i32 m0, s54, 0x2000
	s_nop 0
	global_load_lds_dwordx4 v[156:157], off
	s_waitcnt vmcnt(6)
	s_barrier
	s_setprio 0
	v_mfma_f32_16x16x32_bf16 v[44:47], v[204:207], v[172:175], v[44:47]
	v_mfma_f32_16x16x32_bf16 v[40:43], v[212:215], v[172:175], v[40:43]
	v_mfma_f32_16x16x32_bf16 v[28:31], v[204:207], v[180:183], v[28:31]
	v_mfma_f32_16x16x32_bf16 v[24:27], v[212:215], v[180:183], v[24:27]
	v_mfma_f32_16x16x32_bf16 v[12:15], v[204:207], v[188:191], v[12:15]
	v_mfma_f32_16x16x32_bf16 v[8:11], v[212:215], v[188:191], v[8:11]
	v_mfma_f32_16x16x32_bf16 v[4:7], v[204:207], v[196:199], v[4:7]
	v_mfma_f32_16x16x32_bf16 v[0:3], v[212:215], v[196:199], v[0:3]
	v_mfma_f32_16x16x32_bf16 v[44:47], v[208:211], v[176:179], v[44:47]
	v_mfma_f32_16x16x32_bf16 v[40:43], v[216:219], v[176:179], v[40:43]
	v_mfma_f32_16x16x32_bf16 v[28:31], v[208:211], v[184:187], v[28:31]
	v_mfma_f32_16x16x32_bf16 v[24:27], v[216:219], v[184:187], v[24:27]
	v_mfma_f32_16x16x32_bf16 v[12:15], v[208:211], v[192:195], v[12:15]
	v_mfma_f32_16x16x32_bf16 v[8:11], v[216:219], v[192:195], v[8:11]
	v_mfma_f32_16x16x32_bf16 v[4:7], v[208:211], v[200:203], v[4:7]
	v_mfma_f32_16x16x32_bf16 v[0:3], v[216:219], v[200:203], v[0:3]
	s_setprio 1
	s_add_i32 s85, s85, 2
	s_add_u32 s30, s30, 0x100
	s_addc_u32 s31, s31, 0
	s_add_u32 s83, s83, 0x100
	s_addc_u32 s84, s84, 0
	s_cmp_gt_u32 s85, 61
	s_barrier
	s_cbranch_scc0 .LBB0_776
	v_lshl_add_u32 v156, s16, 8, v149
	v_lshl_or_b32 v158, s80, 8, v151
	v_ashrrev_i32_e32 v157, 31, v156
	v_lshlrev_b64 v[160:161], 11, v[156:157]
	v_ashrrev_i32_e32 v159, 31, v158
	v_lshl_add_u64 v[160:161], s[44:45], 0, v[160:161]
	v_cvt_pk_bf16_f32 v124, v124, v125
	v_cvt_pk_bf16_f32 v125, v126, v127
	v_cvt_pk_bf16_f32 v126, v120, v121
	v_lshlrev_b64 v[120:121], 1, v[158:159]
	v_cvt_pk_bf16_f32 v127, v122, v123
	v_lshl_add_u64 v[122:123], v[160:161], 0, v[120:121]
	v_cvt_pk_bf16_f32 v108, v108, v109
	v_cvt_pk_bf16_f32 v109, v110, v111
	v_cvt_pk_bf16_f32 v110, v104, v105
	v_or_b32_e32 v104, 16, v156
	v_cvt_pk_bf16_f32 v60, v60, v61
	v_cvt_pk_bf16_f32 v61, v62, v63
	v_cvt_pk_bf16_f32 v63, v58, v59
	s_mov_b64 s[30:31], 0x40000
	v_add_co_u32_e32 v58, vcc, s76, v122
	v_ashrrev_i32_e32 v105, 31, v104
	v_cvt_pk_bf16_f32 v62, v56, v57
	v_lshl_add_u64 v[56:57], v[122:123], 0, s[30:31]
	v_addc_co_u32_e32 v59, vcc, 0, v123, vcc
	v_cvt_pk_bf16_f32 v44, v44, v45
	v_cvt_pk_bf16_f32 v45, v46, v47
	v_cvt_pk_bf16_f32 v46, v40, v41
	v_cvt_pk_bf16_f32 v47, v42, v43
	v_cvt_pk_bf16_f32 v111, v106, v107
	v_lshlrev_b64 v[104:105], 11, v[104:105]
	v_cvt_pk_bf16_f32 v92, v92, v93
	v_cvt_pk_bf16_f32 v93, v94, v95
	v_cvt_pk_bf16_f32 v94, v88, v89
	v_or_b32_e32 v88, 32, v156
	global_store_dwordx4 v[56:57], v[44:47], off offset:256
	global_store_dwordx4 v[122:123], v[108:111], off offset:256
	v_ashrrev_i32_e32 v89, 31, v88
	v_add_co_u32_e32 v46, vcc, s77, v122
	v_lshl_add_u64 v[108:109], s[44:45], 0, v[104:105]
	v_lshl_add_u64 v[44:45], v[122:123], 0, s[10:11]
	v_addc_co_u32_e32 v47, vcc, 0, v123, vcc
	v_cvt_pk_bf16_f32 v28, v28, v29
	v_cvt_pk_bf16_f32 v29, v30, v31
	v_cvt_pk_bf16_f32 v30, v24, v25
	v_cvt_pk_bf16_f32 v31, v26, v27
	v_lshl_add_u64 v[108:109], v[108:109], 0, v[120:121]
	v_cvt_pk_bf16_f32 v95, v90, v91
	v_lshlrev_b64 v[88:89], 11, v[88:89]
	v_cvt_pk_bf16_f32 v76, v76, v77
	v_cvt_pk_bf16_f32 v77, v78, v79
	v_cvt_pk_bf16_f32 v78, v72, v73
	v_or_b32_e32 v72, 48, v156
	global_store_dwordx4 v[44:45], v[28:31], off offset:256
	global_store_dwordx4 v[108:109], v[92:95], off offset:256
	v_ashrrev_i32_e32 v73, 31, v72
	v_add_co_u32_e32 v30, vcc, s78, v122
	v_lshl_add_u64 v[92:93], s[44:45], 0, v[88:89]
	v_lshl_add_u64 v[28:29], v[122:123], 0, s[12:13]
	v_addc_co_u32_e32 v31, vcc, 0, v123, vcc
	v_cvt_pk_bf16_f32 v12, v12, v13
	v_cvt_pk_bf16_f32 v13, v14, v15
	v_cvt_pk_bf16_f32 v14, v8, v9
	v_cvt_pk_bf16_f32 v15, v10, v11
	v_lshl_add_u64 v[92:93], v[92:93], 0, v[120:121]
	v_cvt_pk_bf16_f32 v79, v74, v75
	v_lshlrev_b64 v[72:73], 11, v[72:73]
	global_store_dwordx4 v[28:29], v[12:15], off offset:256
	global_store_dwordx4 v[92:93], v[76:79], off offset:256
	v_cvt_pk_bf16_f32 v104, v116, v117
	v_add_co_u32_e32 v14, vcc, s79, v122
	v_lshl_add_u64 v[76:77], s[44:45], 0, v[72:73]
	s_nop 0
	v_addc_co_u32_e32 v15, vcc, 0, v123, vcc
	v_cvt_pk_bf16_f32 v105, v118, v119
	v_cvt_pk_bf16_f32 v106, v112, v113
	v_cvt_pk_bf16_f32 v107, v114, v115
	v_cvt_pk_bf16_f32 v88, v100, v101
	v_cvt_pk_bf16_f32 v89, v102, v103
	v_cvt_pk_bf16_f32 v90, v96, v97
	v_cvt_pk_bf16_f32 v91, v98, v99
	v_cvt_pk_bf16_f32 v72, v84, v85
	v_cvt_pk_bf16_f32 v73, v86, v87
	v_cvt_pk_bf16_f32 v74, v80, v81
	v_cvt_pk_bf16_f32 v75, v82, v83
	v_lshl_add_u64 v[76:77], v[76:77], 0, v[120:121]
	v_cvt_pk_bf16_f32 v68, v68, v69
	v_cvt_pk_bf16_f32 v69, v70, v71
	v_cvt_pk_bf16_f32 v70, v64, v65
	v_cvt_pk_bf16_f32 v71, v66, v67
	v_cvt_pk_bf16_f32 v40, v52, v53
	v_cvt_pk_bf16_f32 v41, v54, v55
	v_cvt_pk_bf16_f32 v42, v48, v49
	v_cvt_pk_bf16_f32 v43, v50, v51
	v_cvt_pk_bf16_f32 v24, v36, v37
	v_cvt_pk_bf16_f32 v25, v38, v39
	v_cvt_pk_bf16_f32 v26, v32, v33
	v_cvt_pk_bf16_f32 v27, v34, v35
	v_cvt_pk_bf16_f32 v8, v20, v21
	v_cvt_pk_bf16_f32 v9, v22, v23
	v_cvt_pk_bf16_f32 v10, v16, v17
	v_cvt_pk_bf16_f32 v11, v18, v19
	v_lshl_add_u64 v[12:13], v[122:123], 0, s[14:15]
	v_cvt_pk_bf16_f32 v4, v4, v5
	v_cvt_pk_bf16_f32 v5, v6, v7
	v_cvt_pk_bf16_f32 v6, v0, v1
	v_cvt_pk_bf16_f32 v7, v2, v3
	s_and_b64 vcc, exec, s[4:5]
	s_mov_b32 s80, s18
	s_mov_b32 s16, s20
	s_mov_b64 s[34:35], s[28:29]
	s_mov_b64 s[30:31], s[26:27]
	global_store_dwordx4 v[122:123], v[124:127], off
	global_store_dwordx4 v[108:109], v[104:107], off
	global_store_dwordx4 v[92:93], v[88:91], off
	global_store_dwordx4 v[76:77], v[72:75], off
	global_store_dwordx4 v[76:77], v[68:71], off offset:256
	global_store_dwordx4 v[58:59], v[60:63], off
	global_store_dwordx4 v[46:47], v[40:43], off
	global_store_dwordx4 v[30:31], v[24:27], off
	global_store_dwordx4 v[14:15], v[8:11], off
	global_store_dwordx4 v[12:13], v[4:7], off offset:256
	s_cbranch_vccz .LBB0_773
	s_waitcnt vmcnt(0)
	s_cmpk_gt_u32 s56, 0xff
	s_cbranch_scc1 .LBB0_780
	s_barrier

.LBB0_912:
	ds_read_b128 v[156:159], v152
	ds_read_b128 v[160:163], v152 offset:1024
	ds_read_b128 v[164:167], v152 offset:2048
	ds_read_b128 v[168:171], v152 offset:3072
	s_add_u32 s54, s34, 0xfffc0080
	s_addc_u32 s55, s35, -1
	s_cmp_eq_u32 s87, 12
	s_cselect_b32 s57, s27, s55
	s_cselect_b32 s56, s83, s54
	s_cselect_b32 s55, s21, s86
	s_cselect_b32 s54, s84, s85
	v_lshl_add_u64 v[204:205], s[34:35], 0, v[138:139]
	s_add_i32 m0, s19, 0xc000
	ds_read_b128 v[172:175], v153
	ds_read_b128 v[176:179], v153 offset:1024
	ds_read_b128 v[180:183], v153 offset:2048
	ds_read_b128 v[184:187], v153 offset:3072
	ds_read_b128 v[188:191], v153 offset:4096
	ds_read_b128 v[192:195], v153 offset:5120
	ds_read_b128 v[196:199], v153 offset:6144
	ds_read_b128 v[200:203], v153 offset:7168
	global_load_lds_dwordx4 v[204:205], off
	v_lshl_add_u64 v[204:205], s[34:35], 0, v[140:141]
	s_add_i32 m0, s19, 0xe000
	s_nop 0
	global_load_lds_dwordx4 v[204:205], off
	s_waitcnt lgkmcnt(8)
	s_barrier
	s_waitcnt lgkmcnt(0)
	s_setprio 0
	s_waitcnt lgkmcnt(0)
	v_mfma_f32_16x16x32_bf16 v[124:127], v[156:159], v[172:175], v[124:127]
	v_mfma_f32_16x16x32_bf16 v[120:123], v[164:167], v[172:175], v[120:123]
	v_mfma_f32_16x16x32_bf16 v[116:119], v[156:159], v[180:183], v[116:119]
	v_mfma_f32_16x16x32_bf16 v[112:115], v[164:167], v[180:183], v[112:115]
	v_mfma_f32_16x16x32_bf16 v[100:103], v[156:159], v[188:191], v[100:103]
	v_mfma_f32_16x16x32_bf16 v[96:99], v[164:167], v[188:191], v[96:99]
	v_mfma_f32_16x16x32_bf16 v[84:87], v[156:159], v[196:199], v[84:87]
	v_mfma_f32_16x16x32_bf16 v[80:83], v[164:167], v[196:199], v[80:83]
	v_mfma_f32_16x16x32_bf16 v[124:127], v[160:163], v[176:179], v[124:127]
	v_mfma_f32_16x16x32_bf16 v[120:123], v[168:171], v[176:179], v[120:123]
	v_mfma_f32_16x16x32_bf16 v[116:119], v[160:163], v[184:187], v[116:119]
	v_mfma_f32_16x16x32_bf16 v[112:115], v[168:171], v[184:187], v[112:115]
	v_mfma_f32_16x16x32_bf16 v[100:103], v[160:163], v[192:195], v[100:103]
	v_mfma_f32_16x16x32_bf16 v[96:99], v[168:171], v[192:195], v[96:99]
	v_mfma_f32_16x16x32_bf16 v[84:87], v[160:163], v[200:203], v[84:87]
	v_mfma_f32_16x16x32_bf16 v[80:83], v[168:171], v[200:203], v[80:83]
	s_setprio 1
	s_barrier
	s_add_i32 s88, s76, s61
	v_lshl_add_u64 v[220:221], s[54:55], 0, v[134:135]
	s_mov_b32 m0, s88
	ds_read_b128 v[204:207], v154
	ds_read_b128 v[208:211], v154 offset:1024
	ds_read_b128 v[212:215], v154 offset:2048
	ds_read_b128 v[216:219], v154 offset:3072
	global_load_lds_dwordx4 v[220:221], off
	v_lshl_add_u64 v[222:223], s[54:55], 0, v[130:131]
	s_add_i32 m0, s88, 0x2000
	s_nop 0
	global_load_lds_dwordx4 v[222:223], off
	s_barrier
	s_waitcnt lgkmcnt(0)
	s_setprio 0
	s_waitcnt lgkmcnt(0)
	v_mfma_f32_16x16x32_bf16 v[108:111], v[204:207], v[172:175], v[108:111]
	v_mfma_f32_16x16x32_bf16 v[104:107], v[212:215], v[172:175], v[104:107]
	v_mfma_f32_16x16x32_bf16 v[92:95], v[204:207], v[180:183], v[92:95]
	v_mfma_f32_16x16x32_bf16 v[88:91], v[212:215], v[180:183], v[88:91]
	v_mfma_f32_16x16x32_bf16 v[76:79], v[204:207], v[188:191], v[76:79]
	v_mfma_f32_16x16x32_bf16 v[72:75], v[212:215], v[188:191], v[72:75]
	v_mfma_f32_16x16x32_bf16 v[68:71], v[204:207], v[196:199], v[68:71]
	v_mfma_f32_16x16x32_bf16 v[64:67], v[212:215], v[196:199], v[64:67]
	v_mfma_f32_16x16x32_bf16 v[108:111], v[208:211], v[176:179], v[108:111]
	v_mfma_f32_16x16x32_bf16 v[104:107], v[216:219], v[176:179], v[104:107]
	v_mfma_f32_16x16x32_bf16 v[92:95], v[208:211], v[184:187], v[92:95]
	v_mfma_f32_16x16x32_bf16 v[88:91], v[216:219], v[184:187], v[88:91]
	v_mfma_f32_16x16x32_bf16 v[76:79], v[208:211], v[192:195], v[76:79]
	v_mfma_f32_16x16x32_bf16 v[72:75], v[216:219], v[192:195], v[72:75]
	v_mfma_f32_16x16x32_bf16 v[68:71], v[208:211], v[200:203], v[68:71]
	v_mfma_f32_16x16x32_bf16 v[64:67], v[216:219], v[200:203], v[64:67]
	s_setprio 1
	s_mov_b32 m0, s19
	v_lshl_add_u64 v[224:225], s[56:57], 0, v[136:137]
	s_barrier
	ds_read_b128 v[172:175], v153 offset:16384
	ds_read_b128 v[176:179], v153 offset:17408
	ds_read_b128 v[180:183], v153 offset:18432
	ds_read_b128 v[184:187], v153 offset:19456
	ds_read_b128 v[188:191], v153 offset:20480
	ds_read_b128 v[192:195], v153 offset:21504
	ds_read_b128 v[196:199], v153 offset:22528
	ds_read_b128 v[200:203], v153 offset:23552
	global_load_lds_dwordx4 v[224:225], off
	v_lshl_add_u64 v[226:227], s[56:57], 0, v[132:133]
	s_mov_b32 m0, s63
	s_nop 0
	global_load_lds_dwordx4 v[226:227], off
	s_barrier
	s_waitcnt lgkmcnt(0)
	s_setprio 0
	s_waitcnt lgkmcnt(0)
	v_mfma_f32_16x16x32_bf16 v[60:63], v[156:159], v[172:175], v[60:63]
	v_mfma_f32_16x16x32_bf16 v[56:59], v[164:167], v[172:175], v[56:59]
	v_mfma_f32_16x16x32_bf16 v[52:55], v[156:159], v[180:183], v[52:55]
	v_mfma_f32_16x16x32_bf16 v[48:51], v[164:167], v[180:183], v[48:51]
	v_mfma_f32_16x16x32_bf16 v[36:39], v[156:159], v[188:191], v[36:39]
	v_mfma_f32_16x16x32_bf16 v[32:35], v[164:167], v[188:191], v[32:35]
	v_mfma_f32_16x16x32_bf16 v[20:23], v[156:159], v[196:199], v[20:23]
	v_mfma_f32_16x16x32_bf16 v[16:19], v[164:167], v[196:199], v[16:19]
	v_mfma_f32_16x16x32_bf16 v[60:63], v[160:163], v[176:179], v[60:63]
	v_mfma_f32_16x16x32_bf16 v[56:59], v[168:171], v[176:179], v[56:59]
	v_mfma_f32_16x16x32_bf16 v[52:55], v[160:163], v[184:187], v[52:55]
	v_mfma_f32_16x16x32_bf16 v[48:51], v[168:171], v[184:187], v[48:51]
	v_mfma_f32_16x16x32_bf16 v[36:39], v[160:163], v[192:195], v[36:39]
	v_mfma_f32_16x16x32_bf16 v[32:35], v[168:171], v[192:195], v[32:35]
	v_mfma_f32_16x16x32_bf16 v[20:23], v[160:163], v[200:203], v[20:23]
	v_mfma_f32_16x16x32_bf16 v[16:19], v[168:171], v[200:203], v[16:19]
	s_setprio 1
	s_barrier
	s_add_u32 s88, s54, 0x40000
	s_addc_u32 s89, s55, 0
	s_add_i32 s90, s77, s61
	v_lshl_add_u64 v[156:157], s[88:89], 0, v[134:135]
	s_mov_b32 m0, s90
	s_nop 0
	global_load_lds_dwordx4 v[156:157], off
	v_lshl_add_u64 v[156:157], s[88:89], 0, v[130:131]
	s_add_i32 m0, s90, 0x2000
	s_nop 0
	global_load_lds_dwordx4 v[156:157], off
	s_waitcnt vmcnt(6)
	s_barrier
	s_setprio 0
	v_mfma_f32_16x16x32_bf16 v[44:47], v[204:207], v[172:175], v[44:47]
	v_mfma_f32_16x16x32_bf16 v[40:43], v[212:215], v[172:175], v[40:43]
	v_mfma_f32_16x16x32_bf16 v[28:31], v[204:207], v[180:183], v[28:31]
	v_mfma_f32_16x16x32_bf16 v[24:27], v[212:215], v[180:183], v[24:27]
	v_mfma_f32_16x16x32_bf16 v[12:15], v[204:207], v[188:191], v[12:15]
	v_mfma_f32_16x16x32_bf16 v[8:11], v[212:215], v[188:191], v[8:11]
	v_mfma_f32_16x16x32_bf16 v[4:7], v[204:207], v[196:199], v[4:7]
	v_mfma_f32_16x16x32_bf16 v[0:3], v[212:215], v[196:199], v[0:3]
	v_mfma_f32_16x16x32_bf16 v[44:47], v[208:211], v[176:179], v[44:47]
	v_mfma_f32_16x16x32_bf16 v[40:43], v[216:219], v[176:179], v[40:43]
	v_mfma_f32_16x16x32_bf16 v[28:31], v[208:211], v[184:187], v[28:31]
	v_mfma_f32_16x16x32_bf16 v[24:27], v[216:219], v[184:187], v[24:27]
	v_mfma_f32_16x16x32_bf16 v[12:15], v[208:211], v[192:195], v[12:15]
	v_mfma_f32_16x16x32_bf16 v[8:11], v[216:219], v[192:195], v[8:11]
	v_mfma_f32_16x16x32_bf16 v[4:7], v[208:211], v[200:203], v[4:7]
	v_mfma_f32_16x16x32_bf16 v[0:3], v[216:219], v[200:203], v[0:3]
	s_setprio 1
	s_add_i32 s88, 0, 0x18000
	v_add_u32_e32 v155, s88, v150
	s_barrier
	ds_read_b128 v[156:159], v155
	ds_read_b128 v[160:163], v155 offset:1024
	ds_read_b128 v[164:167], v155 offset:2048
	ds_read_b128 v[168:171], v155 offset:3072
	s_add_u32 s56, s56, 0x40000
	s_addc_u32 s57, s57, 0
	s_mov_b32 m0, s70
	v_lshl_add_u64 v[204:205], s[56:57], 0, v[136:137]
	ds_read_b128 v[172:175], v153 offset:32768
	ds_read_b128 v[176:179], v153 offset:33792
	ds_read_b128 v[180:183], v153 offset:34816
	ds_read_b128 v[184:187], v153 offset:35840
	ds_read_b128 v[188:191], v153 offset:36864
	ds_read_b128 v[192:195], v153 offset:37888
	ds_read_b128 v[196:199], v153 offset:38912
	ds_read_b128 v[200:203], v153 offset:39936
	global_load_lds_dwordx4 v[204:205], off
	v_lshl_add_u64 v[204:205], s[56:57], 0, v[132:133]
	s_mov_b32 m0, s71
	s_nop 0
	global_load_lds_dwordx4 v[204:205], off
	s_waitcnt lgkmcnt(8)
	s_barrier
	s_waitcnt lgkmcnt(0)
	s_setprio 0
	s_waitcnt lgkmcnt(0)
	v_mfma_f32_16x16x32_bf16 v[124:127], v[156:159], v[172:175], v[124:127]
	v_mfma_f32_16x16x32_bf16 v[120:123], v[164:167], v[172:175], v[120:123]
	v_mfma_f32_16x16x32_bf16 v[116:119], v[156:159], v[180:183], v[116:119]
	v_mfma_f32_16x16x32_bf16 v[112:115], v[164:167], v[180:183], v[112:115]
	v_mfma_f32_16x16x32_bf16 v[100:103], v[156:159], v[188:191], v[100:103]
	v_mfma_f32_16x16x32_bf16 v[96:99], v[164:167], v[188:191], v[96:99]
	v_mfma_f32_16x16x32_bf16 v[84:87], v[156:159], v[196:199], v[84:87]
	v_mfma_f32_16x16x32_bf16 v[80:83], v[164:167], v[196:199], v[80:83]
	v_mfma_f32_16x16x32_bf16 v[124:127], v[160:163], v[176:179], v[124:127]
	v_mfma_f32_16x16x32_bf16 v[120:123], v[168:171], v[176:179], v[120:123]
	v_mfma_f32_16x16x32_bf16 v[116:119], v[160:163], v[184:187], v[116:119]
	v_mfma_f32_16x16x32_bf16 v[112:115], v[168:171], v[184:187], v[112:115]
	v_mfma_f32_16x16x32_bf16 v[100:103], v[160:163], v[192:195], v[100:103]
	v_mfma_f32_16x16x32_bf16 v[96:99], v[168:171], v[192:195], v[96:99]
	v_mfma_f32_16x16x32_bf16 v[84:87], v[160:163], v[200:203], v[84:87]
	v_mfma_f32_16x16x32_bf16 v[80:83], v[168:171], v[200:203], v[80:83]
	s_setprio 1
	s_barrier
	s_add_i32 s56, 0, 0x1c000
	s_add_i32 s57, s88, s61
	v_add_u32_e32 v155, s56, v150
	v_lshl_add_u64 v[220:221], v[220:221], 0, s[10:11]
	s_mov_b32 m0, s57
	ds_read_b128 v[204:207], v155
	ds_read_b128 v[208:211], v155 offset:1024
	ds_read_b128 v[212:215], v155 offset:2048
	ds_read_b128 v[216:219], v155 offset:3072
	global_load_lds_dwordx4 v[220:221], off
	v_lshl_add_u64 v[220:221], v[222:223], 0, s[10:11]
	s_add_i32 m0, s57, 0x2000
	s_nop 0
	global_load_lds_dwordx4 v[220:221], off
	s_barrier
	s_waitcnt lgkmcnt(0)
	s_setprio 0
	s_waitcnt lgkmcnt(0)
	v_mfma_f32_16x16x32_bf16 v[108:111], v[204:207], v[172:175], v[108:111]
	v_mfma_f32_16x16x32_bf16 v[104:107], v[212:215], v[172:175], v[104:107]
	v_mfma_f32_16x16x32_bf16 v[92:95], v[204:207], v[180:183], v[92:95]
	v_mfma_f32_16x16x32_bf16 v[88:91], v[212:215], v[180:183], v[88:91]
	v_mfma_f32_16x16x32_bf16 v[76:79], v[204:207], v[188:191], v[76:79]
	v_mfma_f32_16x16x32_bf16 v[72:75], v[212:215], v[188:191], v[72:75]
	v_mfma_f32_16x16x32_bf16 v[68:71], v[204:207], v[196:199], v[68:71]
	v_mfma_f32_16x16x32_bf16 v[64:67], v[212:215], v[196:199], v[64:67]
	v_mfma_f32_16x16x32_bf16 v[108:111], v[208:211], v[176:179], v[108:111]
	v_mfma_f32_16x16x32_bf16 v[104:107], v[216:219], v[176:179], v[104:107]
	v_mfma_f32_16x16x32_bf16 v[92:95], v[208:211], v[184:187], v[92:95]
	v_mfma_f32_16x16x32_bf16 v[88:91], v[216:219], v[184:187], v[88:91]
	v_mfma_f32_16x16x32_bf16 v[76:79], v[208:211], v[192:195], v[76:79]
	v_mfma_f32_16x16x32_bf16 v[72:75], v[216:219], v[192:195], v[72:75]
	v_mfma_f32_16x16x32_bf16 v[68:71], v[208:211], v[200:203], v[68:71]
	v_mfma_f32_16x16x32_bf16 v[64:67], v[216:219], v[200:203], v[64:67]
	s_setprio 1
	s_mov_b32 m0, s73
	v_lshl_add_u64 v[220:221], v[224:225], 0, s[10:11]
	s_barrier
	ds_read_b128 v[172:175], v153 offset:49152
	ds_read_b128 v[176:179], v153 offset:50176
	ds_read_b128 v[180:183], v153 offset:51200
	ds_read_b128 v[184:187], v153 offset:52224
	ds_read_b128 v[188:191], v153 offset:53248
	ds_read_b128 v[192:195], v153 offset:54272
	ds_read_b128 v[196:199], v153 offset:55296
	ds_read_b128 v[200:203], v153 offset:56320
	global_load_lds_dwordx4 v[220:221], off
	v_lshl_add_u64 v[220:221], v[226:227], 0, s[10:11]
	s_mov_b32 m0, s74
	s_nop 0
	global_load_lds_dwordx4 v[220:221], off
	s_barrier
	s_waitcnt lgkmcnt(0)
	s_setprio 0
	s_waitcnt lgkmcnt(0)
	v_mfma_f32_16x16x32_bf16 v[60:63], v[156:159], v[172:175], v[60:63]
	v_mfma_f32_16x16x32_bf16 v[56:59], v[164:167], v[172:175], v[56:59]
	v_mfma_f32_16x16x32_bf16 v[52:55], v[156:159], v[180:183], v[52:55]
	v_mfma_f32_16x16x32_bf16 v[48:51], v[164:167], v[180:183], v[48:51]
	v_mfma_f32_16x16x32_bf16 v[36:39], v[156:159], v[188:191], v[36:39]
	v_mfma_f32_16x16x32_bf16 v[32:35], v[164:167], v[188:191], v[32:35]
	v_mfma_f32_16x16x32_bf16 v[20:23], v[156:159], v[196:199], v[20:23]
	v_mfma_f32_16x16x32_bf16 v[16:19], v[164:167], v[196:199], v[16:19]
	v_mfma_f32_16x16x32_bf16 v[60:63], v[160:163], v[176:179], v[60:63]
	v_mfma_f32_16x16x32_bf16 v[56:59], v[168:171], v[176:179], v[56:59]
	v_mfma_f32_16x16x32_bf16 v[52:55], v[160:163], v[184:187], v[52:55]
	v_mfma_f32_16x16x32_bf16 v[48:51], v[168:171], v[184:187], v[48:51]
	v_mfma_f32_16x16x32_bf16 v[36:39], v[160:163], v[192:195], v[36:39]
	v_mfma_f32_16x16x32_bf16 v[32:35], v[168:171], v[192:195], v[32:35]
	v_mfma_f32_16x16x32_bf16 v[20:23], v[160:163], v[200:203], v[20:23]
	v_mfma_f32_16x16x32_bf16 v[16:19], v[168:171], v[200:203], v[16:19]
	s_setprio 1
	s_barrier
	s_add_u32 s54, s54, 0x40080
	s_addc_u32 s55, s55, 0
	s_add_i32 s56, s56, s61
	v_lshl_add_u64 v[156:157], s[54:55], 0, v[134:135]
	s_mov_b32 m0, s56
	s_nop 0
	global_load_lds_dwordx4 v[156:157], off
	v_lshl_add_u64 v[156:157], s[54:55], 0, v[130:131]
	s_add_i32 m0, s56, 0x2000
	s_nop 0
	global_load_lds_dwordx4 v[156:157], off
	s_waitcnt vmcnt(6)
	s_barrier
	s_setprio 0
	v_mfma_f32_16x16x32_bf16 v[44:47], v[204:207], v[172:175], v[44:47]
	v_mfma_f32_16x16x32_bf16 v[40:43], v[212:215], v[172:175], v[40:43]
	v_mfma_f32_16x16x32_bf16 v[28:31], v[204:207], v[180:183], v[28:31]
	v_mfma_f32_16x16x32_bf16 v[24:27], v[212:215], v[180:183], v[24:27]
	v_mfma_f32_16x16x32_bf16 v[12:15], v[204:207], v[188:191], v[12:15]
	v_mfma_f32_16x16x32_bf16 v[8:11], v[212:215], v[188:191], v[8:11]
	v_mfma_f32_16x16x32_bf16 v[4:7], v[204:207], v[196:199], v[4:7]
	v_mfma_f32_16x16x32_bf16 v[0:3], v[212:215], v[196:199], v[0:3]
	v_mfma_f32_16x16x32_bf16 v[44:47], v[208:211], v[176:179], v[44:47]
	v_mfma_f32_16x16x32_bf16 v[40:43], v[216:219], v[176:179], v[40:43]
	v_mfma_f32_16x16x32_bf16 v[28:31], v[208:211], v[184:187], v[28:31]
	v_mfma_f32_16x16x32_bf16 v[24:27], v[216:219], v[184:187], v[24:27]
	v_mfma_f32_16x16x32_bf16 v[12:15], v[208:211], v[192:195], v[12:15]
	v_mfma_f32_16x16x32_bf16 v[8:11], v[216:219], v[192:195], v[8:11]
	v_mfma_f32_16x16x32_bf16 v[4:7], v[208:211], v[200:203], v[4:7]
	v_mfma_f32_16x16x32_bf16 v[0:3], v[216:219], v[200:203], v[0:3]
	s_setprio 1
	s_add_i32 s87, s87, 2
	s_add_u32 s34, s34, 0x100
	s_addc_u32 s35, s35, 0
	s_add_u32 s85, s85, 0x100
	s_addc_u32 s86, s86, 0
	s_cmp_gt_u32 s87, 13
	s_barrier
	s_cbranch_scc0 .LBB0_912
	v_lshl_add_u32 v156, s18, 8, v149
	v_lshl_or_b32 v158, s82, 8, v151
	v_ashrrev_i32_e32 v157, 31, v156
	v_lshlrev_b64 v[160:161], 11, v[156:157]
	v_ashrrev_i32_e32 v159, 31, v158
	v_lshl_add_u64 v[160:161], s[46:47], 0, v[160:161]
	v_cvt_pk_bf16_f32 v124, v124, v125
	v_cvt_pk_bf16_f32 v125, v126, v127
	v_cvt_pk_bf16_f32 v126, v120, v121
	v_lshlrev_b64 v[120:121], 1, v[158:159]
	v_cvt_pk_bf16_f32 v127, v122, v123
	v_lshl_add_u64 v[122:123], v[160:161], 0, v[120:121]
	v_cvt_pk_bf16_f32 v108, v108, v109
	v_cvt_pk_bf16_f32 v109, v110, v111
	v_cvt_pk_bf16_f32 v110, v104, v105
	v_or_b32_e32 v104, 16, v156
	v_cvt_pk_bf16_f32 v60, v60, v61
	v_cvt_pk_bf16_f32 v61, v62, v63
	v_cvt_pk_bf16_f32 v63, v58, v59
	v_add_co_u32_e32 v58, vcc, s78, v122
	v_ashrrev_i32_e32 v105, 31, v104
	v_cvt_pk_bf16_f32 v62, v56, v57
	v_lshl_add_u64 v[56:57], v[122:123], 0, s[8:9]
	v_addc_co_u32_e32 v59, vcc, 0, v123, vcc
	v_cvt_pk_bf16_f32 v44, v44, v45
	v_cvt_pk_bf16_f32 v45, v46, v47
	v_cvt_pk_bf16_f32 v46, v40, v41
	v_cvt_pk_bf16_f32 v47, v42, v43
	v_cvt_pk_bf16_f32 v111, v106, v107
	v_lshlrev_b64 v[104:105], 11, v[104:105]
	v_cvt_pk_bf16_f32 v92, v92, v93
	v_cvt_pk_bf16_f32 v93, v94, v95
	v_cvt_pk_bf16_f32 v94, v88, v89
	v_or_b32_e32 v88, 32, v156
	global_store_dwordx4 v[56:57], v[44:47], off offset:256
	global_store_dwordx4 v[122:123], v[108:111], off offset:256
	v_ashrrev_i32_e32 v89, 31, v88
	v_add_co_u32_e32 v46, vcc, s79, v122
	v_lshl_add_u64 v[108:109], s[46:47], 0, v[104:105]
	v_lshl_add_u64 v[44:45], v[122:123], 0, s[12:13]
	v_addc_co_u32_e32 v47, vcc, 0, v123, vcc
	v_cvt_pk_bf16_f32 v28, v28, v29
	v_cvt_pk_bf16_f32 v29, v30, v31
	v_cvt_pk_bf16_f32 v30, v24, v25
	v_cvt_pk_bf16_f32 v31, v26, v27
	v_lshl_add_u64 v[108:109], v[108:109], 0, v[120:121]
	v_cvt_pk_bf16_f32 v95, v90, v91
	v_lshlrev_b64 v[88:89], 11, v[88:89]
	v_cvt_pk_bf16_f32 v76, v76, v77
	v_cvt_pk_bf16_f32 v77, v78, v79
	v_cvt_pk_bf16_f32 v78, v72, v73
	v_or_b32_e32 v72, 48, v156
	global_store_dwordx4 v[44:45], v[28:31], off offset:256
	global_store_dwordx4 v[108:109], v[92:95], off offset:256
	v_ashrrev_i32_e32 v73, 31, v72
	v_add_co_u32_e32 v30, vcc, s80, v122
	v_lshl_add_u64 v[92:93], s[46:47], 0, v[88:89]
	v_lshl_add_u64 v[28:29], v[122:123], 0, s[14:15]
	v_addc_co_u32_e32 v31, vcc, 0, v123, vcc
	v_cvt_pk_bf16_f32 v12, v12, v13
	v_cvt_pk_bf16_f32 v13, v14, v15
	v_cvt_pk_bf16_f32 v14, v8, v9
	v_cvt_pk_bf16_f32 v15, v10, v11
	v_lshl_add_u64 v[92:93], v[92:93], 0, v[120:121]
	v_cvt_pk_bf16_f32 v79, v74, v75
	v_lshlrev_b64 v[72:73], 11, v[72:73]
	global_store_dwordx4 v[28:29], v[12:15], off offset:256
	global_store_dwordx4 v[92:93], v[76:79], off offset:256
	v_cvt_pk_bf16_f32 v104, v116, v117
	v_add_co_u32_e32 v14, vcc, s81, v122
	v_lshl_add_u64 v[76:77], s[46:47], 0, v[72:73]
	s_nop 0
	v_addc_co_u32_e32 v15, vcc, 0, v123, vcc
	v_cvt_pk_bf16_f32 v105, v118, v119
	v_cvt_pk_bf16_f32 v106, v112, v113
	v_cvt_pk_bf16_f32 v107, v114, v115
	v_cvt_pk_bf16_f32 v88, v100, v101
	v_cvt_pk_bf16_f32 v89, v102, v103
	v_cvt_pk_bf16_f32 v90, v96, v97
	v_cvt_pk_bf16_f32 v91, v98, v99
	v_cvt_pk_bf16_f32 v72, v84, v85
	v_cvt_pk_bf16_f32 v73, v86, v87
	v_cvt_pk_bf16_f32 v74, v80, v81
	v_cvt_pk_bf16_f32 v75, v82, v83
	v_lshl_add_u64 v[76:77], v[76:77], 0, v[120:121]
	v_cvt_pk_bf16_f32 v68, v68, v69
	v_cvt_pk_bf16_f32 v69, v70, v71
	v_cvt_pk_bf16_f32 v70, v64, v65
	v_cvt_pk_bf16_f32 v71, v66, v67
	v_cvt_pk_bf16_f32 v40, v52, v53
	v_cvt_pk_bf16_f32 v41, v54, v55
	v_cvt_pk_bf16_f32 v42, v48, v49
	v_cvt_pk_bf16_f32 v43, v50, v51
	v_cvt_pk_bf16_f32 v24, v36, v37
	v_cvt_pk_bf16_f32 v25, v38, v39
	v_cvt_pk_bf16_f32 v26, v32, v33
	v_cvt_pk_bf16_f32 v27, v34, v35
	v_cvt_pk_bf16_f32 v8, v20, v21
	v_cvt_pk_bf16_f32 v9, v22, v23
	v_cvt_pk_bf16_f32 v10, v16, v17
	v_cvt_pk_bf16_f32 v11, v18, v19
	v_lshl_add_u64 v[12:13], v[122:123], 0, s[16:17]
	v_cvt_pk_bf16_f32 v4, v4, v5
	v_cvt_pk_bf16_f32 v5, v6, v7
	v_cvt_pk_bf16_f32 v6, v0, v1
	v_cvt_pk_bf16_f32 v7, v2, v3
	s_and_b64 vcc, exec, s[4:5]
	s_mov_b32 s82, s20
	s_mov_b32 s18, s26
	s_mov_b64 s[54:55], s[30:31]
	s_mov_b64 s[34:35], s[28:29]
	global_store_dwordx4 v[122:123], v[124:127], off
	global_store_dwordx4 v[108:109], v[104:107], off
	global_store_dwordx4 v[92:93], v[88:91], off
	global_store_dwordx4 v[76:77], v[72:75], off
	global_store_dwordx4 v[76:77], v[68:71], off offset:256
	global_store_dwordx4 v[58:59], v[60:63], off
	global_store_dwordx4 v[46:47], v[40:43], off
	global_store_dwordx4 v[30:31], v[24:27], off
	global_store_dwordx4 v[14:15], v[8:11], off
	global_store_dwordx4 v[12:13], v[4:7], off offset:256
	s_cbranch_vccz .LBB0_909
	s_waitcnt vmcnt(0)
	s_cmpk_gt_u32 s60, 0xff
	s_cbranch_scc1 .LBB0_916
	s_barrier

.LBB0_1116:
	ds_read_b128 v[154:157], v150
	ds_read_b128 v[158:161], v150 offset:1024
	ds_read_b128 v[162:165], v150 offset:2048
	ds_read_b128 v[166:169], v150 offset:3072
	s_add_u32 s34, s30, 0xfffc0080
	s_addc_u32 s35, s31, -1
	s_cmp_eq_u32 s77, 12
	s_cselect_b32 s37, s19, s35
	s_cselect_b32 s36, s73, s34
	s_cselect_b32 s35, s17, s76
	s_cselect_b32 s34, s74, s75
	v_lshl_add_u64 v[202:203], s[30:31], 0, v[134:135]
	s_add_i32 m0, s29, 0xc000
	ds_read_b128 v[170:173], v151
	ds_read_b128 v[174:177], v151 offset:1024
	ds_read_b128 v[178:181], v151 offset:2048
	ds_read_b128 v[182:185], v151 offset:3072
	ds_read_b128 v[186:189], v151 offset:4096
	ds_read_b128 v[190:193], v151 offset:5120
	ds_read_b128 v[194:197], v151 offset:6144
	ds_read_b128 v[198:201], v151 offset:7168
	global_load_lds_dwordx4 v[202:203], off
	v_lshl_add_u64 v[202:203], s[30:31], 0, v[136:137]
	s_add_i32 m0, s29, 0xe000
	s_nop 0
	global_load_lds_dwordx4 v[202:203], off
	s_waitcnt lgkmcnt(8)
	s_barrier
	s_waitcnt lgkmcnt(0)
	s_setprio 0
	s_waitcnt lgkmcnt(0)
	v_mfma_f32_16x16x32_bf16 v[120:123], v[154:157], v[170:173], v[120:123]
	v_mfma_f32_16x16x32_bf16 v[124:127], v[162:165], v[170:173], v[124:127]
	v_mfma_f32_16x16x32_bf16 v[104:107], v[154:157], v[178:181], v[104:107]
	v_mfma_f32_16x16x32_bf16 v[108:111], v[162:165], v[178:181], v[108:111]
	v_mfma_f32_16x16x32_bf16 v[88:91], v[154:157], v[186:189], v[88:91]
	v_mfma_f32_16x16x32_bf16 v[92:95], v[162:165], v[186:189], v[92:95]
	v_mfma_f32_16x16x32_bf16 v[72:75], v[154:157], v[194:197], v[72:75]
	v_mfma_f32_16x16x32_bf16 v[76:79], v[162:165], v[194:197], v[76:79]
	v_mfma_f32_16x16x32_bf16 v[120:123], v[158:161], v[174:177], v[120:123]
	v_mfma_f32_16x16x32_bf16 v[124:127], v[166:169], v[174:177], v[124:127]
	v_mfma_f32_16x16x32_bf16 v[104:107], v[158:161], v[182:185], v[104:107]
	v_mfma_f32_16x16x32_bf16 v[108:111], v[166:169], v[182:185], v[108:111]
	v_mfma_f32_16x16x32_bf16 v[88:91], v[158:161], v[190:193], v[88:91]
	v_mfma_f32_16x16x32_bf16 v[92:95], v[166:169], v[190:193], v[92:95]
	v_mfma_f32_16x16x32_bf16 v[72:75], v[158:161], v[198:201], v[72:75]
	v_mfma_f32_16x16x32_bf16 v[76:79], v[166:169], v[198:201], v[76:79]
	s_setprio 1
	s_barrier
	s_add_i32 s78, s60, s42
	v_lshl_add_u64 v[218:219], s[34:35], 0, v[130:131]
	s_mov_b32 m0, s78
	ds_read_b128 v[202:205], v152
	ds_read_b128 v[206:209], v152 offset:1024
	ds_read_b128 v[210:213], v152 offset:2048
	ds_read_b128 v[214:217], v152 offset:3072
	global_load_lds_dwordx4 v[218:219], off
	v_lshl_add_u64 v[220:221], s[34:35], 0, v[132:133]
	s_add_i32 m0, s78, 0x2000
	s_nop 0
	global_load_lds_dwordx4 v[220:221], off
	s_barrier
	s_waitcnt lgkmcnt(0)
	s_setprio 0
	s_waitcnt lgkmcnt(0)
	v_mfma_f32_16x16x32_bf16 v[112:115], v[202:205], v[170:173], v[112:115]
	v_mfma_f32_16x16x32_bf16 v[116:119], v[210:213], v[170:173], v[116:119]
	v_mfma_f32_16x16x32_bf16 v[96:99], v[202:205], v[178:181], v[96:99]
	v_mfma_f32_16x16x32_bf16 v[100:103], v[210:213], v[178:181], v[100:103]
	v_mfma_f32_16x16x32_bf16 v[80:83], v[202:205], v[186:189], v[80:83]
	v_mfma_f32_16x16x32_bf16 v[84:87], v[210:213], v[186:189], v[84:87]
	v_mfma_f32_16x16x32_bf16 v[64:67], v[202:205], v[194:197], v[64:67]
	v_mfma_f32_16x16x32_bf16 v[68:71], v[210:213], v[194:197], v[68:71]
	v_mfma_f32_16x16x32_bf16 v[112:115], v[206:209], v[174:177], v[112:115]
	v_mfma_f32_16x16x32_bf16 v[116:119], v[214:217], v[174:177], v[116:119]
	v_mfma_f32_16x16x32_bf16 v[96:99], v[206:209], v[182:185], v[96:99]
	v_mfma_f32_16x16x32_bf16 v[100:103], v[214:217], v[182:185], v[100:103]
	v_mfma_f32_16x16x32_bf16 v[80:83], v[206:209], v[190:193], v[80:83]
	v_mfma_f32_16x16x32_bf16 v[84:87], v[214:217], v[190:193], v[84:87]
	v_mfma_f32_16x16x32_bf16 v[64:67], v[206:209], v[198:201], v[64:67]
	v_mfma_f32_16x16x32_bf16 v[68:71], v[214:217], v[198:201], v[68:71]
	s_setprio 1
	s_mov_b32 m0, s29
	v_lshl_add_u64 v[222:223], s[36:37], 0, v[130:131]
	s_barrier
	ds_read_b128 v[170:173], v151 offset:16384
	ds_read_b128 v[174:177], v151 offset:17408
	ds_read_b128 v[178:181], v151 offset:18432
	ds_read_b128 v[182:185], v151 offset:19456
	ds_read_b128 v[186:189], v151 offset:20480
	ds_read_b128 v[190:193], v151 offset:21504
	ds_read_b128 v[194:197], v151 offset:22528
	ds_read_b128 v[198:201], v151 offset:23552
	global_load_lds_dwordx4 v[222:223], off
	v_lshl_add_u64 v[224:225], s[36:37], 0, v[132:133]
	s_mov_b32 m0, s43
	s_nop 0
	global_load_lds_dwordx4 v[224:225], off
	s_barrier
	s_waitcnt lgkmcnt(0)
	s_setprio 0
	s_waitcnt lgkmcnt(0)
	v_mfma_f32_16x16x32_bf16 v[56:59], v[154:157], v[170:173], v[56:59]
	v_mfma_f32_16x16x32_bf16 v[60:63], v[162:165], v[170:173], v[60:63]
	v_mfma_f32_16x16x32_bf16 v[40:43], v[154:157], v[178:181], v[40:43]
	v_mfma_f32_16x16x32_bf16 v[44:47], v[162:165], v[178:181], v[44:47]
	v_mfma_f32_16x16x32_bf16 v[24:27], v[154:157], v[186:189], v[24:27]
	v_mfma_f32_16x16x32_bf16 v[28:31], v[162:165], v[186:189], v[28:31]
	v_mfma_f32_16x16x32_bf16 v[8:11], v[154:157], v[194:197], v[8:11]
	v_mfma_f32_16x16x32_bf16 v[12:15], v[162:165], v[194:197], v[12:15]
	v_mfma_f32_16x16x32_bf16 v[56:59], v[158:161], v[174:177], v[56:59]
	v_mfma_f32_16x16x32_bf16 v[60:63], v[166:169], v[174:177], v[60:63]
	v_mfma_f32_16x16x32_bf16 v[40:43], v[158:161], v[182:185], v[40:43]
	v_mfma_f32_16x16x32_bf16 v[44:47], v[166:169], v[182:185], v[44:47]
	v_mfma_f32_16x16x32_bf16 v[24:27], v[158:161], v[190:193], v[24:27]
	v_mfma_f32_16x16x32_bf16 v[28:31], v[166:169], v[190:193], v[28:31]
	v_mfma_f32_16x16x32_bf16 v[8:11], v[158:161], v[198:201], v[8:11]
	v_mfma_f32_16x16x32_bf16 v[12:15], v[166:169], v[198:201], v[12:15]
	s_setprio 1
	s_barrier
	s_add_u32 s78, s34, 0x40000
	s_addc_u32 s79, s35, 0
	s_add_i32 s80, s61, s42
	v_lshl_add_u64 v[154:155], s[78:79], 0, v[130:131]
	s_mov_b32 m0, s80
	s_nop 0
	global_load_lds_dwordx4 v[154:155], off
	v_lshl_add_u64 v[154:155], s[78:79], 0, v[132:133]
	s_add_i32 m0, s80, 0x2000
	s_nop 0
	global_load_lds_dwordx4 v[154:155], off
	s_waitcnt vmcnt(6)
	s_barrier
	s_setprio 0
	v_mfma_f32_16x16x32_bf16 v[48:51], v[202:205], v[170:173], v[48:51]
	v_mfma_f32_16x16x32_bf16 v[52:55], v[210:213], v[170:173], v[52:55]
	v_mfma_f32_16x16x32_bf16 v[32:35], v[202:205], v[178:181], v[32:35]
	v_mfma_f32_16x16x32_bf16 v[36:39], v[210:213], v[178:181], v[36:39]
	v_mfma_f32_16x16x32_bf16 v[16:19], v[202:205], v[186:189], v[16:19]
	v_mfma_f32_16x16x32_bf16 v[20:23], v[210:213], v[186:189], v[20:23]
	v_mfma_f32_16x16x32_bf16 v[0:3], v[202:205], v[194:197], v[0:3]
	v_mfma_f32_16x16x32_bf16 v[4:7], v[210:213], v[194:197], v[4:7]
	v_mfma_f32_16x16x32_bf16 v[48:51], v[206:209], v[174:177], v[48:51]
	v_mfma_f32_16x16x32_bf16 v[52:55], v[214:217], v[174:177], v[52:55]
	v_mfma_f32_16x16x32_bf16 v[32:35], v[206:209], v[182:185], v[32:35]
	v_mfma_f32_16x16x32_bf16 v[36:39], v[214:217], v[182:185], v[36:39]
	v_mfma_f32_16x16x32_bf16 v[16:19], v[206:209], v[190:193], v[16:19]
	v_mfma_f32_16x16x32_bf16 v[20:23], v[214:217], v[190:193], v[20:23]
	v_mfma_f32_16x16x32_bf16 v[0:3], v[206:209], v[198:201], v[0:3]
	v_mfma_f32_16x16x32_bf16 v[4:7], v[214:217], v[198:201], v[4:7]
	s_setprio 1
	s_add_i32 s78, 0, 0x18000
	v_add_u32_e32 v153, s78, v148
	s_barrier
	ds_read_b128 v[154:157], v153
	ds_read_b128 v[158:161], v153 offset:1024
	ds_read_b128 v[162:165], v153 offset:2048
	ds_read_b128 v[166:169], v153 offset:3072
	s_add_u32 s36, s36, 0x40000
	s_addc_u32 s37, s37, 0
	s_mov_b32 m0, s52
	v_lshl_add_u64 v[202:203], s[36:37], 0, v[130:131]
	ds_read_b128 v[170:173], v151 offset:32768
	ds_read_b128 v[174:177], v151 offset:33792
	ds_read_b128 v[178:181], v151 offset:34816
	ds_read_b128 v[182:185], v151 offset:35840
	ds_read_b128 v[186:189], v151 offset:36864
	ds_read_b128 v[190:193], v151 offset:37888
	ds_read_b128 v[194:197], v151 offset:38912
	ds_read_b128 v[198:201], v151 offset:39936
	global_load_lds_dwordx4 v[202:203], off
	v_lshl_add_u64 v[202:203], s[36:37], 0, v[132:133]
	s_mov_b32 m0, s53
	s_nop 0
	global_load_lds_dwordx4 v[202:203], off
	s_waitcnt lgkmcnt(8)
	s_barrier
	s_waitcnt lgkmcnt(0)
	s_setprio 0
	s_waitcnt lgkmcnt(0)
	v_mfma_f32_16x16x32_bf16 v[120:123], v[154:157], v[170:173], v[120:123]
	v_mfma_f32_16x16x32_bf16 v[124:127], v[162:165], v[170:173], v[124:127]
	v_mfma_f32_16x16x32_bf16 v[104:107], v[154:157], v[178:181], v[104:107]
	v_mfma_f32_16x16x32_bf16 v[108:111], v[162:165], v[178:181], v[108:111]
	v_mfma_f32_16x16x32_bf16 v[88:91], v[154:157], v[186:189], v[88:91]
	v_mfma_f32_16x16x32_bf16 v[92:95], v[162:165], v[186:189], v[92:95]
	v_mfma_f32_16x16x32_bf16 v[72:75], v[154:157], v[194:197], v[72:75]
	v_mfma_f32_16x16x32_bf16 v[76:79], v[162:165], v[194:197], v[76:79]
	v_mfma_f32_16x16x32_bf16 v[120:123], v[158:161], v[174:177], v[120:123]
	v_mfma_f32_16x16x32_bf16 v[124:127], v[166:169], v[174:177], v[124:127]
	v_mfma_f32_16x16x32_bf16 v[104:107], v[158:161], v[182:185], v[104:107]
	v_mfma_f32_16x16x32_bf16 v[108:111], v[166:169], v[182:185], v[108:111]
	v_mfma_f32_16x16x32_bf16 v[88:91], v[158:161], v[190:193], v[88:91]
	v_mfma_f32_16x16x32_bf16 v[92:95], v[166:169], v[190:193], v[92:95]
	v_mfma_f32_16x16x32_bf16 v[72:75], v[158:161], v[198:201], v[72:75]
	v_mfma_f32_16x16x32_bf16 v[76:79], v[166:169], v[198:201], v[76:79]
	s_setprio 1
	s_barrier
	s_add_i32 s36, 0, 0x1c000
	s_add_i32 s37, s78, s42
	v_add_u32_e32 v153, s36, v148
	v_lshl_add_u64 v[218:219], v[218:219], 0, s[8:9]
	s_mov_b32 m0, s37
	ds_read_b128 v[202:205], v153
	ds_read_b128 v[206:209], v153 offset:1024
	ds_read_b128 v[210:213], v153 offset:2048
	ds_read_b128 v[214:217], v153 offset:3072
	global_load_lds_dwordx4 v[218:219], off
	v_lshl_add_u64 v[218:219], v[220:221], 0, s[8:9]
	s_add_i32 m0, s37, 0x2000
	s_nop 0
	global_load_lds_dwordx4 v[218:219], off
	s_barrier
	s_waitcnt lgkmcnt(0)
	s_setprio 0
	s_waitcnt lgkmcnt(0)
	v_mfma_f32_16x16x32_bf16 v[112:115], v[202:205], v[170:173], v[112:115]
	v_mfma_f32_16x16x32_bf16 v[116:119], v[210:213], v[170:173], v[116:119]
	v_mfma_f32_16x16x32_bf16 v[96:99], v[202:205], v[178:181], v[96:99]
	v_mfma_f32_16x16x32_bf16 v[100:103], v[210:213], v[178:181], v[100:103]
	v_mfma_f32_16x16x32_bf16 v[80:83], v[202:205], v[186:189], v[80:83]
	v_mfma_f32_16x16x32_bf16 v[84:87], v[210:213], v[186:189], v[84:87]
	v_mfma_f32_16x16x32_bf16 v[64:67], v[202:205], v[194:197], v[64:67]
	v_mfma_f32_16x16x32_bf16 v[68:71], v[210:213], v[194:197], v[68:71]
	v_mfma_f32_16x16x32_bf16 v[112:115], v[206:209], v[174:177], v[112:115]
	v_mfma_f32_16x16x32_bf16 v[116:119], v[214:217], v[174:177], v[116:119]
	v_mfma_f32_16x16x32_bf16 v[96:99], v[206:209], v[182:185], v[96:99]
	v_mfma_f32_16x16x32_bf16 v[100:103], v[214:217], v[182:185], v[100:103]
	v_mfma_f32_16x16x32_bf16 v[80:83], v[206:209], v[190:193], v[80:83]
	v_mfma_f32_16x16x32_bf16 v[84:87], v[214:217], v[190:193], v[84:87]
	v_mfma_f32_16x16x32_bf16 v[64:67], v[206:209], v[198:201], v[64:67]
	v_mfma_f32_16x16x32_bf16 v[68:71], v[214:217], v[198:201], v[68:71]
	s_setprio 1
	s_mov_b32 m0, s55
	v_lshl_add_u64 v[218:219], v[222:223], 0, s[8:9]
	s_barrier
	ds_read_b128 v[170:173], v151 offset:49152
	ds_read_b128 v[174:177], v151 offset:50176
	ds_read_b128 v[178:181], v151 offset:51200
	ds_read_b128 v[182:185], v151 offset:52224
	ds_read_b128 v[186:189], v151 offset:53248
	ds_read_b128 v[190:193], v151 offset:54272
	ds_read_b128 v[194:197], v151 offset:55296
	ds_read_b128 v[198:201], v151 offset:56320
	global_load_lds_dwordx4 v[218:219], off
	v_lshl_add_u64 v[218:219], v[224:225], 0, s[8:9]
	s_mov_b32 m0, s56
	s_nop 0
	global_load_lds_dwordx4 v[218:219], off
	s_barrier
	s_waitcnt lgkmcnt(0)
	s_setprio 0
	s_waitcnt lgkmcnt(0)
	v_mfma_f32_16x16x32_bf16 v[56:59], v[154:157], v[170:173], v[56:59]
	v_mfma_f32_16x16x32_bf16 v[60:63], v[162:165], v[170:173], v[60:63]
	v_mfma_f32_16x16x32_bf16 v[40:43], v[154:157], v[178:181], v[40:43]
	v_mfma_f32_16x16x32_bf16 v[44:47], v[162:165], v[178:181], v[44:47]
	v_mfma_f32_16x16x32_bf16 v[24:27], v[154:157], v[186:189], v[24:27]
	v_mfma_f32_16x16x32_bf16 v[28:31], v[162:165], v[186:189], v[28:31]
	v_mfma_f32_16x16x32_bf16 v[8:11], v[154:157], v[194:197], v[8:11]
	v_mfma_f32_16x16x32_bf16 v[12:15], v[162:165], v[194:197], v[12:15]
	v_mfma_f32_16x16x32_bf16 v[56:59], v[158:161], v[174:177], v[56:59]
	v_mfma_f32_16x16x32_bf16 v[60:63], v[166:169], v[174:177], v[60:63]
	v_mfma_f32_16x16x32_bf16 v[40:43], v[158:161], v[182:185], v[40:43]
	v_mfma_f32_16x16x32_bf16 v[44:47], v[166:169], v[182:185], v[44:47]
	v_mfma_f32_16x16x32_bf16 v[24:27], v[158:161], v[190:193], v[24:27]
	v_mfma_f32_16x16x32_bf16 v[28:31], v[166:169], v[190:193], v[28:31]
	v_mfma_f32_16x16x32_bf16 v[8:11], v[158:161], v[198:201], v[8:11]
	v_mfma_f32_16x16x32_bf16 v[12:15], v[166:169], v[198:201], v[12:15]
	s_setprio 1
	s_barrier
	s_add_u32 s34, s34, 0x40080
	s_addc_u32 s35, s35, 0
	s_add_i32 s36, s36, s42
	v_lshl_add_u64 v[154:155], s[34:35], 0, v[130:131]
	s_mov_b32 m0, s36
	s_nop 0
	global_load_lds_dwordx4 v[154:155], off
	v_lshl_add_u64 v[154:155], s[34:35], 0, v[132:133]
	s_add_i32 m0, s36, 0x2000
	s_nop 0
	global_load_lds_dwordx4 v[154:155], off
	s_waitcnt vmcnt(6)
	s_barrier
	s_setprio 0
	v_mfma_f32_16x16x32_bf16 v[48:51], v[202:205], v[170:173], v[48:51]
	v_mfma_f32_16x16x32_bf16 v[52:55], v[210:213], v[170:173], v[52:55]
	v_mfma_f32_16x16x32_bf16 v[32:35], v[202:205], v[178:181], v[32:35]
	v_mfma_f32_16x16x32_bf16 v[36:39], v[210:213], v[178:181], v[36:39]
	v_mfma_f32_16x16x32_bf16 v[16:19], v[202:205], v[186:189], v[16:19]
	v_mfma_f32_16x16x32_bf16 v[20:23], v[210:213], v[186:189], v[20:23]
	v_mfma_f32_16x16x32_bf16 v[0:3], v[202:205], v[194:197], v[0:3]
	v_mfma_f32_16x16x32_bf16 v[4:7], v[210:213], v[194:197], v[4:7]
	v_mfma_f32_16x16x32_bf16 v[48:51], v[206:209], v[174:177], v[48:51]
	v_mfma_f32_16x16x32_bf16 v[52:55], v[214:217], v[174:177], v[52:55]
	v_mfma_f32_16x16x32_bf16 v[32:35], v[206:209], v[182:185], v[32:35]
	v_mfma_f32_16x16x32_bf16 v[36:39], v[214:217], v[182:185], v[36:39]
	v_mfma_f32_16x16x32_bf16 v[16:19], v[206:209], v[190:193], v[16:19]
	v_mfma_f32_16x16x32_bf16 v[20:23], v[214:217], v[190:193], v[20:23]
	v_mfma_f32_16x16x32_bf16 v[0:3], v[206:209], v[198:201], v[0:3]
	v_mfma_f32_16x16x32_bf16 v[4:7], v[214:217], v[198:201], v[4:7]
	s_setprio 1
	s_add_i32 s77, s77, 2
	s_add_u32 s30, s30, 0x100
	s_addc_u32 s31, s31, 0
	s_add_u32 s75, s75, 0x100
	s_addc_u32 s76, s76, 0
	s_cmp_gt_u32 s77, 13
	s_barrier
	s_cbranch_scc0 .LBB0_1116
	v_mul_f32_e32 v124, 0xbfb8aa3b, v124
	v_exp_f32_e32 v154, v124
	v_mul_f32_e32 v124, 0xbfb8aa3b, v125
	v_exp_f32_e32 v155, v124
	v_lshl_add_u32 v124, s28, 8, v145
	v_ashrrev_i32_e32 v125, 31, v124
	v_lshlrev_b64 v[158:159], 11, v[124:125]
	v_pk_add_f32 v[154:155], v[154:155], 1.0 op_sel_hi:[1,0]
	v_mul_f32_e32 v126, 0xbfb8aa3b, v126
	v_div_scale_f32 v153, s[30:31], v155, v155, v121
	v_rcp_f32_e32 v157, v153
	v_mul_f32_e32 v127, 0xbfb8aa3b, v127
	v_exp_f32_e32 v126, v126
	v_exp_f32_e32 v127, v127
	v_fma_f32 v125, -v153, v157, 1.0
	v_fmac_f32_e32 v157, v125, v157
	v_div_scale_f32 v125, vcc, v121, v155, v121
	v_mul_f32_e32 v160, v125, v157
	v_fma_f32 v161, -v153, v160, v125
	v_fmac_f32_e32 v160, v161, v157
	v_fma_f32 v125, -v153, v160, v125
	v_div_scale_f32 v153, s[30:31], v154, v154, v120
	v_rcp_f32_e32 v161, v153
	v_div_fmas_f32 v125, v125, v157, v160
	v_div_fixup_f32 v121, v125, v155, v121
	v_pk_add_f32 v[126:127], v[126:127], 1.0 op_sel_hi:[1,0]
	v_fma_f32 v125, -v153, v161, 1.0
	v_fmac_f32_e32 v161, v125, v161
	v_div_scale_f32 v125, vcc, v120, v154, v120
	v_mul_f32_e32 v155, v125, v161
	v_fma_f32 v157, -v153, v155, v125
	v_fmac_f32_e32 v155, v157, v161
	v_fma_f32 v125, -v153, v155, v125
	v_div_scale_f32 v153, s[30:31], v127, v127, v123
	v_rcp_f32_e32 v157, v153
	v_div_fmas_f32 v125, v125, v161, v155
	v_div_fixup_f32 v120, v125, v154, v120
	v_mul_f32_e32 v116, 0xbfb8aa3b, v116
	v_fma_f32 v125, -v153, v157, 1.0
	v_fmac_f32_e32 v157, v125, v157
	v_div_scale_f32 v125, vcc, v123, v127, v123
	v_mul_f32_e32 v154, v125, v157
	v_fma_f32 v155, -v153, v154, v125
	v_fmac_f32_e32 v154, v155, v157
	v_fma_f32 v125, -v153, v154, v125
	v_div_scale_f32 v153, s[30:31], v126, v126, v122
	v_rcp_f32_e32 v155, v153
	v_div_fmas_f32 v125, v125, v157, v154
	v_div_fixup_f32 v123, v125, v127, v123
	v_mul_f32_e32 v117, 0xbfb8aa3b, v117
	v_fma_f32 v125, -v153, v155, 1.0
	v_fmac_f32_e32 v155, v125, v155
	v_div_scale_f32 v125, vcc, v122, v126, v122
	v_mul_f32_e32 v127, v125, v155
	v_fma_f32 v154, -v153, v127, v125
	v_exp_f32_e32 v116, v116
	v_exp_f32_e32 v117, v117
	v_fmac_f32_e32 v127, v154, v155
	v_fma_f32 v125, -v153, v127, v125
	v_div_fmas_f32 v125, v125, v155, v127
	v_div_fixup_f32 v125, v125, v126, v122
	v_pk_add_f32 v[126:127], v[116:117], 1.0 op_sel_hi:[1,0]
	v_cvt_pk_bf16_f32 v123, v125, v123
	v_div_scale_f32 v125, s[30:31], v127, v127, v113
	v_lshl_or_b32 v156, s72, 7, v149
	v_rcp_f32_e32 v153, v125
	v_ashrrev_i32_e32 v157, 31, v156
	v_lshl_add_u64 v[158:159], s[46:47], 0, v[158:159]
	v_cvt_pk_bf16_f32 v122, v120, v121
	v_lshlrev_b64 v[120:121], 1, v[156:157]
	v_lshl_add_u64 v[116:117], v[158:159], 0, v[120:121]
	global_store_dwordx2 v[116:117], v[122:123], off
	v_fma_f32 v122, -v125, v153, 1.0
	v_fmac_f32_e32 v153, v122, v153
	v_div_scale_f32 v122, vcc, v113, v127, v113
	v_mul_f32_e32 v123, v122, v153
	v_fma_f32 v154, -v125, v123, v122
	v_fmac_f32_e32 v123, v154, v153
	v_fma_f32 v122, -v125, v123, v122
	v_div_scale_f32 v125, s[30:31], v126, v126, v112
	v_rcp_f32_e32 v154, v125
	v_div_fmas_f32 v122, v122, v153, v123
	v_mul_f32_e32 v118, 0xbfb8aa3b, v118
	v_mul_f32_e32 v119, 0xbfb8aa3b, v119
	v_div_fixup_f32 v113, v122, v127, v113
	v_fma_f32 v122, -v125, v154, 1.0
	v_exp_f32_e32 v118, v118
	v_exp_f32_e32 v119, v119
	v_fmac_f32_e32 v154, v122, v154
	v_div_scale_f32 v122, vcc, v112, v126, v112
	v_mul_f32_e32 v123, v122, v154
	v_fma_f32 v127, -v125, v123, v122
	v_fmac_f32_e32 v123, v127, v154
	v_pk_add_f32 v[118:119], v[118:119], 1.0 op_sel_hi:[1,0]
	v_fma_f32 v122, -v125, v123, v122
	v_div_scale_f32 v125, s[30:31], v119, v119, v115
	v_rcp_f32_e32 v127, v125
	v_div_fmas_f32 v122, v122, v154, v123
	v_div_fixup_f32 v112, v122, v126, v112
	v_mul_f32_e32 v108, 0xbfb8aa3b, v108
	v_fma_f32 v122, -v125, v127, 1.0
	v_fmac_f32_e32 v127, v122, v127
	v_div_scale_f32 v122, vcc, v115, v119, v115
	v_mul_f32_e32 v123, v122, v127
	v_fma_f32 v126, -v125, v123, v122
	v_fmac_f32_e32 v123, v126, v127
	v_fma_f32 v122, -v125, v123, v122
	v_div_scale_f32 v125, s[30:31], v118, v118, v114
	v_rcp_f32_e32 v126, v125
	v_div_fmas_f32 v122, v122, v127, v123
	v_div_fixup_f32 v115, v122, v119, v115
	v_mul_f32_e32 v109, 0xbfb8aa3b, v109
	v_fma_f32 v119, -v125, v126, 1.0
	v_fmac_f32_e32 v126, v119, v126
	v_div_scale_f32 v119, vcc, v114, v118, v114
	v_mul_f32_e32 v122, v119, v126
	v_fma_f32 v123, -v125, v122, v119
	v_exp_f32_e32 v108, v108
	v_exp_f32_e32 v109, v109
	v_fmac_f32_e32 v122, v123, v126
	v_fma_f32 v119, -v125, v122, v119
	v_div_fmas_f32 v119, v119, v126, v122
	v_div_fixup_f32 v114, v119, v118, v114
	v_pk_add_f32 v[108:109], v[108:109], 1.0 op_sel_hi:[1,0]
	v_cvt_pk_bf16_f32 v112, v112, v113
	v_cvt_pk_bf16_f32 v113, v114, v115
	v_div_scale_f32 v114, s[30:31], v109, v109, v105
	v_rcp_f32_e32 v115, v114
	v_mul_f32_e32 v110, 0xbfb8aa3b, v110
	v_mul_f32_e32 v111, 0xbfb8aa3b, v111
	v_exp_f32_e32 v110, v110
	v_fma_f32 v118, -v114, v115, 1.0
	v_fmac_f32_e32 v115, v118, v115
	v_div_scale_f32 v118, vcc, v105, v109, v105
	v_mul_f32_e32 v119, v118, v115
	v_fma_f32 v122, -v114, v119, v118
	v_fmac_f32_e32 v119, v122, v115
	v_fma_f32 v114, -v114, v119, v118
	v_div_scale_f32 v118, s[30:31], v108, v108, v104
	v_rcp_f32_e32 v122, v118
	v_div_fmas_f32 v114, v114, v115, v119
	v_exp_f32_e32 v111, v111
	v_div_fixup_f32 v105, v114, v109, v105
	v_fma_f32 v109, -v118, v122, 1.0
	v_fmac_f32_e32 v122, v109, v122
	v_div_scale_f32 v109, vcc, v104, v108, v104
	v_mul_f32_e32 v114, v109, v122
	v_fma_f32 v115, -v118, v114, v109
	v_pk_add_f32 v[110:111], v[110:111], 1.0 op_sel_hi:[1,0]
	v_fmac_f32_e32 v114, v115, v122
	v_div_scale_f32 v115, s[30:31], v111, v111, v107
	v_fma_f32 v109, -v118, v114, v109
	v_rcp_f32_e32 v118, v115
	v_div_fmas_f32 v109, v109, v122, v114
	v_div_fixup_f32 v104, v109, v108, v104
	v_mul_f32_e32 v100, 0xbfb8aa3b, v100
	v_fma_f32 v108, -v115, v118, 1.0
	v_fmac_f32_e32 v118, v108, v118
	v_div_scale_f32 v108, vcc, v107, v111, v107
	v_mul_f32_e32 v109, v108, v118
	v_fma_f32 v114, -v115, v109, v108
	v_fmac_f32_e32 v109, v114, v118
	v_div_scale_f32 v114, s[30:31], v110, v110, v106
	v_fma_f32 v108, -v115, v109, v108
	v_rcp_f32_e32 v115, v114
	v_div_fmas_f32 v108, v108, v118, v109
	v_div_fixup_f32 v107, v108, v111, v107
	v_mul_f32_e32 v101, 0xbfb8aa3b, v101
	v_fma_f32 v108, -v114, v115, 1.0
	v_fmac_f32_e32 v115, v108, v115
	v_div_scale_f32 v108, vcc, v106, v110, v106
	v_mul_f32_e32 v109, v108, v115
	v_exp_f32_e32 v100, v100
	v_exp_f32_e32 v101, v101
	v_fma_f32 v111, -v114, v109, v108
	v_fmac_f32_e32 v109, v111, v115
	v_fma_f32 v108, -v114, v109, v108
	v_div_fmas_f32 v108, v108, v115, v109
	v_pk_add_f32 v[100:101], v[100:101], 1.0 op_sel_hi:[1,0]
	global_store_dwordx2 v[116:117], v[112:113], off offset:128
	v_or_b32_e32 v112, 16, v124
	v_div_fixup_f32 v106, v108, v110, v106
	v_div_scale_f32 v108, s[30:31], v101, v101, v97
	v_ashrrev_i32_e32 v113, 31, v112
	v_rcp_f32_e32 v109, v108
	v_lshlrev_b64 v[112:113], 11, v[112:113]
	v_lshl_add_u64 v[112:113], s[46:47], 0, v[112:113]
	v_cvt_pk_bf16_f32 v104, v104, v105
	v_cvt_pk_bf16_f32 v105, v106, v107
	v_lshl_add_u64 v[106:107], v[112:113], 0, v[120:121]
	global_store_dwordx2 v[106:107], v[104:105], off
	v_fma_f32 v104, -v108, v109, 1.0
	v_fmac_f32_e32 v109, v104, v109
	v_div_scale_f32 v104, vcc, v97, v101, v97
	v_mul_f32_e32 v105, v104, v109
	v_fma_f32 v110, -v108, v105, v104
	v_fmac_f32_e32 v105, v110, v109
	v_fma_f32 v104, -v108, v105, v104
	v_div_scale_f32 v108, s[30:31], v100, v100, v96
	v_rcp_f32_e32 v110, v108
	v_mul_f32_e32 v102, 0xbfb8aa3b, v102
	v_mul_f32_e32 v103, 0xbfb8aa3b, v103
	v_div_fmas_f32 v104, v104, v109, v105
	v_exp_f32_e32 v102, v102
	v_exp_f32_e32 v103, v103
	v_div_fixup_f32 v97, v104, v101, v97
	v_fma_f32 v101, -v108, v110, 1.0
	v_fmac_f32_e32 v110, v101, v110
	v_div_scale_f32 v101, vcc, v96, v100, v96
	v_mul_f32_e32 v104, v101, v110
	v_fma_f32 v105, -v108, v104, v101
	v_pk_add_f32 v[102:103], v[102:103], 1.0 op_sel_hi:[1,0]
	v_fmac_f32_e32 v104, v105, v110
	v_div_scale_f32 v105, s[30:31], v103, v103, v99
	v_fma_f32 v101, -v108, v104, v101
	v_rcp_f32_e32 v108, v105
	v_div_fmas_f32 v101, v101, v110, v104
	v_div_fixup_f32 v96, v101, v100, v96
	v_mul_f32_e32 v92, 0xbfb8aa3b, v92
	v_fma_f32 v100, -v105, v108, 1.0
	v_fmac_f32_e32 v108, v100, v108
	v_div_scale_f32 v100, vcc, v99, v103, v99
	v_mul_f32_e32 v101, v100, v108
	v_fma_f32 v104, -v105, v101, v100
	v_fmac_f32_e32 v101, v104, v108
	v_div_scale_f32 v104, s[30:31], v102, v102, v98
	v_fma_f32 v100, -v105, v101, v100
	v_rcp_f32_e32 v105, v104
	v_div_fmas_f32 v100, v100, v108, v101
	v_div_fixup_f32 v99, v100, v103, v99
	v_mul_f32_e32 v93, 0xbfb8aa3b, v93
	v_fma_f32 v100, -v104, v105, 1.0
	v_fmac_f32_e32 v105, v100, v105
	v_div_scale_f32 v100, vcc, v98, v102, v98
	v_mul_f32_e32 v101, v100, v105
	v_fma_f32 v103, -v104, v101, v100
	v_exp_f32_e32 v92, v92
	v_exp_f32_e32 v93, v93
	v_fmac_f32_e32 v101, v103, v105
	v_fma_f32 v100, -v104, v101, v100
	v_div_fmas_f32 v100, v100, v105, v101
	v_div_fixup_f32 v98, v100, v102, v98
	v_pk_add_f32 v[92:93], v[92:93], 1.0 op_sel_hi:[1,0]
	v_cvt_pk_bf16_f32 v96, v96, v97
	v_cvt_pk_bf16_f32 v97, v98, v99
	v_div_scale_f32 v98, s[30:31], v93, v93, v89
	v_rcp_f32_e32 v99, v98
	v_mul_f32_e32 v94, 0xbfb8aa3b, v94
	v_mul_f32_e32 v95, 0xbfb8aa3b, v95
	v_exp_f32_e32 v94, v94
	v_fma_f32 v100, -v98, v99, 1.0
	v_fmac_f32_e32 v99, v100, v99
	v_div_scale_f32 v100, vcc, v89, v93, v89
	v_mul_f32_e32 v101, v100, v99
	v_fma_f32 v102, -v98, v101, v100
	v_fmac_f32_e32 v101, v102, v99
	v_fma_f32 v98, -v98, v101, v100
	v_div_scale_f32 v100, s[30:31], v92, v92, v88
	v_rcp_f32_e32 v102, v100
	v_div_fmas_f32 v98, v98, v99, v101
	v_exp_f32_e32 v95, v95
	v_div_fixup_f32 v89, v98, v93, v89
	v_fma_f32 v93, -v100, v102, 1.0
	v_fmac_f32_e32 v102, v93, v102
	v_div_scale_f32 v93, vcc, v88, v92, v88
	v_mul_f32_e32 v98, v93, v102
	v_fma_f32 v99, -v100, v98, v93
	v_pk_add_f32 v[94:95], v[94:95], 1.0 op_sel_hi:[1,0]
	v_fmac_f32_e32 v98, v99, v102
	v_div_scale_f32 v99, s[30:31], v95, v95, v91
	v_fma_f32 v93, -v100, v98, v93
	v_rcp_f32_e32 v100, v99
	v_div_fmas_f32 v93, v93, v102, v98
	v_div_fixup_f32 v88, v93, v92, v88
	v_mul_f32_e32 v84, 0xbfb8aa3b, v84
	v_fma_f32 v92, -v99, v100, 1.0
	v_fmac_f32_e32 v100, v92, v100
	v_div_scale_f32 v92, vcc, v91, v95, v91
	v_mul_f32_e32 v93, v92, v100
	v_fma_f32 v98, -v99, v93, v92
	v_fmac_f32_e32 v93, v98, v100
	v_div_scale_f32 v98, s[30:31], v94, v94, v90
	v_fma_f32 v92, -v99, v93, v92
	v_rcp_f32_e32 v99, v98
	v_div_fmas_f32 v92, v92, v100, v93
	v_div_fixup_f32 v91, v92, v95, v91
	v_mul_f32_e32 v85, 0xbfb8aa3b, v85
	v_fma_f32 v92, -v98, v99, 1.0
	v_fmac_f32_e32 v99, v92, v99
	v_div_scale_f32 v92, vcc, v90, v94, v90
	v_mul_f32_e32 v93, v92, v99
	v_exp_f32_e32 v84, v84
	v_exp_f32_e32 v85, v85
	v_fma_f32 v95, -v98, v93, v92
	v_fmac_f32_e32 v93, v95, v99
	v_fma_f32 v92, -v98, v93, v92
	v_div_fmas_f32 v92, v92, v99, v93
	v_pk_add_f32 v[84:85], v[84:85], 1.0 op_sel_hi:[1,0]
	global_store_dwordx2 v[106:107], v[96:97], off offset:128
	v_or_b32_e32 v96, 32, v124
	v_div_fixup_f32 v90, v92, v94, v90
	v_div_scale_f32 v92, s[30:31], v85, v85, v81
	v_ashrrev_i32_e32 v97, 31, v96
	v_rcp_f32_e32 v93, v92
	v_lshlrev_b64 v[96:97], 11, v[96:97]
	v_lshl_add_u64 v[96:97], s[46:47], 0, v[96:97]
	v_cvt_pk_bf16_f32 v88, v88, v89
	v_cvt_pk_bf16_f32 v89, v90, v91
	v_lshl_add_u64 v[90:91], v[96:97], 0, v[120:121]
	global_store_dwordx2 v[90:91], v[88:89], off
	v_fma_f32 v88, -v92, v93, 1.0
	v_fmac_f32_e32 v93, v88, v93
	v_div_scale_f32 v88, vcc, v81, v85, v81
	v_mul_f32_e32 v89, v88, v93
	v_fma_f32 v94, -v92, v89, v88
	v_fmac_f32_e32 v89, v94, v93
	v_fma_f32 v88, -v92, v89, v88
	v_div_scale_f32 v92, s[30:31], v84, v84, v80
	v_rcp_f32_e32 v94, v92
	v_mul_f32_e32 v86, 0xbfb8aa3b, v86
	v_mul_f32_e32 v87, 0xbfb8aa3b, v87
	v_div_fmas_f32 v88, v88, v93, v89
	v_exp_f32_e32 v86, v86
	v_exp_f32_e32 v87, v87
	v_div_fixup_f32 v81, v88, v85, v81
	v_fma_f32 v85, -v92, v94, 1.0
	v_fmac_f32_e32 v94, v85, v94
	v_div_scale_f32 v85, vcc, v80, v84, v80
	v_mul_f32_e32 v88, v85, v94
	v_fma_f32 v89, -v92, v88, v85
	v_pk_add_f32 v[86:87], v[86:87], 1.0 op_sel_hi:[1,0]
	v_fmac_f32_e32 v88, v89, v94
	v_div_scale_f32 v89, s[30:31], v87, v87, v83
	v_fma_f32 v85, -v92, v88, v85
	v_rcp_f32_e32 v92, v89
	v_div_fmas_f32 v85, v85, v94, v88
	v_div_fixup_f32 v80, v85, v84, v80
	v_mul_f32_e32 v76, 0xbfb8aa3b, v76
	v_fma_f32 v84, -v89, v92, 1.0
	v_fmac_f32_e32 v92, v84, v92
	v_div_scale_f32 v84, vcc, v83, v87, v83
	v_mul_f32_e32 v85, v84, v92
	v_fma_f32 v88, -v89, v85, v84
	v_fmac_f32_e32 v85, v88, v92
	v_div_scale_f32 v88, s[30:31], v86, v86, v82
	v_fma_f32 v84, -v89, v85, v84
	v_rcp_f32_e32 v89, v88
	v_div_fmas_f32 v84, v84, v92, v85
	v_div_fixup_f32 v83, v84, v87, v83
	v_mul_f32_e32 v77, 0xbfb8aa3b, v77
	v_fma_f32 v84, -v88, v89, 1.0
	v_fmac_f32_e32 v89, v84, v89
	v_div_scale_f32 v84, vcc, v82, v86, v82
	v_mul_f32_e32 v85, v84, v89
	v_fma_f32 v87, -v88, v85, v84
	v_exp_f32_e32 v76, v76
	v_exp_f32_e32 v77, v77
	v_fmac_f32_e32 v85, v87, v89
	v_fma_f32 v84, -v88, v85, v84
	v_div_fmas_f32 v84, v84, v89, v85
	v_div_fixup_f32 v82, v84, v86, v82
	v_pk_add_f32 v[76:77], v[76:77], 1.0 op_sel_hi:[1,0]
	v_cvt_pk_bf16_f32 v80, v80, v81
	v_cvt_pk_bf16_f32 v81, v82, v83
	v_div_scale_f32 v82, s[30:31], v77, v77, v73
	v_rcp_f32_e32 v83, v82
	v_mul_f32_e32 v78, 0xbfb8aa3b, v78
	v_mul_f32_e32 v79, 0xbfb8aa3b, v79
	v_exp_f32_e32 v78, v78
	v_fma_f32 v84, -v82, v83, 1.0
	v_fmac_f32_e32 v83, v84, v83
	v_div_scale_f32 v84, vcc, v73, v77, v73
	v_mul_f32_e32 v85, v84, v83
	v_fma_f32 v86, -v82, v85, v84
	v_fmac_f32_e32 v85, v86, v83
	v_fma_f32 v82, -v82, v85, v84
	v_div_scale_f32 v84, s[30:31], v76, v76, v72
	v_rcp_f32_e32 v86, v84
	v_div_fmas_f32 v82, v82, v83, v85
	v_exp_f32_e32 v79, v79
	v_div_fixup_f32 v73, v82, v77, v73
	v_fma_f32 v77, -v84, v86, 1.0
	v_fmac_f32_e32 v86, v77, v86
	v_div_scale_f32 v77, vcc, v72, v76, v72
	v_mul_f32_e32 v82, v77, v86
	v_fma_f32 v83, -v84, v82, v77
	v_pk_add_f32 v[78:79], v[78:79], 1.0 op_sel_hi:[1,0]
	v_fmac_f32_e32 v82, v83, v86
	v_div_scale_f32 v83, s[30:31], v79, v79, v75
	v_fma_f32 v77, -v84, v82, v77
	v_rcp_f32_e32 v84, v83
	v_div_fmas_f32 v77, v77, v86, v82
	v_div_fixup_f32 v72, v77, v76, v72
	v_mul_f32_e32 v68, 0xbfb8aa3b, v68
	v_fma_f32 v76, -v83, v84, 1.0
	v_fmac_f32_e32 v84, v76, v84
	v_div_scale_f32 v76, vcc, v75, v79, v75
	v_mul_f32_e32 v77, v76, v84
	v_fma_f32 v82, -v83, v77, v76
	v_fmac_f32_e32 v77, v82, v84
	v_div_scale_f32 v82, s[30:31], v78, v78, v74
	v_fma_f32 v76, -v83, v77, v76
	v_rcp_f32_e32 v83, v82
	v_div_fmas_f32 v76, v76, v84, v77
	v_div_fixup_f32 v75, v76, v79, v75
	v_mul_f32_e32 v69, 0xbfb8aa3b, v69
	v_fma_f32 v76, -v82, v83, 1.0
	v_fmac_f32_e32 v83, v76, v83
	v_div_scale_f32 v76, vcc, v74, v78, v74
	v_mul_f32_e32 v77, v76, v83
	v_exp_f32_e32 v68, v68
	v_exp_f32_e32 v69, v69
	v_fma_f32 v79, -v82, v77, v76
	v_fmac_f32_e32 v77, v79, v83
	v_fma_f32 v76, -v82, v77, v76
	v_div_fmas_f32 v76, v76, v83, v77
	v_pk_add_f32 v[68:69], v[68:69], 1.0 op_sel_hi:[1,0]
	global_store_dwordx2 v[90:91], v[80:81], off offset:128
	v_or_b32_e32 v80, 48, v124
	v_div_fixup_f32 v74, v76, v78, v74
	v_div_scale_f32 v76, s[30:31], v69, v69, v65
	v_ashrrev_i32_e32 v81, 31, v80
	v_rcp_f32_e32 v77, v76
	v_lshlrev_b64 v[80:81], 11, v[80:81]
	v_lshl_add_u64 v[80:81], s[46:47], 0, v[80:81]
	v_cvt_pk_bf16_f32 v72, v72, v73
	v_cvt_pk_bf16_f32 v73, v74, v75
	v_lshl_add_u64 v[74:75], v[80:81], 0, v[120:121]
	global_store_dwordx2 v[74:75], v[72:73], off
	v_fma_f32 v72, -v76, v77, 1.0
	v_fmac_f32_e32 v77, v72, v77
	v_div_scale_f32 v72, vcc, v65, v69, v65
	v_mul_f32_e32 v73, v72, v77
	v_fma_f32 v78, -v76, v73, v72
	v_fmac_f32_e32 v73, v78, v77
	v_fma_f32 v72, -v76, v73, v72
	v_div_scale_f32 v76, s[30:31], v68, v68, v64
	v_rcp_f32_e32 v78, v76
	v_mul_f32_e32 v70, 0xbfb8aa3b, v70
	v_mul_f32_e32 v71, 0xbfb8aa3b, v71
	v_div_fmas_f32 v72, v72, v77, v73
	v_exp_f32_e32 v70, v70
	v_exp_f32_e32 v71, v71
	v_div_fixup_f32 v65, v72, v69, v65
	v_fma_f32 v69, -v76, v78, 1.0
	v_fmac_f32_e32 v78, v69, v78
	v_div_scale_f32 v69, vcc, v64, v68, v64
	v_mul_f32_e32 v72, v69, v78
	v_fma_f32 v73, -v76, v72, v69
	v_pk_add_f32 v[70:71], v[70:71], 1.0 op_sel_hi:[1,0]
	v_fmac_f32_e32 v72, v73, v78
	v_div_scale_f32 v73, s[30:31], v71, v71, v67
	v_fma_f32 v69, -v76, v72, v69
	v_rcp_f32_e32 v76, v73
	v_div_fmas_f32 v69, v69, v78, v72
	v_div_fixup_f32 v64, v69, v68, v64
	v_mul_f32_e32 v60, 0xbfb8aa3b, v60
	v_fma_f32 v68, -v73, v76, 1.0
	v_fmac_f32_e32 v76, v68, v76
	v_div_scale_f32 v68, vcc, v67, v71, v67
	v_mul_f32_e32 v69, v68, v76
	v_fma_f32 v72, -v73, v69, v68
	v_fmac_f32_e32 v69, v72, v76
	v_div_scale_f32 v72, s[30:31], v70, v70, v66
	v_fma_f32 v68, -v73, v69, v68
	v_rcp_f32_e32 v73, v72
	v_div_fmas_f32 v68, v68, v76, v69
	v_div_fixup_f32 v67, v68, v71, v67
	v_mul_f32_e32 v61, 0xbfb8aa3b, v61
	v_fma_f32 v68, -v72, v73, 1.0
	v_fmac_f32_e32 v73, v68, v73
	v_div_scale_f32 v68, vcc, v66, v70, v66
	v_mul_f32_e32 v69, v68, v73
	v_exp_f32_e32 v60, v60
	v_exp_f32_e32 v61, v61
	v_fma_f32 v71, -v72, v69, v68
	v_fmac_f32_e32 v69, v71, v73
	v_fma_f32 v68, -v72, v69, v68
	v_div_fmas_f32 v68, v68, v73, v69
	v_pk_add_f32 v[60:61], v[60:61], 1.0 op_sel_hi:[1,0]
	v_div_fixup_f32 v66, v68, v70, v66
	v_div_scale_f32 v68, s[30:31], v61, v61, v57
	v_rcp_f32_e32 v69, v68
	v_cvt_pk_bf16_f32 v64, v64, v65
	v_cvt_pk_bf16_f32 v65, v66, v67
	global_store_dwordx2 v[74:75], v[64:65], off offset:128
	v_fma_f32 v64, -v68, v69, 1.0
	v_fmac_f32_e32 v69, v64, v69
	v_div_scale_f32 v64, vcc, v57, v61, v57
	v_mul_f32_e32 v65, v64, v69
	v_fma_f32 v66, -v68, v65, v64
	v_fmac_f32_e32 v65, v66, v69
	v_div_scale_f32 v66, s[30:31], v60, v60, v56
	v_rcp_f32_e32 v67, v66
	v_fma_f32 v64, -v68, v65, v64
	v_mul_f32_e32 v62, 0xbfb8aa3b, v62
	v_mul_f32_e32 v63, 0xbfb8aa3b, v63
	v_div_fmas_f32 v64, v64, v69, v65
	v_exp_f32_e32 v62, v62
	v_exp_f32_e32 v63, v63
	v_div_fixup_f32 v57, v64, v61, v57
	v_fma_f32 v61, -v66, v67, 1.0
	v_fmac_f32_e32 v67, v61, v67
	v_div_scale_f32 v61, vcc, v56, v60, v56
	v_mul_f32_e32 v64, v61, v67
	v_fma_f32 v65, -v66, v64, v61
	v_pk_add_f32 v[62:63], v[62:63], 1.0 op_sel_hi:[1,0]
	v_fmac_f32_e32 v64, v65, v67
	v_div_scale_f32 v65, s[30:31], v63, v63, v59
	v_fma_f32 v61, -v66, v64, v61
	v_rcp_f32_e32 v66, v65
	v_div_fmas_f32 v61, v61, v67, v64
	v_div_fixup_f32 v56, v61, v60, v56
	v_mul_f32_e32 v52, 0xbfb8aa3b, v52
	v_fma_f32 v60, -v65, v66, 1.0
	v_fmac_f32_e32 v66, v60, v66
	v_div_scale_f32 v60, vcc, v59, v63, v59
	v_mul_f32_e32 v61, v60, v66
	v_fma_f32 v64, -v65, v61, v60
	v_fmac_f32_e32 v61, v64, v66
	v_div_scale_f32 v64, s[30:31], v62, v62, v58
	v_fma_f32 v60, -v65, v61, v60
	v_rcp_f32_e32 v65, v64
	v_div_fmas_f32 v60, v60, v66, v61
	v_div_fixup_f32 v59, v60, v63, v59
	v_mul_f32_e32 v53, 0xbfb8aa3b, v53
	v_fma_f32 v60, -v64, v65, 1.0
	v_fmac_f32_e32 v65, v60, v65
	v_div_scale_f32 v60, vcc, v58, v62, v58
	v_mul_f32_e32 v61, v60, v65
	v_exp_f32_e32 v52, v52
	v_exp_f32_e32 v53, v53
	v_fma_f32 v63, -v64, v61, v60
	v_fmac_f32_e32 v61, v63, v65
	v_fma_f32 v60, -v64, v61, v60
	v_div_fmas_f32 v60, v60, v65, v61
	v_pk_add_f32 v[52:53], v[52:53], 1.0 op_sel_hi:[1,0]
	v_div_fixup_f32 v58, v60, v62, v58
	v_div_scale_f32 v62, s[30:31], v53, v53, v49
	v_rcp_f32_e32 v63, v62
	v_add_co_u32_e32 v60, vcc, s62, v116
	v_cvt_pk_bf16_f32 v56, v56, v57
	v_cvt_pk_bf16_f32 v57, v58, v59
	v_addc_co_u32_e32 v61, vcc, 0, v117, vcc
	global_store_dwordx2 v[60:61], v[56:57], off
	v_fma_f32 v56, -v62, v63, 1.0
	v_fmac_f32_e32 v63, v56, v63
	v_div_scale_f32 v56, vcc, v49, v53, v49
	v_mul_f32_e32 v57, v56, v63
	v_fma_f32 v60, -v62, v57, v56
	v_fmac_f32_e32 v57, v60, v63
	v_div_scale_f32 v60, s[30:31], v52, v52, v48
	v_rcp_f32_e32 v61, v60
	v_fma_f32 v56, -v62, v57, v56
	v_mul_f32_e32 v54, 0xbfb8aa3b, v54
	v_mul_f32_e32 v55, 0xbfb8aa3b, v55
	v_div_fmas_f32 v56, v56, v63, v57
	v_exp_f32_e32 v54, v54
	v_exp_f32_e32 v55, v55
	v_div_fixup_f32 v49, v56, v53, v49
	v_fma_f32 v53, -v60, v61, 1.0
	v_fmac_f32_e32 v61, v53, v61
	v_div_scale_f32 v53, vcc, v48, v52, v48
	v_mul_f32_e32 v56, v53, v61
	v_fma_f32 v57, -v60, v56, v53
	v_pk_add_f32 v[54:55], v[54:55], 1.0 op_sel_hi:[1,0]
	v_fmac_f32_e32 v56, v57, v61
	v_div_scale_f32 v57, s[30:31], v55, v55, v51
	v_fma_f32 v53, -v60, v56, v53
	v_rcp_f32_e32 v60, v57
	v_div_fmas_f32 v53, v53, v61, v56
	v_div_fixup_f32 v48, v53, v52, v48
	v_mul_f32_e32 v44, 0xbfb8aa3b, v44
	v_fma_f32 v52, -v57, v60, 1.0
	v_fmac_f32_e32 v60, v52, v60
	v_div_scale_f32 v52, vcc, v51, v55, v51
	v_mul_f32_e32 v53, v52, v60
	v_fma_f32 v56, -v57, v53, v52
	v_fmac_f32_e32 v53, v56, v60
	v_div_scale_f32 v56, s[30:31], v54, v54, v50
	v_fma_f32 v52, -v57, v53, v52
	v_rcp_f32_e32 v57, v56
	v_div_fmas_f32 v52, v52, v60, v53
	v_div_fixup_f32 v51, v52, v55, v51
	v_mul_f32_e32 v45, 0xbfb8aa3b, v45
	v_fma_f32 v52, -v56, v57, 1.0
	v_fmac_f32_e32 v57, v52, v57
	v_div_scale_f32 v52, vcc, v50, v54, v50
	v_mul_f32_e32 v53, v52, v57
	v_exp_f32_e32 v44, v44
	v_exp_f32_e32 v45, v45
	v_fma_f32 v55, -v56, v53, v52
	v_fmac_f32_e32 v53, v55, v57
	v_fma_f32 v52, -v56, v53, v52
	v_div_fmas_f32 v52, v52, v57, v53
	v_pk_add_f32 v[44:45], v[44:45], 1.0 op_sel_hi:[1,0]
	v_div_fixup_f32 v50, v52, v54, v50
	v_div_scale_f32 v52, s[30:31], v45, v45, v41
	v_rcp_f32_e32 v53, v52
	v_lshl_add_u64 v[58:59], v[116:117], 0, s[6:7]
	v_cvt_pk_bf16_f32 v48, v48, v49
	v_cvt_pk_bf16_f32 v49, v50, v51
	global_store_dwordx2 v[58:59], v[48:49], off offset:128
	v_fma_f32 v48, -v52, v53, 1.0
	v_fmac_f32_e32 v53, v48, v53
	v_div_scale_f32 v48, vcc, v41, v45, v41
	v_mul_f32_e32 v49, v48, v53
	v_fma_f32 v50, -v52, v49, v48
	v_fmac_f32_e32 v49, v50, v53
	v_div_scale_f32 v50, s[30:31], v44, v44, v40
	v_rcp_f32_e32 v51, v50
	v_fma_f32 v48, -v52, v49, v48
	v_mul_f32_e32 v46, 0xbfb8aa3b, v46
	v_mul_f32_e32 v47, 0xbfb8aa3b, v47
	v_div_fmas_f32 v48, v48, v53, v49
	v_exp_f32_e32 v46, v46
	v_exp_f32_e32 v47, v47
	v_div_fixup_f32 v41, v48, v45, v41
	v_fma_f32 v45, -v50, v51, 1.0
	v_fmac_f32_e32 v51, v45, v51
	v_div_scale_f32 v45, vcc, v40, v44, v40
	v_mul_f32_e32 v48, v45, v51
	v_fma_f32 v49, -v50, v48, v45
	v_pk_add_f32 v[46:47], v[46:47], 1.0 op_sel_hi:[1,0]
	v_fmac_f32_e32 v48, v49, v51
	v_div_scale_f32 v49, s[30:31], v47, v47, v43
	v_fma_f32 v45, -v50, v48, v45
	v_rcp_f32_e32 v50, v49
	v_div_fmas_f32 v45, v45, v51, v48
	v_div_fixup_f32 v40, v45, v44, v40
	v_mul_f32_e32 v36, 0xbfb8aa3b, v36
	v_fma_f32 v44, -v49, v50, 1.0
	v_fmac_f32_e32 v50, v44, v50
	v_div_scale_f32 v44, vcc, v43, v47, v43
	v_mul_f32_e32 v45, v44, v50
	v_fma_f32 v48, -v49, v45, v44
	v_fmac_f32_e32 v45, v48, v50
	v_div_scale_f32 v48, s[30:31], v46, v46, v42
	v_fma_f32 v44, -v49, v45, v44
	v_rcp_f32_e32 v49, v48
	v_div_fmas_f32 v44, v44, v50, v45
	v_div_fixup_f32 v43, v44, v47, v43
	v_mul_f32_e32 v37, 0xbfb8aa3b, v37
	v_fma_f32 v44, -v48, v49, 1.0
	v_fmac_f32_e32 v49, v44, v49
	v_div_scale_f32 v44, vcc, v42, v46, v42
	v_mul_f32_e32 v45, v44, v49
	v_exp_f32_e32 v36, v36
	v_exp_f32_e32 v37, v37
	v_fma_f32 v47, -v48, v45, v44
	v_fmac_f32_e32 v45, v47, v49
	v_fma_f32 v44, -v48, v45, v44
	v_div_fmas_f32 v44, v44, v49, v45
	v_pk_add_f32 v[36:37], v[36:37], 1.0 op_sel_hi:[1,0]
	v_div_fixup_f32 v42, v44, v46, v42
	v_div_scale_f32 v46, s[30:31], v37, v37, v33
	v_rcp_f32_e32 v47, v46
	v_add_co_u32_e32 v44, vcc, s63, v116
	v_cvt_pk_bf16_f32 v40, v40, v41
	v_cvt_pk_bf16_f32 v41, v42, v43
	v_addc_co_u32_e32 v45, vcc, 0, v117, vcc
	global_store_dwordx2 v[44:45], v[40:41], off
	v_fma_f32 v40, -v46, v47, 1.0
	v_fmac_f32_e32 v47, v40, v47
	v_div_scale_f32 v40, vcc, v33, v37, v33
	v_mul_f32_e32 v41, v40, v47
	v_fma_f32 v44, -v46, v41, v40
	v_fmac_f32_e32 v41, v44, v47
	v_div_scale_f32 v44, s[30:31], v36, v36, v32
	v_rcp_f32_e32 v45, v44
	v_fma_f32 v40, -v46, v41, v40
	v_mul_f32_e32 v38, 0xbfb8aa3b, v38
	v_mul_f32_e32 v39, 0xbfb8aa3b, v39
	v_div_fmas_f32 v40, v40, v47, v41
	v_exp_f32_e32 v38, v38
	v_exp_f32_e32 v39, v39
	v_div_fixup_f32 v33, v40, v37, v33
	v_fma_f32 v37, -v44, v45, 1.0
	v_fmac_f32_e32 v45, v37, v45
	v_div_scale_f32 v37, vcc, v32, v36, v32
	v_mul_f32_e32 v40, v37, v45
	v_fma_f32 v41, -v44, v40, v37
	v_pk_add_f32 v[38:39], v[38:39], 1.0 op_sel_hi:[1,0]
	v_fmac_f32_e32 v40, v41, v45
	v_div_scale_f32 v41, s[30:31], v39, v39, v35
	v_fma_f32 v37, -v44, v40, v37
	v_rcp_f32_e32 v44, v41
	v_div_fmas_f32 v37, v37, v45, v40
	v_div_fixup_f32 v32, v37, v36, v32
	v_mul_f32_e32 v28, 0xbfb8aa3b, v28
	v_fma_f32 v36, -v41, v44, 1.0
	v_fmac_f32_e32 v44, v36, v44
	v_div_scale_f32 v36, vcc, v35, v39, v35
	v_mul_f32_e32 v37, v36, v44
	v_fma_f32 v40, -v41, v37, v36
	v_fmac_f32_e32 v37, v40, v44
	v_div_scale_f32 v40, s[30:31], v38, v38, v34
	v_fma_f32 v36, -v41, v37, v36
	v_rcp_f32_e32 v41, v40
	v_div_fmas_f32 v36, v36, v44, v37
	v_div_fixup_f32 v35, v36, v39, v35
	v_mul_f32_e32 v29, 0xbfb8aa3b, v29
	v_fma_f32 v36, -v40, v41, 1.0
	v_fmac_f32_e32 v41, v36, v41
	v_div_scale_f32 v36, vcc, v34, v38, v34
	v_mul_f32_e32 v37, v36, v41
	v_exp_f32_e32 v28, v28
	v_exp_f32_e32 v29, v29
	v_fma_f32 v39, -v40, v37, v36
	v_fmac_f32_e32 v37, v39, v41
	v_fma_f32 v36, -v40, v37, v36
	v_div_fmas_f32 v36, v36, v41, v37
	v_pk_add_f32 v[28:29], v[28:29], 1.0 op_sel_hi:[1,0]
	v_div_fixup_f32 v34, v36, v38, v34
	v_div_scale_f32 v36, s[30:31], v29, v29, v25
	v_rcp_f32_e32 v37, v36
	v_lshl_add_u64 v[42:43], v[116:117], 0, s[10:11]
	v_cvt_pk_bf16_f32 v32, v32, v33
	v_cvt_pk_bf16_f32 v33, v34, v35
	global_store_dwordx2 v[42:43], v[32:33], off offset:128
	v_fma_f32 v32, -v36, v37, 1.0
	v_fmac_f32_e32 v37, v32, v37
	v_div_scale_f32 v32, vcc, v25, v29, v25
	v_mul_f32_e32 v33, v32, v37
	v_fma_f32 v34, -v36, v33, v32
	v_fmac_f32_e32 v33, v34, v37
	v_div_scale_f32 v34, s[30:31], v28, v28, v24
	v_rcp_f32_e32 v35, v34
	v_fma_f32 v32, -v36, v33, v32
	v_mul_f32_e32 v30, 0xbfb8aa3b, v30
	v_mul_f32_e32 v31, 0xbfb8aa3b, v31
	v_div_fmas_f32 v32, v32, v37, v33
	v_exp_f32_e32 v30, v30
	v_exp_f32_e32 v31, v31
	v_div_fixup_f32 v25, v32, v29, v25
	v_fma_f32 v29, -v34, v35, 1.0
	v_fmac_f32_e32 v35, v29, v35
	v_div_scale_f32 v29, vcc, v24, v28, v24
	v_mul_f32_e32 v32, v29, v35
	v_fma_f32 v33, -v34, v32, v29
	v_pk_add_f32 v[30:31], v[30:31], 1.0 op_sel_hi:[1,0]
	v_fmac_f32_e32 v32, v33, v35
	v_div_scale_f32 v33, s[30:31], v31, v31, v27
	v_fma_f32 v29, -v34, v32, v29
	v_rcp_f32_e32 v34, v33
	v_div_fmas_f32 v29, v29, v35, v32
	v_div_fixup_f32 v24, v29, v28, v24
	v_mul_f32_e32 v20, 0xbfb8aa3b, v20
	v_fma_f32 v28, -v33, v34, 1.0
	v_fmac_f32_e32 v34, v28, v34
	v_div_scale_f32 v28, vcc, v27, v31, v27
	v_mul_f32_e32 v29, v28, v34
	v_fma_f32 v32, -v33, v29, v28
	v_fmac_f32_e32 v29, v32, v34
	v_div_scale_f32 v32, s[30:31], v30, v30, v26
	v_fma_f32 v28, -v33, v29, v28
	v_rcp_f32_e32 v33, v32
	v_div_fmas_f32 v28, v28, v34, v29
	v_div_fixup_f32 v27, v28, v31, v27
	v_mul_f32_e32 v21, 0xbfb8aa3b, v21
	v_fma_f32 v28, -v32, v33, 1.0
	v_fmac_f32_e32 v33, v28, v33
	v_div_scale_f32 v28, vcc, v26, v30, v26
	v_mul_f32_e32 v29, v28, v33
	v_exp_f32_e32 v20, v20
	v_exp_f32_e32 v21, v21
	v_fma_f32 v31, -v32, v29, v28
	v_fmac_f32_e32 v29, v31, v33
	v_fma_f32 v28, -v32, v29, v28
	v_div_fmas_f32 v28, v28, v33, v29
	v_pk_add_f32 v[20:21], v[20:21], 1.0 op_sel_hi:[1,0]
	v_div_fixup_f32 v26, v28, v30, v26
	v_div_scale_f32 v30, s[30:31], v21, v21, v17
	v_rcp_f32_e32 v31, v30
	v_add_co_u32_e32 v28, vcc, s70, v116
	v_cvt_pk_bf16_f32 v24, v24, v25
	v_cvt_pk_bf16_f32 v25, v26, v27
	v_addc_co_u32_e32 v29, vcc, 0, v117, vcc
	global_store_dwordx2 v[28:29], v[24:25], off
	v_fma_f32 v24, -v30, v31, 1.0
	v_fmac_f32_e32 v31, v24, v31
	v_div_scale_f32 v24, vcc, v17, v21, v17
	v_mul_f32_e32 v25, v24, v31
	v_fma_f32 v28, -v30, v25, v24
	v_fmac_f32_e32 v25, v28, v31
	v_div_scale_f32 v28, s[30:31], v20, v20, v16
	v_rcp_f32_e32 v29, v28
	v_fma_f32 v24, -v30, v25, v24
	v_mul_f32_e32 v22, 0xbfb8aa3b, v22
	v_mul_f32_e32 v23, 0xbfb8aa3b, v23
	v_div_fmas_f32 v24, v24, v31, v25
	v_exp_f32_e32 v22, v22
	v_exp_f32_e32 v23, v23
	v_div_fixup_f32 v17, v24, v21, v17
	v_fma_f32 v21, -v28, v29, 1.0
	v_fmac_f32_e32 v29, v21, v29
	v_div_scale_f32 v21, vcc, v16, v20, v16
	v_mul_f32_e32 v24, v21, v29
	v_fma_f32 v25, -v28, v24, v21
	v_pk_add_f32 v[22:23], v[22:23], 1.0 op_sel_hi:[1,0]
	v_fmac_f32_e32 v24, v25, v29
	v_div_scale_f32 v25, s[30:31], v23, v23, v19
	v_fma_f32 v21, -v28, v24, v21
	v_rcp_f32_e32 v28, v25
	v_div_fmas_f32 v21, v21, v29, v24
	v_div_fixup_f32 v16, v21, v20, v16
	v_mul_f32_e32 v12, 0xbfb8aa3b, v12
	v_fma_f32 v20, -v25, v28, 1.0
	v_fmac_f32_e32 v28, v20, v28
	v_div_scale_f32 v20, vcc, v19, v23, v19
	v_mul_f32_e32 v21, v20, v28
	v_fma_f32 v24, -v25, v21, v20
	v_fmac_f32_e32 v21, v24, v28
	v_div_scale_f32 v24, s[30:31], v22, v22, v18
	v_fma_f32 v20, -v25, v21, v20
	v_rcp_f32_e32 v25, v24
	v_div_fmas_f32 v20, v20, v28, v21
	v_div_fixup_f32 v19, v20, v23, v19
	v_mul_f32_e32 v13, 0xbfb8aa3b, v13
	v_fma_f32 v20, -v24, v25, 1.0
	v_fmac_f32_e32 v25, v20, v25
	v_div_scale_f32 v20, vcc, v18, v22, v18
	v_mul_f32_e32 v21, v20, v25
	v_exp_f32_e32 v12, v12
	v_exp_f32_e32 v13, v13
	v_fma_f32 v23, -v24, v21, v20
	v_fmac_f32_e32 v21, v23, v25
	v_fma_f32 v20, -v24, v21, v20
	v_div_fmas_f32 v20, v20, v25, v21
	v_pk_add_f32 v[12:13], v[12:13], 1.0 op_sel_hi:[1,0]
	v_div_fixup_f32 v18, v20, v22, v18
	v_div_scale_f32 v20, s[30:31], v13, v13, v9
	v_rcp_f32_e32 v21, v20
	v_lshl_add_u64 v[26:27], v[116:117], 0, s[12:13]
	v_cvt_pk_bf16_f32 v16, v16, v17
	v_cvt_pk_bf16_f32 v17, v18, v19
	global_store_dwordx2 v[26:27], v[16:17], off offset:128
	v_fma_f32 v16, -v20, v21, 1.0
	v_fmac_f32_e32 v21, v16, v21
	v_div_scale_f32 v16, vcc, v9, v13, v9
	v_mul_f32_e32 v17, v16, v21
	v_fma_f32 v18, -v20, v17, v16
	v_fmac_f32_e32 v17, v18, v21
	v_div_scale_f32 v18, s[30:31], v12, v12, v8
	v_rcp_f32_e32 v19, v18
	v_fma_f32 v16, -v20, v17, v16
	v_mul_f32_e32 v14, 0xbfb8aa3b, v14
	v_mul_f32_e32 v15, 0xbfb8aa3b, v15
	v_div_fmas_f32 v16, v16, v21, v17
	v_exp_f32_e32 v14, v14
	v_exp_f32_e32 v15, v15
	v_div_fixup_f32 v9, v16, v13, v9
	v_fma_f32 v13, -v18, v19, 1.0
	v_fmac_f32_e32 v19, v13, v19
	v_div_scale_f32 v13, vcc, v8, v12, v8
	v_mul_f32_e32 v16, v13, v19
	v_fma_f32 v17, -v18, v16, v13
	v_pk_add_f32 v[14:15], v[14:15], 1.0 op_sel_hi:[1,0]
	v_fmac_f32_e32 v16, v17, v19
	v_div_scale_f32 v17, s[30:31], v15, v15, v11
	v_fma_f32 v13, -v18, v16, v13
	v_rcp_f32_e32 v18, v17
	v_div_fmas_f32 v13, v13, v19, v16
	v_div_fixup_f32 v8, v13, v12, v8
	v_mul_f32_e32 v4, 0xbfb8aa3b, v4
	v_fma_f32 v12, -v17, v18, 1.0
	v_fmac_f32_e32 v18, v12, v18
	v_div_scale_f32 v12, vcc, v11, v15, v11
	v_mul_f32_e32 v13, v12, v18
	v_fma_f32 v16, -v17, v13, v12
	v_fmac_f32_e32 v13, v16, v18
	v_div_scale_f32 v16, s[30:31], v14, v14, v10
	v_fma_f32 v12, -v17, v13, v12
	v_rcp_f32_e32 v17, v16
	v_div_fmas_f32 v12, v12, v18, v13
	v_div_fixup_f32 v11, v12, v15, v11
	v_mul_f32_e32 v5, 0xbfb8aa3b, v5
	v_fma_f32 v12, -v16, v17, 1.0
	v_fmac_f32_e32 v17, v12, v17
	v_div_scale_f32 v12, vcc, v10, v14, v10
	v_mul_f32_e32 v13, v12, v17
	v_exp_f32_e32 v4, v4
	v_exp_f32_e32 v5, v5
	v_fma_f32 v15, -v16, v13, v12
	v_fmac_f32_e32 v13, v15, v17
	v_fma_f32 v12, -v16, v13, v12
	v_div_fmas_f32 v12, v12, v17, v13
	v_pk_add_f32 v[4:5], v[4:5], 1.0 op_sel_hi:[1,0]
	v_div_fixup_f32 v10, v12, v14, v10
	v_div_scale_f32 v14, s[30:31], v5, v5, v1
	v_rcp_f32_e32 v15, v14
	v_add_co_u32_e32 v12, vcc, s71, v116
	v_cvt_pk_bf16_f32 v8, v8, v9
	v_cvt_pk_bf16_f32 v9, v10, v11
	v_addc_co_u32_e32 v13, vcc, 0, v117, vcc
	global_store_dwordx2 v[12:13], v[8:9], off
	v_fma_f32 v8, -v14, v15, 1.0
	v_fmac_f32_e32 v15, v8, v15
	v_div_scale_f32 v8, vcc, v1, v5, v1
	v_mul_f32_e32 v9, v8, v15
	v_fma_f32 v12, -v14, v9, v8
	v_fmac_f32_e32 v9, v12, v15
	v_div_scale_f32 v12, s[30:31], v4, v4, v0
	v_rcp_f32_e32 v13, v12
	v_fma_f32 v8, -v14, v9, v8
	v_mul_f32_e32 v6, 0xbfb8aa3b, v6
	v_mul_f32_e32 v7, 0xbfb8aa3b, v7
	v_div_fmas_f32 v8, v8, v15, v9
	v_exp_f32_e32 v6, v6
	v_exp_f32_e32 v7, v7
	v_div_fixup_f32 v1, v8, v5, v1
	v_fma_f32 v5, -v12, v13, 1.0
	v_fmac_f32_e32 v13, v5, v13
	v_div_scale_f32 v5, vcc, v0, v4, v0
	v_mul_f32_e32 v8, v5, v13
	v_fma_f32 v9, -v12, v8, v5
	v_pk_add_f32 v[6:7], v[6:7], 1.0 op_sel_hi:[1,0]
	v_fmac_f32_e32 v8, v9, v13
	v_div_scale_f32 v9, s[30:31], v7, v7, v3
	v_fma_f32 v5, -v12, v8, v5
	v_rcp_f32_e32 v12, v9
	v_div_fmas_f32 v5, v5, v13, v8
	v_div_fixup_f32 v0, v5, v4, v0
	v_lshl_add_u64 v[10:11], v[116:117], 0, s[14:15]
	v_fma_f32 v4, -v9, v12, 1.0
	v_fmac_f32_e32 v12, v4, v12
	v_div_scale_f32 v4, vcc, v3, v7, v3
	v_mul_f32_e32 v5, v4, v12
	v_fma_f32 v8, -v9, v5, v4
	v_fmac_f32_e32 v5, v8, v12
	v_div_scale_f32 v8, s[30:31], v6, v6, v2
	v_fma_f32 v4, -v9, v5, v4
	v_rcp_f32_e32 v9, v8
	v_div_fmas_f32 v4, v4, v12, v5
	v_div_fixup_f32 v3, v4, v7, v3
	v_cvt_pk_bf16_f32 v0, v0, v1
	v_fma_f32 v4, -v8, v9, 1.0
	v_fmac_f32_e32 v9, v4, v9
	v_div_scale_f32 v4, vcc, v2, v6, v2
	v_mul_f32_e32 v5, v4, v9
	v_fma_f32 v7, -v8, v5, v4
	v_fmac_f32_e32 v5, v7, v9
	v_fma_f32 v4, -v8, v5, v4
	v_div_fmas_f32 v4, v4, v9, v5
	v_div_fixup_f32 v2, v4, v6, v2
	v_cvt_pk_bf16_f32 v1, v2, v3
	s_and_b64 vcc, exec, s[4:5]
	s_mov_b32 s72, s16
	s_mov_b32 s28, s18
	s_mov_b64 s[34:35], s[26:27]
	s_mov_b64 s[30:31], s[20:21]
	global_store_dwordx2 v[10:11], v[0:1], off offset:128
	s_cbranch_vccz .LBB0_1109
	s_waitcnt vmcnt(0)
	s_cmpk_gt_u32 s40, 0xff
	s_cbranch_scc1 .LBB0_1120
	s_barrier

.LBB0_1141:
	ds_read_b128 v[150:153], v145
	ds_read_b128 v[154:157], v145 offset:1024
	ds_read_b128 v[158:161], v145 offset:2048
	ds_read_b128 v[162:165], v145 offset:3072
	s_add_u32 s34, s30, 0xfffc0080
	s_addc_u32 s35, s31, -1
	s_cmp_eq_u32 s77, 12
	s_cselect_b32 s37, s19, s35
	s_cselect_b32 s36, s73, s34
	s_cselect_b32 s35, s17, s76
	s_cselect_b32 s34, s74, s75
	v_lshl_add_u64 v[198:199], s[30:31], 0, v[134:135]
	s_add_i32 m0, s29, 0xc000
	ds_read_b128 v[166:169], v148
	ds_read_b128 v[170:173], v148 offset:1024
	ds_read_b128 v[174:177], v148 offset:2048
	ds_read_b128 v[178:181], v148 offset:3072
	ds_read_b128 v[182:185], v148 offset:4096
	ds_read_b128 v[186:189], v148 offset:5120
	ds_read_b128 v[190:193], v148 offset:6144
	ds_read_b128 v[194:197], v148 offset:7168
	global_load_lds_dwordx4 v[198:199], off
	v_lshl_add_u64 v[198:199], s[30:31], 0, v[136:137]
	s_add_i32 m0, s29, 0xe000
	s_nop 0
	global_load_lds_dwordx4 v[198:199], off
	s_waitcnt lgkmcnt(8)
	s_barrier
	s_waitcnt lgkmcnt(0)
	s_setprio 0
	s_waitcnt lgkmcnt(0)
	v_mfma_f32_16x16x32_bf16 v[120:123], v[150:153], v[166:169], v[120:123]
	v_mfma_f32_16x16x32_bf16 v[124:127], v[158:161], v[166:169], v[124:127]
	v_mfma_f32_16x16x32_bf16 v[104:107], v[150:153], v[174:177], v[104:107]
	v_mfma_f32_16x16x32_bf16 v[108:111], v[158:161], v[174:177], v[108:111]
	v_mfma_f32_16x16x32_bf16 v[88:91], v[150:153], v[182:185], v[88:91]
	v_mfma_f32_16x16x32_bf16 v[92:95], v[158:161], v[182:185], v[92:95]
	v_mfma_f32_16x16x32_bf16 v[72:75], v[150:153], v[190:193], v[72:75]
	v_mfma_f32_16x16x32_bf16 v[76:79], v[158:161], v[190:193], v[76:79]
	v_mfma_f32_16x16x32_bf16 v[120:123], v[154:157], v[170:173], v[120:123]
	v_mfma_f32_16x16x32_bf16 v[124:127], v[162:165], v[170:173], v[124:127]
	v_mfma_f32_16x16x32_bf16 v[104:107], v[154:157], v[178:181], v[104:107]
	v_mfma_f32_16x16x32_bf16 v[108:111], v[162:165], v[178:181], v[108:111]
	v_mfma_f32_16x16x32_bf16 v[88:91], v[154:157], v[186:189], v[88:91]
	v_mfma_f32_16x16x32_bf16 v[92:95], v[162:165], v[186:189], v[92:95]
	v_mfma_f32_16x16x32_bf16 v[72:75], v[154:157], v[194:197], v[72:75]
	v_mfma_f32_16x16x32_bf16 v[76:79], v[162:165], v[194:197], v[76:79]
	s_setprio 1
	s_barrier
	s_add_i32 s78, s60, s42
	v_lshl_add_u64 v[214:215], s[34:35], 0, v[130:131]
	s_mov_b32 m0, s78
	ds_read_b128 v[198:201], v149
	ds_read_b128 v[202:205], v149 offset:1024
	ds_read_b128 v[206:209], v149 offset:2048
	ds_read_b128 v[210:213], v149 offset:3072
	global_load_lds_dwordx4 v[214:215], off
	v_lshl_add_u64 v[216:217], s[34:35], 0, v[132:133]
	s_add_i32 m0, s78, 0x2000
	s_nop 0
	global_load_lds_dwordx4 v[216:217], off
	s_barrier
	s_waitcnt lgkmcnt(0)
	s_setprio 0
	s_waitcnt lgkmcnt(0)
	v_mfma_f32_16x16x32_bf16 v[112:115], v[198:201], v[166:169], v[112:115]
	v_mfma_f32_16x16x32_bf16 v[116:119], v[206:209], v[166:169], v[116:119]
	v_mfma_f32_16x16x32_bf16 v[96:99], v[198:201], v[174:177], v[96:99]
	v_mfma_f32_16x16x32_bf16 v[100:103], v[206:209], v[174:177], v[100:103]
	v_mfma_f32_16x16x32_bf16 v[80:83], v[198:201], v[182:185], v[80:83]
	v_mfma_f32_16x16x32_bf16 v[84:87], v[206:209], v[182:185], v[84:87]
	v_mfma_f32_16x16x32_bf16 v[64:67], v[198:201], v[190:193], v[64:67]
	v_mfma_f32_16x16x32_bf16 v[68:71], v[206:209], v[190:193], v[68:71]
	v_mfma_f32_16x16x32_bf16 v[112:115], v[202:205], v[170:173], v[112:115]
	v_mfma_f32_16x16x32_bf16 v[116:119], v[210:213], v[170:173], v[116:119]
	v_mfma_f32_16x16x32_bf16 v[96:99], v[202:205], v[178:181], v[96:99]
	v_mfma_f32_16x16x32_bf16 v[100:103], v[210:213], v[178:181], v[100:103]
	v_mfma_f32_16x16x32_bf16 v[80:83], v[202:205], v[186:189], v[80:83]
	v_mfma_f32_16x16x32_bf16 v[84:87], v[210:213], v[186:189], v[84:87]
	v_mfma_f32_16x16x32_bf16 v[64:67], v[202:205], v[194:197], v[64:67]
	v_mfma_f32_16x16x32_bf16 v[68:71], v[210:213], v[194:197], v[68:71]
	s_setprio 1
	s_mov_b32 m0, s29
	v_lshl_add_u64 v[218:219], s[36:37], 0, v[130:131]
	s_barrier
	ds_read_b128 v[166:169], v148 offset:16384
	ds_read_b128 v[170:173], v148 offset:17408
	ds_read_b128 v[174:177], v148 offset:18432
	ds_read_b128 v[178:181], v148 offset:19456
	ds_read_b128 v[182:185], v148 offset:20480
	ds_read_b128 v[186:189], v148 offset:21504
	ds_read_b128 v[190:193], v148 offset:22528
	ds_read_b128 v[194:197], v148 offset:23552
	global_load_lds_dwordx4 v[218:219], off
	v_lshl_add_u64 v[220:221], s[36:37], 0, v[132:133]
	s_mov_b32 m0, s43
	s_nop 0
	global_load_lds_dwordx4 v[220:221], off
	s_barrier
	s_waitcnt lgkmcnt(0)
	s_setprio 0
	s_waitcnt lgkmcnt(0)
	v_mfma_f32_16x16x32_bf16 v[56:59], v[150:153], v[166:169], v[56:59]
	v_mfma_f32_16x16x32_bf16 v[60:63], v[158:161], v[166:169], v[60:63]
	v_mfma_f32_16x16x32_bf16 v[40:43], v[150:153], v[174:177], v[40:43]
	v_mfma_f32_16x16x32_bf16 v[44:47], v[158:161], v[174:177], v[44:47]
	v_mfma_f32_16x16x32_bf16 v[24:27], v[150:153], v[182:185], v[24:27]
	v_mfma_f32_16x16x32_bf16 v[28:31], v[158:161], v[182:185], v[28:31]
	v_mfma_f32_16x16x32_bf16 v[8:11], v[150:153], v[190:193], v[8:11]
	v_mfma_f32_16x16x32_bf16 v[12:15], v[158:161], v[190:193], v[12:15]
	v_mfma_f32_16x16x32_bf16 v[56:59], v[154:157], v[170:173], v[56:59]
	v_mfma_f32_16x16x32_bf16 v[60:63], v[162:165], v[170:173], v[60:63]
	v_mfma_f32_16x16x32_bf16 v[40:43], v[154:157], v[178:181], v[40:43]
	v_mfma_f32_16x16x32_bf16 v[44:47], v[162:165], v[178:181], v[44:47]
	v_mfma_f32_16x16x32_bf16 v[24:27], v[154:157], v[186:189], v[24:27]
	v_mfma_f32_16x16x32_bf16 v[28:31], v[162:165], v[186:189], v[28:31]
	v_mfma_f32_16x16x32_bf16 v[8:11], v[154:157], v[194:197], v[8:11]
	v_mfma_f32_16x16x32_bf16 v[12:15], v[162:165], v[194:197], v[12:15]
	s_setprio 1
	s_barrier
	s_add_u32 s78, s34, 0x40000
	s_addc_u32 s79, s35, 0
	s_add_i32 s80, s61, s42
	v_lshl_add_u64 v[150:151], s[78:79], 0, v[130:131]
	s_mov_b32 m0, s80
	s_nop 0
	global_load_lds_dwordx4 v[150:151], off
	v_lshl_add_u64 v[150:151], s[78:79], 0, v[132:133]
	s_add_i32 m0, s80, 0x2000
	s_nop 0
	global_load_lds_dwordx4 v[150:151], off
	s_waitcnt vmcnt(6)
	s_barrier
	s_setprio 0
	v_mfma_f32_16x16x32_bf16 v[48:51], v[198:201], v[166:169], v[48:51]
	v_mfma_f32_16x16x32_bf16 v[52:55], v[206:209], v[166:169], v[52:55]
	v_mfma_f32_16x16x32_bf16 v[32:35], v[198:201], v[174:177], v[32:35]
	v_mfma_f32_16x16x32_bf16 v[36:39], v[206:209], v[174:177], v[36:39]
	v_mfma_f32_16x16x32_bf16 v[16:19], v[198:201], v[182:185], v[16:19]
	v_mfma_f32_16x16x32_bf16 v[20:23], v[206:209], v[182:185], v[20:23]
	v_mfma_f32_16x16x32_bf16 v[0:3], v[198:201], v[190:193], v[0:3]
	v_mfma_f32_16x16x32_bf16 v[4:7], v[206:209], v[190:193], v[4:7]
	v_mfma_f32_16x16x32_bf16 v[48:51], v[202:205], v[170:173], v[48:51]
	v_mfma_f32_16x16x32_bf16 v[52:55], v[210:213], v[170:173], v[52:55]
	v_mfma_f32_16x16x32_bf16 v[32:35], v[202:205], v[178:181], v[32:35]
	v_mfma_f32_16x16x32_bf16 v[36:39], v[210:213], v[178:181], v[36:39]
	v_mfma_f32_16x16x32_bf16 v[16:19], v[202:205], v[186:189], v[16:19]
	v_mfma_f32_16x16x32_bf16 v[20:23], v[210:213], v[186:189], v[20:23]
	v_mfma_f32_16x16x32_bf16 v[0:3], v[202:205], v[194:197], v[0:3]
	v_mfma_f32_16x16x32_bf16 v[4:7], v[210:213], v[194:197], v[4:7]
	s_setprio 1
	s_add_i32 s78, 0, 0x18000
	v_add_u32_e32 v162, s78, v143
	s_barrier
	ds_read_b128 v[150:153], v162
	ds_read_b128 v[154:157], v162 offset:1024
	ds_read_b128 v[158:161], v162 offset:2048
	ds_read_b128 v[162:165], v162 offset:3072
	s_add_u32 s36, s36, 0x40000
	s_addc_u32 s37, s37, 0
	s_mov_b32 m0, s52
	v_lshl_add_u64 v[198:199], s[36:37], 0, v[130:131]
	ds_read_b128 v[166:169], v148 offset:32768
	ds_read_b128 v[170:173], v148 offset:33792
	ds_read_b128 v[174:177], v148 offset:34816
	ds_read_b128 v[178:181], v148 offset:35840
	ds_read_b128 v[182:185], v148 offset:36864
	ds_read_b128 v[186:189], v148 offset:37888
	ds_read_b128 v[190:193], v148 offset:38912
	ds_read_b128 v[194:197], v148 offset:39936
	global_load_lds_dwordx4 v[198:199], off
	v_lshl_add_u64 v[198:199], s[36:37], 0, v[132:133]
	s_mov_b32 m0, s53
	s_nop 0
	global_load_lds_dwordx4 v[198:199], off
	s_waitcnt lgkmcnt(8)
	s_barrier
	s_waitcnt lgkmcnt(0)
	s_setprio 0
	s_waitcnt lgkmcnt(0)
	v_mfma_f32_16x16x32_bf16 v[120:123], v[150:153], v[166:169], v[120:123]
	v_mfma_f32_16x16x32_bf16 v[124:127], v[158:161], v[166:169], v[124:127]
	v_mfma_f32_16x16x32_bf16 v[104:107], v[150:153], v[174:177], v[104:107]
	v_mfma_f32_16x16x32_bf16 v[108:111], v[158:161], v[174:177], v[108:111]
	v_mfma_f32_16x16x32_bf16 v[88:91], v[150:153], v[182:185], v[88:91]
	v_mfma_f32_16x16x32_bf16 v[92:95], v[158:161], v[182:185], v[92:95]
	v_mfma_f32_16x16x32_bf16 v[72:75], v[150:153], v[190:193], v[72:75]
	v_mfma_f32_16x16x32_bf16 v[76:79], v[158:161], v[190:193], v[76:79]
	v_mfma_f32_16x16x32_bf16 v[120:123], v[154:157], v[170:173], v[120:123]
	v_mfma_f32_16x16x32_bf16 v[124:127], v[162:165], v[170:173], v[124:127]
	v_mfma_f32_16x16x32_bf16 v[104:107], v[154:157], v[178:181], v[104:107]
	v_mfma_f32_16x16x32_bf16 v[108:111], v[162:165], v[178:181], v[108:111]
	v_mfma_f32_16x16x32_bf16 v[88:91], v[154:157], v[186:189], v[88:91]
	v_mfma_f32_16x16x32_bf16 v[92:95], v[162:165], v[186:189], v[92:95]
	v_mfma_f32_16x16x32_bf16 v[72:75], v[154:157], v[194:197], v[72:75]
	v_mfma_f32_16x16x32_bf16 v[76:79], v[162:165], v[194:197], v[76:79]
	s_setprio 1
	s_barrier
	s_add_i32 s36, 0, 0x1c000
	s_add_i32 s37, s78, s42
	v_add_u32_e32 v210, s36, v143
	v_lshl_add_u64 v[214:215], v[214:215], 0, s[8:9]
	s_mov_b32 m0, s37
	ds_read_b128 v[198:201], v210
	ds_read_b128 v[202:205], v210 offset:1024
	ds_read_b128 v[206:209], v210 offset:2048
	ds_read_b128 v[210:213], v210 offset:3072
	global_load_lds_dwordx4 v[214:215], off
	v_lshl_add_u64 v[214:215], v[216:217], 0, s[8:9]
	s_add_i32 m0, s37, 0x2000
	s_nop 0
	global_load_lds_dwordx4 v[214:215], off
	s_barrier
	s_waitcnt lgkmcnt(0)
	s_setprio 0
	s_waitcnt lgkmcnt(0)
	v_mfma_f32_16x16x32_bf16 v[112:115], v[198:201], v[166:169], v[112:115]
	v_mfma_f32_16x16x32_bf16 v[116:119], v[206:209], v[166:169], v[116:119]
	v_mfma_f32_16x16x32_bf16 v[96:99], v[198:201], v[174:177], v[96:99]
	v_mfma_f32_16x16x32_bf16 v[100:103], v[206:209], v[174:177], v[100:103]
	v_mfma_f32_16x16x32_bf16 v[80:83], v[198:201], v[182:185], v[80:83]
	v_mfma_f32_16x16x32_bf16 v[84:87], v[206:209], v[182:185], v[84:87]
	v_mfma_f32_16x16x32_bf16 v[64:67], v[198:201], v[190:193], v[64:67]
	v_mfma_f32_16x16x32_bf16 v[68:71], v[206:209], v[190:193], v[68:71]
	v_mfma_f32_16x16x32_bf16 v[112:115], v[202:205], v[170:173], v[112:115]
	v_mfma_f32_16x16x32_bf16 v[116:119], v[210:213], v[170:173], v[116:119]
	v_mfma_f32_16x16x32_bf16 v[96:99], v[202:205], v[178:181], v[96:99]
	v_mfma_f32_16x16x32_bf16 v[100:103], v[210:213], v[178:181], v[100:103]
	v_mfma_f32_16x16x32_bf16 v[80:83], v[202:205], v[186:189], v[80:83]
	v_mfma_f32_16x16x32_bf16 v[84:87], v[210:213], v[186:189], v[84:87]
	v_mfma_f32_16x16x32_bf16 v[64:67], v[202:205], v[194:197], v[64:67]
	v_mfma_f32_16x16x32_bf16 v[68:71], v[210:213], v[194:197], v[68:71]
	s_setprio 1
	s_mov_b32 m0, s55
	v_lshl_add_u64 v[214:215], v[218:219], 0, s[8:9]
	s_barrier
	ds_read_b128 v[166:169], v148 offset:49152
	ds_read_b128 v[170:173], v148 offset:50176
	ds_read_b128 v[174:177], v148 offset:51200
	ds_read_b128 v[178:181], v148 offset:52224
	ds_read_b128 v[182:185], v148 offset:53248
	ds_read_b128 v[186:189], v148 offset:54272
	ds_read_b128 v[190:193], v148 offset:55296
	ds_read_b128 v[194:197], v148 offset:56320
	global_load_lds_dwordx4 v[214:215], off
	v_lshl_add_u64 v[214:215], v[220:221], 0, s[8:9]
	s_mov_b32 m0, s56
	s_nop 0
	global_load_lds_dwordx4 v[214:215], off
	s_barrier
	s_waitcnt lgkmcnt(0)
	s_setprio 0
	s_waitcnt lgkmcnt(0)
	v_mfma_f32_16x16x32_bf16 v[56:59], v[150:153], v[166:169], v[56:59]
	v_mfma_f32_16x16x32_bf16 v[60:63], v[158:161], v[166:169], v[60:63]
	v_mfma_f32_16x16x32_bf16 v[40:43], v[150:153], v[174:177], v[40:43]
	v_mfma_f32_16x16x32_bf16 v[44:47], v[158:161], v[174:177], v[44:47]
	v_mfma_f32_16x16x32_bf16 v[24:27], v[150:153], v[182:185], v[24:27]
	v_mfma_f32_16x16x32_bf16 v[28:31], v[158:161], v[182:185], v[28:31]
	v_mfma_f32_16x16x32_bf16 v[8:11], v[150:153], v[190:193], v[8:11]
	v_mfma_f32_16x16x32_bf16 v[12:15], v[158:161], v[190:193], v[12:15]
	v_mfma_f32_16x16x32_bf16 v[56:59], v[154:157], v[170:173], v[56:59]
	v_mfma_f32_16x16x32_bf16 v[60:63], v[162:165], v[170:173], v[60:63]
	v_mfma_f32_16x16x32_bf16 v[40:43], v[154:157], v[178:181], v[40:43]
	v_mfma_f32_16x16x32_bf16 v[44:47], v[162:165], v[178:181], v[44:47]
	v_mfma_f32_16x16x32_bf16 v[24:27], v[154:157], v[186:189], v[24:27]
	v_mfma_f32_16x16x32_bf16 v[28:31], v[162:165], v[186:189], v[28:31]
	v_mfma_f32_16x16x32_bf16 v[8:11], v[154:157], v[194:197], v[8:11]
	v_mfma_f32_16x16x32_bf16 v[12:15], v[162:165], v[194:197], v[12:15]
	s_setprio 1
	s_barrier
	s_add_u32 s34, s34, 0x40080
	s_addc_u32 s35, s35, 0
	s_add_i32 s36, s36, s42
	v_lshl_add_u64 v[150:151], s[34:35], 0, v[130:131]
	s_mov_b32 m0, s36
	s_nop 0
	global_load_lds_dwordx4 v[150:151], off
	v_lshl_add_u64 v[150:151], s[34:35], 0, v[132:133]
	s_add_i32 m0, s36, 0x2000
	s_nop 0
	global_load_lds_dwordx4 v[150:151], off
	s_waitcnt vmcnt(6)
	s_barrier
	s_setprio 0
	v_mfma_f32_16x16x32_bf16 v[48:51], v[198:201], v[166:169], v[48:51]
	v_mfma_f32_16x16x32_bf16 v[52:55], v[206:209], v[166:169], v[52:55]
	v_mfma_f32_16x16x32_bf16 v[32:35], v[198:201], v[174:177], v[32:35]
	v_mfma_f32_16x16x32_bf16 v[36:39], v[206:209], v[174:177], v[36:39]
	v_mfma_f32_16x16x32_bf16 v[16:19], v[198:201], v[182:185], v[16:19]
	v_mfma_f32_16x16x32_bf16 v[20:23], v[206:209], v[182:185], v[20:23]
	v_mfma_f32_16x16x32_bf16 v[0:3], v[198:201], v[190:193], v[0:3]
	v_mfma_f32_16x16x32_bf16 v[4:7], v[206:209], v[190:193], v[4:7]
	v_mfma_f32_16x16x32_bf16 v[48:51], v[202:205], v[170:173], v[48:51]
	v_mfma_f32_16x16x32_bf16 v[52:55], v[210:213], v[170:173], v[52:55]
	v_mfma_f32_16x16x32_bf16 v[32:35], v[202:205], v[178:181], v[32:35]
	v_mfma_f32_16x16x32_bf16 v[36:39], v[210:213], v[178:181], v[36:39]
	v_mfma_f32_16x16x32_bf16 v[16:19], v[202:205], v[186:189], v[16:19]
	v_mfma_f32_16x16x32_bf16 v[20:23], v[210:213], v[186:189], v[20:23]
	v_mfma_f32_16x16x32_bf16 v[0:3], v[202:205], v[194:197], v[0:3]
	v_mfma_f32_16x16x32_bf16 v[4:7], v[210:213], v[194:197], v[4:7]
	s_setprio 1
	s_add_i32 s77, s77, 2
	s_add_u32 s30, s30, 0x100
	s_addc_u32 s31, s31, 0
	s_add_u32 s75, s75, 0x100
	s_addc_u32 s76, s76, 0
	s_cmp_gt_u32 s77, 13
	s_barrier
	s_cbranch_scc0 .LBB0_1141
	v_mul_f32_e32 v124, 0xbfb8aa3b, v124
	v_exp_f32_e32 v150, v124
	v_mul_f32_e32 v124, 0xbfb8aa3b, v125
	v_exp_f32_e32 v151, v124
	v_lshl_add_u32 v124, s28, 8, v142
	v_ashrrev_i32_e32 v125, 31, v124
	v_lshlrev_b64 v[154:155], 11, v[124:125]
	v_pk_add_f32 v[150:151], v[150:151], 1.0 op_sel_hi:[1,0]
	v_mul_f32_e32 v126, 0xbfb8aa3b, v126
	v_div_scale_f32 v153, s[30:31], v151, v151, v121
	v_rcp_f32_e32 v156, v153
	v_mul_f32_e32 v127, 0xbfb8aa3b, v127
	v_exp_f32_e32 v126, v126
	v_exp_f32_e32 v127, v127
	v_fma_f32 v125, -v153, v156, 1.0
	v_fmac_f32_e32 v156, v125, v156
	v_div_scale_f32 v125, vcc, v121, v151, v121
	v_mul_f32_e32 v157, v125, v156
	v_fma_f32 v158, -v153, v157, v125
	v_fmac_f32_e32 v157, v158, v156
	v_fma_f32 v125, -v153, v157, v125
	v_div_scale_f32 v153, s[30:31], v150, v150, v120
	v_rcp_f32_e32 v158, v153
	v_div_fmas_f32 v125, v125, v156, v157
	v_div_fixup_f32 v121, v125, v151, v121
	v_pk_add_f32 v[126:127], v[126:127], 1.0 op_sel_hi:[1,0]
	v_fma_f32 v125, -v153, v158, 1.0
	v_fmac_f32_e32 v158, v125, v158
	v_div_scale_f32 v125, vcc, v120, v150, v120
	v_mul_f32_e32 v151, v125, v158
	v_fma_f32 v156, -v153, v151, v125
	v_fmac_f32_e32 v151, v156, v158
	v_fma_f32 v125, -v153, v151, v125
	v_div_scale_f32 v153, s[30:31], v127, v127, v123
	v_rcp_f32_e32 v156, v153
	v_div_fmas_f32 v125, v125, v158, v151
	v_div_fixup_f32 v120, v125, v150, v120
	v_mul_f32_e32 v116, 0xbfb8aa3b, v116
	v_fma_f32 v125, -v153, v156, 1.0
	v_fmac_f32_e32 v156, v125, v156
	v_div_scale_f32 v125, vcc, v123, v127, v123
	v_mul_f32_e32 v150, v125, v156
	v_fma_f32 v151, -v153, v150, v125
	v_fmac_f32_e32 v150, v151, v156
	v_div_scale_f32 v151, s[30:31], v126, v126, v122
	v_fma_f32 v125, -v153, v150, v125
	v_rcp_f32_e32 v153, v151
	v_div_fmas_f32 v125, v125, v156, v150
	v_div_fixup_f32 v123, v125, v127, v123
	v_mul_f32_e32 v117, 0xbfb8aa3b, v117
	v_fma_f32 v125, -v151, v153, 1.0
	v_fmac_f32_e32 v153, v125, v153
	v_div_scale_f32 v125, vcc, v122, v126, v122
	v_mul_f32_e32 v127, v125, v153
	v_fma_f32 v150, -v151, v127, v125
	v_exp_f32_e32 v116, v116
	v_exp_f32_e32 v117, v117
	v_fmac_f32_e32 v127, v150, v153
	v_fma_f32 v125, -v151, v127, v125
	v_div_fmas_f32 v125, v125, v153, v127
	v_div_fixup_f32 v125, v125, v126, v122
	v_pk_add_f32 v[126:127], v[116:117], 1.0 op_sel_hi:[1,0]
	v_cvt_pk_bf16_f32 v123, v125, v123
	v_div_scale_f32 v125, s[30:31], v127, v127, v113
	v_lshl_or_b32 v152, s72, 7, v144
	v_rcp_f32_e32 v150, v125
	v_ashrrev_i32_e32 v153, 31, v152
	v_lshl_add_u64 v[154:155], s[46:47], 0, v[154:155]
	v_cvt_pk_bf16_f32 v122, v120, v121
	v_lshlrev_b64 v[120:121], 1, v[152:153]
	v_lshl_add_u64 v[116:117], v[154:155], 0, v[120:121]
	global_store_dwordx2 v[116:117], v[122:123], off
	v_fma_f32 v122, -v125, v150, 1.0
	v_fmac_f32_e32 v150, v122, v150
	v_div_scale_f32 v122, vcc, v113, v127, v113
	v_mul_f32_e32 v123, v122, v150
	v_fma_f32 v151, -v125, v123, v122
	v_fmac_f32_e32 v123, v151, v150
	v_fma_f32 v122, -v125, v123, v122
	v_div_scale_f32 v125, s[30:31], v126, v126, v112
	v_rcp_f32_e32 v151, v125
	v_div_fmas_f32 v122, v122, v150, v123
	v_mul_f32_e32 v118, 0xbfb8aa3b, v118
	v_mul_f32_e32 v119, 0xbfb8aa3b, v119
	v_div_fixup_f32 v113, v122, v127, v113
	v_fma_f32 v122, -v125, v151, 1.0
	v_exp_f32_e32 v118, v118
	v_exp_f32_e32 v119, v119
	v_fmac_f32_e32 v151, v122, v151
	v_div_scale_f32 v122, vcc, v112, v126, v112
	v_mul_f32_e32 v123, v122, v151
	v_fma_f32 v127, -v125, v123, v122
	v_fmac_f32_e32 v123, v127, v151
	v_pk_add_f32 v[118:119], v[118:119], 1.0 op_sel_hi:[1,0]
	v_fma_f32 v122, -v125, v123, v122
	v_div_scale_f32 v125, s[30:31], v119, v119, v115
	v_rcp_f32_e32 v127, v125
	v_div_fmas_f32 v122, v122, v151, v123
	v_div_fixup_f32 v112, v122, v126, v112
	v_mul_f32_e32 v108, 0xbfb8aa3b, v108
	v_fma_f32 v122, -v125, v127, 1.0
	v_fmac_f32_e32 v127, v122, v127
	v_div_scale_f32 v122, vcc, v115, v119, v115
	v_mul_f32_e32 v123, v122, v127
	v_fma_f32 v126, -v125, v123, v122
	v_fmac_f32_e32 v123, v126, v127
	v_fma_f32 v122, -v125, v123, v122
	v_div_scale_f32 v125, s[30:31], v118, v118, v114
	v_rcp_f32_e32 v126, v125
	v_div_fmas_f32 v122, v122, v127, v123
	v_div_fixup_f32 v115, v122, v119, v115
	v_mul_f32_e32 v109, 0xbfb8aa3b, v109
	v_fma_f32 v119, -v125, v126, 1.0
	v_fmac_f32_e32 v126, v119, v126
	v_div_scale_f32 v119, vcc, v114, v118, v114
	v_mul_f32_e32 v122, v119, v126
	v_fma_f32 v123, -v125, v122, v119
	v_exp_f32_e32 v108, v108
	v_exp_f32_e32 v109, v109
	v_fmac_f32_e32 v122, v123, v126
	v_fma_f32 v119, -v125, v122, v119
	v_div_fmas_f32 v119, v119, v126, v122
	v_div_fixup_f32 v114, v119, v118, v114
	v_pk_add_f32 v[108:109], v[108:109], 1.0 op_sel_hi:[1,0]
	v_cvt_pk_bf16_f32 v112, v112, v113
	v_cvt_pk_bf16_f32 v113, v114, v115
	v_div_scale_f32 v114, s[30:31], v109, v109, v105
	v_rcp_f32_e32 v115, v114
	v_mul_f32_e32 v110, 0xbfb8aa3b, v110
	v_mul_f32_e32 v111, 0xbfb8aa3b, v111
	v_exp_f32_e32 v110, v110
	v_fma_f32 v118, -v114, v115, 1.0
	v_fmac_f32_e32 v115, v118, v115
	v_div_scale_f32 v118, vcc, v105, v109, v105
	v_mul_f32_e32 v119, v118, v115
	v_fma_f32 v122, -v114, v119, v118
	v_fmac_f32_e32 v119, v122, v115
	v_fma_f32 v114, -v114, v119, v118
	v_div_scale_f32 v118, s[30:31], v108, v108, v104
	v_rcp_f32_e32 v122, v118
	v_div_fmas_f32 v114, v114, v115, v119
	v_exp_f32_e32 v111, v111
	v_div_fixup_f32 v105, v114, v109, v105
	v_fma_f32 v109, -v118, v122, 1.0
	v_fmac_f32_e32 v122, v109, v122
	v_div_scale_f32 v109, vcc, v104, v108, v104
	v_mul_f32_e32 v114, v109, v122
	v_fma_f32 v115, -v118, v114, v109
	v_pk_add_f32 v[110:111], v[110:111], 1.0 op_sel_hi:[1,0]
	v_fmac_f32_e32 v114, v115, v122
	v_div_scale_f32 v115, s[30:31], v111, v111, v107
	v_fma_f32 v109, -v118, v114, v109
	v_rcp_f32_e32 v118, v115
	v_div_fmas_f32 v109, v109, v122, v114
	v_div_fixup_f32 v104, v109, v108, v104
	v_mul_f32_e32 v100, 0xbfb8aa3b, v100
	v_fma_f32 v108, -v115, v118, 1.0
	v_fmac_f32_e32 v118, v108, v118
	v_div_scale_f32 v108, vcc, v107, v111, v107
	v_mul_f32_e32 v109, v108, v118
	v_fma_f32 v114, -v115, v109, v108
	v_fmac_f32_e32 v109, v114, v118
	v_div_scale_f32 v114, s[30:31], v110, v110, v106
	v_fma_f32 v108, -v115, v109, v108
	v_rcp_f32_e32 v115, v114
	v_div_fmas_f32 v108, v108, v118, v109
	v_div_fixup_f32 v107, v108, v111, v107
	v_mul_f32_e32 v101, 0xbfb8aa3b, v101
	v_fma_f32 v108, -v114, v115, 1.0
	v_fmac_f32_e32 v115, v108, v115
	v_div_scale_f32 v108, vcc, v106, v110, v106
	v_mul_f32_e32 v109, v108, v115
	v_exp_f32_e32 v100, v100
	v_exp_f32_e32 v101, v101
	v_fma_f32 v111, -v114, v109, v108
	v_fmac_f32_e32 v109, v111, v115
	v_fma_f32 v108, -v114, v109, v108
	v_div_fmas_f32 v108, v108, v115, v109
	v_pk_add_f32 v[100:101], v[100:101], 1.0 op_sel_hi:[1,0]
	global_store_dwordx2 v[116:117], v[112:113], off offset:128
	v_or_b32_e32 v112, 16, v124
	v_div_fixup_f32 v106, v108, v110, v106
	v_div_scale_f32 v108, s[30:31], v101, v101, v97
	v_ashrrev_i32_e32 v113, 31, v112
	v_rcp_f32_e32 v109, v108
	v_lshlrev_b64 v[112:113], 11, v[112:113]
	v_lshl_add_u64 v[112:113], s[46:47], 0, v[112:113]
	v_cvt_pk_bf16_f32 v104, v104, v105
	v_cvt_pk_bf16_f32 v105, v106, v107
	v_lshl_add_u64 v[106:107], v[112:113], 0, v[120:121]
	global_store_dwordx2 v[106:107], v[104:105], off
	v_fma_f32 v104, -v108, v109, 1.0
	v_fmac_f32_e32 v109, v104, v109
	v_div_scale_f32 v104, vcc, v97, v101, v97
	v_mul_f32_e32 v105, v104, v109
	v_fma_f32 v110, -v108, v105, v104
	v_fmac_f32_e32 v105, v110, v109
	v_fma_f32 v104, -v108, v105, v104
	v_div_scale_f32 v108, s[30:31], v100, v100, v96
	v_rcp_f32_e32 v110, v108
	v_mul_f32_e32 v102, 0xbfb8aa3b, v102
	v_mul_f32_e32 v103, 0xbfb8aa3b, v103
	v_div_fmas_f32 v104, v104, v109, v105
	v_exp_f32_e32 v102, v102
	v_exp_f32_e32 v103, v103
	v_div_fixup_f32 v97, v104, v101, v97
	v_fma_f32 v101, -v108, v110, 1.0
	v_fmac_f32_e32 v110, v101, v110
	v_div_scale_f32 v101, vcc, v96, v100, v96
	v_mul_f32_e32 v104, v101, v110
	v_fma_f32 v105, -v108, v104, v101
	v_pk_add_f32 v[102:103], v[102:103], 1.0 op_sel_hi:[1,0]
	v_fmac_f32_e32 v104, v105, v110
	v_div_scale_f32 v105, s[30:31], v103, v103, v99
	v_fma_f32 v101, -v108, v104, v101
	v_rcp_f32_e32 v108, v105
	v_div_fmas_f32 v101, v101, v110, v104
	v_div_fixup_f32 v96, v101, v100, v96
	v_mul_f32_e32 v92, 0xbfb8aa3b, v92
	v_fma_f32 v100, -v105, v108, 1.0
	v_fmac_f32_e32 v108, v100, v108
	v_div_scale_f32 v100, vcc, v99, v103, v99
	v_mul_f32_e32 v101, v100, v108
	v_fma_f32 v104, -v105, v101, v100
	v_fmac_f32_e32 v101, v104, v108
	v_div_scale_f32 v104, s[30:31], v102, v102, v98
	v_fma_f32 v100, -v105, v101, v100
	v_rcp_f32_e32 v105, v104
	v_div_fmas_f32 v100, v100, v108, v101
	v_div_fixup_f32 v99, v100, v103, v99
	v_mul_f32_e32 v93, 0xbfb8aa3b, v93
	v_fma_f32 v100, -v104, v105, 1.0
	v_fmac_f32_e32 v105, v100, v105
	v_div_scale_f32 v100, vcc, v98, v102, v98
	v_mul_f32_e32 v101, v100, v105
	v_fma_f32 v103, -v104, v101, v100
	v_exp_f32_e32 v92, v92
	v_exp_f32_e32 v93, v93
	v_fmac_f32_e32 v101, v103, v105
	v_fma_f32 v100, -v104, v101, v100
	v_div_fmas_f32 v100, v100, v105, v101
	v_div_fixup_f32 v98, v100, v102, v98
	v_pk_add_f32 v[92:93], v[92:93], 1.0 op_sel_hi:[1,0]
	v_cvt_pk_bf16_f32 v96, v96, v97
	v_cvt_pk_bf16_f32 v97, v98, v99
	v_div_scale_f32 v98, s[30:31], v93, v93, v89
	v_rcp_f32_e32 v99, v98
	v_mul_f32_e32 v94, 0xbfb8aa3b, v94
	v_mul_f32_e32 v95, 0xbfb8aa3b, v95
	v_exp_f32_e32 v94, v94
	v_fma_f32 v100, -v98, v99, 1.0
	v_fmac_f32_e32 v99, v100, v99
	v_div_scale_f32 v100, vcc, v89, v93, v89
	v_mul_f32_e32 v101, v100, v99
	v_fma_f32 v102, -v98, v101, v100
	v_fmac_f32_e32 v101, v102, v99
	v_fma_f32 v98, -v98, v101, v100
	v_div_scale_f32 v100, s[30:31], v92, v92, v88
	v_rcp_f32_e32 v102, v100
	v_div_fmas_f32 v98, v98, v99, v101
	v_exp_f32_e32 v95, v95
	v_div_fixup_f32 v89, v98, v93, v89
	v_fma_f32 v93, -v100, v102, 1.0
	v_fmac_f32_e32 v102, v93, v102
	v_div_scale_f32 v93, vcc, v88, v92, v88
	v_mul_f32_e32 v98, v93, v102
	v_fma_f32 v99, -v100, v98, v93
	v_pk_add_f32 v[94:95], v[94:95], 1.0 op_sel_hi:[1,0]
	v_fmac_f32_e32 v98, v99, v102
	v_div_scale_f32 v99, s[30:31], v95, v95, v91
	v_fma_f32 v93, -v100, v98, v93
	v_rcp_f32_e32 v100, v99
	v_div_fmas_f32 v93, v93, v102, v98
	v_div_fixup_f32 v88, v93, v92, v88
	v_mul_f32_e32 v84, 0xbfb8aa3b, v84
	v_fma_f32 v92, -v99, v100, 1.0
	v_fmac_f32_e32 v100, v92, v100
	v_div_scale_f32 v92, vcc, v91, v95, v91
	v_mul_f32_e32 v93, v92, v100
	v_fma_f32 v98, -v99, v93, v92
	v_fmac_f32_e32 v93, v98, v100
	v_div_scale_f32 v98, s[30:31], v94, v94, v90
	v_fma_f32 v92, -v99, v93, v92
	v_rcp_f32_e32 v99, v98
	v_div_fmas_f32 v92, v92, v100, v93
	v_div_fixup_f32 v91, v92, v95, v91
	v_mul_f32_e32 v85, 0xbfb8aa3b, v85
	v_fma_f32 v92, -v98, v99, 1.0
	v_fmac_f32_e32 v99, v92, v99
	v_div_scale_f32 v92, vcc, v90, v94, v90
	v_mul_f32_e32 v93, v92, v99
	v_exp_f32_e32 v84, v84
	v_exp_f32_e32 v85, v85
	v_fma_f32 v95, -v98, v93, v92
	v_fmac_f32_e32 v93, v95, v99
	v_fma_f32 v92, -v98, v93, v92
	v_div_fmas_f32 v92, v92, v99, v93
	v_pk_add_f32 v[84:85], v[84:85], 1.0 op_sel_hi:[1,0]
	global_store_dwordx2 v[106:107], v[96:97], off offset:128
	v_or_b32_e32 v96, 32, v124
	v_div_fixup_f32 v90, v92, v94, v90
	v_div_scale_f32 v92, s[30:31], v85, v85, v81
	v_ashrrev_i32_e32 v97, 31, v96
	v_rcp_f32_e32 v93, v92
	v_lshlrev_b64 v[96:97], 11, v[96:97]
	v_lshl_add_u64 v[96:97], s[46:47], 0, v[96:97]
	v_cvt_pk_bf16_f32 v88, v88, v89
	v_cvt_pk_bf16_f32 v89, v90, v91
	v_lshl_add_u64 v[90:91], v[96:97], 0, v[120:121]
	global_store_dwordx2 v[90:91], v[88:89], off
	v_fma_f32 v88, -v92, v93, 1.0
	v_fmac_f32_e32 v93, v88, v93
	v_div_scale_f32 v88, vcc, v81, v85, v81
	v_mul_f32_e32 v89, v88, v93
	v_fma_f32 v94, -v92, v89, v88
	v_fmac_f32_e32 v89, v94, v93
	v_fma_f32 v88, -v92, v89, v88
	v_div_scale_f32 v92, s[30:31], v84, v84, v80
	v_rcp_f32_e32 v94, v92
	v_mul_f32_e32 v86, 0xbfb8aa3b, v86
	v_mul_f32_e32 v87, 0xbfb8aa3b, v87
	v_div_fmas_f32 v88, v88, v93, v89
	v_exp_f32_e32 v86, v86
	v_exp_f32_e32 v87, v87
	v_div_fixup_f32 v81, v88, v85, v81
	v_fma_f32 v85, -v92, v94, 1.0
	v_fmac_f32_e32 v94, v85, v94
	v_div_scale_f32 v85, vcc, v80, v84, v80
	v_mul_f32_e32 v88, v85, v94
	v_fma_f32 v89, -v92, v88, v85
	v_pk_add_f32 v[86:87], v[86:87], 1.0 op_sel_hi:[1,0]
	v_fmac_f32_e32 v88, v89, v94
	v_div_scale_f32 v89, s[30:31], v87, v87, v83
	v_fma_f32 v85, -v92, v88, v85
	v_rcp_f32_e32 v92, v89
	v_div_fmas_f32 v85, v85, v94, v88
	v_div_fixup_f32 v80, v85, v84, v80
	v_mul_f32_e32 v76, 0xbfb8aa3b, v76
	v_fma_f32 v84, -v89, v92, 1.0
	v_fmac_f32_e32 v92, v84, v92
	v_div_scale_f32 v84, vcc, v83, v87, v83
	v_mul_f32_e32 v85, v84, v92
	v_fma_f32 v88, -v89, v85, v84
	v_fmac_f32_e32 v85, v88, v92
	v_div_scale_f32 v88, s[30:31], v86, v86, v82
	v_fma_f32 v84, -v89, v85, v84
	v_rcp_f32_e32 v89, v88
	v_div_fmas_f32 v84, v84, v92, v85
	v_div_fixup_f32 v83, v84, v87, v83
	v_mul_f32_e32 v77, 0xbfb8aa3b, v77
	v_fma_f32 v84, -v88, v89, 1.0
	v_fmac_f32_e32 v89, v84, v89
	v_div_scale_f32 v84, vcc, v82, v86, v82
	v_mul_f32_e32 v85, v84, v89
	v_fma_f32 v87, -v88, v85, v84
	v_exp_f32_e32 v76, v76
	v_exp_f32_e32 v77, v77
	v_fmac_f32_e32 v85, v87, v89
	v_fma_f32 v84, -v88, v85, v84
	v_div_fmas_f32 v84, v84, v89, v85
	v_div_fixup_f32 v82, v84, v86, v82
	v_pk_add_f32 v[76:77], v[76:77], 1.0 op_sel_hi:[1,0]
	v_cvt_pk_bf16_f32 v80, v80, v81
	v_cvt_pk_bf16_f32 v81, v82, v83
	v_div_scale_f32 v82, s[30:31], v77, v77, v73
	v_rcp_f32_e32 v83, v82
	v_mul_f32_e32 v78, 0xbfb8aa3b, v78
	v_mul_f32_e32 v79, 0xbfb8aa3b, v79
	v_exp_f32_e32 v78, v78
	v_fma_f32 v84, -v82, v83, 1.0
	v_fmac_f32_e32 v83, v84, v83
	v_div_scale_f32 v84, vcc, v73, v77, v73
	v_mul_f32_e32 v85, v84, v83
	v_fma_f32 v86, -v82, v85, v84
	v_fmac_f32_e32 v85, v86, v83
	v_fma_f32 v82, -v82, v85, v84
	v_div_scale_f32 v84, s[30:31], v76, v76, v72
	v_rcp_f32_e32 v86, v84
	v_div_fmas_f32 v82, v82, v83, v85
	v_exp_f32_e32 v79, v79
	v_div_fixup_f32 v73, v82, v77, v73
	v_fma_f32 v77, -v84, v86, 1.0
	v_fmac_f32_e32 v86, v77, v86
	v_div_scale_f32 v77, vcc, v72, v76, v72
	v_mul_f32_e32 v82, v77, v86
	v_fma_f32 v83, -v84, v82, v77
	v_pk_add_f32 v[78:79], v[78:79], 1.0 op_sel_hi:[1,0]
	v_fmac_f32_e32 v82, v83, v86
	v_div_scale_f32 v83, s[30:31], v79, v79, v75
	v_fma_f32 v77, -v84, v82, v77
	v_rcp_f32_e32 v84, v83
	v_div_fmas_f32 v77, v77, v86, v82
	v_div_fixup_f32 v72, v77, v76, v72
	v_mul_f32_e32 v68, 0xbfb8aa3b, v68
	v_fma_f32 v76, -v83, v84, 1.0
	v_fmac_f32_e32 v84, v76, v84
	v_div_scale_f32 v76, vcc, v75, v79, v75
	v_mul_f32_e32 v77, v76, v84
	v_fma_f32 v82, -v83, v77, v76
	v_fmac_f32_e32 v77, v82, v84
	v_div_scale_f32 v82, s[30:31], v78, v78, v74
	v_fma_f32 v76, -v83, v77, v76
	v_rcp_f32_e32 v83, v82
	v_div_fmas_f32 v76, v76, v84, v77
	v_div_fixup_f32 v75, v76, v79, v75
	v_mul_f32_e32 v69, 0xbfb8aa3b, v69
	v_fma_f32 v76, -v82, v83, 1.0
	v_fmac_f32_e32 v83, v76, v83
	v_div_scale_f32 v76, vcc, v74, v78, v74
	v_mul_f32_e32 v77, v76, v83
	v_exp_f32_e32 v68, v68
	v_exp_f32_e32 v69, v69
	v_fma_f32 v79, -v82, v77, v76
	v_fmac_f32_e32 v77, v79, v83
	v_fma_f32 v76, -v82, v77, v76
	v_div_fmas_f32 v76, v76, v83, v77
	v_pk_add_f32 v[68:69], v[68:69], 1.0 op_sel_hi:[1,0]
	global_store_dwordx2 v[90:91], v[80:81], off offset:128
	v_or_b32_e32 v80, 48, v124
	v_div_fixup_f32 v74, v76, v78, v74
	v_div_scale_f32 v76, s[30:31], v69, v69, v65
	v_ashrrev_i32_e32 v81, 31, v80
	v_rcp_f32_e32 v77, v76
	v_lshlrev_b64 v[80:81], 11, v[80:81]
	v_lshl_add_u64 v[80:81], s[46:47], 0, v[80:81]
	v_cvt_pk_bf16_f32 v72, v72, v73
	v_cvt_pk_bf16_f32 v73, v74, v75
	v_lshl_add_u64 v[74:75], v[80:81], 0, v[120:121]
	global_store_dwordx2 v[74:75], v[72:73], off
	v_fma_f32 v72, -v76, v77, 1.0
	v_fmac_f32_e32 v77, v72, v77
	v_div_scale_f32 v72, vcc, v65, v69, v65
	v_mul_f32_e32 v73, v72, v77
	v_fma_f32 v78, -v76, v73, v72
	v_fmac_f32_e32 v73, v78, v77
	v_fma_f32 v72, -v76, v73, v72
	v_div_scale_f32 v76, s[30:31], v68, v68, v64
	v_rcp_f32_e32 v78, v76
	v_mul_f32_e32 v70, 0xbfb8aa3b, v70
	v_mul_f32_e32 v71, 0xbfb8aa3b, v71
	v_div_fmas_f32 v72, v72, v77, v73
	v_exp_f32_e32 v70, v70
	v_exp_f32_e32 v71, v71
	v_div_fixup_f32 v65, v72, v69, v65
	v_fma_f32 v69, -v76, v78, 1.0
	v_fmac_f32_e32 v78, v69, v78
	v_div_scale_f32 v69, vcc, v64, v68, v64
	v_mul_f32_e32 v72, v69, v78
	v_fma_f32 v73, -v76, v72, v69
	v_pk_add_f32 v[70:71], v[70:71], 1.0 op_sel_hi:[1,0]
	v_fmac_f32_e32 v72, v73, v78
	v_div_scale_f32 v73, s[30:31], v71, v71, v67
	v_fma_f32 v69, -v76, v72, v69
	v_rcp_f32_e32 v76, v73
	v_div_fmas_f32 v69, v69, v78, v72
	v_div_fixup_f32 v64, v69, v68, v64
	v_mul_f32_e32 v60, 0xbfb8aa3b, v60
	v_fma_f32 v68, -v73, v76, 1.0
	v_fmac_f32_e32 v76, v68, v76
	v_div_scale_f32 v68, vcc, v67, v71, v67
	v_mul_f32_e32 v69, v68, v76
	v_fma_f32 v72, -v73, v69, v68
	v_fmac_f32_e32 v69, v72, v76
	v_div_scale_f32 v72, s[30:31], v70, v70, v66
	v_fma_f32 v68, -v73, v69, v68
	v_rcp_f32_e32 v73, v72
	v_div_fmas_f32 v68, v68, v76, v69
	v_div_fixup_f32 v67, v68, v71, v67
	v_mul_f32_e32 v61, 0xbfb8aa3b, v61
	v_fma_f32 v68, -v72, v73, 1.0
	v_fmac_f32_e32 v73, v68, v73
	v_div_scale_f32 v68, vcc, v66, v70, v66
	v_mul_f32_e32 v69, v68, v73
	v_exp_f32_e32 v60, v60
	v_exp_f32_e32 v61, v61
	v_fma_f32 v71, -v72, v69, v68
	v_fmac_f32_e32 v69, v71, v73
	v_fma_f32 v68, -v72, v69, v68
	v_div_fmas_f32 v68, v68, v73, v69
	v_pk_add_f32 v[60:61], v[60:61], 1.0 op_sel_hi:[1,0]
	v_div_fixup_f32 v66, v68, v70, v66
	v_div_scale_f32 v68, s[30:31], v61, v61, v57
	v_rcp_f32_e32 v69, v68
	v_cvt_pk_bf16_f32 v64, v64, v65
	v_cvt_pk_bf16_f32 v65, v66, v67
	global_store_dwordx2 v[74:75], v[64:65], off offset:128
	v_fma_f32 v64, -v68, v69, 1.0
	v_fmac_f32_e32 v69, v64, v69
	v_div_scale_f32 v64, vcc, v57, v61, v57
	v_mul_f32_e32 v65, v64, v69
	v_fma_f32 v66, -v68, v65, v64
	v_fmac_f32_e32 v65, v66, v69
	v_div_scale_f32 v66, s[30:31], v60, v60, v56
	v_rcp_f32_e32 v67, v66
	v_fma_f32 v64, -v68, v65, v64
	v_mul_f32_e32 v62, 0xbfb8aa3b, v62
	v_mul_f32_e32 v63, 0xbfb8aa3b, v63
	v_div_fmas_f32 v64, v64, v69, v65
	v_exp_f32_e32 v62, v62
	v_exp_f32_e32 v63, v63
	v_div_fixup_f32 v57, v64, v61, v57
	v_fma_f32 v61, -v66, v67, 1.0
	v_fmac_f32_e32 v67, v61, v67
	v_div_scale_f32 v61, vcc, v56, v60, v56
	v_mul_f32_e32 v64, v61, v67
	v_fma_f32 v65, -v66, v64, v61
	v_pk_add_f32 v[62:63], v[62:63], 1.0 op_sel_hi:[1,0]
	v_fmac_f32_e32 v64, v65, v67
	v_div_scale_f32 v65, s[30:31], v63, v63, v59
	v_fma_f32 v61, -v66, v64, v61
	v_rcp_f32_e32 v66, v65
	v_div_fmas_f32 v61, v61, v67, v64
	v_div_fixup_f32 v56, v61, v60, v56
	v_mul_f32_e32 v52, 0xbfb8aa3b, v52
	v_fma_f32 v60, -v65, v66, 1.0
	v_fmac_f32_e32 v66, v60, v66
	v_div_scale_f32 v60, vcc, v59, v63, v59
	v_mul_f32_e32 v61, v60, v66
	v_fma_f32 v64, -v65, v61, v60
	v_fmac_f32_e32 v61, v64, v66
	v_div_scale_f32 v64, s[30:31], v62, v62, v58
	v_fma_f32 v60, -v65, v61, v60
	v_rcp_f32_e32 v65, v64
	v_div_fmas_f32 v60, v60, v66, v61
	v_div_fixup_f32 v59, v60, v63, v59
	v_mul_f32_e32 v53, 0xbfb8aa3b, v53
	v_fma_f32 v60, -v64, v65, 1.0
	v_fmac_f32_e32 v65, v60, v65
	v_div_scale_f32 v60, vcc, v58, v62, v58
	v_mul_f32_e32 v61, v60, v65
	v_exp_f32_e32 v52, v52
	v_exp_f32_e32 v53, v53
	v_fma_f32 v63, -v64, v61, v60
	v_fmac_f32_e32 v61, v63, v65
	v_fma_f32 v60, -v64, v61, v60
	v_div_fmas_f32 v60, v60, v65, v61
	v_pk_add_f32 v[52:53], v[52:53], 1.0 op_sel_hi:[1,0]
	v_div_fixup_f32 v58, v60, v62, v58
	v_div_scale_f32 v62, s[30:31], v53, v53, v49
	v_rcp_f32_e32 v63, v62
	v_add_co_u32_e32 v60, vcc, s62, v116
	v_cvt_pk_bf16_f32 v56, v56, v57
	v_cvt_pk_bf16_f32 v57, v58, v59
	v_addc_co_u32_e32 v61, vcc, 0, v117, vcc
	global_store_dwordx2 v[60:61], v[56:57], off
	v_fma_f32 v56, -v62, v63, 1.0
	v_fmac_f32_e32 v63, v56, v63
	v_div_scale_f32 v56, vcc, v49, v53, v49
	v_mul_f32_e32 v57, v56, v63
	v_fma_f32 v60, -v62, v57, v56
	v_fmac_f32_e32 v57, v60, v63
	v_div_scale_f32 v60, s[30:31], v52, v52, v48
	v_rcp_f32_e32 v61, v60
	v_fma_f32 v56, -v62, v57, v56
	v_mul_f32_e32 v54, 0xbfb8aa3b, v54
	v_mul_f32_e32 v55, 0xbfb8aa3b, v55
	v_div_fmas_f32 v56, v56, v63, v57
	v_exp_f32_e32 v54, v54
	v_exp_f32_e32 v55, v55
	v_div_fixup_f32 v49, v56, v53, v49
	v_fma_f32 v53, -v60, v61, 1.0
	v_fmac_f32_e32 v61, v53, v61
	v_div_scale_f32 v53, vcc, v48, v52, v48
	v_mul_f32_e32 v56, v53, v61
	v_fma_f32 v57, -v60, v56, v53
	v_pk_add_f32 v[54:55], v[54:55], 1.0 op_sel_hi:[1,0]
	v_fmac_f32_e32 v56, v57, v61
	v_div_scale_f32 v57, s[30:31], v55, v55, v51
	v_fma_f32 v53, -v60, v56, v53
	v_rcp_f32_e32 v60, v57
	v_div_fmas_f32 v53, v53, v61, v56
	v_div_fixup_f32 v48, v53, v52, v48
	v_mul_f32_e32 v44, 0xbfb8aa3b, v44
	v_fma_f32 v52, -v57, v60, 1.0
	v_fmac_f32_e32 v60, v52, v60
	v_div_scale_f32 v52, vcc, v51, v55, v51
	v_mul_f32_e32 v53, v52, v60
	v_fma_f32 v56, -v57, v53, v52
	v_fmac_f32_e32 v53, v56, v60
	v_div_scale_f32 v56, s[30:31], v54, v54, v50
	v_fma_f32 v52, -v57, v53, v52
	v_rcp_f32_e32 v57, v56
	v_div_fmas_f32 v52, v52, v60, v53
	v_div_fixup_f32 v51, v52, v55, v51
	v_mul_f32_e32 v45, 0xbfb8aa3b, v45
	v_fma_f32 v52, -v56, v57, 1.0
	v_fmac_f32_e32 v57, v52, v57
	v_div_scale_f32 v52, vcc, v50, v54, v50
	v_mul_f32_e32 v53, v52, v57
	v_exp_f32_e32 v44, v44
	v_exp_f32_e32 v45, v45
	v_fma_f32 v55, -v56, v53, v52
	v_fmac_f32_e32 v53, v55, v57
	v_fma_f32 v52, -v56, v53, v52
	v_div_fmas_f32 v52, v52, v57, v53
	v_pk_add_f32 v[44:45], v[44:45], 1.0 op_sel_hi:[1,0]
	v_div_fixup_f32 v50, v52, v54, v50
	v_div_scale_f32 v52, s[30:31], v45, v45, v41
	v_rcp_f32_e32 v53, v52
	v_lshl_add_u64 v[58:59], v[116:117], 0, s[6:7]
	v_cvt_pk_bf16_f32 v48, v48, v49
	v_cvt_pk_bf16_f32 v49, v50, v51
	global_store_dwordx2 v[58:59], v[48:49], off offset:128
	v_fma_f32 v48, -v52, v53, 1.0
	v_fmac_f32_e32 v53, v48, v53
	v_div_scale_f32 v48, vcc, v41, v45, v41
	v_mul_f32_e32 v49, v48, v53
	v_fma_f32 v50, -v52, v49, v48
	v_fmac_f32_e32 v49, v50, v53
	v_div_scale_f32 v50, s[30:31], v44, v44, v40
	v_rcp_f32_e32 v51, v50
	v_fma_f32 v48, -v52, v49, v48
	v_mul_f32_e32 v46, 0xbfb8aa3b, v46
	v_mul_f32_e32 v47, 0xbfb8aa3b, v47
	v_div_fmas_f32 v48, v48, v53, v49
	v_exp_f32_e32 v46, v46
	v_exp_f32_e32 v47, v47
	v_div_fixup_f32 v41, v48, v45, v41
	v_fma_f32 v45, -v50, v51, 1.0
	v_fmac_f32_e32 v51, v45, v51
	v_div_scale_f32 v45, vcc, v40, v44, v40
	v_mul_f32_e32 v48, v45, v51
	v_fma_f32 v49, -v50, v48, v45
	v_pk_add_f32 v[46:47], v[46:47], 1.0 op_sel_hi:[1,0]
	v_fmac_f32_e32 v48, v49, v51
	v_div_scale_f32 v49, s[30:31], v47, v47, v43
	v_fma_f32 v45, -v50, v48, v45
	v_rcp_f32_e32 v50, v49
	v_div_fmas_f32 v45, v45, v51, v48
	v_div_fixup_f32 v40, v45, v44, v40
	v_mul_f32_e32 v36, 0xbfb8aa3b, v36
	v_fma_f32 v44, -v49, v50, 1.0
	v_fmac_f32_e32 v50, v44, v50
	v_div_scale_f32 v44, vcc, v43, v47, v43
	v_mul_f32_e32 v45, v44, v50
	v_fma_f32 v48, -v49, v45, v44
	v_fmac_f32_e32 v45, v48, v50
	v_div_scale_f32 v48, s[30:31], v46, v46, v42
	v_fma_f32 v44, -v49, v45, v44
	v_rcp_f32_e32 v49, v48
	v_div_fmas_f32 v44, v44, v50, v45
	v_div_fixup_f32 v43, v44, v47, v43
	v_mul_f32_e32 v37, 0xbfb8aa3b, v37
	v_fma_f32 v44, -v48, v49, 1.0
	v_fmac_f32_e32 v49, v44, v49
	v_div_scale_f32 v44, vcc, v42, v46, v42
	v_mul_f32_e32 v45, v44, v49
	v_exp_f32_e32 v36, v36
	v_exp_f32_e32 v37, v37
	v_fma_f32 v47, -v48, v45, v44
	v_fmac_f32_e32 v45, v47, v49
	v_fma_f32 v44, -v48, v45, v44
	v_div_fmas_f32 v44, v44, v49, v45
	v_pk_add_f32 v[36:37], v[36:37], 1.0 op_sel_hi:[1,0]
	v_div_fixup_f32 v42, v44, v46, v42
	v_div_scale_f32 v46, s[30:31], v37, v37, v33
	v_rcp_f32_e32 v47, v46
	v_add_co_u32_e32 v44, vcc, s63, v116
	v_cvt_pk_bf16_f32 v40, v40, v41
	v_cvt_pk_bf16_f32 v41, v42, v43
	v_addc_co_u32_e32 v45, vcc, 0, v117, vcc
	global_store_dwordx2 v[44:45], v[40:41], off
	v_fma_f32 v40, -v46, v47, 1.0
	v_fmac_f32_e32 v47, v40, v47
	v_div_scale_f32 v40, vcc, v33, v37, v33
	v_mul_f32_e32 v41, v40, v47
	v_fma_f32 v44, -v46, v41, v40
	v_fmac_f32_e32 v41, v44, v47
	v_div_scale_f32 v44, s[30:31], v36, v36, v32
	v_rcp_f32_e32 v45, v44
	v_fma_f32 v40, -v46, v41, v40
	v_mul_f32_e32 v38, 0xbfb8aa3b, v38
	v_mul_f32_e32 v39, 0xbfb8aa3b, v39
	v_div_fmas_f32 v40, v40, v47, v41
	v_exp_f32_e32 v38, v38
	v_exp_f32_e32 v39, v39
	v_div_fixup_f32 v33, v40, v37, v33
	v_fma_f32 v37, -v44, v45, 1.0
	v_fmac_f32_e32 v45, v37, v45
	v_div_scale_f32 v37, vcc, v32, v36, v32
	v_mul_f32_e32 v40, v37, v45
	v_fma_f32 v41, -v44, v40, v37
	v_pk_add_f32 v[38:39], v[38:39], 1.0 op_sel_hi:[1,0]
	v_fmac_f32_e32 v40, v41, v45
	v_div_scale_f32 v41, s[30:31], v39, v39, v35
	v_fma_f32 v37, -v44, v40, v37
	v_rcp_f32_e32 v44, v41
	v_div_fmas_f32 v37, v37, v45, v40
	v_div_fixup_f32 v32, v37, v36, v32
	v_mul_f32_e32 v28, 0xbfb8aa3b, v28
	v_fma_f32 v36, -v41, v44, 1.0
	v_fmac_f32_e32 v44, v36, v44
	v_div_scale_f32 v36, vcc, v35, v39, v35
	v_mul_f32_e32 v37, v36, v44
	v_fma_f32 v40, -v41, v37, v36
	v_fmac_f32_e32 v37, v40, v44
	v_div_scale_f32 v40, s[30:31], v38, v38, v34
	v_fma_f32 v36, -v41, v37, v36
	v_rcp_f32_e32 v41, v40
	v_div_fmas_f32 v36, v36, v44, v37
	v_div_fixup_f32 v35, v36, v39, v35
	v_mul_f32_e32 v29, 0xbfb8aa3b, v29
	v_fma_f32 v36, -v40, v41, 1.0
	v_fmac_f32_e32 v41, v36, v41
	v_div_scale_f32 v36, vcc, v34, v38, v34
	v_mul_f32_e32 v37, v36, v41
	v_exp_f32_e32 v28, v28
	v_exp_f32_e32 v29, v29
	v_fma_f32 v39, -v40, v37, v36
	v_fmac_f32_e32 v37, v39, v41
	v_fma_f32 v36, -v40, v37, v36
	v_div_fmas_f32 v36, v36, v41, v37
	v_pk_add_f32 v[28:29], v[28:29], 1.0 op_sel_hi:[1,0]
	v_div_fixup_f32 v34, v36, v38, v34
	v_div_scale_f32 v36, s[30:31], v29, v29, v25
	v_rcp_f32_e32 v37, v36
	v_lshl_add_u64 v[42:43], v[116:117], 0, s[10:11]
	v_cvt_pk_bf16_f32 v32, v32, v33
	v_cvt_pk_bf16_f32 v33, v34, v35
	global_store_dwordx2 v[42:43], v[32:33], off offset:128
	v_fma_f32 v32, -v36, v37, 1.0
	v_fmac_f32_e32 v37, v32, v37
	v_div_scale_f32 v32, vcc, v25, v29, v25
	v_mul_f32_e32 v33, v32, v37
	v_fma_f32 v34, -v36, v33, v32
	v_fmac_f32_e32 v33, v34, v37
	v_div_scale_f32 v34, s[30:31], v28, v28, v24
	v_rcp_f32_e32 v35, v34
	v_fma_f32 v32, -v36, v33, v32
	v_mul_f32_e32 v30, 0xbfb8aa3b, v30
	v_mul_f32_e32 v31, 0xbfb8aa3b, v31
	v_div_fmas_f32 v32, v32, v37, v33
	v_exp_f32_e32 v30, v30
	v_exp_f32_e32 v31, v31
	v_div_fixup_f32 v25, v32, v29, v25
	v_fma_f32 v29, -v34, v35, 1.0
	v_fmac_f32_e32 v35, v29, v35
	v_div_scale_f32 v29, vcc, v24, v28, v24
	v_mul_f32_e32 v32, v29, v35
	v_fma_f32 v33, -v34, v32, v29
	v_pk_add_f32 v[30:31], v[30:31], 1.0 op_sel_hi:[1,0]
	v_fmac_f32_e32 v32, v33, v35
	v_div_scale_f32 v33, s[30:31], v31, v31, v27
	v_fma_f32 v29, -v34, v32, v29
	v_rcp_f32_e32 v34, v33
	v_div_fmas_f32 v29, v29, v35, v32
	v_div_fixup_f32 v24, v29, v28, v24
	v_mul_f32_e32 v20, 0xbfb8aa3b, v20
	v_fma_f32 v28, -v33, v34, 1.0
	v_fmac_f32_e32 v34, v28, v34
	v_div_scale_f32 v28, vcc, v27, v31, v27
	v_mul_f32_e32 v29, v28, v34
	v_fma_f32 v32, -v33, v29, v28
	v_fmac_f32_e32 v29, v32, v34
	v_div_scale_f32 v32, s[30:31], v30, v30, v26
	v_fma_f32 v28, -v33, v29, v28
	v_rcp_f32_e32 v33, v32
	v_div_fmas_f32 v28, v28, v34, v29
	v_div_fixup_f32 v27, v28, v31, v27
	v_mul_f32_e32 v21, 0xbfb8aa3b, v21
	v_fma_f32 v28, -v32, v33, 1.0
	v_fmac_f32_e32 v33, v28, v33
	v_div_scale_f32 v28, vcc, v26, v30, v26
	v_mul_f32_e32 v29, v28, v33
	v_exp_f32_e32 v20, v20
	v_exp_f32_e32 v21, v21
	v_fma_f32 v31, -v32, v29, v28
	v_fmac_f32_e32 v29, v31, v33
	v_fma_f32 v28, -v32, v29, v28
	v_div_fmas_f32 v28, v28, v33, v29
	v_pk_add_f32 v[20:21], v[20:21], 1.0 op_sel_hi:[1,0]
	v_div_fixup_f32 v26, v28, v30, v26
	v_div_scale_f32 v30, s[30:31], v21, v21, v17
	v_rcp_f32_e32 v31, v30
	v_add_co_u32_e32 v28, vcc, s70, v116
	v_cvt_pk_bf16_f32 v24, v24, v25
	v_cvt_pk_bf16_f32 v25, v26, v27
	v_addc_co_u32_e32 v29, vcc, 0, v117, vcc
	global_store_dwordx2 v[28:29], v[24:25], off
	v_fma_f32 v24, -v30, v31, 1.0
	v_fmac_f32_e32 v31, v24, v31
	v_div_scale_f32 v24, vcc, v17, v21, v17
	v_mul_f32_e32 v25, v24, v31
	v_fma_f32 v28, -v30, v25, v24
	v_fmac_f32_e32 v25, v28, v31
	v_div_scale_f32 v28, s[30:31], v20, v20, v16
	v_rcp_f32_e32 v29, v28
	v_fma_f32 v24, -v30, v25, v24
	v_mul_f32_e32 v22, 0xbfb8aa3b, v22
	v_mul_f32_e32 v23, 0xbfb8aa3b, v23
	v_div_fmas_f32 v24, v24, v31, v25
	v_exp_f32_e32 v22, v22
	v_exp_f32_e32 v23, v23
	v_div_fixup_f32 v17, v24, v21, v17
	v_fma_f32 v21, -v28, v29, 1.0
	v_fmac_f32_e32 v29, v21, v29
	v_div_scale_f32 v21, vcc, v16, v20, v16
	v_mul_f32_e32 v24, v21, v29
	v_fma_f32 v25, -v28, v24, v21
	v_pk_add_f32 v[22:23], v[22:23], 1.0 op_sel_hi:[1,0]
	v_fmac_f32_e32 v24, v25, v29
	v_div_scale_f32 v25, s[30:31], v23, v23, v19
	v_fma_f32 v21, -v28, v24, v21
	v_rcp_f32_e32 v28, v25
	v_div_fmas_f32 v21, v21, v29, v24
	v_div_fixup_f32 v16, v21, v20, v16
	v_mul_f32_e32 v12, 0xbfb8aa3b, v12
	v_fma_f32 v20, -v25, v28, 1.0
	v_fmac_f32_e32 v28, v20, v28
	v_div_scale_f32 v20, vcc, v19, v23, v19
	v_mul_f32_e32 v21, v20, v28
	v_fma_f32 v24, -v25, v21, v20
	v_fmac_f32_e32 v21, v24, v28
	v_div_scale_f32 v24, s[30:31], v22, v22, v18
	v_fma_f32 v20, -v25, v21, v20
	v_rcp_f32_e32 v25, v24
	v_div_fmas_f32 v20, v20, v28, v21
	v_div_fixup_f32 v19, v20, v23, v19
	v_mul_f32_e32 v13, 0xbfb8aa3b, v13
	v_fma_f32 v20, -v24, v25, 1.0
	v_fmac_f32_e32 v25, v20, v25
	v_div_scale_f32 v20, vcc, v18, v22, v18
	v_mul_f32_e32 v21, v20, v25
	v_exp_f32_e32 v12, v12
	v_exp_f32_e32 v13, v13
	v_fma_f32 v23, -v24, v21, v20
	v_fmac_f32_e32 v21, v23, v25
	v_fma_f32 v20, -v24, v21, v20
	v_div_fmas_f32 v20, v20, v25, v21
	v_pk_add_f32 v[12:13], v[12:13], 1.0 op_sel_hi:[1,0]
	v_div_fixup_f32 v18, v20, v22, v18
	v_div_scale_f32 v20, s[30:31], v13, v13, v9
	v_rcp_f32_e32 v21, v20
	v_lshl_add_u64 v[26:27], v[116:117], 0, s[12:13]
	v_cvt_pk_bf16_f32 v16, v16, v17
	v_cvt_pk_bf16_f32 v17, v18, v19
	global_store_dwordx2 v[26:27], v[16:17], off offset:128
	v_fma_f32 v16, -v20, v21, 1.0
	v_fmac_f32_e32 v21, v16, v21
	v_div_scale_f32 v16, vcc, v9, v13, v9
	v_mul_f32_e32 v17, v16, v21
	v_fma_f32 v18, -v20, v17, v16
	v_fmac_f32_e32 v17, v18, v21
	v_div_scale_f32 v18, s[30:31], v12, v12, v8
	v_rcp_f32_e32 v19, v18
	v_fma_f32 v16, -v20, v17, v16
	v_mul_f32_e32 v14, 0xbfb8aa3b, v14
	v_mul_f32_e32 v15, 0xbfb8aa3b, v15
	v_div_fmas_f32 v16, v16, v21, v17
	v_exp_f32_e32 v14, v14
	v_exp_f32_e32 v15, v15
	v_div_fixup_f32 v9, v16, v13, v9
	v_fma_f32 v13, -v18, v19, 1.0
	v_fmac_f32_e32 v19, v13, v19
	v_div_scale_f32 v13, vcc, v8, v12, v8
	v_mul_f32_e32 v16, v13, v19
	v_fma_f32 v17, -v18, v16, v13
	v_pk_add_f32 v[14:15], v[14:15], 1.0 op_sel_hi:[1,0]
	v_fmac_f32_e32 v16, v17, v19
	v_div_scale_f32 v17, s[30:31], v15, v15, v11
	v_fma_f32 v13, -v18, v16, v13
	v_rcp_f32_e32 v18, v17
	v_div_fmas_f32 v13, v13, v19, v16
	v_div_fixup_f32 v8, v13, v12, v8
	v_mul_f32_e32 v4, 0xbfb8aa3b, v4
	v_fma_f32 v12, -v17, v18, 1.0
	v_fmac_f32_e32 v18, v12, v18
	v_div_scale_f32 v12, vcc, v11, v15, v11
	v_mul_f32_e32 v13, v12, v18
	v_fma_f32 v16, -v17, v13, v12
	v_fmac_f32_e32 v13, v16, v18
	v_div_scale_f32 v16, s[30:31], v14, v14, v10
	v_fma_f32 v12, -v17, v13, v12
	v_rcp_f32_e32 v17, v16
	v_div_fmas_f32 v12, v12, v18, v13
	v_div_fixup_f32 v11, v12, v15, v11
	v_mul_f32_e32 v5, 0xbfb8aa3b, v5
	v_fma_f32 v12, -v16, v17, 1.0
	v_fmac_f32_e32 v17, v12, v17
	v_div_scale_f32 v12, vcc, v10, v14, v10
	v_mul_f32_e32 v13, v12, v17
	v_exp_f32_e32 v4, v4
	v_exp_f32_e32 v5, v5
	v_fma_f32 v15, -v16, v13, v12
	v_fmac_f32_e32 v13, v15, v17
	v_fma_f32 v12, -v16, v13, v12
	v_div_fmas_f32 v12, v12, v17, v13
	v_pk_add_f32 v[4:5], v[4:5], 1.0 op_sel_hi:[1,0]
	v_div_fixup_f32 v10, v12, v14, v10
	v_div_scale_f32 v14, s[30:31], v5, v5, v1
	v_rcp_f32_e32 v15, v14
	v_add_co_u32_e32 v12, vcc, s71, v116
	v_cvt_pk_bf16_f32 v8, v8, v9
	v_cvt_pk_bf16_f32 v9, v10, v11
	v_addc_co_u32_e32 v13, vcc, 0, v117, vcc
	global_store_dwordx2 v[12:13], v[8:9], off
	v_fma_f32 v8, -v14, v15, 1.0
	v_fmac_f32_e32 v15, v8, v15
	v_div_scale_f32 v8, vcc, v1, v5, v1
	v_mul_f32_e32 v9, v8, v15
	v_fma_f32 v12, -v14, v9, v8
	v_fmac_f32_e32 v9, v12, v15
	v_div_scale_f32 v12, s[30:31], v4, v4, v0
	v_rcp_f32_e32 v13, v12
	v_fma_f32 v8, -v14, v9, v8
	v_mul_f32_e32 v6, 0xbfb8aa3b, v6
	v_mul_f32_e32 v7, 0xbfb8aa3b, v7
	v_div_fmas_f32 v8, v8, v15, v9
	v_exp_f32_e32 v6, v6
	v_exp_f32_e32 v7, v7
	v_div_fixup_f32 v1, v8, v5, v1
	v_fma_f32 v5, -v12, v13, 1.0
	v_fmac_f32_e32 v13, v5, v13
	v_div_scale_f32 v5, vcc, v0, v4, v0
	v_mul_f32_e32 v8, v5, v13
	v_fma_f32 v9, -v12, v8, v5
	v_pk_add_f32 v[6:7], v[6:7], 1.0 op_sel_hi:[1,0]
	v_fmac_f32_e32 v8, v9, v13
	v_div_scale_f32 v9, s[30:31], v7, v7, v3
	v_fma_f32 v5, -v12, v8, v5
	v_rcp_f32_e32 v12, v9
	v_div_fmas_f32 v5, v5, v13, v8
	v_div_fixup_f32 v0, v5, v4, v0
	v_lshl_add_u64 v[10:11], v[116:117], 0, s[14:15]
	v_fma_f32 v4, -v9, v12, 1.0
	v_fmac_f32_e32 v12, v4, v12
	v_div_scale_f32 v4, vcc, v3, v7, v3
	v_mul_f32_e32 v5, v4, v12
	v_fma_f32 v8, -v9, v5, v4
	v_fmac_f32_e32 v5, v8, v12
	v_div_scale_f32 v8, s[30:31], v6, v6, v2
	v_fma_f32 v4, -v9, v5, v4
	v_rcp_f32_e32 v9, v8
	v_div_fmas_f32 v4, v4, v12, v5
	v_div_fixup_f32 v3, v4, v7, v3
	v_cvt_pk_bf16_f32 v0, v0, v1
	v_fma_f32 v4, -v8, v9, 1.0
	v_fmac_f32_e32 v9, v4, v9
	v_div_scale_f32 v4, vcc, v2, v6, v2
	v_mul_f32_e32 v5, v4, v9
	v_fma_f32 v7, -v8, v5, v4
	v_fmac_f32_e32 v5, v7, v9
	v_fma_f32 v4, -v8, v5, v4
	v_div_fmas_f32 v4, v4, v9, v5
	v_div_fixup_f32 v2, v4, v6, v2
	v_cvt_pk_bf16_f32 v1, v2, v3
	s_and_b64 vcc, exec, s[4:5]
	s_mov_b32 s72, s16
	s_mov_b32 s28, s18
	s_mov_b64 s[34:35], s[26:27]
	s_mov_b64 s[30:31], s[20:21]
	global_store_dwordx2 v[10:11], v[0:1], off offset:128
	s_cbranch_vccz .LBB0_1134
	s_waitcnt vmcnt(0)
	s_cmpk_gt_u32 s40, 0xff
	s_cbranch_scc1 .LBB0_1145
	s_barrier

.LBB0_1291:
	ds_read_b128 v[154:157], v151
	ds_read_b128 v[158:161], v151 offset:1024
	ds_read_b128 v[162:165], v151 offset:2048
	ds_read_b128 v[166:169], v151 offset:3072
	s_add_u32 s36, s34, 0xfffc0080
	s_addc_u32 s37, s35, -1
	s_cmp_eq_u32 s79, 12
	s_cselect_b32 s39, s21, s37
	s_cselect_b32 s38, s75, s36
	s_cselect_b32 s37, s19, s78
	s_cselect_b32 s36, s76, s77
	v_lshl_add_u64 v[202:203], s[34:35], 0, v[138:139]
	s_add_i32 m0, s31, 0xc000
	ds_read_b128 v[170:173], v152
	ds_read_b128 v[174:177], v152 offset:1024
	ds_read_b128 v[178:181], v152 offset:2048
	ds_read_b128 v[182:185], v152 offset:3072
	ds_read_b128 v[186:189], v152 offset:4096
	ds_read_b128 v[190:193], v152 offset:5120
	ds_read_b128 v[194:197], v152 offset:6144
	ds_read_b128 v[198:201], v152 offset:7168
	global_load_lds_dwordx4 v[202:203], off
	v_lshl_add_u64 v[202:203], s[34:35], 0, v[140:141]
	s_add_i32 m0, s31, 0xe000
	s_nop 0
	global_load_lds_dwordx4 v[202:203], off
	s_waitcnt lgkmcnt(8)
	s_barrier
	s_waitcnt lgkmcnt(0)
	s_setprio 0
	s_waitcnt lgkmcnt(0)
	v_mfma_f32_16x16x32_bf16 v[124:127], v[154:157], v[170:173], v[124:127]
	v_mfma_f32_16x16x32_bf16 v[120:123], v[162:165], v[170:173], v[120:123]
	v_mfma_f32_16x16x32_bf16 v[108:111], v[154:157], v[178:181], v[108:111]
	v_mfma_f32_16x16x32_bf16 v[104:107], v[162:165], v[178:181], v[104:107]
	v_mfma_f32_16x16x32_bf16 v[92:95], v[154:157], v[186:189], v[92:95]
	v_mfma_f32_16x16x32_bf16 v[88:91], v[162:165], v[186:189], v[88:91]
	v_mfma_f32_16x16x32_bf16 v[76:79], v[154:157], v[194:197], v[76:79]
	v_mfma_f32_16x16x32_bf16 v[72:75], v[162:165], v[194:197], v[72:75]
	v_mfma_f32_16x16x32_bf16 v[124:127], v[158:161], v[174:177], v[124:127]
	v_mfma_f32_16x16x32_bf16 v[120:123], v[166:169], v[174:177], v[120:123]
	v_mfma_f32_16x16x32_bf16 v[108:111], v[158:161], v[182:185], v[108:111]
	v_mfma_f32_16x16x32_bf16 v[104:107], v[166:169], v[182:185], v[104:107]
	v_mfma_f32_16x16x32_bf16 v[92:95], v[158:161], v[190:193], v[92:95]
	v_mfma_f32_16x16x32_bf16 v[88:91], v[166:169], v[190:193], v[88:91]
	v_mfma_f32_16x16x32_bf16 v[76:79], v[158:161], v[198:201], v[76:79]
	v_mfma_f32_16x16x32_bf16 v[72:75], v[166:169], v[198:201], v[72:75]
	s_setprio 1
	s_barrier
	s_add_i32 s80, s62, s52
	v_lshl_add_u64 v[218:219], s[36:37], 0, v[132:133]
	s_mov_b32 m0, s80
	ds_read_b128 v[202:205], v153
	ds_read_b128 v[206:209], v153 offset:1024
	ds_read_b128 v[210:213], v153 offset:2048
	ds_read_b128 v[214:217], v153 offset:3072
	global_load_lds_dwordx4 v[218:219], off
	v_lshl_add_u64 v[220:221], s[36:37], 0, v[136:137]
	s_add_i32 m0, s80, 0x2000
	s_nop 0
	global_load_lds_dwordx4 v[220:221], off
	s_barrier
	s_waitcnt lgkmcnt(0)
	s_setprio 0
	s_waitcnt lgkmcnt(0)
	v_mfma_f32_16x16x32_bf16 v[116:119], v[202:205], v[170:173], v[116:119]
	v_mfma_f32_16x16x32_bf16 v[112:115], v[210:213], v[170:173], v[112:115]
	v_mfma_f32_16x16x32_bf16 v[100:103], v[202:205], v[178:181], v[100:103]
	v_mfma_f32_16x16x32_bf16 v[96:99], v[210:213], v[178:181], v[96:99]
	v_mfma_f32_16x16x32_bf16 v[84:87], v[202:205], v[186:189], v[84:87]
	v_mfma_f32_16x16x32_bf16 v[80:83], v[210:213], v[186:189], v[80:83]
	v_mfma_f32_16x16x32_bf16 v[68:71], v[202:205], v[194:197], v[68:71]
	v_mfma_f32_16x16x32_bf16 v[64:67], v[210:213], v[194:197], v[64:67]
	v_mfma_f32_16x16x32_bf16 v[116:119], v[206:209], v[174:177], v[116:119]
	v_mfma_f32_16x16x32_bf16 v[112:115], v[214:217], v[174:177], v[112:115]
	v_mfma_f32_16x16x32_bf16 v[100:103], v[206:209], v[182:185], v[100:103]
	v_mfma_f32_16x16x32_bf16 v[96:99], v[214:217], v[182:185], v[96:99]
	v_mfma_f32_16x16x32_bf16 v[84:87], v[206:209], v[190:193], v[84:87]
	v_mfma_f32_16x16x32_bf16 v[80:83], v[214:217], v[190:193], v[80:83]
	v_mfma_f32_16x16x32_bf16 v[68:71], v[206:209], v[198:201], v[68:71]
	v_mfma_f32_16x16x32_bf16 v[64:67], v[214:217], v[198:201], v[64:67]
	s_setprio 1
	s_mov_b32 m0, s31
	v_lshl_add_u64 v[222:223], s[38:39], 0, v[130:131]
	s_barrier
	ds_read_b128 v[170:173], v152 offset:16384
	ds_read_b128 v[174:177], v152 offset:17408
	ds_read_b128 v[178:181], v152 offset:18432
	ds_read_b128 v[182:185], v152 offset:19456
	ds_read_b128 v[186:189], v152 offset:20480
	ds_read_b128 v[190:193], v152 offset:21504
	ds_read_b128 v[194:197], v152 offset:22528
	ds_read_b128 v[198:201], v152 offset:23552
	global_load_lds_dwordx4 v[222:223], off
	v_lshl_add_u64 v[224:225], s[38:39], 0, v[134:135]
	s_mov_b32 m0, s53
	s_nop 0
	global_load_lds_dwordx4 v[224:225], off
	s_barrier
	s_waitcnt lgkmcnt(0)
	s_setprio 0
	s_waitcnt lgkmcnt(0)
	v_mfma_f32_16x16x32_bf16 v[60:63], v[154:157], v[170:173], v[60:63]
	v_mfma_f32_16x16x32_bf16 v[56:59], v[162:165], v[170:173], v[56:59]
	v_mfma_f32_16x16x32_bf16 v[44:47], v[154:157], v[178:181], v[44:47]
	v_mfma_f32_16x16x32_bf16 v[40:43], v[162:165], v[178:181], v[40:43]
	v_mfma_f32_16x16x32_bf16 v[28:31], v[154:157], v[186:189], v[28:31]
	v_mfma_f32_16x16x32_bf16 v[24:27], v[162:165], v[186:189], v[24:27]
	v_mfma_f32_16x16x32_bf16 v[12:15], v[154:157], v[194:197], v[12:15]
	v_mfma_f32_16x16x32_bf16 v[8:11], v[162:165], v[194:197], v[8:11]
	v_mfma_f32_16x16x32_bf16 v[60:63], v[158:161], v[174:177], v[60:63]
	v_mfma_f32_16x16x32_bf16 v[56:59], v[166:169], v[174:177], v[56:59]
	v_mfma_f32_16x16x32_bf16 v[44:47], v[158:161], v[182:185], v[44:47]
	v_mfma_f32_16x16x32_bf16 v[40:43], v[166:169], v[182:185], v[40:43]
	v_mfma_f32_16x16x32_bf16 v[28:31], v[158:161], v[190:193], v[28:31]
	v_mfma_f32_16x16x32_bf16 v[24:27], v[166:169], v[190:193], v[24:27]
	v_mfma_f32_16x16x32_bf16 v[12:15], v[158:161], v[198:201], v[12:15]
	v_mfma_f32_16x16x32_bf16 v[8:11], v[166:169], v[198:201], v[8:11]
	s_setprio 1
	s_barrier
	s_add_u32 s80, s36, 0x40000
	s_addc_u32 s81, s37, 0
	s_add_i32 s82, s63, s52
	v_lshl_add_u64 v[154:155], s[80:81], 0, v[132:133]
	s_mov_b32 m0, s82
	s_nop 0
	global_load_lds_dwordx4 v[154:155], off
	v_lshl_add_u64 v[154:155], s[80:81], 0, v[136:137]
	s_add_i32 m0, s82, 0x2000
	s_nop 0
	global_load_lds_dwordx4 v[154:155], off
	s_waitcnt vmcnt(6)
	s_barrier
	s_setprio 0
	v_mfma_f32_16x16x32_bf16 v[52:55], v[202:205], v[170:173], v[52:55]
	v_mfma_f32_16x16x32_bf16 v[48:51], v[210:213], v[170:173], v[48:51]
	v_mfma_f32_16x16x32_bf16 v[36:39], v[202:205], v[178:181], v[36:39]
	v_mfma_f32_16x16x32_bf16 v[32:35], v[210:213], v[178:181], v[32:35]
	v_mfma_f32_16x16x32_bf16 v[20:23], v[202:205], v[186:189], v[20:23]
	v_mfma_f32_16x16x32_bf16 v[16:19], v[210:213], v[186:189], v[16:19]
	v_mfma_f32_16x16x32_bf16 v[4:7], v[202:205], v[194:197], v[4:7]
	v_mfma_f32_16x16x32_bf16 v[0:3], v[210:213], v[194:197], v[0:3]
	v_mfma_f32_16x16x32_bf16 v[52:55], v[206:209], v[174:177], v[52:55]
	v_mfma_f32_16x16x32_bf16 v[48:51], v[214:217], v[174:177], v[48:51]
	v_mfma_f32_16x16x32_bf16 v[36:39], v[206:209], v[182:185], v[36:39]
	v_mfma_f32_16x16x32_bf16 v[32:35], v[214:217], v[182:185], v[32:35]
	v_mfma_f32_16x16x32_bf16 v[20:23], v[206:209], v[190:193], v[20:23]
	v_mfma_f32_16x16x32_bf16 v[16:19], v[214:217], v[190:193], v[16:19]
	v_mfma_f32_16x16x32_bf16 v[4:7], v[206:209], v[198:201], v[4:7]
	v_mfma_f32_16x16x32_bf16 v[0:3], v[214:217], v[198:201], v[0:3]
	s_setprio 1
	s_add_i32 s80, 0, 0x18000
	v_add_u32_e32 v166, s80, v149
	s_barrier
	ds_read_b128 v[154:157], v166
	ds_read_b128 v[158:161], v166 offset:1024
	ds_read_b128 v[162:165], v166 offset:2048
	ds_read_b128 v[166:169], v166 offset:3072
	s_add_u32 s38, s38, 0x40000
	s_addc_u32 s39, s39, 0
	s_mov_b32 m0, s54
	v_lshl_add_u64 v[202:203], s[38:39], 0, v[130:131]
	ds_read_b128 v[170:173], v152 offset:32768
	ds_read_b128 v[174:177], v152 offset:33792
	ds_read_b128 v[178:181], v152 offset:34816
	ds_read_b128 v[182:185], v152 offset:35840
	ds_read_b128 v[186:189], v152 offset:36864
	ds_read_b128 v[190:193], v152 offset:37888
	ds_read_b128 v[194:197], v152 offset:38912
	ds_read_b128 v[198:201], v152 offset:39936
	global_load_lds_dwordx4 v[202:203], off
	v_lshl_add_u64 v[202:203], s[38:39], 0, v[134:135]
	s_mov_b32 m0, s55
	s_nop 0
	global_load_lds_dwordx4 v[202:203], off
	s_waitcnt lgkmcnt(8)
	s_barrier
	s_waitcnt lgkmcnt(0)
	s_setprio 0
	s_waitcnt lgkmcnt(0)
	v_mfma_f32_16x16x32_bf16 v[124:127], v[154:157], v[170:173], v[124:127]
	v_mfma_f32_16x16x32_bf16 v[120:123], v[162:165], v[170:173], v[120:123]
	v_mfma_f32_16x16x32_bf16 v[108:111], v[154:157], v[178:181], v[108:111]
	v_mfma_f32_16x16x32_bf16 v[104:107], v[162:165], v[178:181], v[104:107]
	v_mfma_f32_16x16x32_bf16 v[92:95], v[154:157], v[186:189], v[92:95]
	v_mfma_f32_16x16x32_bf16 v[88:91], v[162:165], v[186:189], v[88:91]
	v_mfma_f32_16x16x32_bf16 v[76:79], v[154:157], v[194:197], v[76:79]
	v_mfma_f32_16x16x32_bf16 v[72:75], v[162:165], v[194:197], v[72:75]
	v_mfma_f32_16x16x32_bf16 v[124:127], v[158:161], v[174:177], v[124:127]
	v_mfma_f32_16x16x32_bf16 v[120:123], v[166:169], v[174:177], v[120:123]
	v_mfma_f32_16x16x32_bf16 v[108:111], v[158:161], v[182:185], v[108:111]
	v_mfma_f32_16x16x32_bf16 v[104:107], v[166:169], v[182:185], v[104:107]
	v_mfma_f32_16x16x32_bf16 v[92:95], v[158:161], v[190:193], v[92:95]
	v_mfma_f32_16x16x32_bf16 v[88:91], v[166:169], v[190:193], v[88:91]
	v_mfma_f32_16x16x32_bf16 v[76:79], v[158:161], v[198:201], v[76:79]
	v_mfma_f32_16x16x32_bf16 v[72:75], v[166:169], v[198:201], v[72:75]
	s_setprio 1
	s_barrier
	s_add_i32 s38, 0, 0x1c000
	s_add_i32 s39, s80, s52
	v_add_u32_e32 v214, s38, v149
	v_lshl_add_u64 v[218:219], v[218:219], 0, s[8:9]
	s_mov_b32 m0, s39
	ds_read_b128 v[202:205], v214
	ds_read_b128 v[206:209], v214 offset:1024
	ds_read_b128 v[210:213], v214 offset:2048
	ds_read_b128 v[214:217], v214 offset:3072
	global_load_lds_dwordx4 v[218:219], off
	v_lshl_add_u64 v[218:219], v[220:221], 0, s[8:9]
	s_add_i32 m0, s39, 0x2000
	s_nop 0
	global_load_lds_dwordx4 v[218:219], off
	s_barrier
	s_waitcnt lgkmcnt(0)
	s_setprio 0
	s_waitcnt lgkmcnt(0)
	v_mfma_f32_16x16x32_bf16 v[116:119], v[202:205], v[170:173], v[116:119]
	v_mfma_f32_16x16x32_bf16 v[112:115], v[210:213], v[170:173], v[112:115]
	v_mfma_f32_16x16x32_bf16 v[100:103], v[202:205], v[178:181], v[100:103]
	v_mfma_f32_16x16x32_bf16 v[96:99], v[210:213], v[178:181], v[96:99]
	v_mfma_f32_16x16x32_bf16 v[84:87], v[202:205], v[186:189], v[84:87]
	v_mfma_f32_16x16x32_bf16 v[80:83], v[210:213], v[186:189], v[80:83]
	v_mfma_f32_16x16x32_bf16 v[68:71], v[202:205], v[194:197], v[68:71]
	v_mfma_f32_16x16x32_bf16 v[64:67], v[210:213], v[194:197], v[64:67]
	v_mfma_f32_16x16x32_bf16 v[116:119], v[206:209], v[174:177], v[116:119]
	v_mfma_f32_16x16x32_bf16 v[112:115], v[214:217], v[174:177], v[112:115]
	v_mfma_f32_16x16x32_bf16 v[100:103], v[206:209], v[182:185], v[100:103]
	v_mfma_f32_16x16x32_bf16 v[96:99], v[214:217], v[182:185], v[96:99]
	v_mfma_f32_16x16x32_bf16 v[84:87], v[206:209], v[190:193], v[84:87]
	v_mfma_f32_16x16x32_bf16 v[80:83], v[214:217], v[190:193], v[80:83]
	v_mfma_f32_16x16x32_bf16 v[68:71], v[206:209], v[198:201], v[68:71]
	v_mfma_f32_16x16x32_bf16 v[64:67], v[214:217], v[198:201], v[64:67]
	s_setprio 1
	s_mov_b32 m0, s57
	v_lshl_add_u64 v[218:219], v[222:223], 0, s[8:9]
	s_barrier
	ds_read_b128 v[170:173], v152 offset:49152
	ds_read_b128 v[174:177], v152 offset:50176
	ds_read_b128 v[178:181], v152 offset:51200
	ds_read_b128 v[182:185], v152 offset:52224
	ds_read_b128 v[186:189], v152 offset:53248
	ds_read_b128 v[190:193], v152 offset:54272
	ds_read_b128 v[194:197], v152 offset:55296
	ds_read_b128 v[198:201], v152 offset:56320
	global_load_lds_dwordx4 v[218:219], off
	v_lshl_add_u64 v[218:219], v[224:225], 0, s[8:9]
	s_mov_b32 m0, s60
	s_nop 0
	global_load_lds_dwordx4 v[218:219], off
	s_barrier
	s_waitcnt lgkmcnt(0)
	s_setprio 0
	s_waitcnt lgkmcnt(0)
	v_mfma_f32_16x16x32_bf16 v[60:63], v[154:157], v[170:173], v[60:63]
	v_mfma_f32_16x16x32_bf16 v[56:59], v[162:165], v[170:173], v[56:59]
	v_mfma_f32_16x16x32_bf16 v[44:47], v[154:157], v[178:181], v[44:47]
	v_mfma_f32_16x16x32_bf16 v[40:43], v[162:165], v[178:181], v[40:43]
	v_mfma_f32_16x16x32_bf16 v[28:31], v[154:157], v[186:189], v[28:31]
	v_mfma_f32_16x16x32_bf16 v[24:27], v[162:165], v[186:189], v[24:27]
	v_mfma_f32_16x16x32_bf16 v[12:15], v[154:157], v[194:197], v[12:15]
	v_mfma_f32_16x16x32_bf16 v[8:11], v[162:165], v[194:197], v[8:11]
	v_mfma_f32_16x16x32_bf16 v[60:63], v[158:161], v[174:177], v[60:63]
	v_mfma_f32_16x16x32_bf16 v[56:59], v[166:169], v[174:177], v[56:59]
	v_mfma_f32_16x16x32_bf16 v[44:47], v[158:161], v[182:185], v[44:47]
	v_mfma_f32_16x16x32_bf16 v[40:43], v[166:169], v[182:185], v[40:43]
	v_mfma_f32_16x16x32_bf16 v[28:31], v[158:161], v[190:193], v[28:31]
	v_mfma_f32_16x16x32_bf16 v[24:27], v[166:169], v[190:193], v[24:27]
	v_mfma_f32_16x16x32_bf16 v[12:15], v[158:161], v[198:201], v[12:15]
	v_mfma_f32_16x16x32_bf16 v[8:11], v[166:169], v[198:201], v[8:11]
	s_setprio 1
	s_barrier
	s_add_u32 s36, s36, 0x40080
	s_addc_u32 s37, s37, 0
	s_add_i32 s38, s38, s52
	v_lshl_add_u64 v[154:155], s[36:37], 0, v[132:133]
	s_mov_b32 m0, s38
	s_nop 0
	global_load_lds_dwordx4 v[154:155], off
	v_lshl_add_u64 v[154:155], s[36:37], 0, v[136:137]
	s_add_i32 m0, s38, 0x2000
	s_nop 0
	global_load_lds_dwordx4 v[154:155], off
	s_waitcnt vmcnt(6)
	s_barrier
	s_setprio 0
	v_mfma_f32_16x16x32_bf16 v[52:55], v[202:205], v[170:173], v[52:55]
	v_mfma_f32_16x16x32_bf16 v[48:51], v[210:213], v[170:173], v[48:51]
	v_mfma_f32_16x16x32_bf16 v[36:39], v[202:205], v[178:181], v[36:39]
	v_mfma_f32_16x16x32_bf16 v[32:35], v[210:213], v[178:181], v[32:35]
	v_mfma_f32_16x16x32_bf16 v[20:23], v[202:205], v[186:189], v[20:23]
	v_mfma_f32_16x16x32_bf16 v[16:19], v[210:213], v[186:189], v[16:19]
	v_mfma_f32_16x16x32_bf16 v[4:7], v[202:205], v[194:197], v[4:7]
	v_mfma_f32_16x16x32_bf16 v[0:3], v[210:213], v[194:197], v[0:3]
	v_mfma_f32_16x16x32_bf16 v[52:55], v[206:209], v[174:177], v[52:55]
	v_mfma_f32_16x16x32_bf16 v[48:51], v[214:217], v[174:177], v[48:51]
	v_mfma_f32_16x16x32_bf16 v[36:39], v[206:209], v[182:185], v[36:39]
	v_mfma_f32_16x16x32_bf16 v[32:35], v[214:217], v[182:185], v[32:35]
	v_mfma_f32_16x16x32_bf16 v[20:23], v[206:209], v[190:193], v[20:23]
	v_mfma_f32_16x16x32_bf16 v[16:19], v[214:217], v[190:193], v[16:19]
	v_mfma_f32_16x16x32_bf16 v[4:7], v[206:209], v[198:201], v[4:7]
	v_mfma_f32_16x16x32_bf16 v[0:3], v[214:217], v[198:201], v[0:3]
	s_setprio 1
	s_add_i32 s79, s79, 2
	s_add_u32 s34, s34, 0x100
	s_addc_u32 s35, s35, 0
	s_add_u32 s77, s77, 0x100
	s_addc_u32 s78, s78, 0
	s_cmp_gt_u32 s79, 13
	s_barrier
	s_cbranch_scc0 .LBB0_1291
	v_lshl_add_u32 v154, s30, 8, v148
	v_max_f32_e32 v126, v126, v126
	v_max_f32_e32 v127, v127, v127
	v_lshl_or_b32 v156, s74, 8, v150
	v_ashrrev_i32_e32 v155, 31, v154
	v_max_f32_e32 v124, v124, v124
	v_max_f32_e32 v120, v120, v120
	v_max_f32_e32 v125, v125, v125
	v_max_f32_e32 v121, v121, v121
	v_max_f32_e32 v126, 0, v126
	v_max_f32_e32 v122, v122, v122
	v_max_f32_e32 v127, 0, v127
	v_max_f32_e32 v123, v123, v123
	v_lshlrev_b64 v[158:159], 13, v[154:155]
	v_max_f32_e32 v124, 0, v124
	v_max_f32_e32 v120, 0, v120
	v_max_f32_e32 v125, 0, v125
	v_max_f32_e32 v121, 0, v121
	v_max_f32_e32 v122, 0, v122
	v_max_f32_e32 v123, 0, v123
	v_pk_mul_f32 v[126:127], v[126:127], v[126:127]
	v_ashrrev_i32_e32 v157, 31, v156
	v_lshl_add_u64 v[158:159], s[46:47], 0, v[158:159]
	v_pk_mul_f32 v[124:125], v[124:125], v[124:125]
	v_pk_mul_f32 v[120:121], v[120:121], v[120:121]
	v_pk_mul_f32 v[160:161], v[122:123], v[122:123]
	v_cvt_pk_bf16_f32 v123, v126, v127
	v_lshlrev_b64 v[126:127], 1, v[156:157]
	v_max_f32_e32 v112, v112, v112
	v_max_f32_e32 v113, v113, v113
	v_cvt_pk_bf16_f32 v122, v124, v125
	v_cvt_pk_bf16_f32 v124, v120, v121
	v_cvt_pk_bf16_f32 v125, v160, v161
	v_lshl_add_u64 v[120:121], v[158:159], 0, v[126:127]
	v_max_f32_e32 v112, 0, v112
	v_max_f32_e32 v113, 0, v113
	global_store_dwordx4 v[120:121], v[122:125], off
	v_max_f32_e32 v116, v116, v116
	v_max_f32_e32 v117, v117, v117
	v_pk_mul_f32 v[122:123], v[112:113], v[112:113]
	v_max_f32_e32 v113, v114, v114
	v_max_f32_e32 v112, v118, v118
	v_max_f32_e32 v114, 0, v113
	v_max_f32_e32 v113, v119, v119
	v_max_f32_e32 v115, v115, v115
	v_max_f32_e32 v116, 0, v116
	v_max_f32_e32 v117, 0, v117
	v_max_f32_e32 v112, 0, v112
	v_max_f32_e32 v113, 0, v113
	v_max_f32_e32 v115, 0, v115
	v_pk_mul_f32 v[116:117], v[116:117], v[116:117]
	v_pk_mul_f32 v[118:119], v[112:113], v[112:113]
	v_pk_mul_f32 v[124:125], v[114:115], v[114:115]
	v_max_f32_e32 v104, v104, v104
	v_max_f32_e32 v105, v105, v105
	v_cvt_pk_bf16_f32 v112, v116, v117
	v_cvt_pk_bf16_f32 v113, v118, v119
	v_cvt_pk_bf16_f32 v114, v122, v123
	v_cvt_pk_bf16_f32 v115, v124, v125
	v_max_f32_e32 v104, 0, v104
	v_max_f32_e32 v105, 0, v105
	global_store_dwordx4 v[120:121], v[112:115], off offset:256
	v_max_f32_e32 v108, v108, v108
	v_max_f32_e32 v109, v109, v109
	v_or_b32_e32 v112, 16, v154
	v_pk_mul_f32 v[114:115], v[104:105], v[104:105]
	v_max_f32_e32 v105, v106, v106
	v_ashrrev_i32_e32 v113, 31, v112
	v_max_f32_e32 v104, v110, v110
	v_max_f32_e32 v106, 0, v105
	v_max_f32_e32 v105, v111, v111
	v_max_f32_e32 v107, v107, v107
	v_lshlrev_b64 v[112:113], 13, v[112:113]
	v_max_f32_e32 v108, 0, v108
	v_max_f32_e32 v109, 0, v109
	v_max_f32_e32 v104, 0, v104
	v_max_f32_e32 v105, 0, v105
	v_max_f32_e32 v107, 0, v107
	v_lshl_add_u64 v[112:113], s[46:47], 0, v[112:113]
	v_pk_mul_f32 v[108:109], v[108:109], v[108:109]
	v_pk_mul_f32 v[110:111], v[104:105], v[104:105]
	v_pk_mul_f32 v[116:117], v[106:107], v[106:107]
	v_max_f32_e32 v96, v96, v96
	v_max_f32_e32 v97, v97, v97
	v_cvt_pk_bf16_f32 v104, v108, v109
	v_cvt_pk_bf16_f32 v105, v110, v111
	v_cvt_pk_bf16_f32 v106, v114, v115
	v_cvt_pk_bf16_f32 v107, v116, v117
	v_lshl_add_u64 v[108:109], v[112:113], 0, v[126:127]
	v_max_f32_e32 v96, 0, v96
	v_max_f32_e32 v97, 0, v97
	global_store_dwordx4 v[108:109], v[104:107], off
	v_max_f32_e32 v100, v100, v100
	v_max_f32_e32 v101, v101, v101
	v_pk_mul_f32 v[104:105], v[96:97], v[96:97]
	v_max_f32_e32 v97, v98, v98
	v_max_f32_e32 v96, v102, v102
	v_max_f32_e32 v98, 0, v97
	v_max_f32_e32 v97, v103, v103
	v_max_f32_e32 v99, v99, v99
	v_max_f32_e32 v100, 0, v100
	v_max_f32_e32 v101, 0, v101
	v_max_f32_e32 v96, 0, v96
	v_max_f32_e32 v97, 0, v97
	v_max_f32_e32 v99, 0, v99
	v_pk_mul_f32 v[100:101], v[100:101], v[100:101]
	v_pk_mul_f32 v[102:103], v[96:97], v[96:97]
	v_pk_mul_f32 v[106:107], v[98:99], v[98:99]
	v_max_f32_e32 v88, v88, v88
	v_max_f32_e32 v89, v89, v89
	v_cvt_pk_bf16_f32 v96, v100, v101
	v_cvt_pk_bf16_f32 v97, v102, v103
	v_cvt_pk_bf16_f32 v98, v104, v105
	v_cvt_pk_bf16_f32 v99, v106, v107
	v_max_f32_e32 v88, 0, v88
	v_max_f32_e32 v89, 0, v89
	global_store_dwordx4 v[108:109], v[96:99], off offset:256
	v_max_f32_e32 v92, v92, v92
	v_max_f32_e32 v93, v93, v93
	v_or_b32_e32 v96, 32, v154
	v_pk_mul_f32 v[98:99], v[88:89], v[88:89]
	v_max_f32_e32 v89, v90, v90
	v_ashrrev_i32_e32 v97, 31, v96
	v_max_f32_e32 v88, v94, v94
	v_max_f32_e32 v90, 0, v89
	v_max_f32_e32 v89, v95, v95
	v_max_f32_e32 v91, v91, v91
	v_lshlrev_b64 v[96:97], 13, v[96:97]
	v_max_f32_e32 v92, 0, v92
	v_max_f32_e32 v93, 0, v93
	v_max_f32_e32 v88, 0, v88
	v_max_f32_e32 v89, 0, v89
	v_max_f32_e32 v91, 0, v91
	v_lshl_add_u64 v[96:97], s[46:47], 0, v[96:97]
	v_pk_mul_f32 v[92:93], v[92:93], v[92:93]
	v_pk_mul_f32 v[94:95], v[88:89], v[88:89]
	v_pk_mul_f32 v[100:101], v[90:91], v[90:91]
	v_max_f32_e32 v80, v80, v80
	v_max_f32_e32 v81, v81, v81
	v_cvt_pk_bf16_f32 v88, v92, v93
	v_cvt_pk_bf16_f32 v89, v94, v95
	v_cvt_pk_bf16_f32 v90, v98, v99
	v_cvt_pk_bf16_f32 v91, v100, v101
	v_lshl_add_u64 v[92:93], v[96:97], 0, v[126:127]
	v_max_f32_e32 v80, 0, v80
	v_max_f32_e32 v81, 0, v81
	global_store_dwordx4 v[92:93], v[88:91], off
	v_max_f32_e32 v84, v84, v84
	v_max_f32_e32 v85, v85, v85
	v_pk_mul_f32 v[88:89], v[80:81], v[80:81]
	v_max_f32_e32 v81, v82, v82
	v_max_f32_e32 v80, v86, v86
	v_max_f32_e32 v82, 0, v81
	v_max_f32_e32 v81, v87, v87
	v_max_f32_e32 v83, v83, v83
	v_max_f32_e32 v84, 0, v84
	v_max_f32_e32 v85, 0, v85
	v_max_f32_e32 v80, 0, v80
	v_max_f32_e32 v81, 0, v81
	v_max_f32_e32 v83, 0, v83
	v_pk_mul_f32 v[84:85], v[84:85], v[84:85]
	v_pk_mul_f32 v[86:87], v[80:81], v[80:81]
	v_pk_mul_f32 v[90:91], v[82:83], v[82:83]
	v_max_f32_e32 v72, v72, v72
	v_max_f32_e32 v73, v73, v73
	v_cvt_pk_bf16_f32 v80, v84, v85
	v_cvt_pk_bf16_f32 v81, v86, v87
	v_cvt_pk_bf16_f32 v82, v88, v89
	v_cvt_pk_bf16_f32 v83, v90, v91
	v_max_f32_e32 v72, 0, v72
	v_max_f32_e32 v73, 0, v73
	global_store_dwordx4 v[92:93], v[80:83], off offset:256
	v_max_f32_e32 v76, v76, v76
	v_max_f32_e32 v77, v77, v77
	v_or_b32_e32 v80, 48, v154
	v_pk_mul_f32 v[82:83], v[72:73], v[72:73]
	v_max_f32_e32 v73, v74, v74
	v_ashrrev_i32_e32 v81, 31, v80
	v_max_f32_e32 v72, v78, v78
	v_max_f32_e32 v74, 0, v73
	v_max_f32_e32 v73, v79, v79
	v_max_f32_e32 v75, v75, v75
	v_lshlrev_b64 v[80:81], 13, v[80:81]
	v_max_f32_e32 v76, 0, v76
	v_max_f32_e32 v77, 0, v77
	v_max_f32_e32 v72, 0, v72
	v_max_f32_e32 v73, 0, v73
	v_max_f32_e32 v75, 0, v75
	v_lshl_add_u64 v[80:81], s[46:47], 0, v[80:81]
	v_pk_mul_f32 v[76:77], v[76:77], v[76:77]
	v_pk_mul_f32 v[78:79], v[72:73], v[72:73]
	v_pk_mul_f32 v[84:85], v[74:75], v[74:75]
	v_max_f32_e32 v64, v64, v64
	v_max_f32_e32 v65, v65, v65
	v_cvt_pk_bf16_f32 v72, v76, v77
	v_cvt_pk_bf16_f32 v73, v78, v79
	v_cvt_pk_bf16_f32 v74, v82, v83
	v_cvt_pk_bf16_f32 v75, v84, v85
	v_lshl_add_u64 v[76:77], v[80:81], 0, v[126:127]
	v_max_f32_e32 v64, 0, v64
	v_max_f32_e32 v65, 0, v65
	global_store_dwordx4 v[76:77], v[72:75], off
	v_max_f32_e32 v68, v68, v68
	v_max_f32_e32 v69, v69, v69
	v_pk_mul_f32 v[72:73], v[64:65], v[64:65]
	v_max_f32_e32 v65, v66, v66
	v_max_f32_e32 v64, v70, v70
	v_max_f32_e32 v66, 0, v65
	v_max_f32_e32 v65, v71, v71
	v_max_f32_e32 v67, v67, v67
	v_max_f32_e32 v68, 0, v68
	v_max_f32_e32 v69, 0, v69
	v_max_f32_e32 v64, 0, v64
	v_max_f32_e32 v65, 0, v65
	v_max_f32_e32 v67, 0, v67
	v_pk_mul_f32 v[68:69], v[68:69], v[68:69]
	v_pk_mul_f32 v[70:71], v[64:65], v[64:65]
	v_pk_mul_f32 v[74:75], v[66:67], v[66:67]
	v_max_f32_e32 v56, v56, v56
	v_max_f32_e32 v57, v57, v57
	v_cvt_pk_bf16_f32 v64, v68, v69
	v_cvt_pk_bf16_f32 v65, v70, v71
	v_cvt_pk_bf16_f32 v66, v72, v73
	v_cvt_pk_bf16_f32 v67, v74, v75
	v_max_f32_e32 v56, 0, v56
	v_max_f32_e32 v57, 0, v57
	global_store_dwordx4 v[76:77], v[64:67], off offset:256
	v_max_f32_e32 v60, v60, v60
	v_max_f32_e32 v61, v61, v61
	v_pk_mul_f32 v[64:65], v[56:57], v[56:57]
	v_max_f32_e32 v57, v58, v58
	v_max_f32_e32 v56, v62, v62
	v_max_f32_e32 v58, 0, v57
	v_max_f32_e32 v57, v63, v63
	v_max_f32_e32 v56, 0, v56
	v_max_f32_e32 v57, 0, v57
	v_max_f32_e32 v59, v59, v59
	v_max_f32_e32 v60, 0, v60
	v_max_f32_e32 v61, 0, v61
	v_max_f32_e32 v59, 0, v59
	v_pk_mul_f32 v[62:63], v[56:57], v[56:57]
	v_pk_mul_f32 v[60:61], v[60:61], v[60:61]
	v_pk_mul_f32 v[66:67], v[58:59], v[58:59]
	v_cvt_pk_bf16_f32 v57, v62, v63
	v_add_co_u32_e32 v62, vcc, s70, v120
	v_max_f32_e32 v48, v48, v48
	v_max_f32_e32 v49, v49, v49
	v_cvt_pk_bf16_f32 v56, v60, v61
	v_cvt_pk_bf16_f32 v58, v64, v65
	v_cvt_pk_bf16_f32 v59, v66, v67
	v_addc_co_u32_e32 v63, vcc, 0, v121, vcc
	v_max_f32_e32 v48, 0, v48
	v_max_f32_e32 v49, 0, v49
	global_store_dwordx4 v[62:63], v[56:59], off
	v_max_f32_e32 v52, v52, v52
	v_max_f32_e32 v53, v53, v53
	v_pk_mul_f32 v[56:57], v[48:49], v[48:49]
	v_max_f32_e32 v49, v50, v50
	v_max_f32_e32 v48, v54, v54
	v_max_f32_e32 v50, 0, v49
	v_max_f32_e32 v49, v55, v55
	v_max_f32_e32 v51, v51, v51
	v_max_f32_e32 v52, 0, v52
	v_max_f32_e32 v53, 0, v53
	v_max_f32_e32 v48, 0, v48
	v_max_f32_e32 v49, 0, v49
	v_max_f32_e32 v51, 0, v51
	v_pk_mul_f32 v[52:53], v[52:53], v[52:53]
	v_pk_mul_f32 v[54:55], v[48:49], v[48:49]
	v_pk_mul_f32 v[58:59], v[50:51], v[50:51]
	v_max_f32_e32 v40, v40, v40
	v_max_f32_e32 v41, v41, v41
	v_lshl_add_u64 v[60:61], v[120:121], 0, s[10:11]
	v_cvt_pk_bf16_f32 v48, v52, v53
	v_cvt_pk_bf16_f32 v49, v54, v55
	v_cvt_pk_bf16_f32 v50, v56, v57
	v_cvt_pk_bf16_f32 v51, v58, v59
	v_max_f32_e32 v40, 0, v40
	v_max_f32_e32 v41, 0, v41
	global_store_dwordx4 v[60:61], v[48:51], off offset:256
	v_max_f32_e32 v44, v44, v44
	v_max_f32_e32 v45, v45, v45
	v_pk_mul_f32 v[48:49], v[40:41], v[40:41]
	v_max_f32_e32 v41, v42, v42
	v_max_f32_e32 v40, v46, v46
	v_max_f32_e32 v42, 0, v41
	v_max_f32_e32 v41, v47, v47
	v_max_f32_e32 v40, 0, v40
	v_max_f32_e32 v41, 0, v41
	v_max_f32_e32 v43, v43, v43
	v_max_f32_e32 v44, 0, v44
	v_max_f32_e32 v45, 0, v45
	v_max_f32_e32 v43, 0, v43
	v_pk_mul_f32 v[46:47], v[40:41], v[40:41]
	v_pk_mul_f32 v[44:45], v[44:45], v[44:45]
	v_pk_mul_f32 v[50:51], v[42:43], v[42:43]
	v_cvt_pk_bf16_f32 v41, v46, v47
	v_add_co_u32_e32 v46, vcc, s71, v120
	v_max_f32_e32 v32, v32, v32
	v_max_f32_e32 v33, v33, v33
	v_cvt_pk_bf16_f32 v40, v44, v45
	v_cvt_pk_bf16_f32 v42, v48, v49
	v_cvt_pk_bf16_f32 v43, v50, v51
	v_addc_co_u32_e32 v47, vcc, 0, v121, vcc
	v_max_f32_e32 v32, 0, v32
	v_max_f32_e32 v33, 0, v33
	global_store_dwordx4 v[46:47], v[40:43], off
	v_max_f32_e32 v36, v36, v36
	v_max_f32_e32 v37, v37, v37
	v_pk_mul_f32 v[40:41], v[32:33], v[32:33]
	v_max_f32_e32 v33, v34, v34
	v_max_f32_e32 v32, v38, v38
	v_max_f32_e32 v34, 0, v33
	v_max_f32_e32 v33, v39, v39
	v_max_f32_e32 v35, v35, v35
	v_max_f32_e32 v36, 0, v36
	v_max_f32_e32 v37, 0, v37
	v_max_f32_e32 v32, 0, v32
	v_max_f32_e32 v33, 0, v33
	v_max_f32_e32 v35, 0, v35
	v_pk_mul_f32 v[36:37], v[36:37], v[36:37]
	v_pk_mul_f32 v[38:39], v[32:33], v[32:33]
	v_pk_mul_f32 v[42:43], v[34:35], v[34:35]
	v_max_f32_e32 v24, v24, v24
	v_max_f32_e32 v25, v25, v25
	v_lshl_add_u64 v[44:45], v[120:121], 0, s[12:13]
	v_cvt_pk_bf16_f32 v32, v36, v37
	v_cvt_pk_bf16_f32 v33, v38, v39
	v_cvt_pk_bf16_f32 v34, v40, v41
	v_cvt_pk_bf16_f32 v35, v42, v43
	v_max_f32_e32 v24, 0, v24
	v_max_f32_e32 v25, 0, v25
	global_store_dwordx4 v[44:45], v[32:35], off offset:256
	v_max_f32_e32 v28, v28, v28
	v_max_f32_e32 v29, v29, v29
	v_pk_mul_f32 v[32:33], v[24:25], v[24:25]
	v_max_f32_e32 v25, v26, v26
	v_max_f32_e32 v24, v30, v30
	v_max_f32_e32 v26, 0, v25
	v_max_f32_e32 v25, v31, v31
	v_max_f32_e32 v24, 0, v24
	v_max_f32_e32 v25, 0, v25
	v_max_f32_e32 v27, v27, v27
	v_max_f32_e32 v28, 0, v28
	v_max_f32_e32 v29, 0, v29
	v_max_f32_e32 v27, 0, v27
	v_pk_mul_f32 v[30:31], v[24:25], v[24:25]
	v_pk_mul_f32 v[28:29], v[28:29], v[28:29]
	v_pk_mul_f32 v[34:35], v[26:27], v[26:27]
	v_cvt_pk_bf16_f32 v25, v30, v31
	v_add_co_u32_e32 v30, vcc, s72, v120
	v_max_f32_e32 v16, v16, v16
	v_max_f32_e32 v17, v17, v17
	v_cvt_pk_bf16_f32 v24, v28, v29
	v_cvt_pk_bf16_f32 v26, v32, v33
	v_cvt_pk_bf16_f32 v27, v34, v35
	v_addc_co_u32_e32 v31, vcc, 0, v121, vcc
	v_max_f32_e32 v16, 0, v16
	v_max_f32_e32 v17, 0, v17
	global_store_dwordx4 v[30:31], v[24:27], off
	v_max_f32_e32 v20, v20, v20
	v_max_f32_e32 v21, v21, v21
	v_pk_mul_f32 v[24:25], v[16:17], v[16:17]
	v_max_f32_e32 v17, v18, v18
	v_max_f32_e32 v16, v22, v22
	v_max_f32_e32 v18, 0, v17
	v_max_f32_e32 v17, v23, v23
	v_max_f32_e32 v19, v19, v19
	v_max_f32_e32 v20, 0, v20
	v_max_f32_e32 v21, 0, v21
	v_max_f32_e32 v16, 0, v16
	v_max_f32_e32 v17, 0, v17
	v_max_f32_e32 v19, 0, v19
	v_pk_mul_f32 v[20:21], v[20:21], v[20:21]
	v_pk_mul_f32 v[22:23], v[16:17], v[16:17]
	v_pk_mul_f32 v[26:27], v[18:19], v[18:19]
	v_max_f32_e32 v8, v8, v8
	v_max_f32_e32 v9, v9, v9
	v_lshl_add_u64 v[28:29], v[120:121], 0, s[14:15]
	v_cvt_pk_bf16_f32 v16, v20, v21
	v_cvt_pk_bf16_f32 v17, v22, v23
	v_cvt_pk_bf16_f32 v18, v24, v25
	v_cvt_pk_bf16_f32 v19, v26, v27
	v_max_f32_e32 v8, 0, v8
	v_max_f32_e32 v9, 0, v9
	global_store_dwordx4 v[28:29], v[16:19], off offset:256
	v_max_f32_e32 v12, v12, v12
	v_max_f32_e32 v13, v13, v13
	v_pk_mul_f32 v[16:17], v[8:9], v[8:9]
	v_max_f32_e32 v9, v10, v10
	v_max_f32_e32 v8, v14, v14
	v_max_f32_e32 v10, 0, v9
	v_max_f32_e32 v9, v15, v15
	v_max_f32_e32 v8, 0, v8
	v_max_f32_e32 v9, 0, v9
	v_max_f32_e32 v11, v11, v11
	v_max_f32_e32 v12, 0, v12
	v_max_f32_e32 v13, 0, v13
	v_max_f32_e32 v11, 0, v11
	v_pk_mul_f32 v[14:15], v[8:9], v[8:9]
	v_pk_mul_f32 v[12:13], v[12:13], v[12:13]
	v_pk_mul_f32 v[18:19], v[10:11], v[10:11]
	v_cvt_pk_bf16_f32 v9, v14, v15
	v_add_co_u32_e32 v14, vcc, s73, v120
	v_max_f32_e32 v0, v0, v0
	v_max_f32_e32 v1, v1, v1
	v_cvt_pk_bf16_f32 v8, v12, v13
	v_cvt_pk_bf16_f32 v10, v16, v17
	v_cvt_pk_bf16_f32 v11, v18, v19
	v_addc_co_u32_e32 v15, vcc, 0, v121, vcc
	v_max_f32_e32 v0, 0, v0
	v_max_f32_e32 v1, 0, v1
	global_store_dwordx4 v[14:15], v[8:11], off
	v_max_f32_e32 v4, v4, v4
	v_max_f32_e32 v5, v5, v5
	v_pk_mul_f32 v[8:9], v[0:1], v[0:1]
	v_max_f32_e32 v1, v2, v2
	v_max_f32_e32 v0, v6, v6
	v_max_f32_e32 v2, 0, v1
	v_max_f32_e32 v1, v7, v7
	v_max_f32_e32 v3, v3, v3
	v_max_f32_e32 v4, 0, v4
	v_max_f32_e32 v5, 0, v5
	v_max_f32_e32 v0, 0, v0
	v_max_f32_e32 v1, 0, v1
	v_max_f32_e32 v3, 0, v3
	v_pk_mul_f32 v[4:5], v[4:5], v[4:5]
	v_pk_mul_f32 v[6:7], v[0:1], v[0:1]
	v_pk_mul_f32 v[10:11], v[2:3], v[2:3]
	v_lshl_add_u64 v[12:13], v[120:121], 0, s[16:17]
	v_cvt_pk_bf16_f32 v0, v4, v5
	v_cvt_pk_bf16_f32 v1, v6, v7
	v_cvt_pk_bf16_f32 v2, v8, v9
	v_cvt_pk_bf16_f32 v3, v10, v11
	s_and_b64 vcc, exec, s[4:5]
	s_mov_b32 s74, s18
	s_mov_b32 s30, s20
	s_mov_b64 s[36:37], s[28:29]
	s_mov_b64 s[34:35], s[26:27]
	global_store_dwordx4 v[12:13], v[0:3], off offset:256
	s_cbranch_vccz .LBB0_1284
	s_waitcnt vmcnt(0)
	s_cmpk_gt_u32 s40, 0xff
	s_cbranch_scc1 .LBB0_1295
	s_barrier

.LBB0_1310:
	ds_read_b128 v[154:157], v151
	ds_read_b128 v[158:161], v151 offset:1024
	ds_read_b128 v[162:165], v151 offset:2048
	ds_read_b128 v[166:169], v151 offset:3072
	s_add_u32 s38, s36, 0xfffc0080
	s_addc_u32 s39, s37, -1
	s_cmp_eq_u32 s77, 12
	s_cselect_b32 s41, s27, s39
	s_cselect_b32 s40, s73, s38
	s_cselect_b32 s39, s21, s76
	s_cselect_b32 s38, s74, s75
	v_lshl_add_u64 v[202:203], s[36:37], 0, v[138:139]
	s_add_i32 m0, s35, 0xc000
	ds_read_b128 v[170:173], v152
	ds_read_b128 v[174:177], v152 offset:1024
	ds_read_b128 v[178:181], v152 offset:2048
	ds_read_b128 v[182:185], v152 offset:3072
	ds_read_b128 v[186:189], v152 offset:4096
	ds_read_b128 v[190:193], v152 offset:5120
	ds_read_b128 v[194:197], v152 offset:6144
	ds_read_b128 v[198:201], v152 offset:7168
	global_load_lds_dwordx4 v[202:203], off
	v_lshl_add_u64 v[202:203], s[36:37], 0, v[140:141]
	s_add_i32 m0, s35, 0xe000
	s_nop 0
	global_load_lds_dwordx4 v[202:203], off
	s_waitcnt lgkmcnt(8)
	s_barrier
	s_waitcnt lgkmcnt(0)
	s_setprio 0
	s_waitcnt lgkmcnt(0)
	v_mfma_f32_16x16x32_bf16 v[124:127], v[154:157], v[170:173], v[124:127]
	v_mfma_f32_16x16x32_bf16 v[120:123], v[162:165], v[170:173], v[120:123]
	v_mfma_f32_16x16x32_bf16 v[108:111], v[154:157], v[178:181], v[108:111]
	v_mfma_f32_16x16x32_bf16 v[104:107], v[162:165], v[178:181], v[104:107]
	v_mfma_f32_16x16x32_bf16 v[92:95], v[154:157], v[186:189], v[92:95]
	v_mfma_f32_16x16x32_bf16 v[88:91], v[162:165], v[186:189], v[88:91]
	v_mfma_f32_16x16x32_bf16 v[76:79], v[154:157], v[194:197], v[76:79]
	v_mfma_f32_16x16x32_bf16 v[72:75], v[162:165], v[194:197], v[72:75]
	v_mfma_f32_16x16x32_bf16 v[124:127], v[158:161], v[174:177], v[124:127]
	v_mfma_f32_16x16x32_bf16 v[120:123], v[166:169], v[174:177], v[120:123]
	v_mfma_f32_16x16x32_bf16 v[108:111], v[158:161], v[182:185], v[108:111]
	v_mfma_f32_16x16x32_bf16 v[104:107], v[166:169], v[182:185], v[104:107]
	v_mfma_f32_16x16x32_bf16 v[92:95], v[158:161], v[190:193], v[92:95]
	v_mfma_f32_16x16x32_bf16 v[88:91], v[166:169], v[190:193], v[88:91]
	v_mfma_f32_16x16x32_bf16 v[76:79], v[158:161], v[198:201], v[76:79]
	v_mfma_f32_16x16x32_bf16 v[72:75], v[166:169], v[198:201], v[72:75]
	s_setprio 1
	s_barrier
	s_add_i32 s78, s62, s52
	v_lshl_add_u64 v[218:219], s[38:39], 0, v[132:133]
	s_mov_b32 m0, s78
	ds_read_b128 v[202:205], v153
	ds_read_b128 v[206:209], v153 offset:1024
	ds_read_b128 v[210:213], v153 offset:2048
	ds_read_b128 v[214:217], v153 offset:3072
	global_load_lds_dwordx4 v[218:219], off
	v_lshl_add_u64 v[220:221], s[38:39], 0, v[136:137]
	s_add_i32 m0, s78, 0x2000
	s_nop 0
	global_load_lds_dwordx4 v[220:221], off
	s_barrier
	s_waitcnt lgkmcnt(0)
	s_setprio 0
	s_waitcnt lgkmcnt(0)
	v_mfma_f32_16x16x32_bf16 v[116:119], v[202:205], v[170:173], v[116:119]
	v_mfma_f32_16x16x32_bf16 v[112:115], v[210:213], v[170:173], v[112:115]
	v_mfma_f32_16x16x32_bf16 v[100:103], v[202:205], v[178:181], v[100:103]
	v_mfma_f32_16x16x32_bf16 v[96:99], v[210:213], v[178:181], v[96:99]
	v_mfma_f32_16x16x32_bf16 v[84:87], v[202:205], v[186:189], v[84:87]
	v_mfma_f32_16x16x32_bf16 v[80:83], v[210:213], v[186:189], v[80:83]
	v_mfma_f32_16x16x32_bf16 v[68:71], v[202:205], v[194:197], v[68:71]
	v_mfma_f32_16x16x32_bf16 v[64:67], v[210:213], v[194:197], v[64:67]
	v_mfma_f32_16x16x32_bf16 v[116:119], v[206:209], v[174:177], v[116:119]
	v_mfma_f32_16x16x32_bf16 v[112:115], v[214:217], v[174:177], v[112:115]
	v_mfma_f32_16x16x32_bf16 v[100:103], v[206:209], v[182:185], v[100:103]
	v_mfma_f32_16x16x32_bf16 v[96:99], v[214:217], v[182:185], v[96:99]
	v_mfma_f32_16x16x32_bf16 v[84:87], v[206:209], v[190:193], v[84:87]
	v_mfma_f32_16x16x32_bf16 v[80:83], v[214:217], v[190:193], v[80:83]
	v_mfma_f32_16x16x32_bf16 v[68:71], v[206:209], v[198:201], v[68:71]
	v_mfma_f32_16x16x32_bf16 v[64:67], v[214:217], v[198:201], v[64:67]
	s_setprio 1
	s_mov_b32 m0, s35
	v_lshl_add_u64 v[222:223], s[40:41], 0, v[130:131]
	s_barrier
	ds_read_b128 v[170:173], v152 offset:16384
	ds_read_b128 v[174:177], v152 offset:17408
	ds_read_b128 v[178:181], v152 offset:18432
	ds_read_b128 v[182:185], v152 offset:19456
	ds_read_b128 v[186:189], v152 offset:20480
	ds_read_b128 v[190:193], v152 offset:21504
	ds_read_b128 v[194:197], v152 offset:22528
	ds_read_b128 v[198:201], v152 offset:23552
	global_load_lds_dwordx4 v[222:223], off
	v_lshl_add_u64 v[224:225], s[40:41], 0, v[134:135]
	s_mov_b32 m0, s53
	s_nop 0
	global_load_lds_dwordx4 v[224:225], off
	s_barrier
	s_waitcnt lgkmcnt(0)
	s_setprio 0
	s_waitcnt lgkmcnt(0)
	v_mfma_f32_16x16x32_bf16 v[60:63], v[154:157], v[170:173], v[60:63]
	v_mfma_f32_16x16x32_bf16 v[56:59], v[162:165], v[170:173], v[56:59]
	v_mfma_f32_16x16x32_bf16 v[44:47], v[154:157], v[178:181], v[44:47]
	v_mfma_f32_16x16x32_bf16 v[40:43], v[162:165], v[178:181], v[40:43]
	v_mfma_f32_16x16x32_bf16 v[28:31], v[154:157], v[186:189], v[28:31]
	v_mfma_f32_16x16x32_bf16 v[24:27], v[162:165], v[186:189], v[24:27]
	v_mfma_f32_16x16x32_bf16 v[12:15], v[154:157], v[194:197], v[12:15]
	v_mfma_f32_16x16x32_bf16 v[8:11], v[162:165], v[194:197], v[8:11]
	v_mfma_f32_16x16x32_bf16 v[60:63], v[158:161], v[174:177], v[60:63]
	v_mfma_f32_16x16x32_bf16 v[56:59], v[166:169], v[174:177], v[56:59]
	v_mfma_f32_16x16x32_bf16 v[44:47], v[158:161], v[182:185], v[44:47]
	v_mfma_f32_16x16x32_bf16 v[40:43], v[166:169], v[182:185], v[40:43]
	v_mfma_f32_16x16x32_bf16 v[28:31], v[158:161], v[190:193], v[28:31]
	v_mfma_f32_16x16x32_bf16 v[24:27], v[166:169], v[190:193], v[24:27]
	v_mfma_f32_16x16x32_bf16 v[12:15], v[158:161], v[198:201], v[12:15]
	v_mfma_f32_16x16x32_bf16 v[8:11], v[166:169], v[198:201], v[8:11]
	s_setprio 1
	s_barrier
	s_add_u32 s78, s38, 0x40000
	s_addc_u32 s79, s39, 0
	s_add_i32 s80, s63, s52
	v_lshl_add_u64 v[154:155], s[78:79], 0, v[132:133]
	s_mov_b32 m0, s80
	s_nop 0
	global_load_lds_dwordx4 v[154:155], off
	v_lshl_add_u64 v[154:155], s[78:79], 0, v[136:137]
	s_add_i32 m0, s80, 0x2000
	s_nop 0
	global_load_lds_dwordx4 v[154:155], off
	s_waitcnt vmcnt(6)
	s_barrier
	s_setprio 0
	v_mfma_f32_16x16x32_bf16 v[52:55], v[202:205], v[170:173], v[52:55]
	v_mfma_f32_16x16x32_bf16 v[48:51], v[210:213], v[170:173], v[48:51]
	v_mfma_f32_16x16x32_bf16 v[36:39], v[202:205], v[178:181], v[36:39]
	v_mfma_f32_16x16x32_bf16 v[32:35], v[210:213], v[178:181], v[32:35]
	v_mfma_f32_16x16x32_bf16 v[20:23], v[202:205], v[186:189], v[20:23]
	v_mfma_f32_16x16x32_bf16 v[16:19], v[210:213], v[186:189], v[16:19]
	v_mfma_f32_16x16x32_bf16 v[4:7], v[202:205], v[194:197], v[4:7]
	v_mfma_f32_16x16x32_bf16 v[0:3], v[210:213], v[194:197], v[0:3]
	v_mfma_f32_16x16x32_bf16 v[52:55], v[206:209], v[174:177], v[52:55]
	v_mfma_f32_16x16x32_bf16 v[48:51], v[214:217], v[174:177], v[48:51]
	v_mfma_f32_16x16x32_bf16 v[36:39], v[206:209], v[182:185], v[36:39]
	v_mfma_f32_16x16x32_bf16 v[32:35], v[214:217], v[182:185], v[32:35]
	v_mfma_f32_16x16x32_bf16 v[20:23], v[206:209], v[190:193], v[20:23]
	v_mfma_f32_16x16x32_bf16 v[16:19], v[214:217], v[190:193], v[16:19]
	v_mfma_f32_16x16x32_bf16 v[4:7], v[206:209], v[198:201], v[4:7]
	v_mfma_f32_16x16x32_bf16 v[0:3], v[214:217], v[198:201], v[0:3]
	s_setprio 1
	s_add_i32 s78, 0, 0x18000
	v_add_u32_e32 v166, s78, v149
	s_barrier
	ds_read_b128 v[154:157], v166
	ds_read_b128 v[158:161], v166 offset:1024
	ds_read_b128 v[162:165], v166 offset:2048
	ds_read_b128 v[166:169], v166 offset:3072
	s_add_u32 s40, s40, 0x40000
	s_addc_u32 s41, s41, 0
	s_mov_b32 m0, s54
	v_lshl_add_u64 v[202:203], s[40:41], 0, v[130:131]
	ds_read_b128 v[170:173], v152 offset:32768
	ds_read_b128 v[174:177], v152 offset:33792
	ds_read_b128 v[178:181], v152 offset:34816
	ds_read_b128 v[182:185], v152 offset:35840
	ds_read_b128 v[186:189], v152 offset:36864
	ds_read_b128 v[190:193], v152 offset:37888
	ds_read_b128 v[194:197], v152 offset:38912
	ds_read_b128 v[198:201], v152 offset:39936
	global_load_lds_dwordx4 v[202:203], off
	v_lshl_add_u64 v[202:203], s[40:41], 0, v[134:135]
	s_mov_b32 m0, s55
	s_nop 0
	global_load_lds_dwordx4 v[202:203], off
	s_waitcnt lgkmcnt(8)
	s_barrier
	s_waitcnt lgkmcnt(0)
	s_setprio 0
	s_waitcnt lgkmcnt(0)
	v_mfma_f32_16x16x32_bf16 v[124:127], v[154:157], v[170:173], v[124:127]
	v_mfma_f32_16x16x32_bf16 v[120:123], v[162:165], v[170:173], v[120:123]
	v_mfma_f32_16x16x32_bf16 v[108:111], v[154:157], v[178:181], v[108:111]
	v_mfma_f32_16x16x32_bf16 v[104:107], v[162:165], v[178:181], v[104:107]
	v_mfma_f32_16x16x32_bf16 v[92:95], v[154:157], v[186:189], v[92:95]
	v_mfma_f32_16x16x32_bf16 v[88:91], v[162:165], v[186:189], v[88:91]
	v_mfma_f32_16x16x32_bf16 v[76:79], v[154:157], v[194:197], v[76:79]
	v_mfma_f32_16x16x32_bf16 v[72:75], v[162:165], v[194:197], v[72:75]
	v_mfma_f32_16x16x32_bf16 v[124:127], v[158:161], v[174:177], v[124:127]
	v_mfma_f32_16x16x32_bf16 v[120:123], v[166:169], v[174:177], v[120:123]
	v_mfma_f32_16x16x32_bf16 v[108:111], v[158:161], v[182:185], v[108:111]
	v_mfma_f32_16x16x32_bf16 v[104:107], v[166:169], v[182:185], v[104:107]
	v_mfma_f32_16x16x32_bf16 v[92:95], v[158:161], v[190:193], v[92:95]
	v_mfma_f32_16x16x32_bf16 v[88:91], v[166:169], v[190:193], v[88:91]
	v_mfma_f32_16x16x32_bf16 v[76:79], v[158:161], v[198:201], v[76:79]
	v_mfma_f32_16x16x32_bf16 v[72:75], v[166:169], v[198:201], v[72:75]
	s_setprio 1
	s_barrier
	s_add_i32 s40, 0, 0x1c000
	s_add_i32 s41, s78, s52
	v_add_u32_e32 v214, s40, v149
	v_lshl_add_u64 v[218:219], v[218:219], 0, s[10:11]
	s_mov_b32 m0, s41
	ds_read_b128 v[202:205], v214
	ds_read_b128 v[206:209], v214 offset:1024
	ds_read_b128 v[210:213], v214 offset:2048
	ds_read_b128 v[214:217], v214 offset:3072
	global_load_lds_dwordx4 v[218:219], off
	v_lshl_add_u64 v[218:219], v[220:221], 0, s[10:11]
	s_add_i32 m0, s41, 0x2000
	s_nop 0
	global_load_lds_dwordx4 v[218:219], off
	s_barrier
	s_waitcnt lgkmcnt(0)
	s_setprio 0
	s_waitcnt lgkmcnt(0)
	v_mfma_f32_16x16x32_bf16 v[116:119], v[202:205], v[170:173], v[116:119]
	v_mfma_f32_16x16x32_bf16 v[112:115], v[210:213], v[170:173], v[112:115]
	v_mfma_f32_16x16x32_bf16 v[100:103], v[202:205], v[178:181], v[100:103]
	v_mfma_f32_16x16x32_bf16 v[96:99], v[210:213], v[178:181], v[96:99]
	v_mfma_f32_16x16x32_bf16 v[84:87], v[202:205], v[186:189], v[84:87]
	v_mfma_f32_16x16x32_bf16 v[80:83], v[210:213], v[186:189], v[80:83]
	v_mfma_f32_16x16x32_bf16 v[68:71], v[202:205], v[194:197], v[68:71]
	v_mfma_f32_16x16x32_bf16 v[64:67], v[210:213], v[194:197], v[64:67]
	v_mfma_f32_16x16x32_bf16 v[116:119], v[206:209], v[174:177], v[116:119]
	v_mfma_f32_16x16x32_bf16 v[112:115], v[214:217], v[174:177], v[112:115]
	v_mfma_f32_16x16x32_bf16 v[100:103], v[206:209], v[182:185], v[100:103]
	v_mfma_f32_16x16x32_bf16 v[96:99], v[214:217], v[182:185], v[96:99]
	v_mfma_f32_16x16x32_bf16 v[84:87], v[206:209], v[190:193], v[84:87]
	v_mfma_f32_16x16x32_bf16 v[80:83], v[214:217], v[190:193], v[80:83]
	v_mfma_f32_16x16x32_bf16 v[68:71], v[206:209], v[198:201], v[68:71]
	v_mfma_f32_16x16x32_bf16 v[64:67], v[214:217], v[198:201], v[64:67]
	s_setprio 1
	s_mov_b32 m0, s57
	v_lshl_add_u64 v[218:219], v[222:223], 0, s[10:11]
	s_barrier
	ds_read_b128 v[170:173], v152 offset:49152
	ds_read_b128 v[174:177], v152 offset:50176
	ds_read_b128 v[178:181], v152 offset:51200
	ds_read_b128 v[182:185], v152 offset:52224
	ds_read_b128 v[186:189], v152 offset:53248
	ds_read_b128 v[190:193], v152 offset:54272
	ds_read_b128 v[194:197], v152 offset:55296
	ds_read_b128 v[198:201], v152 offset:56320
	global_load_lds_dwordx4 v[218:219], off
	v_lshl_add_u64 v[218:219], v[224:225], 0, s[10:11]
	s_mov_b32 m0, s60
	s_nop 0
	global_load_lds_dwordx4 v[218:219], off
	s_barrier
	s_waitcnt lgkmcnt(0)
	s_setprio 0
	s_waitcnt lgkmcnt(0)
	v_mfma_f32_16x16x32_bf16 v[60:63], v[154:157], v[170:173], v[60:63]
	v_mfma_f32_16x16x32_bf16 v[56:59], v[162:165], v[170:173], v[56:59]
	v_mfma_f32_16x16x32_bf16 v[44:47], v[154:157], v[178:181], v[44:47]
	v_mfma_f32_16x16x32_bf16 v[40:43], v[162:165], v[178:181], v[40:43]
	v_mfma_f32_16x16x32_bf16 v[28:31], v[154:157], v[186:189], v[28:31]
	v_mfma_f32_16x16x32_bf16 v[24:27], v[162:165], v[186:189], v[24:27]
	v_mfma_f32_16x16x32_bf16 v[12:15], v[154:157], v[194:197], v[12:15]
	v_mfma_f32_16x16x32_bf16 v[8:11], v[162:165], v[194:197], v[8:11]
	v_mfma_f32_16x16x32_bf16 v[60:63], v[158:161], v[174:177], v[60:63]
	v_mfma_f32_16x16x32_bf16 v[56:59], v[166:169], v[174:177], v[56:59]
	v_mfma_f32_16x16x32_bf16 v[44:47], v[158:161], v[182:185], v[44:47]
	v_mfma_f32_16x16x32_bf16 v[40:43], v[166:169], v[182:185], v[40:43]
	v_mfma_f32_16x16x32_bf16 v[28:31], v[158:161], v[190:193], v[28:31]
	v_mfma_f32_16x16x32_bf16 v[24:27], v[166:169], v[190:193], v[24:27]
	v_mfma_f32_16x16x32_bf16 v[12:15], v[158:161], v[198:201], v[12:15]
	v_mfma_f32_16x16x32_bf16 v[8:11], v[166:169], v[198:201], v[8:11]
	s_setprio 1
	s_barrier
	s_add_u32 s38, s38, 0x40080
	s_addc_u32 s39, s39, 0
	s_add_i32 s40, s40, s52
	v_lshl_add_u64 v[154:155], s[38:39], 0, v[132:133]
	s_mov_b32 m0, s40
	s_nop 0
	global_load_lds_dwordx4 v[154:155], off
	v_lshl_add_u64 v[154:155], s[38:39], 0, v[136:137]
	s_add_i32 m0, s40, 0x2000
	s_nop 0
	global_load_lds_dwordx4 v[154:155], off
	s_waitcnt vmcnt(6)
	s_barrier
	s_setprio 0
	v_mfma_f32_16x16x32_bf16 v[52:55], v[202:205], v[170:173], v[52:55]
	v_mfma_f32_16x16x32_bf16 v[48:51], v[210:213], v[170:173], v[48:51]
	v_mfma_f32_16x16x32_bf16 v[36:39], v[202:205], v[178:181], v[36:39]
	v_mfma_f32_16x16x32_bf16 v[32:35], v[210:213], v[178:181], v[32:35]
	v_mfma_f32_16x16x32_bf16 v[20:23], v[202:205], v[186:189], v[20:23]
	v_mfma_f32_16x16x32_bf16 v[16:19], v[210:213], v[186:189], v[16:19]
	v_mfma_f32_16x16x32_bf16 v[4:7], v[202:205], v[194:197], v[4:7]
	v_mfma_f32_16x16x32_bf16 v[0:3], v[210:213], v[194:197], v[0:3]
	v_mfma_f32_16x16x32_bf16 v[52:55], v[206:209], v[174:177], v[52:55]
	v_mfma_f32_16x16x32_bf16 v[48:51], v[214:217], v[174:177], v[48:51]
	v_mfma_f32_16x16x32_bf16 v[36:39], v[206:209], v[182:185], v[36:39]
	v_mfma_f32_16x16x32_bf16 v[32:35], v[214:217], v[182:185], v[32:35]
	v_mfma_f32_16x16x32_bf16 v[20:23], v[206:209], v[190:193], v[20:23]
	v_mfma_f32_16x16x32_bf16 v[16:19], v[214:217], v[190:193], v[16:19]
	v_mfma_f32_16x16x32_bf16 v[4:7], v[206:209], v[198:201], v[4:7]
	v_mfma_f32_16x16x32_bf16 v[0:3], v[214:217], v[198:201], v[0:3]
	s_setprio 1
	s_add_i32 s77, s77, 2
	s_add_u32 s36, s36, 0x100
	s_addc_u32 s37, s37, 0
	s_add_u32 s75, s75, 0x100
	s_addc_u32 s76, s76, 0
	s_cmp_gt_u32 s77, 13
	s_barrier
	s_cbranch_scc0 .LBB0_1310
	v_lshl_add_u32 v154, s34, 8, v148
	v_max_f32_e32 v126, v126, v126
	v_max_f32_e32 v127, v127, v127
	v_lshl_or_b32 v156, s72, 8, v150
	v_ashrrev_i32_e32 v155, 31, v154
	v_max_f32_e32 v124, v124, v124
	v_max_f32_e32 v120, v120, v120
	v_max_f32_e32 v125, v125, v125
	v_max_f32_e32 v121, v121, v121
	v_max_f32_e32 v126, 0, v126
	v_max_f32_e32 v122, v122, v122
	v_max_f32_e32 v127, 0, v127
	v_max_f32_e32 v123, v123, v123
	v_lshlrev_b64 v[158:159], 13, v[154:155]
	v_max_f32_e32 v124, 0, v124
	v_max_f32_e32 v120, 0, v120
	v_max_f32_e32 v125, 0, v125
	v_max_f32_e32 v121, 0, v121
	v_max_f32_e32 v122, 0, v122
	v_max_f32_e32 v123, 0, v123
	v_pk_mul_f32 v[126:127], v[126:127], v[126:127]
	v_ashrrev_i32_e32 v157, 31, v156
	v_lshl_add_u64 v[158:159], s[46:47], 0, v[158:159]
	v_pk_mul_f32 v[124:125], v[124:125], v[124:125]
	v_pk_mul_f32 v[120:121], v[120:121], v[120:121]
	v_pk_mul_f32 v[160:161], v[122:123], v[122:123]
	v_cvt_pk_bf16_f32 v123, v126, v127
	v_lshlrev_b64 v[126:127], 1, v[156:157]
	v_max_f32_e32 v112, v112, v112
	v_max_f32_e32 v113, v113, v113
	v_cvt_pk_bf16_f32 v122, v124, v125
	v_cvt_pk_bf16_f32 v124, v120, v121
	v_cvt_pk_bf16_f32 v125, v160, v161
	v_lshl_add_u64 v[120:121], v[158:159], 0, v[126:127]
	v_max_f32_e32 v112, 0, v112
	v_max_f32_e32 v113, 0, v113
	global_store_dwordx4 v[120:121], v[122:125], off
	v_max_f32_e32 v116, v116, v116
	v_max_f32_e32 v117, v117, v117
	v_pk_mul_f32 v[122:123], v[112:113], v[112:113]
	v_max_f32_e32 v113, v114, v114
	v_max_f32_e32 v112, v118, v118
	v_max_f32_e32 v114, 0, v113
	v_max_f32_e32 v113, v119, v119
	v_max_f32_e32 v115, v115, v115
	v_max_f32_e32 v116, 0, v116
	v_max_f32_e32 v117, 0, v117
	v_max_f32_e32 v112, 0, v112
	v_max_f32_e32 v113, 0, v113
	v_max_f32_e32 v115, 0, v115
	v_pk_mul_f32 v[116:117], v[116:117], v[116:117]
	v_pk_mul_f32 v[118:119], v[112:113], v[112:113]
	v_pk_mul_f32 v[124:125], v[114:115], v[114:115]
	v_max_f32_e32 v104, v104, v104
	v_max_f32_e32 v105, v105, v105
	v_cvt_pk_bf16_f32 v112, v116, v117
	v_cvt_pk_bf16_f32 v113, v118, v119
	v_cvt_pk_bf16_f32 v114, v122, v123
	v_cvt_pk_bf16_f32 v115, v124, v125
	v_max_f32_e32 v104, 0, v104
	v_max_f32_e32 v105, 0, v105
	global_store_dwordx4 v[120:121], v[112:115], off offset:256
	v_max_f32_e32 v108, v108, v108
	v_max_f32_e32 v109, v109, v109
	v_or_b32_e32 v112, 16, v154
	v_pk_mul_f32 v[114:115], v[104:105], v[104:105]
	v_max_f32_e32 v105, v106, v106
	v_ashrrev_i32_e32 v113, 31, v112
	v_max_f32_e32 v104, v110, v110
	v_max_f32_e32 v106, 0, v105
	v_max_f32_e32 v105, v111, v111
	v_max_f32_e32 v107, v107, v107
	v_lshlrev_b64 v[112:113], 13, v[112:113]
	v_max_f32_e32 v108, 0, v108
	v_max_f32_e32 v109, 0, v109
	v_max_f32_e32 v104, 0, v104
	v_max_f32_e32 v105, 0, v105
	v_max_f32_e32 v107, 0, v107
	v_lshl_add_u64 v[112:113], s[46:47], 0, v[112:113]
	v_pk_mul_f32 v[108:109], v[108:109], v[108:109]
	v_pk_mul_f32 v[110:111], v[104:105], v[104:105]
	v_pk_mul_f32 v[116:117], v[106:107], v[106:107]
	v_max_f32_e32 v96, v96, v96
	v_max_f32_e32 v97, v97, v97
	v_cvt_pk_bf16_f32 v104, v108, v109
	v_cvt_pk_bf16_f32 v105, v110, v111
	v_cvt_pk_bf16_f32 v106, v114, v115
	v_cvt_pk_bf16_f32 v107, v116, v117
	v_lshl_add_u64 v[108:109], v[112:113], 0, v[126:127]
	v_max_f32_e32 v96, 0, v96
	v_max_f32_e32 v97, 0, v97
	global_store_dwordx4 v[108:109], v[104:107], off
	v_max_f32_e32 v100, v100, v100
	v_max_f32_e32 v101, v101, v101
	v_pk_mul_f32 v[104:105], v[96:97], v[96:97]
	v_max_f32_e32 v97, v98, v98
	v_max_f32_e32 v96, v102, v102
	v_max_f32_e32 v98, 0, v97
	v_max_f32_e32 v97, v103, v103
	v_max_f32_e32 v99, v99, v99
	v_max_f32_e32 v100, 0, v100
	v_max_f32_e32 v101, 0, v101
	v_max_f32_e32 v96, 0, v96
	v_max_f32_e32 v97, 0, v97
	v_max_f32_e32 v99, 0, v99
	v_pk_mul_f32 v[100:101], v[100:101], v[100:101]
	v_pk_mul_f32 v[102:103], v[96:97], v[96:97]
	v_pk_mul_f32 v[106:107], v[98:99], v[98:99]
	v_max_f32_e32 v88, v88, v88
	v_max_f32_e32 v89, v89, v89
	v_cvt_pk_bf16_f32 v96, v100, v101
	v_cvt_pk_bf16_f32 v97, v102, v103
	v_cvt_pk_bf16_f32 v98, v104, v105
	v_cvt_pk_bf16_f32 v99, v106, v107
	v_max_f32_e32 v88, 0, v88
	v_max_f32_e32 v89, 0, v89
	global_store_dwordx4 v[108:109], v[96:99], off offset:256
	v_max_f32_e32 v92, v92, v92
	v_max_f32_e32 v93, v93, v93
	v_or_b32_e32 v96, 32, v154
	v_pk_mul_f32 v[98:99], v[88:89], v[88:89]
	v_max_f32_e32 v89, v90, v90
	v_ashrrev_i32_e32 v97, 31, v96
	v_max_f32_e32 v88, v94, v94
	v_max_f32_e32 v90, 0, v89
	v_max_f32_e32 v89, v95, v95
	v_max_f32_e32 v91, v91, v91
	v_lshlrev_b64 v[96:97], 13, v[96:97]
	v_max_f32_e32 v92, 0, v92
	v_max_f32_e32 v93, 0, v93
	v_max_f32_e32 v88, 0, v88
	v_max_f32_e32 v89, 0, v89
	v_max_f32_e32 v91, 0, v91
	v_lshl_add_u64 v[96:97], s[46:47], 0, v[96:97]
	v_pk_mul_f32 v[92:93], v[92:93], v[92:93]
	v_pk_mul_f32 v[94:95], v[88:89], v[88:89]
	v_pk_mul_f32 v[100:101], v[90:91], v[90:91]
	v_max_f32_e32 v80, v80, v80
	v_max_f32_e32 v81, v81, v81
	v_cvt_pk_bf16_f32 v88, v92, v93
	v_cvt_pk_bf16_f32 v89, v94, v95
	v_cvt_pk_bf16_f32 v90, v98, v99
	v_cvt_pk_bf16_f32 v91, v100, v101
	v_lshl_add_u64 v[92:93], v[96:97], 0, v[126:127]
	v_max_f32_e32 v80, 0, v80
	v_max_f32_e32 v81, 0, v81
	global_store_dwordx4 v[92:93], v[88:91], off
	v_max_f32_e32 v84, v84, v84
	v_max_f32_e32 v85, v85, v85
	v_pk_mul_f32 v[88:89], v[80:81], v[80:81]
	v_max_f32_e32 v81, v82, v82
	v_max_f32_e32 v80, v86, v86
	v_max_f32_e32 v82, 0, v81
	v_max_f32_e32 v81, v87, v87
	v_max_f32_e32 v83, v83, v83
	v_max_f32_e32 v84, 0, v84
	v_max_f32_e32 v85, 0, v85
	v_max_f32_e32 v80, 0, v80
	v_max_f32_e32 v81, 0, v81
	v_max_f32_e32 v83, 0, v83
	v_pk_mul_f32 v[84:85], v[84:85], v[84:85]
	v_pk_mul_f32 v[86:87], v[80:81], v[80:81]
	v_pk_mul_f32 v[90:91], v[82:83], v[82:83]
	v_max_f32_e32 v72, v72, v72
	v_max_f32_e32 v73, v73, v73
	v_cvt_pk_bf16_f32 v80, v84, v85
	v_cvt_pk_bf16_f32 v81, v86, v87
	v_cvt_pk_bf16_f32 v82, v88, v89
	v_cvt_pk_bf16_f32 v83, v90, v91
	v_max_f32_e32 v72, 0, v72
	v_max_f32_e32 v73, 0, v73
	global_store_dwordx4 v[92:93], v[80:83], off offset:256
	v_max_f32_e32 v76, v76, v76
	v_max_f32_e32 v77, v77, v77
	v_or_b32_e32 v80, 48, v154
	v_pk_mul_f32 v[82:83], v[72:73], v[72:73]
	v_max_f32_e32 v73, v74, v74
	v_ashrrev_i32_e32 v81, 31, v80
	v_max_f32_e32 v72, v78, v78
	v_max_f32_e32 v74, 0, v73
	v_max_f32_e32 v73, v79, v79
	v_max_f32_e32 v75, v75, v75
	v_lshlrev_b64 v[80:81], 13, v[80:81]
	v_max_f32_e32 v76, 0, v76
	v_max_f32_e32 v77, 0, v77
	v_max_f32_e32 v72, 0, v72
	v_max_f32_e32 v73, 0, v73
	v_max_f32_e32 v75, 0, v75
	v_lshl_add_u64 v[80:81], s[46:47], 0, v[80:81]
	v_pk_mul_f32 v[76:77], v[76:77], v[76:77]
	v_pk_mul_f32 v[78:79], v[72:73], v[72:73]
	v_pk_mul_f32 v[84:85], v[74:75], v[74:75]
	v_max_f32_e32 v64, v64, v64
	v_max_f32_e32 v65, v65, v65
	v_cvt_pk_bf16_f32 v72, v76, v77
	v_cvt_pk_bf16_f32 v73, v78, v79
	v_cvt_pk_bf16_f32 v74, v82, v83
	v_cvt_pk_bf16_f32 v75, v84, v85
	v_lshl_add_u64 v[76:77], v[80:81], 0, v[126:127]
	v_max_f32_e32 v64, 0, v64
	v_max_f32_e32 v65, 0, v65
	global_store_dwordx4 v[76:77], v[72:75], off
	v_max_f32_e32 v68, v68, v68
	v_max_f32_e32 v69, v69, v69
	v_pk_mul_f32 v[72:73], v[64:65], v[64:65]
	v_max_f32_e32 v65, v66, v66
	v_max_f32_e32 v64, v70, v70
	v_max_f32_e32 v66, 0, v65
	v_max_f32_e32 v65, v71, v71
	v_max_f32_e32 v67, v67, v67
	v_max_f32_e32 v68, 0, v68
	v_max_f32_e32 v69, 0, v69
	v_max_f32_e32 v64, 0, v64
	v_max_f32_e32 v65, 0, v65
	v_max_f32_e32 v67, 0, v67
	v_pk_mul_f32 v[68:69], v[68:69], v[68:69]
	v_pk_mul_f32 v[70:71], v[64:65], v[64:65]
	v_pk_mul_f32 v[74:75], v[66:67], v[66:67]
	v_max_f32_e32 v56, v56, v56
	v_max_f32_e32 v57, v57, v57
	v_cvt_pk_bf16_f32 v64, v68, v69
	v_cvt_pk_bf16_f32 v65, v70, v71
	v_cvt_pk_bf16_f32 v66, v72, v73
	v_cvt_pk_bf16_f32 v67, v74, v75
	v_max_f32_e32 v56, 0, v56
	v_max_f32_e32 v57, 0, v57
	global_store_dwordx4 v[76:77], v[64:67], off offset:256
	v_max_f32_e32 v60, v60, v60
	v_max_f32_e32 v61, v61, v61
	v_pk_mul_f32 v[64:65], v[56:57], v[56:57]
	v_max_f32_e32 v57, v58, v58
	v_max_f32_e32 v56, v62, v62
	v_max_f32_e32 v58, 0, v57
	v_max_f32_e32 v57, v63, v63
	v_max_f32_e32 v56, 0, v56
	v_max_f32_e32 v57, 0, v57
	v_max_f32_e32 v59, v59, v59
	v_max_f32_e32 v60, 0, v60
	v_max_f32_e32 v61, 0, v61
	v_max_f32_e32 v59, 0, v59
	v_pk_mul_f32 v[62:63], v[56:57], v[56:57]
	v_pk_mul_f32 v[60:61], v[60:61], v[60:61]
	v_pk_mul_f32 v[66:67], v[58:59], v[58:59]
	v_cvt_pk_bf16_f32 v57, v62, v63
	v_add_co_u32_e32 v62, vcc, s64, v120
	v_max_f32_e32 v48, v48, v48
	v_max_f32_e32 v49, v49, v49
	v_cvt_pk_bf16_f32 v56, v60, v61
	v_cvt_pk_bf16_f32 v58, v64, v65
	v_cvt_pk_bf16_f32 v59, v66, v67
	v_addc_co_u32_e32 v63, vcc, 0, v121, vcc
	v_max_f32_e32 v48, 0, v48
	v_max_f32_e32 v49, 0, v49
	global_store_dwordx4 v[62:63], v[56:59], off
	v_max_f32_e32 v52, v52, v52
	v_max_f32_e32 v53, v53, v53
	v_pk_mul_f32 v[56:57], v[48:49], v[48:49]
	v_max_f32_e32 v49, v50, v50
	v_max_f32_e32 v48, v54, v54
	v_max_f32_e32 v50, 0, v49
	v_max_f32_e32 v49, v55, v55
	v_max_f32_e32 v51, v51, v51
	v_max_f32_e32 v52, 0, v52
	v_max_f32_e32 v53, 0, v53
	v_max_f32_e32 v48, 0, v48
	v_max_f32_e32 v49, 0, v49
	v_max_f32_e32 v51, 0, v51
	v_pk_mul_f32 v[52:53], v[52:53], v[52:53]
	v_pk_mul_f32 v[54:55], v[48:49], v[48:49]
	v_pk_mul_f32 v[58:59], v[50:51], v[50:51]
	v_max_f32_e32 v40, v40, v40
	v_max_f32_e32 v41, v41, v41
	v_lshl_add_u64 v[60:61], v[120:121], 0, s[12:13]
	v_cvt_pk_bf16_f32 v48, v52, v53
	v_cvt_pk_bf16_f32 v49, v54, v55
	v_cvt_pk_bf16_f32 v50, v56, v57
	v_cvt_pk_bf16_f32 v51, v58, v59
	v_max_f32_e32 v40, 0, v40
	v_max_f32_e32 v41, 0, v41
	global_store_dwordx4 v[60:61], v[48:51], off offset:256
	v_max_f32_e32 v44, v44, v44
	v_max_f32_e32 v45, v45, v45
	v_pk_mul_f32 v[48:49], v[40:41], v[40:41]
	v_max_f32_e32 v41, v42, v42
	v_max_f32_e32 v40, v46, v46
	v_max_f32_e32 v42, 0, v41
	v_max_f32_e32 v41, v47, v47
	v_max_f32_e32 v40, 0, v40
	v_max_f32_e32 v41, 0, v41
	v_max_f32_e32 v43, v43, v43
	v_max_f32_e32 v44, 0, v44
	v_max_f32_e32 v45, 0, v45
	v_max_f32_e32 v43, 0, v43
	v_pk_mul_f32 v[46:47], v[40:41], v[40:41]
	v_pk_mul_f32 v[44:45], v[44:45], v[44:45]
	v_pk_mul_f32 v[50:51], v[42:43], v[42:43]
	v_cvt_pk_bf16_f32 v41, v46, v47
	v_add_co_u32_e32 v46, vcc, s65, v120
	v_max_f32_e32 v32, v32, v32
	v_max_f32_e32 v33, v33, v33
	v_cvt_pk_bf16_f32 v40, v44, v45
	v_cvt_pk_bf16_f32 v42, v48, v49
	v_cvt_pk_bf16_f32 v43, v50, v51
	v_addc_co_u32_e32 v47, vcc, 0, v121, vcc
	v_max_f32_e32 v32, 0, v32
	v_max_f32_e32 v33, 0, v33
	global_store_dwordx4 v[46:47], v[40:43], off
	v_max_f32_e32 v36, v36, v36
	v_max_f32_e32 v37, v37, v37
	v_pk_mul_f32 v[40:41], v[32:33], v[32:33]
	v_max_f32_e32 v33, v34, v34
	v_max_f32_e32 v32, v38, v38
	v_max_f32_e32 v34, 0, v33
	v_max_f32_e32 v33, v39, v39
	v_max_f32_e32 v35, v35, v35
	v_max_f32_e32 v36, 0, v36
	v_max_f32_e32 v37, 0, v37
	v_max_f32_e32 v32, 0, v32
	v_max_f32_e32 v33, 0, v33
	v_max_f32_e32 v35, 0, v35
	v_pk_mul_f32 v[36:37], v[36:37], v[36:37]
	v_pk_mul_f32 v[38:39], v[32:33], v[32:33]
	v_pk_mul_f32 v[42:43], v[34:35], v[34:35]
	v_max_f32_e32 v24, v24, v24
	v_max_f32_e32 v25, v25, v25
	v_lshl_add_u64 v[44:45], v[120:121], 0, s[14:15]
	v_cvt_pk_bf16_f32 v32, v36, v37
	v_cvt_pk_bf16_f32 v33, v38, v39
	v_cvt_pk_bf16_f32 v34, v40, v41
	v_cvt_pk_bf16_f32 v35, v42, v43
	v_max_f32_e32 v24, 0, v24
	v_max_f32_e32 v25, 0, v25
	global_store_dwordx4 v[44:45], v[32:35], off offset:256
	v_max_f32_e32 v28, v28, v28
	v_max_f32_e32 v29, v29, v29
	v_pk_mul_f32 v[32:33], v[24:25], v[24:25]
	v_max_f32_e32 v25, v26, v26
	v_max_f32_e32 v24, v30, v30
	v_max_f32_e32 v26, 0, v25
	v_max_f32_e32 v25, v31, v31
	v_max_f32_e32 v24, 0, v24
	v_max_f32_e32 v25, 0, v25
	v_max_f32_e32 v27, v27, v27
	v_max_f32_e32 v28, 0, v28
	v_max_f32_e32 v29, 0, v29
	v_max_f32_e32 v27, 0, v27
	v_pk_mul_f32 v[30:31], v[24:25], v[24:25]
	v_pk_mul_f32 v[28:29], v[28:29], v[28:29]
	v_pk_mul_f32 v[34:35], v[26:27], v[26:27]
	v_cvt_pk_bf16_f32 v25, v30, v31
	v_add_co_u32_e32 v30, vcc, s70, v120
	v_max_f32_e32 v16, v16, v16
	v_max_f32_e32 v17, v17, v17
	v_cvt_pk_bf16_f32 v24, v28, v29
	v_cvt_pk_bf16_f32 v26, v32, v33
	v_cvt_pk_bf16_f32 v27, v34, v35
	v_addc_co_u32_e32 v31, vcc, 0, v121, vcc
	v_max_f32_e32 v16, 0, v16
	v_max_f32_e32 v17, 0, v17
	global_store_dwordx4 v[30:31], v[24:27], off
	v_max_f32_e32 v20, v20, v20
	v_max_f32_e32 v21, v21, v21
	v_pk_mul_f32 v[24:25], v[16:17], v[16:17]
	v_max_f32_e32 v17, v18, v18
	v_max_f32_e32 v16, v22, v22
	v_max_f32_e32 v18, 0, v17
	v_max_f32_e32 v17, v23, v23
	v_max_f32_e32 v19, v19, v19
	v_max_f32_e32 v20, 0, v20
	v_max_f32_e32 v21, 0, v21
	v_max_f32_e32 v16, 0, v16
	v_max_f32_e32 v17, 0, v17
	v_max_f32_e32 v19, 0, v19
	v_pk_mul_f32 v[20:21], v[20:21], v[20:21]
	v_pk_mul_f32 v[22:23], v[16:17], v[16:17]
	v_pk_mul_f32 v[26:27], v[18:19], v[18:19]
	v_max_f32_e32 v8, v8, v8
	v_max_f32_e32 v9, v9, v9
	v_lshl_add_u64 v[28:29], v[120:121], 0, s[16:17]
	v_cvt_pk_bf16_f32 v16, v20, v21
	v_cvt_pk_bf16_f32 v17, v22, v23
	v_cvt_pk_bf16_f32 v18, v24, v25
	v_cvt_pk_bf16_f32 v19, v26, v27
	v_max_f32_e32 v8, 0, v8
	v_max_f32_e32 v9, 0, v9
	global_store_dwordx4 v[28:29], v[16:19], off offset:256
	v_max_f32_e32 v12, v12, v12
	v_max_f32_e32 v13, v13, v13
	v_pk_mul_f32 v[16:17], v[8:9], v[8:9]
	v_max_f32_e32 v9, v10, v10
	v_max_f32_e32 v8, v14, v14
	v_max_f32_e32 v10, 0, v9
	v_max_f32_e32 v9, v15, v15
	v_max_f32_e32 v8, 0, v8
	v_max_f32_e32 v9, 0, v9
	v_max_f32_e32 v11, v11, v11
	v_max_f32_e32 v12, 0, v12
	v_max_f32_e32 v13, 0, v13
	v_max_f32_e32 v11, 0, v11
	v_pk_mul_f32 v[14:15], v[8:9], v[8:9]
	v_pk_mul_f32 v[12:13], v[12:13], v[12:13]
	v_pk_mul_f32 v[18:19], v[10:11], v[10:11]
	v_cvt_pk_bf16_f32 v9, v14, v15
	v_add_co_u32_e32 v14, vcc, s71, v120
	v_max_f32_e32 v0, v0, v0
	v_max_f32_e32 v1, v1, v1
	v_cvt_pk_bf16_f32 v8, v12, v13
	v_cvt_pk_bf16_f32 v10, v16, v17
	v_cvt_pk_bf16_f32 v11, v18, v19
	v_addc_co_u32_e32 v15, vcc, 0, v121, vcc
	v_max_f32_e32 v0, 0, v0
	v_max_f32_e32 v1, 0, v1
	global_store_dwordx4 v[14:15], v[8:11], off
	v_max_f32_e32 v4, v4, v4
	v_max_f32_e32 v5, v5, v5
	v_pk_mul_f32 v[8:9], v[0:1], v[0:1]
	v_max_f32_e32 v1, v2, v2
	v_max_f32_e32 v0, v6, v6
	v_max_f32_e32 v2, 0, v1
	v_max_f32_e32 v1, v7, v7
	v_max_f32_e32 v3, v3, v3
	v_max_f32_e32 v4, 0, v4
	v_max_f32_e32 v5, 0, v5
	v_max_f32_e32 v0, 0, v0
	v_max_f32_e32 v1, 0, v1
	v_max_f32_e32 v3, 0, v3
	v_pk_mul_f32 v[4:5], v[4:5], v[4:5]
	v_pk_mul_f32 v[6:7], v[0:1], v[0:1]
	v_pk_mul_f32 v[10:11], v[2:3], v[2:3]
	v_lshl_add_u64 v[12:13], v[120:121], 0, s[18:19]
	v_cvt_pk_bf16_f32 v0, v4, v5
	v_cvt_pk_bf16_f32 v1, v6, v7
	v_cvt_pk_bf16_f32 v2, v8, v9
	v_cvt_pk_bf16_f32 v3, v10, v11
	s_and_b64 vcc, exec, s[4:5]
	s_mov_b32 s72, s20
	s_mov_b32 s34, s26
	s_mov_b64 s[38:39], s[30:31]
	s_mov_b64 s[36:37], s[28:29]
	global_store_dwordx4 v[12:13], v[0:3], off offset:256
	s_cbranch_vccz .LBB0_1303
	s_waitcnt vmcnt(0)
	s_cmpk_gt_u32 s42, 0xff
	s_cbranch_scc1 .LBB0_1314
	s_barrier

.LBB0_1384:
	ds_read_b128 v[156:159], v153
	ds_read_b128 v[160:163], v153 offset:1024
	ds_read_b128 v[164:167], v153 offset:2048
	ds_read_b128 v[168:171], v153 offset:3072
	s_add_u32 s36, s34, 0xfff00080
	s_addc_u32 s37, s35, -1
	s_cmp_eq_u32 s77, 60
	s_cselect_b32 s39, s27, s37
	s_cselect_b32 s38, s73, s36
	s_cselect_b32 s37, s21, s76
	s_cselect_b32 s36, s74, s75
	v_lshl_add_u64 v[204:205], s[34:35], 0, v[138:139]
	s_add_i32 m0, s19, 0xc000
	ds_read_b128 v[172:175], v154
	ds_read_b128 v[176:179], v154 offset:1024
	ds_read_b128 v[180:183], v154 offset:2048
	ds_read_b128 v[184:187], v154 offset:3072
	ds_read_b128 v[188:191], v154 offset:4096
	ds_read_b128 v[192:195], v154 offset:5120
	ds_read_b128 v[196:199], v154 offset:6144
	ds_read_b128 v[200:203], v154 offset:7168
	global_load_lds_dwordx4 v[204:205], off
	v_lshl_add_u64 v[204:205], s[34:35], 0, v[140:141]
	s_add_i32 m0, s19, 0xe000
	s_nop 0
	global_load_lds_dwordx4 v[204:205], off
	s_waitcnt lgkmcnt(8)
	s_barrier
	s_waitcnt lgkmcnt(0)
	s_setprio 0
	s_waitcnt lgkmcnt(0)
	v_mfma_f32_16x16x32_bf16 v[124:127], v[156:159], v[172:175], v[124:127]
	v_mfma_f32_16x16x32_bf16 v[120:123], v[164:167], v[172:175], v[120:123]
	v_mfma_f32_16x16x32_bf16 v[116:119], v[156:159], v[180:183], v[116:119]
	v_mfma_f32_16x16x32_bf16 v[112:115], v[164:167], v[180:183], v[112:115]
	v_mfma_f32_16x16x32_bf16 v[100:103], v[156:159], v[188:191], v[100:103]
	v_mfma_f32_16x16x32_bf16 v[96:99], v[164:167], v[188:191], v[96:99]
	v_mfma_f32_16x16x32_bf16 v[84:87], v[156:159], v[196:199], v[84:87]
	v_mfma_f32_16x16x32_bf16 v[80:83], v[164:167], v[196:199], v[80:83]
	v_mfma_f32_16x16x32_bf16 v[124:127], v[160:163], v[176:179], v[124:127]
	v_mfma_f32_16x16x32_bf16 v[120:123], v[168:171], v[176:179], v[120:123]
	v_mfma_f32_16x16x32_bf16 v[116:119], v[160:163], v[184:187], v[116:119]
	v_mfma_f32_16x16x32_bf16 v[112:115], v[168:171], v[184:187], v[112:115]
	v_mfma_f32_16x16x32_bf16 v[100:103], v[160:163], v[192:195], v[100:103]
	v_mfma_f32_16x16x32_bf16 v[96:99], v[168:171], v[192:195], v[96:99]
	v_mfma_f32_16x16x32_bf16 v[84:87], v[160:163], v[200:203], v[84:87]
	v_mfma_f32_16x16x32_bf16 v[80:83], v[168:171], v[200:203], v[80:83]
	s_setprio 1
	s_barrier
	s_add_i32 s78, s62, s43
	v_lshl_add_u64 v[220:221], s[36:37], 0, v[134:135]
	s_mov_b32 m0, s78
	ds_read_b128 v[204:207], v155
	ds_read_b128 v[208:211], v155 offset:1024
	ds_read_b128 v[212:215], v155 offset:2048
	ds_read_b128 v[216:219], v155 offset:3072
	global_load_lds_dwordx4 v[220:221], off
	v_lshl_add_u64 v[222:223], s[36:37], 0, v[130:131]
	s_add_i32 m0, s78, 0x2000
	s_nop 0
	global_load_lds_dwordx4 v[222:223], off
	s_barrier
	s_waitcnt lgkmcnt(0)
	s_setprio 0
	s_waitcnt lgkmcnt(0)
	v_mfma_f32_16x16x32_bf16 v[108:111], v[204:207], v[172:175], v[108:111]
	v_mfma_f32_16x16x32_bf16 v[104:107], v[212:215], v[172:175], v[104:107]
	v_mfma_f32_16x16x32_bf16 v[92:95], v[204:207], v[180:183], v[92:95]
	v_mfma_f32_16x16x32_bf16 v[88:91], v[212:215], v[180:183], v[88:91]
	v_mfma_f32_16x16x32_bf16 v[76:79], v[204:207], v[188:191], v[76:79]
	v_mfma_f32_16x16x32_bf16 v[72:75], v[212:215], v[188:191], v[72:75]
	v_mfma_f32_16x16x32_bf16 v[68:71], v[204:207], v[196:199], v[68:71]
	v_mfma_f32_16x16x32_bf16 v[64:67], v[212:215], v[196:199], v[64:67]
	v_mfma_f32_16x16x32_bf16 v[108:111], v[208:211], v[176:179], v[108:111]
	v_mfma_f32_16x16x32_bf16 v[104:107], v[216:219], v[176:179], v[104:107]
	v_mfma_f32_16x16x32_bf16 v[92:95], v[208:211], v[184:187], v[92:95]
	v_mfma_f32_16x16x32_bf16 v[88:91], v[216:219], v[184:187], v[88:91]
	v_mfma_f32_16x16x32_bf16 v[76:79], v[208:211], v[192:195], v[76:79]
	v_mfma_f32_16x16x32_bf16 v[72:75], v[216:219], v[192:195], v[72:75]
	v_mfma_f32_16x16x32_bf16 v[68:71], v[208:211], v[200:203], v[68:71]
	v_mfma_f32_16x16x32_bf16 v[64:67], v[216:219], v[200:203], v[64:67]
	s_setprio 1
	s_mov_b32 m0, s19
	v_lshl_add_u64 v[224:225], s[38:39], 0, v[136:137]
	s_barrier
	ds_read_b128 v[172:175], v154 offset:16384
	ds_read_b128 v[176:179], v154 offset:17408
	ds_read_b128 v[180:183], v154 offset:18432
	ds_read_b128 v[184:187], v154 offset:19456
	ds_read_b128 v[188:191], v154 offset:20480
	ds_read_b128 v[192:195], v154 offset:21504
	ds_read_b128 v[196:199], v154 offset:22528
	ds_read_b128 v[200:203], v154 offset:23552
	global_load_lds_dwordx4 v[224:225], off
	v_lshl_add_u64 v[226:227], s[38:39], 0, v[132:133]
	s_mov_b32 m0, s53
	s_nop 0
	global_load_lds_dwordx4 v[226:227], off
	s_barrier
	s_waitcnt lgkmcnt(0)
	s_setprio 0
	s_waitcnt lgkmcnt(0)
	v_mfma_f32_16x16x32_bf16 v[60:63], v[156:159], v[172:175], v[60:63]
	v_mfma_f32_16x16x32_bf16 v[56:59], v[164:167], v[172:175], v[56:59]
	v_mfma_f32_16x16x32_bf16 v[52:55], v[156:159], v[180:183], v[52:55]
	v_mfma_f32_16x16x32_bf16 v[48:51], v[164:167], v[180:183], v[48:51]
	v_mfma_f32_16x16x32_bf16 v[36:39], v[156:159], v[188:191], v[36:39]
	v_mfma_f32_16x16x32_bf16 v[32:35], v[164:167], v[188:191], v[32:35]
	v_mfma_f32_16x16x32_bf16 v[20:23], v[156:159], v[196:199], v[20:23]
	v_mfma_f32_16x16x32_bf16 v[16:19], v[164:167], v[196:199], v[16:19]
	v_mfma_f32_16x16x32_bf16 v[60:63], v[160:163], v[176:179], v[60:63]
	v_mfma_f32_16x16x32_bf16 v[56:59], v[168:171], v[176:179], v[56:59]
	v_mfma_f32_16x16x32_bf16 v[52:55], v[160:163], v[184:187], v[52:55]
	v_mfma_f32_16x16x32_bf16 v[48:51], v[168:171], v[184:187], v[48:51]
	v_mfma_f32_16x16x32_bf16 v[36:39], v[160:163], v[192:195], v[36:39]
	v_mfma_f32_16x16x32_bf16 v[32:35], v[168:171], v[192:195], v[32:35]
	v_mfma_f32_16x16x32_bf16 v[20:23], v[160:163], v[200:203], v[20:23]
	v_mfma_f32_16x16x32_bf16 v[16:19], v[168:171], v[200:203], v[16:19]
	s_setprio 1
	s_barrier
	s_add_u32 s78, s36, 0x100000
	s_addc_u32 s79, s37, 0
	s_add_i32 s80, s63, s43
	v_lshl_add_u64 v[156:157], s[78:79], 0, v[134:135]
	s_mov_b32 m0, s80
	s_nop 0
	global_load_lds_dwordx4 v[156:157], off
	v_lshl_add_u64 v[156:157], s[78:79], 0, v[130:131]
	s_add_i32 m0, s80, 0x2000
	s_nop 0
	global_load_lds_dwordx4 v[156:157], off
	s_waitcnt vmcnt(6)
	s_barrier
	s_setprio 0
	v_mfma_f32_16x16x32_bf16 v[44:47], v[204:207], v[172:175], v[44:47]
	v_mfma_f32_16x16x32_bf16 v[40:43], v[212:215], v[172:175], v[40:43]
	v_mfma_f32_16x16x32_bf16 v[28:31], v[204:207], v[180:183], v[28:31]
	v_mfma_f32_16x16x32_bf16 v[24:27], v[212:215], v[180:183], v[24:27]
	v_mfma_f32_16x16x32_bf16 v[12:15], v[204:207], v[188:191], v[12:15]
	v_mfma_f32_16x16x32_bf16 v[8:11], v[212:215], v[188:191], v[8:11]
	v_mfma_f32_16x16x32_bf16 v[4:7], v[204:207], v[196:199], v[4:7]
	v_mfma_f32_16x16x32_bf16 v[0:3], v[212:215], v[196:199], v[0:3]
	v_mfma_f32_16x16x32_bf16 v[44:47], v[208:211], v[176:179], v[44:47]
	v_mfma_f32_16x16x32_bf16 v[40:43], v[216:219], v[176:179], v[40:43]
	v_mfma_f32_16x16x32_bf16 v[28:31], v[208:211], v[184:187], v[28:31]
	v_mfma_f32_16x16x32_bf16 v[24:27], v[216:219], v[184:187], v[24:27]
	v_mfma_f32_16x16x32_bf16 v[12:15], v[208:211], v[192:195], v[12:15]
	v_mfma_f32_16x16x32_bf16 v[8:11], v[216:219], v[192:195], v[8:11]
	v_mfma_f32_16x16x32_bf16 v[4:7], v[208:211], v[200:203], v[4:7]
	v_mfma_f32_16x16x32_bf16 v[0:3], v[216:219], v[200:203], v[0:3]
	s_setprio 1
	s_add_i32 s78, 0, 0x18000
	v_add_u32_e32 v168, s78, v151
	s_barrier
	ds_read_b128 v[156:159], v168
	ds_read_b128 v[160:163], v168 offset:1024
	ds_read_b128 v[164:167], v168 offset:2048
	ds_read_b128 v[168:171], v168 offset:3072
	s_add_u32 s38, s38, 0x100000
	s_addc_u32 s39, s39, 0
	s_mov_b32 m0, s54
	v_lshl_add_u64 v[204:205], s[38:39], 0, v[136:137]
	ds_read_b128 v[172:175], v154 offset:32768
	ds_read_b128 v[176:179], v154 offset:33792
	ds_read_b128 v[180:183], v154 offset:34816
	ds_read_b128 v[184:187], v154 offset:35840
	ds_read_b128 v[188:191], v154 offset:36864
	ds_read_b128 v[192:195], v154 offset:37888
	ds_read_b128 v[196:199], v154 offset:38912
	ds_read_b128 v[200:203], v154 offset:39936
	global_load_lds_dwordx4 v[204:205], off
	v_lshl_add_u64 v[204:205], s[38:39], 0, v[132:133]
	s_mov_b32 m0, s55
	s_nop 0
	global_load_lds_dwordx4 v[204:205], off
	s_waitcnt lgkmcnt(8)
	s_barrier
	s_waitcnt lgkmcnt(0)
	s_setprio 0
	s_waitcnt lgkmcnt(0)
	v_mfma_f32_16x16x32_bf16 v[124:127], v[156:159], v[172:175], v[124:127]
	v_mfma_f32_16x16x32_bf16 v[120:123], v[164:167], v[172:175], v[120:123]
	v_mfma_f32_16x16x32_bf16 v[116:119], v[156:159], v[180:183], v[116:119]
	v_mfma_f32_16x16x32_bf16 v[112:115], v[164:167], v[180:183], v[112:115]
	v_mfma_f32_16x16x32_bf16 v[100:103], v[156:159], v[188:191], v[100:103]
	v_mfma_f32_16x16x32_bf16 v[96:99], v[164:167], v[188:191], v[96:99]
	v_mfma_f32_16x16x32_bf16 v[84:87], v[156:159], v[196:199], v[84:87]
	v_mfma_f32_16x16x32_bf16 v[80:83], v[164:167], v[196:199], v[80:83]
	v_mfma_f32_16x16x32_bf16 v[124:127], v[160:163], v[176:179], v[124:127]
	v_mfma_f32_16x16x32_bf16 v[120:123], v[168:171], v[176:179], v[120:123]
	v_mfma_f32_16x16x32_bf16 v[116:119], v[160:163], v[184:187], v[116:119]
	v_mfma_f32_16x16x32_bf16 v[112:115], v[168:171], v[184:187], v[112:115]
	v_mfma_f32_16x16x32_bf16 v[100:103], v[160:163], v[192:195], v[100:103]
	v_mfma_f32_16x16x32_bf16 v[96:99], v[168:171], v[192:195], v[96:99]
	v_mfma_f32_16x16x32_bf16 v[84:87], v[160:163], v[200:203], v[84:87]
	v_mfma_f32_16x16x32_bf16 v[80:83], v[168:171], v[200:203], v[80:83]
	s_setprio 1
	s_barrier
	s_add_i32 s38, 0, 0x1c000
	s_add_i32 s39, s78, s43
	v_add_u32_e32 v216, s38, v151
	v_lshl_add_u64 v[220:221], v[220:221], 0, s[8:9]
	s_mov_b32 m0, s39
	ds_read_b128 v[204:207], v216
	ds_read_b128 v[208:211], v216 offset:1024
	ds_read_b128 v[212:215], v216 offset:2048
	ds_read_b128 v[216:219], v216 offset:3072
	global_load_lds_dwordx4 v[220:221], off
	v_lshl_add_u64 v[220:221], v[222:223], 0, s[8:9]
	s_add_i32 m0, s39, 0x2000
	s_nop 0
	global_load_lds_dwordx4 v[220:221], off
	s_barrier
	s_waitcnt lgkmcnt(0)
	s_setprio 0
	s_waitcnt lgkmcnt(0)
	v_mfma_f32_16x16x32_bf16 v[108:111], v[204:207], v[172:175], v[108:111]
	v_mfma_f32_16x16x32_bf16 v[104:107], v[212:215], v[172:175], v[104:107]
	v_mfma_f32_16x16x32_bf16 v[92:95], v[204:207], v[180:183], v[92:95]
	v_mfma_f32_16x16x32_bf16 v[88:91], v[212:215], v[180:183], v[88:91]
	v_mfma_f32_16x16x32_bf16 v[76:79], v[204:207], v[188:191], v[76:79]
	v_mfma_f32_16x16x32_bf16 v[72:75], v[212:215], v[188:191], v[72:75]
	v_mfma_f32_16x16x32_bf16 v[68:71], v[204:207], v[196:199], v[68:71]
	v_mfma_f32_16x16x32_bf16 v[64:67], v[212:215], v[196:199], v[64:67]
	v_mfma_f32_16x16x32_bf16 v[108:111], v[208:211], v[176:179], v[108:111]
	v_mfma_f32_16x16x32_bf16 v[104:107], v[216:219], v[176:179], v[104:107]
	v_mfma_f32_16x16x32_bf16 v[92:95], v[208:211], v[184:187], v[92:95]
	v_mfma_f32_16x16x32_bf16 v[88:91], v[216:219], v[184:187], v[88:91]
	v_mfma_f32_16x16x32_bf16 v[76:79], v[208:211], v[192:195], v[76:79]
	v_mfma_f32_16x16x32_bf16 v[72:75], v[216:219], v[192:195], v[72:75]
	v_mfma_f32_16x16x32_bf16 v[68:71], v[208:211], v[200:203], v[68:71]
	v_mfma_f32_16x16x32_bf16 v[64:67], v[216:219], v[200:203], v[64:67]
	s_setprio 1
	s_mov_b32 m0, s57
	v_lshl_add_u64 v[220:221], v[224:225], 0, s[8:9]
	s_barrier
	ds_read_b128 v[172:175], v154 offset:49152
	ds_read_b128 v[176:179], v154 offset:50176
	ds_read_b128 v[180:183], v154 offset:51200
	ds_read_b128 v[184:187], v154 offset:52224
	ds_read_b128 v[188:191], v154 offset:53248
	ds_read_b128 v[192:195], v154 offset:54272
	ds_read_b128 v[196:199], v154 offset:55296
	ds_read_b128 v[200:203], v154 offset:56320
	global_load_lds_dwordx4 v[220:221], off
	v_lshl_add_u64 v[220:221], v[226:227], 0, s[8:9]
	s_mov_b32 m0, s60
	s_nop 0
	global_load_lds_dwordx4 v[220:221], off
	s_barrier
	s_waitcnt lgkmcnt(0)
	s_setprio 0
	s_waitcnt lgkmcnt(0)
	v_mfma_f32_16x16x32_bf16 v[60:63], v[156:159], v[172:175], v[60:63]
	v_mfma_f32_16x16x32_bf16 v[56:59], v[164:167], v[172:175], v[56:59]
	v_mfma_f32_16x16x32_bf16 v[52:55], v[156:159], v[180:183], v[52:55]
	v_mfma_f32_16x16x32_bf16 v[48:51], v[164:167], v[180:183], v[48:51]
	v_mfma_f32_16x16x32_bf16 v[36:39], v[156:159], v[188:191], v[36:39]
	v_mfma_f32_16x16x32_bf16 v[32:35], v[164:167], v[188:191], v[32:35]
	v_mfma_f32_16x16x32_bf16 v[20:23], v[156:159], v[196:199], v[20:23]
	v_mfma_f32_16x16x32_bf16 v[16:19], v[164:167], v[196:199], v[16:19]
	v_mfma_f32_16x16x32_bf16 v[60:63], v[160:163], v[176:179], v[60:63]
	v_mfma_f32_16x16x32_bf16 v[56:59], v[168:171], v[176:179], v[56:59]
	v_mfma_f32_16x16x32_bf16 v[52:55], v[160:163], v[184:187], v[52:55]
	v_mfma_f32_16x16x32_bf16 v[48:51], v[168:171], v[184:187], v[48:51]
	v_mfma_f32_16x16x32_bf16 v[36:39], v[160:163], v[192:195], v[36:39]
	v_mfma_f32_16x16x32_bf16 v[32:35], v[168:171], v[192:195], v[32:35]
	v_mfma_f32_16x16x32_bf16 v[20:23], v[160:163], v[200:203], v[20:23]
	v_mfma_f32_16x16x32_bf16 v[16:19], v[168:171], v[200:203], v[16:19]
	s_setprio 1
	s_barrier
	s_add_u32 s36, s36, 0x100080
	s_addc_u32 s37, s37, 0
	s_add_i32 s38, s38, s43
	v_lshl_add_u64 v[156:157], s[36:37], 0, v[134:135]
	s_mov_b32 m0, s38
	s_nop 0
	global_load_lds_dwordx4 v[156:157], off
	v_lshl_add_u64 v[156:157], s[36:37], 0, v[130:131]
	s_add_i32 m0, s38, 0x2000
	s_nop 0
	global_load_lds_dwordx4 v[156:157], off
	s_waitcnt vmcnt(6)
	s_barrier
	s_setprio 0
	v_mfma_f32_16x16x32_bf16 v[44:47], v[204:207], v[172:175], v[44:47]
	v_mfma_f32_16x16x32_bf16 v[40:43], v[212:215], v[172:175], v[40:43]
	v_mfma_f32_16x16x32_bf16 v[28:31], v[204:207], v[180:183], v[28:31]
	v_mfma_f32_16x16x32_bf16 v[24:27], v[212:215], v[180:183], v[24:27]
	v_mfma_f32_16x16x32_bf16 v[12:15], v[204:207], v[188:191], v[12:15]
	v_mfma_f32_16x16x32_bf16 v[8:11], v[212:215], v[188:191], v[8:11]
	v_mfma_f32_16x16x32_bf16 v[4:7], v[204:207], v[196:199], v[4:7]
	v_mfma_f32_16x16x32_bf16 v[0:3], v[212:215], v[196:199], v[0:3]
	v_mfma_f32_16x16x32_bf16 v[44:47], v[208:211], v[176:179], v[44:47]
	v_mfma_f32_16x16x32_bf16 v[40:43], v[216:219], v[176:179], v[40:43]
	v_mfma_f32_16x16x32_bf16 v[28:31], v[208:211], v[184:187], v[28:31]
	v_mfma_f32_16x16x32_bf16 v[24:27], v[216:219], v[184:187], v[24:27]
	v_mfma_f32_16x16x32_bf16 v[12:15], v[208:211], v[192:195], v[12:15]
	v_mfma_f32_16x16x32_bf16 v[8:11], v[216:219], v[192:195], v[8:11]
	v_mfma_f32_16x16x32_bf16 v[4:7], v[208:211], v[200:203], v[4:7]
	v_mfma_f32_16x16x32_bf16 v[0:3], v[216:219], v[200:203], v[0:3]
	s_setprio 1
	s_add_i32 s77, s77, 2
	s_add_u32 s34, s34, 0x100
	s_addc_u32 s35, s35, 0
	s_add_u32 s75, s75, 0x100
	s_addc_u32 s76, s76, 0
	s_cmp_gt_u32 s77, 61
	s_barrier
	s_cbranch_scc0 .LBB0_1384
	v_lshl_add_u32 v156, s18, 8, v150
	v_lshl_or_b32 v158, s72, 8, v152
	v_ashrrev_i32_e32 v157, 31, v156
	v_lshlrev_b64 v[160:161], 11, v[156:157]
	v_ashrrev_i32_e32 v159, 31, v158
	v_lshl_add_u64 v[160:161], s[44:45], 0, v[160:161]
	v_cvt_pk_bf16_f32 v124, v124, v125
	v_cvt_pk_bf16_f32 v125, v126, v127
	v_cvt_pk_bf16_f32 v126, v120, v121
	v_lshlrev_b64 v[120:121], 1, v[158:159]
	v_cvt_pk_bf16_f32 v127, v122, v123
	v_lshl_add_u64 v[122:123], v[160:161], 0, v[120:121]
	v_cvt_pk_bf16_f32 v108, v108, v109
	v_cvt_pk_bf16_f32 v109, v110, v111
	v_cvt_pk_bf16_f32 v110, v104, v105
	v_or_b32_e32 v104, 16, v156
	v_cvt_pk_bf16_f32 v60, v60, v61
	v_cvt_pk_bf16_f32 v61, v62, v63
	v_cvt_pk_bf16_f32 v63, v58, v59
	v_add_co_u32_e32 v58, vcc, s64, v122
	v_ashrrev_i32_e32 v105, 31, v104
	v_cvt_pk_bf16_f32 v62, v56, v57
	v_lshl_add_u64 v[56:57], v[122:123], 0, s[10:11]
	v_addc_co_u32_e32 v59, vcc, 0, v123, vcc
	v_cvt_pk_bf16_f32 v44, v44, v45
	v_cvt_pk_bf16_f32 v45, v46, v47
	v_cvt_pk_bf16_f32 v46, v40, v41
	v_cvt_pk_bf16_f32 v47, v42, v43
	v_cvt_pk_bf16_f32 v111, v106, v107
	v_lshlrev_b64 v[104:105], 11, v[104:105]
	v_cvt_pk_bf16_f32 v92, v92, v93
	v_cvt_pk_bf16_f32 v93, v94, v95
	v_cvt_pk_bf16_f32 v94, v88, v89
	v_or_b32_e32 v88, 32, v156
	global_store_dwordx4 v[56:57], v[44:47], off offset:256
	global_store_dwordx4 v[122:123], v[108:111], off offset:256
	v_ashrrev_i32_e32 v89, 31, v88
	v_add_co_u32_e32 v46, vcc, s65, v122
	v_lshl_add_u64 v[108:109], s[44:45], 0, v[104:105]
	v_lshl_add_u64 v[44:45], v[122:123], 0, s[12:13]
	v_addc_co_u32_e32 v47, vcc, 0, v123, vcc
	v_cvt_pk_bf16_f32 v28, v28, v29
	v_cvt_pk_bf16_f32 v29, v30, v31
	v_cvt_pk_bf16_f32 v30, v24, v25
	v_cvt_pk_bf16_f32 v31, v26, v27
	v_lshl_add_u64 v[108:109], v[108:109], 0, v[120:121]
	v_cvt_pk_bf16_f32 v95, v90, v91
	v_lshlrev_b64 v[88:89], 11, v[88:89]
	v_cvt_pk_bf16_f32 v76, v76, v77
	v_cvt_pk_bf16_f32 v77, v78, v79
	v_cvt_pk_bf16_f32 v78, v72, v73
	v_or_b32_e32 v72, 48, v156
	global_store_dwordx4 v[44:45], v[28:31], off offset:256
	global_store_dwordx4 v[108:109], v[92:95], off offset:256
	v_ashrrev_i32_e32 v73, 31, v72
	v_add_co_u32_e32 v30, vcc, s70, v122
	v_lshl_add_u64 v[92:93], s[44:45], 0, v[88:89]
	v_lshl_add_u64 v[28:29], v[122:123], 0, s[14:15]
	v_addc_co_u32_e32 v31, vcc, 0, v123, vcc
	v_cvt_pk_bf16_f32 v12, v12, v13
	v_cvt_pk_bf16_f32 v13, v14, v15
	v_cvt_pk_bf16_f32 v14, v8, v9
	v_cvt_pk_bf16_f32 v15, v10, v11
	v_lshl_add_u64 v[92:93], v[92:93], 0, v[120:121]
	v_cvt_pk_bf16_f32 v79, v74, v75
	v_lshlrev_b64 v[72:73], 11, v[72:73]
	global_store_dwordx4 v[28:29], v[12:15], off offset:256
	global_store_dwordx4 v[92:93], v[76:79], off offset:256
	v_cvt_pk_bf16_f32 v104, v116, v117
	v_add_co_u32_e32 v14, vcc, s71, v122
	v_lshl_add_u64 v[76:77], s[44:45], 0, v[72:73]
	s_nop 0
	v_addc_co_u32_e32 v15, vcc, 0, v123, vcc
	v_cvt_pk_bf16_f32 v105, v118, v119
	v_cvt_pk_bf16_f32 v106, v112, v113
	v_cvt_pk_bf16_f32 v107, v114, v115
	v_cvt_pk_bf16_f32 v88, v100, v101
	v_cvt_pk_bf16_f32 v89, v102, v103
	v_cvt_pk_bf16_f32 v90, v96, v97
	v_cvt_pk_bf16_f32 v91, v98, v99
	v_cvt_pk_bf16_f32 v72, v84, v85
	v_cvt_pk_bf16_f32 v73, v86, v87
	v_cvt_pk_bf16_f32 v74, v80, v81
	v_cvt_pk_bf16_f32 v75, v82, v83
	v_lshl_add_u64 v[76:77], v[76:77], 0, v[120:121]
	v_cvt_pk_bf16_f32 v68, v68, v69
	v_cvt_pk_bf16_f32 v69, v70, v71
	v_cvt_pk_bf16_f32 v70, v64, v65
	v_cvt_pk_bf16_f32 v71, v66, v67
	v_cvt_pk_bf16_f32 v40, v52, v53
	v_cvt_pk_bf16_f32 v41, v54, v55
	v_cvt_pk_bf16_f32 v42, v48, v49
	v_cvt_pk_bf16_f32 v43, v50, v51
	v_cvt_pk_bf16_f32 v24, v36, v37
	v_cvt_pk_bf16_f32 v25, v38, v39
	v_cvt_pk_bf16_f32 v26, v32, v33
	v_cvt_pk_bf16_f32 v27, v34, v35
	v_cvt_pk_bf16_f32 v8, v20, v21
	v_cvt_pk_bf16_f32 v9, v22, v23
	v_cvt_pk_bf16_f32 v10, v16, v17
	v_cvt_pk_bf16_f32 v11, v18, v19
	v_lshl_add_u64 v[12:13], v[122:123], 0, s[16:17]
	v_cvt_pk_bf16_f32 v4, v4, v5
	v_cvt_pk_bf16_f32 v5, v6, v7
	v_cvt_pk_bf16_f32 v6, v0, v1
	v_cvt_pk_bf16_f32 v7, v2, v3
	s_and_b64 vcc, exec, s[4:5]
	s_mov_b32 s72, s20
	s_mov_b32 s18, s26
	s_mov_b64 s[36:37], s[30:31]
	s_mov_b64 s[34:35], s[28:29]
	global_store_dwordx4 v[122:123], v[124:127], off
	global_store_dwordx4 v[108:109], v[104:107], off
	global_store_dwordx4 v[92:93], v[88:91], off
	global_store_dwordx4 v[76:77], v[72:75], off
	global_store_dwordx4 v[76:77], v[68:71], off offset:256
	global_store_dwordx4 v[58:59], v[60:63], off
	global_store_dwordx4 v[46:47], v[40:43], off
	global_store_dwordx4 v[30:31], v[24:27], off
	global_store_dwordx4 v[14:15], v[8:11], off
	global_store_dwordx4 v[12:13], v[4:7], off offset:256
	s_cbranch_vccz .LBB0_1381
	s_waitcnt vmcnt(0)
	s_cmpk_gt_u32 s40, 0xff
	s_cbranch_scc1 .LBB0_1388
	s_barrier
